# all cross-CU data stores sc1 write-through, grid barrier buffer_wbl2 dropped (on top of early invalidate)
# baseline (speedup 1.0000x reference)
; __device__ __forceinline__ void p0_transpose_item(const float* W, int ld, int K, int ncols, bf16* WT, LAS float* scr, int item, int lane) {
;     const int nblk = ncols / 32, kb = item / nblk, nb = item % nblk, k0 = 64 * kb, n0 = 32 * nb;
; #pragma unroll 8
;     for (int i = 0; i < 32; ++i) { const int kk = 2 * i + (lane >> 5); scr[kk * 33 + (lane & 31)] = W[(size_t)(k0 + kk) * ld + n0 + (lane & 31)]; }
.LBB0_20:
	s_lshl_b32 s27, s23, 1
	s_lshl_b32 s28, s24, 1
	v_or_b32_e32 v4, s28, v26
	s_add_i32 s30, s27, 4
	s_add_i32 s31, s28, 4
	v_mov_b32_e32 v35, v5
	s_add_i32 s34, s28, 8
	v_lshlrev_b64 v[48:49], 12, v[4:5]
	v_or_b32_e32 v34, s30, v3
	v_or_b32_e32 v4, s31, v26
	v_mov_b32_e32 v33, v5
	v_or_b32_e32 v32, s27, v3
	s_add_i32 s36, s28, 12
	v_lshlrev_b64 v[34:35], 12, v[34:35]
	v_lshlrev_b64 v[50:51], 12, v[4:5]
	v_or_b32_e32 v4, s34, v26
	s_add_i32 s33, s27, 8
	s_add_i32 s35, s27, 12
	s_add_i32 s38, s28, 16
	v_lshlrev_b64 v[32:33], 12, v[32:33]
	v_lshl_add_u64 v[48:49], v[24:25], 0, v[48:49]
	v_lshl_add_u64 v[34:35], v[24:25], 0, v[34:35]
	v_lshlrev_b64 v[52:53], 12, v[4:5]
	v_or_b32_e32 v4, s36, v26
	v_mov_b32_e32 v37, v5
	v_mov_b32_e32 v39, v5
	s_add_i32 s40, s28, 20
	v_or_b32_e32 v36, s33, v3
	v_or_b32_e32 v38, s35, v3
	v_lshl_add_u64 v[32:33], v[24:25], 0, v[32:33]
	v_lshl_add_u64 v[50:51], v[24:25], 0, v[50:51]
	global_load_dword v21, v[48:49], off
	global_load_dword v23, v[32:33], off
	global_load_dword v64, v[50:51], off
	global_load_dword v65, v[34:35], off
	v_lshlrev_b64 v[34:35], 12, v[4:5]
	v_or_b32_e32 v4, s38, v26
	s_add_i32 s37, s27, 16
	s_add_i32 s39, s27, 20
	s_add_i32 s42, s28, 24
	v_lshlrev_b64 v[36:37], 12, v[36:37]
	v_lshlrev_b64 v[38:39], 12, v[38:39]
	v_lshl_add_u64 v[32:33], v[24:25], 0, v[52:53]
	v_lshl_add_u64 v[34:35], v[24:25], 0, v[34:35]
	v_lshlrev_b64 v[48:49], 12, v[4:5]
	v_or_b32_e32 v4, s40, v26
	v_mov_b32_e32 v41, v5
	v_mov_b32_e32 v43, v5
	s_add_i32 s41, s27, 24
	s_add_i32 s43, s27, 28
	s_add_i32 s44, s28, 28
	v_or_b32_e32 v40, s37, v3
	v_or_b32_e32 v42, s39, v3
	v_lshl_add_u64 v[36:37], v[24:25], 0, v[36:37]
	v_lshl_add_u64 v[38:39], v[24:25], 0, v[38:39]
	global_load_dword v66, v[32:33], off
	global_load_dword v67, v[36:37], off
	global_load_dword v68, v[34:35], off
	global_load_dword v69, v[38:39], off
	v_lshlrev_b64 v[34:35], 12, v[4:5]
	v_or_b32_e32 v4, s42, v26
	v_mov_b32_e32 v45, v5
	v_mov_b32_e32 v47, v5
	v_or_b32_e32 v44, s41, v3
	v_or_b32_e32 v46, s43, v3
	v_lshlrev_b64 v[40:41], 12, v[40:41]
	v_lshlrev_b64 v[42:43], 12, v[42:43]
	v_lshl_add_u64 v[32:33], v[24:25], 0, v[48:49]
	v_lshl_add_u64 v[34:35], v[24:25], 0, v[34:35]
	v_lshlrev_b64 v[36:37], 12, v[4:5]
	v_or_b32_e32 v4, s44, v26
	v_lshlrev_b64 v[44:45], 12, v[44:45]
	v_lshlrev_b64 v[46:47], 12, v[46:47]
	v_lshl_add_u64 v[40:41], v[24:25], 0, v[40:41]
	v_lshl_add_u64 v[42:43], v[24:25], 0, v[42:43]
	global_load_dword v70, v[32:33], off
	global_load_dword v71, v[40:41], off
	global_load_dword v72, v[34:35], off
	global_load_dword v73, v[42:43], off
	v_lshl_add_u64 v[32:33], v[24:25], 0, v[36:37]
	v_lshlrev_b64 v[34:35], 12, v[4:5]
	v_lshl_add_u64 v[44:45], v[24:25], 0, v[44:45]
	v_lshl_add_u64 v[46:47], v[24:25], 0, v[46:47]
	v_lshl_add_u64 v[34:35], v[24:25], 0, v[34:35]
	global_load_dword v4, v[32:33], off
	global_load_dword v74, v[44:45], off
	global_load_dword v75, v[34:35], off
	global_load_dword v76, v[46:47], off
	v_or_b32_e32 v34, s27, v1
	v_or_b32_e32 v32, s28, v2
	s_add_i32 s24, s24, 16
	s_add_i32 s23, s23, 16
	s_add_i32 s25, s25, -16
	v_mad_u64_u32 v[32:33], s[28:29], v32, s13, v[8:9]
	v_mad_u64_u32 v[34:35], s[28:29], v34, s13, v[8:9]
	v_or_b32_e32 v33, s30, v1
	v_or_b32_e32 v35, s31, v2
	v_or_b32_e32 v42, s33, v1
	v_or_b32_e32 v40, s34, v2
	v_or_b32_e32 v46, s35, v1
	v_or_b32_e32 v44, s36, v2
	v_or_b32_e32 v50, s37, v1
	v_or_b32_e32 v48, s38, v2
	v_or_b32_e32 v54, s39, v1
	v_or_b32_e32 v52, s40, v2
	v_or_b32_e32 v58, s41, v1
	v_or_b32_e32 v56, s42, v2
	v_or_b32_e32 v62, s43, v1
	v_or_b32_e32 v60, s44, v2
	s_cmp_lg_u32 s25, 0
	v_mad_u64_u32 v[36:37], s[28:29], v35, s13, v[8:9]
	v_mad_u64_u32 v[38:39], s[28:29], v33, s13, v[8:9]
	v_mad_u64_u32 v[40:41], s[28:29], v40, s13, v[8:9]
	v_mad_u64_u32 v[42:43], s[28:29], v42, s13, v[8:9]
	v_mad_u64_u32 v[44:45], s[28:29], v44, s13, v[8:9]
	v_mad_u64_u32 v[46:47], s[28:29], v46, s13, v[8:9]
	v_mad_u64_u32 v[48:49], s[28:29], v48, s13, v[8:9]
	v_mad_u64_u32 v[50:51], s[28:29], v50, s13, v[8:9]
	v_mad_u64_u32 v[52:53], s[28:29], v52, s13, v[8:9]
	v_mad_u64_u32 v[54:55], s[28:29], v54, s13, v[8:9]
	v_mad_u64_u32 v[56:57], s[28:29], v56, s13, v[8:9]
	v_mad_u64_u32 v[58:59], s[28:29], v58, s13, v[8:9]
	v_mad_u64_u32 v[60:61], s[28:29], v60, s13, v[8:9]
	v_mad_u64_u32 v[62:63], s[28:29], v62, s13, v[8:9]
	s_waitcnt vmcnt(15)
	ds_write_b32 v32, v21
	s_waitcnt vmcnt(14)
	ds_write_b32 v34, v23
	s_waitcnt vmcnt(13)
	ds_write_b32 v36, v64
	s_waitcnt vmcnt(12)
	ds_write_b32 v38, v65
	s_waitcnt vmcnt(11)
	ds_write_b32 v40, v66
	s_waitcnt vmcnt(10)
	ds_write_b32 v42, v67
	s_waitcnt vmcnt(9)
	ds_write_b32 v44, v68
	s_waitcnt vmcnt(8)
	ds_write_b32 v46, v69
	s_waitcnt vmcnt(7)
	ds_write_b32 v48, v70
	s_waitcnt vmcnt(6)
	ds_write_b32 v50, v71
	s_waitcnt vmcnt(5)
	ds_write_b32 v52, v72
	s_waitcnt vmcnt(4)
	ds_write_b32 v54, v73
	s_waitcnt vmcnt(3)
	ds_write_b32 v56, v4
	s_waitcnt vmcnt(2)
	ds_write_b32 v58, v74
	s_waitcnt vmcnt(1)
	ds_write_b32 v60, v75
	s_waitcnt vmcnt(0)
	ds_write_b32 v62, v76
	s_cbranch_scc1 .LBB0_20
; #define GAS __attribute__((address_space(1)))
; #define LAS __attribute__((address_space(3)))
; #define LDS_WAIT() asm volatile("s_waitcnt lgkmcnt(0)" ::: "memory")
; __device__ __forceinline__ unsigned f2bf(float f) { unsigned u = __builtin_bit_cast(unsigned, f); return (u + 0x7fffu + ((u >> 16) & 1u)) >> 16; }
; __device__ __forceinline__ unsigned pk2(float lo, float hi) { return f2bf(lo) | (f2bf(hi) << 16); }
; __device__ __forceinline__ void p0_transpose_item(const float* W, int ld, int K, int ncols, bf16* WT, LAS float* scr, int item, int lane) {
;     ...
;     const int c = lane & 7;
; #pragma unroll
;     for (int j = 0; j < 4; ++j) { const int n = (lane >> 3) + 8 * j; const LAS float* s = scr + (8 * c) * 33 + n;
;         v4u o; o.x = pk2(s[0 * 33], s[1 * 33]); o.y = pk2(s[2 * 33], s[3 * 33]); o.z = pk2(s[4 * 33], s[5 * 33]); o.w = pk2(s[6 * 33], s[7 * 33]);
;         *(GAS v4u*)(WT + (size_t)(n0 + n) * K + k0 + 8 * c) = o; }
;     LDS_WAIT(); asm volatile("" ::: "memory");
	s_waitcnt lgkmcnt(0)
	ds_read2_b32 v[24:25], v28 offset1:8
	ds_read2_b32 v[38:39], v28 offset0:33 offset1:41
	ds_read2_b32 v[40:41], v28 offset0:66 offset1:74
	ds_read2_b32 v[42:43], v28 offset0:99 offset1:107
	ds_read2_b32 v[44:45], v28 offset0:132 offset1:140
	ds_read2_b32 v[46:47], v28 offset0:165 offset1:173
	s_waitcnt lgkmcnt(5)
	v_bfe_u32 v3, v24, 16, 1
	v_add3_u32 v3, v24, v3, s15
	s_waitcnt lgkmcnt(4)
	v_bfe_u32 v4, v38, 16, 1
	v_lshrrev_b32_e32 v3, 16, v3
	v_add3_u32 v4, v38, v4, s15
	v_and_or_b32 v32, v4, s16, v3
	s_waitcnt lgkmcnt(3)
	v_bfe_u32 v3, v40, 16, 1
	v_add3_u32 v3, v40, v3, s15
	s_waitcnt lgkmcnt(2)
	v_bfe_u32 v4, v42, 16, 1
	ds_read2_b32 v[48:49], v28 offset0:198 offset1:206
	v_lshrrev_b32_e32 v3, 16, v3
	v_add3_u32 v4, v42, v4, s15
	ds_read2_b32 v[50:51], v28 offset0:231 offset1:239
	v_and_or_b32 v33, v4, s16, v3
	s_waitcnt lgkmcnt(3)
	v_bfe_u32 v3, v44, 16, 1
	v_add3_u32 v3, v44, v3, s15
	s_waitcnt lgkmcnt(2)
	v_bfe_u32 v4, v46, 16, 1
	v_lshrrev_b32_e32 v3, 16, v3
	v_add3_u32 v4, v46, v4, s15
	v_and_or_b32 v34, v4, s16, v3
	s_waitcnt lgkmcnt(1)
	v_bfe_u32 v3, v48, 16, 1
	v_add3_u32 v3, v48, v3, s15
	s_waitcnt lgkmcnt(0)
	v_bfe_u32 v4, v50, 16, 1
	v_lshrrev_b32_e32 v3, 16, v3
	v_add3_u32 v4, v50, v4, s15
	s_lshl_b32 s6, s6, 1
	v_and_or_b32 v35, v4, s16, v3
	v_or_b32_e32 v3, s22, v27
	v_lshl_add_u64 v[36:37], v[10:11], 0, s[6:7]
	v_lshlrev_b32_e32 v4, 11, v3
	v_bfe_u32 v3, v25, 16, 1
	v_lshl_add_u64 v[52:53], v[36:37], 0, v[4:5]
	v_add3_u32 v3, v25, v3, s15
	v_bfe_u32 v4, v39, 16, 1
	v_lshrrev_b32_e32 v3, 16, v3
	v_add3_u32 v4, v39, v4, s15
	global_store_dwordx4 v[52:53], v[32:35], off sc1
	ds_read2_b32 v[24:25], v28 offset0:16 offset1:24
	s_nop 0
	v_and_or_b32 v32, v4, s16, v3
	v_bfe_u32 v3, v41, 16, 1
	v_add3_u32 v3, v41, v3, s15
	v_bfe_u32 v4, v43, 16, 1
	v_lshrrev_b32_e32 v3, 16, v3
	v_add3_u32 v4, v43, v4, s15
	v_and_or_b32 v33, v4, s16, v3
	v_bfe_u32 v3, v45, 16, 1
	v_add3_u32 v3, v45, v3, s15
	v_bfe_u32 v4, v47, 16, 1
	v_lshrrev_b32_e32 v3, 16, v3
	v_add3_u32 v4, v47, v4, s15
	v_and_or_b32 v34, v4, s16, v3
	v_bfe_u32 v3, v49, 16, 1
	v_add3_u32 v3, v49, v3, s15
	v_bfe_u32 v4, v51, 16, 1
	v_lshrrev_b32_e32 v3, 16, v3
	v_add3_u32 v4, v51, v4, s15
	v_and_or_b32 v35, v4, s16, v3
	v_or_b32_e32 v3, s22, v29
	v_lshlrev_b32_e32 v4, 11, v3
	v_lshl_add_u64 v[38:39], v[36:37], 0, v[4:5]
	global_store_dwordx4 v[38:39], v[32:35], off sc1
	ds_read2_b32 v[38:39], v28 offset0:49 offset1:57
	ds_read2_b32 v[40:41], v28 offset0:82 offset1:90
	ds_read2_b32 v[42:43], v28 offset0:115 offset1:123
	s_waitcnt lgkmcnt(3)
	v_bfe_u32 v3, v24, 16, 1
	v_add3_u32 v3, v24, v3, s15
	s_waitcnt lgkmcnt(2)
	v_bfe_u32 v4, v38, 16, 1
	ds_read2_b32 v[44:45], v28 offset0:148 offset1:156
	v_lshrrev_b32_e32 v3, 16, v3
	v_add3_u32 v4, v38, v4, s15
	ds_read2_b32 v[46:47], v28 offset0:181 offset1:189
	v_and_or_b32 v32, v4, s16, v3
	s_waitcnt lgkmcnt(3)
	v_bfe_u32 v3, v40, 16, 1
	v_add3_u32 v3, v40, v3, s15
	s_waitcnt lgkmcnt(2)
	v_bfe_u32 v4, v42, 16, 1
	ds_read2_b32 v[48:49], v28 offset0:214 offset1:222
	v_lshrrev_b32_e32 v3, 16, v3
	v_add3_u32 v4, v42, v4, s15
	ds_read2_b32 v[50:51], v28 offset0:247 offset1:255
	v_and_or_b32 v33, v4, s16, v3
	s_waitcnt lgkmcnt(3)
	v_bfe_u32 v3, v44, 16, 1
	v_add3_u32 v3, v44, v3, s15
	s_waitcnt lgkmcnt(2)
	v_bfe_u32 v4, v46, 16, 1
	v_lshrrev_b32_e32 v3, 16, v3
	v_add3_u32 v4, v46, v4, s15
	v_and_or_b32 v34, v4, s16, v3
	s_waitcnt lgkmcnt(1)
	v_bfe_u32 v3, v48, 16, 1
	v_add3_u32 v3, v48, v3, s15
	s_waitcnt lgkmcnt(0)
	v_bfe_u32 v4, v50, 16, 1
	v_lshrrev_b32_e32 v3, 16, v3
	v_add3_u32 v4, v50, v4, s15
	v_and_or_b32 v35, v4, s16, v3
	v_or_b32_e32 v3, s22, v30
	v_lshlrev_b32_e32 v4, 11, v3
	v_bfe_u32 v3, v25, 16, 1
	v_lshl_add_u64 v[52:53], v[36:37], 0, v[4:5]
	v_add3_u32 v3, v25, v3, s15
	v_bfe_u32 v4, v39, 16, 1
	v_lshrrev_b32_e32 v3, 16, v3
	v_add3_u32 v4, v39, v4, s15
	global_store_dwordx4 v[52:53], v[32:35], off sc1
	s_nop 1
	v_and_or_b32 v32, v4, s16, v3
	v_bfe_u32 v3, v41, 16, 1
	v_add3_u32 v3, v41, v3, s15
	v_bfe_u32 v4, v43, 16, 1
	v_lshrrev_b32_e32 v3, 16, v3
	v_add3_u32 v4, v43, v4, s15
	v_and_or_b32 v33, v4, s16, v3
	v_bfe_u32 v3, v45, 16, 1
	v_add3_u32 v3, v45, v3, s15
	v_bfe_u32 v4, v47, 16, 1
	v_lshrrev_b32_e32 v3, 16, v3
	v_add3_u32 v4, v47, v4, s15
	v_and_or_b32 v34, v4, s16, v3
	v_bfe_u32 v3, v49, 16, 1
	v_add3_u32 v3, v49, v3, s15
	v_bfe_u32 v4, v51, 16, 1
	v_lshrrev_b32_e32 v3, 16, v3
	v_add3_u32 v4, v51, v4, s15
	v_and_or_b32 v35, v4, s16, v3
	v_or_b32_e32 v3, s22, v31
	v_lshlrev_b32_e32 v4, 11, v3
	v_lshl_add_u64 v[24:25], v[36:37], 0, v[4:5]
	global_store_dwordx4 v[24:25], v[32:35], off sc1
	s_waitcnt lgkmcnt(0)
	s_mov_b64 s[22:23], 0

; __device__ __forceinline__ void p0_transpose_item(const float* W, int ld, int K, int ncols, bf16* WT, LAS float* scr, int item, int lane) {
;     const int nblk = ncols / 32, kb = item / nblk, nb = item % nblk, k0 = 64 * kb, n0 = 32 * nb;
; #pragma unroll 8
;     for (int i = 0; i < 32; ++i) { const int kk = 2 * i + (lane >> 5); scr[kk * 33 + (lane & 31)] = W[(size_t)(k0 + kk) * ld + n0 + (lane & 31)]; }
.LBB0_24:
	s_lshl_b32 s29, s25, 1
	s_lshl_b32 s30, s27, 1
	v_or_b32_e32 v4, s30, v26
	s_add_i32 s33, s29, 4
	s_add_i32 s34, s30, 4
	v_mov_b32_e32 v35, v5
	s_add_i32 s36, s30, 8
	v_lshlrev_b64 v[48:49], 12, v[4:5]
	v_or_b32_e32 v34, s33, v3
	v_or_b32_e32 v4, s34, v26
	v_mov_b32_e32 v33, v5
	v_or_b32_e32 v32, s29, v3
	s_add_i32 s38, s30, 12
	v_lshlrev_b64 v[34:35], 12, v[34:35]
	v_lshlrev_b64 v[50:51], 12, v[4:5]
	v_or_b32_e32 v4, s36, v26
	s_add_i32 s35, s29, 8
	s_add_i32 s37, s29, 12
	s_add_i32 s40, s30, 16
	v_lshlrev_b64 v[32:33], 12, v[32:33]
	v_lshl_add_u64 v[48:49], v[24:25], 0, v[48:49]
	v_lshl_add_u64 v[34:35], v[24:25], 0, v[34:35]
	v_lshlrev_b64 v[52:53], 12, v[4:5]
	v_or_b32_e32 v4, s38, v26
	v_mov_b32_e32 v37, v5
	v_mov_b32_e32 v39, v5
	s_add_i32 s42, s30, 20
	v_or_b32_e32 v36, s35, v3
	v_or_b32_e32 v38, s37, v3
	v_lshl_add_u64 v[32:33], v[24:25], 0, v[32:33]
	v_lshl_add_u64 v[50:51], v[24:25], 0, v[50:51]
	global_load_dword v21, v[48:49], off
	global_load_dword v23, v[32:33], off
	global_load_dword v64, v[50:51], off
	global_load_dword v65, v[34:35], off
	v_lshlrev_b64 v[34:35], 12, v[4:5]
	v_or_b32_e32 v4, s40, v26
	s_add_i32 s39, s29, 16
	s_add_i32 s41, s29, 20
	s_add_i32 s44, s30, 24
	v_lshlrev_b64 v[36:37], 12, v[36:37]
	v_lshlrev_b64 v[38:39], 12, v[38:39]
	v_lshl_add_u64 v[32:33], v[24:25], 0, v[52:53]
	v_lshl_add_u64 v[34:35], v[24:25], 0, v[34:35]
	v_lshlrev_b64 v[48:49], 12, v[4:5]
	v_or_b32_e32 v4, s42, v26
	v_mov_b32_e32 v41, v5
	v_mov_b32_e32 v43, v5
	s_add_i32 s43, s29, 24
	s_add_i32 s45, s29, 28
	s_add_i32 s46, s30, 28
	v_or_b32_e32 v40, s39, v3
	v_or_b32_e32 v42, s41, v3
	v_lshl_add_u64 v[36:37], v[24:25], 0, v[36:37]
	v_lshl_add_u64 v[38:39], v[24:25], 0, v[38:39]
	global_load_dword v66, v[32:33], off
	global_load_dword v67, v[36:37], off
	global_load_dword v68, v[34:35], off
	global_load_dword v69, v[38:39], off
	v_lshlrev_b64 v[34:35], 12, v[4:5]
	v_or_b32_e32 v4, s44, v26
	v_mov_b32_e32 v45, v5
	v_mov_b32_e32 v47, v5
	v_or_b32_e32 v44, s43, v3
	v_or_b32_e32 v46, s45, v3
	v_lshlrev_b64 v[40:41], 12, v[40:41]
	v_lshlrev_b64 v[42:43], 12, v[42:43]
	v_lshl_add_u64 v[32:33], v[24:25], 0, v[48:49]
	v_lshl_add_u64 v[34:35], v[24:25], 0, v[34:35]
	v_lshlrev_b64 v[36:37], 12, v[4:5]
	v_or_b32_e32 v4, s46, v26
	v_lshlrev_b64 v[44:45], 12, v[44:45]
	v_lshlrev_b64 v[46:47], 12, v[46:47]
	v_lshl_add_u64 v[40:41], v[24:25], 0, v[40:41]
	v_lshl_add_u64 v[42:43], v[24:25], 0, v[42:43]
	global_load_dword v70, v[32:33], off
	global_load_dword v71, v[40:41], off
	global_load_dword v72, v[34:35], off
	global_load_dword v73, v[42:43], off
	v_lshl_add_u64 v[32:33], v[24:25], 0, v[36:37]
	v_lshlrev_b64 v[34:35], 12, v[4:5]
	v_lshl_add_u64 v[44:45], v[24:25], 0, v[44:45]
	v_lshl_add_u64 v[46:47], v[24:25], 0, v[46:47]
	v_lshl_add_u64 v[34:35], v[24:25], 0, v[34:35]
	global_load_dword v4, v[32:33], off
	global_load_dword v74, v[44:45], off
	global_load_dword v75, v[34:35], off
	global_load_dword v76, v[46:47], off
	v_or_b32_e32 v34, s29, v1
	v_or_b32_e32 v32, s30, v2
	s_add_i32 s27, s27, 16
	s_add_i32 s25, s25, 16
	s_add_i32 s28, s28, -16
	v_mad_u64_u32 v[32:33], s[30:31], v32, s13, v[8:9]
	v_mad_u64_u32 v[34:35], s[30:31], v34, s13, v[8:9]
	v_or_b32_e32 v33, s33, v1
	v_or_b32_e32 v35, s34, v2
	v_or_b32_e32 v42, s35, v1
	v_or_b32_e32 v40, s36, v2
	v_or_b32_e32 v46, s37, v1
	v_or_b32_e32 v44, s38, v2
	v_or_b32_e32 v50, s39, v1
	v_or_b32_e32 v48, s40, v2
	v_or_b32_e32 v54, s41, v1
	v_or_b32_e32 v52, s42, v2
	v_or_b32_e32 v58, s43, v1
	v_or_b32_e32 v56, s44, v2
	v_or_b32_e32 v62, s45, v1
	v_or_b32_e32 v60, s46, v2
	s_cmp_lg_u32 s28, 0
	v_mad_u64_u32 v[36:37], s[30:31], v35, s13, v[8:9]
	v_mad_u64_u32 v[38:39], s[30:31], v33, s13, v[8:9]
	v_mad_u64_u32 v[40:41], s[30:31], v40, s13, v[8:9]
	v_mad_u64_u32 v[42:43], s[30:31], v42, s13, v[8:9]
	v_mad_u64_u32 v[44:45], s[30:31], v44, s13, v[8:9]
	v_mad_u64_u32 v[46:47], s[30:31], v46, s13, v[8:9]
	v_mad_u64_u32 v[48:49], s[30:31], v48, s13, v[8:9]
	v_mad_u64_u32 v[50:51], s[30:31], v50, s13, v[8:9]
	v_mad_u64_u32 v[52:53], s[30:31], v52, s13, v[8:9]
	v_mad_u64_u32 v[54:55], s[30:31], v54, s13, v[8:9]
	v_mad_u64_u32 v[56:57], s[30:31], v56, s13, v[8:9]
	v_mad_u64_u32 v[58:59], s[30:31], v58, s13, v[8:9]
	v_mad_u64_u32 v[60:61], s[30:31], v60, s13, v[8:9]
	v_mad_u64_u32 v[62:63], s[30:31], v62, s13, v[8:9]
	s_waitcnt vmcnt(15)
	ds_write_b32 v32, v21
	s_waitcnt vmcnt(14)
	ds_write_b32 v34, v23
	s_waitcnt vmcnt(13)
	ds_write_b32 v36, v64
	s_waitcnt vmcnt(12)
	ds_write_b32 v38, v65
	s_waitcnt vmcnt(11)
	ds_write_b32 v40, v66
	s_waitcnt vmcnt(10)
	ds_write_b32 v42, v67
	s_waitcnt vmcnt(9)
	ds_write_b32 v44, v68
	s_waitcnt vmcnt(8)
	ds_write_b32 v46, v69
	s_waitcnt vmcnt(7)
	ds_write_b32 v48, v70
	s_waitcnt vmcnt(6)
	ds_write_b32 v50, v71
	s_waitcnt vmcnt(5)
	ds_write_b32 v52, v72
	s_waitcnt vmcnt(4)
	ds_write_b32 v54, v73
	s_waitcnt vmcnt(3)
	ds_write_b32 v56, v4
	s_waitcnt vmcnt(2)
	ds_write_b32 v58, v74
	s_waitcnt vmcnt(1)
	ds_write_b32 v60, v75
	s_waitcnt vmcnt(0)
	ds_write_b32 v62, v76
	s_cbranch_scc1 .LBB0_24
; #define GAS __attribute__((address_space(1)))
; #define LAS __attribute__((address_space(3)))
; #define LDS_WAIT() asm volatile("s_waitcnt lgkmcnt(0)" ::: "memory")
; __device__ __forceinline__ unsigned f2bf(float f) { unsigned u = __builtin_bit_cast(unsigned, f); return (u + 0x7fffu + ((u >> 16) & 1u)) >> 16; }
; __device__ __forceinline__ unsigned pk2(float lo, float hi) { return f2bf(lo) | (f2bf(hi) << 16); }
; __device__ __forceinline__ void p0_transpose_item(const float* W, int ld, int K, int ncols, bf16* WT, LAS float* scr, int item, int lane) {
;     ...
;     const int c = lane & 7;
; #pragma unroll
;     for (int j = 0; j < 4; ++j) { const int n = (lane >> 3) + 8 * j; const LAS float* s = scr + (8 * c) * 33 + n;
;         v4u o; o.x = pk2(s[0 * 33], s[1 * 33]); o.y = pk2(s[2 * 33], s[3 * 33]); o.z = pk2(s[4 * 33], s[5 * 33]); o.w = pk2(s[6 * 33], s[7 * 33]);
;         *(GAS v4u*)(WT + (size_t)(n0 + n) * K + k0 + 8 * c) = o; }
;     LDS_WAIT(); asm volatile("" ::: "memory");
	s_waitcnt lgkmcnt(0)
	ds_read2_b32 v[24:25], v28 offset1:8
	ds_read2_b32 v[38:39], v28 offset0:33 offset1:41
	ds_read2_b32 v[40:41], v28 offset0:66 offset1:74
	ds_read2_b32 v[42:43], v28 offset0:99 offset1:107
	ds_read2_b32 v[44:45], v28 offset0:132 offset1:140
	s_waitcnt lgkmcnt(4)
	v_bfe_u32 v3, v24, 16, 1
	v_add3_u32 v3, v24, v3, s15
	s_waitcnt lgkmcnt(3)
	v_bfe_u32 v4, v38, 16, 1
	v_lshrrev_b32_e32 v3, 16, v3
	v_add3_u32 v4, v38, v4, s15
	ds_read2_b32 v[46:47], v28 offset0:165 offset1:173
	v_and_or_b32 v32, v4, s16, v3
	s_waitcnt lgkmcnt(3)
	v_bfe_u32 v3, v40, 16, 1
	v_add3_u32 v3, v40, v3, s15
	s_waitcnt lgkmcnt(2)
	v_bfe_u32 v4, v42, 16, 1
	ds_read2_b32 v[48:49], v28 offset0:198 offset1:206
	v_lshrrev_b32_e32 v3, 16, v3
	v_add3_u32 v4, v42, v4, s15
	ds_read2_b32 v[50:51], v28 offset0:231 offset1:239
	v_and_or_b32 v33, v4, s16, v3
	s_waitcnt lgkmcnt(3)
	v_bfe_u32 v3, v44, 16, 1
	v_add3_u32 v3, v44, v3, s15
	s_waitcnt lgkmcnt(2)
	v_bfe_u32 v4, v46, 16, 1
	s_lshl_b64 s[22:23], s[22:23], 1
	v_lshrrev_b32_e32 v3, 16, v3
	v_add3_u32 v4, v46, v4, s15
	s_add_u32 s22, s2, s22
	v_and_or_b32 v34, v4, s16, v3
	s_waitcnt lgkmcnt(1)
	v_bfe_u32 v3, v48, 16, 1
	s_addc_u32 s23, s3, s23
	s_lshl_b32 s24, s24, 1
	v_add3_u32 v3, v48, v3, s15
	s_waitcnt lgkmcnt(0)
	v_bfe_u32 v4, v50, 16, 1
	s_add_u32 s22, s22, s24
	v_lshrrev_b32_e32 v3, 16, v3
	v_add3_u32 v4, v50, v4, s15
	s_addc_u32 s23, s23, 0
	v_mov_b32_e32 v21, v5
	v_and_or_b32 v35, v4, s16, v3
	v_or_b32_e32 v3, s6, v27
	v_lshl_add_u64 v[36:37], s[22:23], 0, v[20:21]
	v_lshlrev_b32_e32 v4, 11, v3
	v_bfe_u32 v3, v25, 16, 1
	v_lshl_add_u64 v[52:53], v[36:37], 0, v[4:5]
	v_add3_u32 v3, v25, v3, s15
	v_bfe_u32 v4, v39, 16, 1
	v_lshrrev_b32_e32 v3, 16, v3
	v_add3_u32 v4, v39, v4, s15
	global_store_dwordx4 v[52:53], v[32:35], off sc1
	ds_read2_b32 v[24:25], v28 offset0:16 offset1:24
	s_nop 0
	v_and_or_b32 v32, v4, s16, v3
	v_bfe_u32 v3, v41, 16, 1
	v_add3_u32 v3, v41, v3, s15
	v_bfe_u32 v4, v43, 16, 1
	v_lshrrev_b32_e32 v3, 16, v3
	v_add3_u32 v4, v43, v4, s15
	v_and_or_b32 v33, v4, s16, v3
	v_bfe_u32 v3, v45, 16, 1
	v_add3_u32 v3, v45, v3, s15
	v_bfe_u32 v4, v47, 16, 1
	v_lshrrev_b32_e32 v3, 16, v3
	v_add3_u32 v4, v47, v4, s15
	v_and_or_b32 v34, v4, s16, v3
	v_bfe_u32 v3, v49, 16, 1
	v_add3_u32 v3, v49, v3, s15
	v_bfe_u32 v4, v51, 16, 1
	v_lshrrev_b32_e32 v3, 16, v3
	v_add3_u32 v4, v51, v4, s15
	v_and_or_b32 v35, v4, s16, v3
	v_or_b32_e32 v3, s6, v29
	v_lshlrev_b32_e32 v4, 11, v3
	v_lshl_add_u64 v[38:39], v[36:37], 0, v[4:5]
	global_store_dwordx4 v[38:39], v[32:35], off sc1
	ds_read2_b32 v[38:39], v28 offset0:49 offset1:57
	ds_read2_b32 v[40:41], v28 offset0:82 offset1:90
	ds_read2_b32 v[42:43], v28 offset0:115 offset1:123
	s_waitcnt lgkmcnt(3)
	v_bfe_u32 v3, v24, 16, 1
	v_add3_u32 v3, v24, v3, s15
	s_waitcnt lgkmcnt(2)
	v_bfe_u32 v4, v38, 16, 1
	ds_read2_b32 v[44:45], v28 offset0:148 offset1:156
	v_lshrrev_b32_e32 v3, 16, v3
	v_add3_u32 v4, v38, v4, s15
	ds_read2_b32 v[46:47], v28 offset0:181 offset1:189
	v_and_or_b32 v32, v4, s16, v3
	s_waitcnt lgkmcnt(3)
	v_bfe_u32 v3, v40, 16, 1
	v_add3_u32 v3, v40, v3, s15
	s_waitcnt lgkmcnt(2)
	v_bfe_u32 v4, v42, 16, 1
	ds_read2_b32 v[48:49], v28 offset0:214 offset1:222
	v_lshrrev_b32_e32 v3, 16, v3
	v_add3_u32 v4, v42, v4, s15
	ds_read2_b32 v[50:51], v28 offset0:247 offset1:255
	v_and_or_b32 v33, v4, s16, v3
	s_waitcnt lgkmcnt(3)
	v_bfe_u32 v3, v44, 16, 1
	v_add3_u32 v3, v44, v3, s15
	s_waitcnt lgkmcnt(2)
	v_bfe_u32 v4, v46, 16, 1
	v_lshrrev_b32_e32 v3, 16, v3
	v_add3_u32 v4, v46, v4, s15
	v_and_or_b32 v34, v4, s16, v3
	s_waitcnt lgkmcnt(1)
	v_bfe_u32 v3, v48, 16, 1
	v_add3_u32 v3, v48, v3, s15
	s_waitcnt lgkmcnt(0)
	v_bfe_u32 v4, v50, 16, 1
	v_lshrrev_b32_e32 v3, 16, v3
	v_add3_u32 v4, v50, v4, s15
	v_and_or_b32 v35, v4, s16, v3
	v_or_b32_e32 v3, s6, v30
	v_lshlrev_b32_e32 v4, 11, v3
	v_bfe_u32 v3, v25, 16, 1
	v_lshl_add_u64 v[52:53], v[36:37], 0, v[4:5]
	v_add3_u32 v3, v25, v3, s15
	v_bfe_u32 v4, v39, 16, 1
	v_lshrrev_b32_e32 v3, 16, v3
	v_add3_u32 v4, v39, v4, s15
	global_store_dwordx4 v[52:53], v[32:35], off sc1
	s_nop 1
	v_and_or_b32 v32, v4, s16, v3
	v_bfe_u32 v3, v41, 16, 1
	v_add3_u32 v3, v41, v3, s15
	v_bfe_u32 v4, v43, 16, 1
	v_lshrrev_b32_e32 v3, 16, v3
	v_add3_u32 v4, v43, v4, s15
	v_and_or_b32 v33, v4, s16, v3
	v_bfe_u32 v3, v45, 16, 1
	v_add3_u32 v3, v45, v3, s15
	v_bfe_u32 v4, v47, 16, 1
	v_lshrrev_b32_e32 v3, 16, v3
	v_add3_u32 v4, v47, v4, s15
	v_and_or_b32 v34, v4, s16, v3
	v_bfe_u32 v3, v49, 16, 1
	v_add3_u32 v3, v49, v3, s15
	v_bfe_u32 v4, v51, 16, 1
	v_lshrrev_b32_e32 v3, 16, v3
	v_add3_u32 v4, v51, v4, s15
	v_and_or_b32 v35, v4, s16, v3
	v_or_b32_e32 v3, s6, v31
	v_lshlrev_b32_e32 v4, 11, v3
	v_lshl_add_u64 v[24:25], v[36:37], 0, v[4:5]
	global_store_dwordx4 v[24:25], v[32:35], off sc1
	s_waitcnt lgkmcnt(0)

; __device__ __forceinline__ void p0_transpose_item(const float* W, int ld, int K, int ncols, bf16* WT, LAS float* scr, int item, int lane) {
;     const int nblk = ncols / 32, kb = item / nblk, nb = item % nblk, k0 = 64 * kb, n0 = 32 * nb;
; #pragma unroll 8
;     for (int i = 0; i < 32; ++i) { const int kk = 2 * i + (lane >> 5); scr[kk * 33 + (lane & 31)] = W[(size_t)(k0 + kk) * ld + n0 + (lane & 31)]; }
.LBB0_29:
	s_lshl_b32 s27, s23, 1
	s_lshl_b32 s28, s24, 1
	v_or_b32_e32 v4, s28, v26
	s_add_i32 s30, s27, 4
	s_add_i32 s31, s28, 4
	v_mov_b32_e32 v35, v5
	s_add_i32 s34, s28, 8
	v_lshlrev_b64 v[48:49], 12, v[4:5]
	v_or_b32_e32 v34, s30, v3
	v_or_b32_e32 v4, s31, v26
	v_mov_b32_e32 v33, v5
	v_or_b32_e32 v32, s27, v3
	s_add_i32 s36, s28, 12
	v_lshlrev_b64 v[34:35], 12, v[34:35]
	v_lshlrev_b64 v[50:51], 12, v[4:5]
	v_or_b32_e32 v4, s34, v26
	s_add_i32 s33, s27, 8
	s_add_i32 s35, s27, 12
	s_add_i32 s38, s28, 16
	v_lshlrev_b64 v[32:33], 12, v[32:33]
	v_lshl_add_u64 v[48:49], v[24:25], 0, v[48:49]
	v_lshl_add_u64 v[34:35], v[24:25], 0, v[34:35]
	v_lshlrev_b64 v[52:53], 12, v[4:5]
	v_or_b32_e32 v4, s36, v26
	v_mov_b32_e32 v37, v5
	v_mov_b32_e32 v39, v5
	s_add_i32 s40, s28, 20
	v_or_b32_e32 v36, s33, v3
	v_or_b32_e32 v38, s35, v3
	v_lshl_add_u64 v[32:33], v[24:25], 0, v[32:33]
	v_lshl_add_u64 v[50:51], v[24:25], 0, v[50:51]
	global_load_dword v21, v[48:49], off
	global_load_dword v23, v[32:33], off
	global_load_dword v64, v[50:51], off
	global_load_dword v65, v[34:35], off
	v_lshlrev_b64 v[34:35], 12, v[4:5]
	v_or_b32_e32 v4, s38, v26
	s_add_i32 s37, s27, 16
	s_add_i32 s39, s27, 20
	s_add_i32 s42, s28, 24
	v_lshlrev_b64 v[36:37], 12, v[36:37]
	v_lshlrev_b64 v[38:39], 12, v[38:39]
	v_lshl_add_u64 v[32:33], v[24:25], 0, v[52:53]
	v_lshl_add_u64 v[34:35], v[24:25], 0, v[34:35]
	v_lshlrev_b64 v[48:49], 12, v[4:5]
	v_or_b32_e32 v4, s40, v26
	v_mov_b32_e32 v41, v5
	v_mov_b32_e32 v43, v5
	s_add_i32 s41, s27, 24
	s_add_i32 s43, s27, 28
	s_add_i32 s44, s28, 28
	v_or_b32_e32 v40, s37, v3
	v_or_b32_e32 v42, s39, v3
	v_lshl_add_u64 v[36:37], v[24:25], 0, v[36:37]
	v_lshl_add_u64 v[38:39], v[24:25], 0, v[38:39]
	global_load_dword v66, v[32:33], off
	global_load_dword v67, v[36:37], off
	global_load_dword v68, v[34:35], off
	global_load_dword v69, v[38:39], off
	v_lshlrev_b64 v[34:35], 12, v[4:5]
	v_or_b32_e32 v4, s42, v26
	v_mov_b32_e32 v45, v5
	v_mov_b32_e32 v47, v5
	v_or_b32_e32 v44, s41, v3
	v_or_b32_e32 v46, s43, v3
	v_lshlrev_b64 v[40:41], 12, v[40:41]
	v_lshlrev_b64 v[42:43], 12, v[42:43]
	v_lshl_add_u64 v[32:33], v[24:25], 0, v[48:49]
	v_lshl_add_u64 v[34:35], v[24:25], 0, v[34:35]
	v_lshlrev_b64 v[36:37], 12, v[4:5]
	v_or_b32_e32 v4, s44, v26
	v_lshlrev_b64 v[44:45], 12, v[44:45]
	v_lshlrev_b64 v[46:47], 12, v[46:47]
	v_lshl_add_u64 v[40:41], v[24:25], 0, v[40:41]
	v_lshl_add_u64 v[42:43], v[24:25], 0, v[42:43]
	global_load_dword v70, v[32:33], off
	global_load_dword v71, v[40:41], off
	global_load_dword v72, v[34:35], off
	global_load_dword v73, v[42:43], off
	v_lshl_add_u64 v[32:33], v[24:25], 0, v[36:37]
	v_lshlrev_b64 v[34:35], 12, v[4:5]
	v_lshl_add_u64 v[44:45], v[24:25], 0, v[44:45]
	v_lshl_add_u64 v[46:47], v[24:25], 0, v[46:47]
	v_lshl_add_u64 v[34:35], v[24:25], 0, v[34:35]
	global_load_dword v4, v[32:33], off
	global_load_dword v74, v[44:45], off
	global_load_dword v75, v[34:35], off
	global_load_dword v76, v[46:47], off
	v_or_b32_e32 v34, s27, v1
	v_or_b32_e32 v32, s28, v2
	s_add_i32 s24, s24, 16
	s_add_i32 s23, s23, 16
	s_add_i32 s25, s25, -16
	v_mad_u64_u32 v[32:33], s[28:29], v32, s13, v[8:9]
	v_mad_u64_u32 v[34:35], s[28:29], v34, s13, v[8:9]
	v_or_b32_e32 v33, s30, v1
	v_or_b32_e32 v35, s31, v2
	v_or_b32_e32 v42, s33, v1
	v_or_b32_e32 v40, s34, v2
	v_or_b32_e32 v46, s35, v1
	v_or_b32_e32 v44, s36, v2
	v_or_b32_e32 v50, s37, v1
	v_or_b32_e32 v48, s38, v2
	v_or_b32_e32 v54, s39, v1
	v_or_b32_e32 v52, s40, v2
	v_or_b32_e32 v58, s41, v1
	v_or_b32_e32 v56, s42, v2
	v_or_b32_e32 v62, s43, v1
	v_or_b32_e32 v60, s44, v2
	s_cmp_lg_u32 s25, 0
	v_mad_u64_u32 v[36:37], s[28:29], v35, s13, v[8:9]
	v_mad_u64_u32 v[38:39], s[28:29], v33, s13, v[8:9]
	v_mad_u64_u32 v[40:41], s[28:29], v40, s13, v[8:9]
	v_mad_u64_u32 v[42:43], s[28:29], v42, s13, v[8:9]
	v_mad_u64_u32 v[44:45], s[28:29], v44, s13, v[8:9]
	v_mad_u64_u32 v[46:47], s[28:29], v46, s13, v[8:9]
	v_mad_u64_u32 v[48:49], s[28:29], v48, s13, v[8:9]
	v_mad_u64_u32 v[50:51], s[28:29], v50, s13, v[8:9]
	v_mad_u64_u32 v[52:53], s[28:29], v52, s13, v[8:9]
	v_mad_u64_u32 v[54:55], s[28:29], v54, s13, v[8:9]
	v_mad_u64_u32 v[56:57], s[28:29], v56, s13, v[8:9]
	v_mad_u64_u32 v[58:59], s[28:29], v58, s13, v[8:9]
	v_mad_u64_u32 v[60:61], s[28:29], v60, s13, v[8:9]
	v_mad_u64_u32 v[62:63], s[28:29], v62, s13, v[8:9]
	s_waitcnt vmcnt(15)
	ds_write_b32 v32, v21
	s_waitcnt vmcnt(14)
	ds_write_b32 v34, v23
	s_waitcnt vmcnt(13)
	ds_write_b32 v36, v64
	s_waitcnt vmcnt(12)
	ds_write_b32 v38, v65
	s_waitcnt vmcnt(11)
	ds_write_b32 v40, v66
	s_waitcnt vmcnt(10)
	ds_write_b32 v42, v67
	s_waitcnt vmcnt(9)
	ds_write_b32 v44, v68
	s_waitcnt vmcnt(8)
	ds_write_b32 v46, v69
	s_waitcnt vmcnt(7)
	ds_write_b32 v48, v70
	s_waitcnt vmcnt(6)
	ds_write_b32 v50, v71
	s_waitcnt vmcnt(5)
	ds_write_b32 v52, v72
	s_waitcnt vmcnt(4)
	ds_write_b32 v54, v73
	s_waitcnt vmcnt(3)
	ds_write_b32 v56, v4
	s_waitcnt vmcnt(2)
	ds_write_b32 v58, v74
	s_waitcnt vmcnt(1)
	ds_write_b32 v60, v75
	s_waitcnt vmcnt(0)
	ds_write_b32 v62, v76
	s_cbranch_scc1 .LBB0_29
; #define GAS __attribute__((address_space(1)))
; #define LAS __attribute__((address_space(3)))
; #define LDS_WAIT() asm volatile("s_waitcnt lgkmcnt(0)" ::: "memory")
; __device__ __forceinline__ unsigned f2bf(float f) { unsigned u = __builtin_bit_cast(unsigned, f); return (u + 0x7fffu + ((u >> 16) & 1u)) >> 16; }
; __device__ __forceinline__ unsigned pk2(float lo, float hi) { return f2bf(lo) | (f2bf(hi) << 16); }
; __device__ __forceinline__ void p0_transpose_item(const float* W, int ld, int K, int ncols, bf16* WT, LAS float* scr, int item, int lane) {
;     ...
;     const int c = lane & 7;
; #pragma unroll
;     for (int j = 0; j < 4; ++j) { const int n = (lane >> 3) + 8 * j; const LAS float* s = scr + (8 * c) * 33 + n;
;         v4u o; o.x = pk2(s[0 * 33], s[1 * 33]); o.y = pk2(s[2 * 33], s[3 * 33]); o.z = pk2(s[4 * 33], s[5 * 33]); o.w = pk2(s[6 * 33], s[7 * 33]);
;         *(GAS v4u*)(WT + (size_t)(n0 + n) * K + k0 + 8 * c) = o; }
;     LDS_WAIT(); asm volatile("" ::: "memory");
	s_waitcnt lgkmcnt(0)
	ds_read2_b32 v[24:25], v28 offset1:8
	ds_read2_b32 v[38:39], v28 offset0:33 offset1:41
	ds_read2_b32 v[40:41], v28 offset0:66 offset1:74
	ds_read2_b32 v[42:43], v28 offset0:99 offset1:107
	ds_read2_b32 v[44:45], v28 offset0:132 offset1:140
	ds_read2_b32 v[46:47], v28 offset0:165 offset1:173
	s_waitcnt lgkmcnt(5)
	v_bfe_u32 v3, v24, 16, 1
	v_add3_u32 v3, v24, v3, s15
	s_waitcnt lgkmcnt(4)
	v_bfe_u32 v4, v38, 16, 1
	v_lshrrev_b32_e32 v3, 16, v3
	v_add3_u32 v4, v38, v4, s15
	v_and_or_b32 v32, v4, s16, v3
	s_waitcnt lgkmcnt(3)
	v_bfe_u32 v3, v40, 16, 1
	v_add3_u32 v3, v40, v3, s15
	s_waitcnt lgkmcnt(2)
	v_bfe_u32 v4, v42, 16, 1
	ds_read2_b32 v[48:49], v28 offset0:198 offset1:206
	v_lshrrev_b32_e32 v3, 16, v3
	v_add3_u32 v4, v42, v4, s15
	ds_read2_b32 v[50:51], v28 offset0:231 offset1:239
	v_and_or_b32 v33, v4, s16, v3
	s_waitcnt lgkmcnt(3)
	v_bfe_u32 v3, v44, 16, 1
	v_add3_u32 v3, v44, v3, s15
	s_waitcnt lgkmcnt(2)
	v_bfe_u32 v4, v46, 16, 1
	v_lshrrev_b32_e32 v3, 16, v3
	v_add3_u32 v4, v46, v4, s15
	v_and_or_b32 v34, v4, s16, v3
	s_waitcnt lgkmcnt(1)
	v_bfe_u32 v3, v48, 16, 1
	v_add3_u32 v3, v48, v3, s15
	s_waitcnt lgkmcnt(0)
	v_bfe_u32 v4, v50, 16, 1
	v_lshrrev_b32_e32 v3, 16, v3
	v_add3_u32 v4, v50, v4, s15
	s_lshl_b32 s6, s6, 1
	v_and_or_b32 v35, v4, s16, v3
	v_or_b32_e32 v3, s22, v27
	v_lshl_add_u64 v[36:37], v[12:13], 0, s[6:7]
	v_lshlrev_b32_e32 v4, 11, v3
	v_bfe_u32 v3, v25, 16, 1
	v_lshl_add_u64 v[52:53], v[36:37], 0, v[4:5]
	v_add3_u32 v3, v25, v3, s15
	v_bfe_u32 v4, v39, 16, 1
	v_lshrrev_b32_e32 v3, 16, v3
	v_add3_u32 v4, v39, v4, s15
	global_store_dwordx4 v[52:53], v[32:35], off sc1
	ds_read2_b32 v[24:25], v28 offset0:16 offset1:24
	s_nop 0
	v_and_or_b32 v32, v4, s16, v3
	v_bfe_u32 v3, v41, 16, 1
	v_add3_u32 v3, v41, v3, s15
	v_bfe_u32 v4, v43, 16, 1
	v_lshrrev_b32_e32 v3, 16, v3
	v_add3_u32 v4, v43, v4, s15
	v_and_or_b32 v33, v4, s16, v3
	v_bfe_u32 v3, v45, 16, 1
	v_add3_u32 v3, v45, v3, s15
	v_bfe_u32 v4, v47, 16, 1
	v_lshrrev_b32_e32 v3, 16, v3
	v_add3_u32 v4, v47, v4, s15
	v_and_or_b32 v34, v4, s16, v3
	v_bfe_u32 v3, v49, 16, 1
	v_add3_u32 v3, v49, v3, s15
	v_bfe_u32 v4, v51, 16, 1
	v_lshrrev_b32_e32 v3, 16, v3
	v_add3_u32 v4, v51, v4, s15
	v_and_or_b32 v35, v4, s16, v3
	v_or_b32_e32 v3, s22, v29
	v_lshlrev_b32_e32 v4, 11, v3
	v_lshl_add_u64 v[38:39], v[36:37], 0, v[4:5]
	global_store_dwordx4 v[38:39], v[32:35], off sc1
	ds_read2_b32 v[38:39], v28 offset0:49 offset1:57
	ds_read2_b32 v[40:41], v28 offset0:82 offset1:90
	ds_read2_b32 v[42:43], v28 offset0:115 offset1:123
	s_waitcnt lgkmcnt(3)
	v_bfe_u32 v3, v24, 16, 1
	v_add3_u32 v3, v24, v3, s15
	s_waitcnt lgkmcnt(2)
	v_bfe_u32 v4, v38, 16, 1
	ds_read2_b32 v[44:45], v28 offset0:148 offset1:156
	v_lshrrev_b32_e32 v3, 16, v3
	v_add3_u32 v4, v38, v4, s15
	ds_read2_b32 v[46:47], v28 offset0:181 offset1:189
	v_and_or_b32 v32, v4, s16, v3
	s_waitcnt lgkmcnt(3)
	v_bfe_u32 v3, v40, 16, 1
	v_add3_u32 v3, v40, v3, s15
	s_waitcnt lgkmcnt(2)
	v_bfe_u32 v4, v42, 16, 1
	ds_read2_b32 v[48:49], v28 offset0:214 offset1:222
	v_lshrrev_b32_e32 v3, 16, v3
	v_add3_u32 v4, v42, v4, s15
	ds_read2_b32 v[50:51], v28 offset0:247 offset1:255
	v_and_or_b32 v33, v4, s16, v3
	s_waitcnt lgkmcnt(3)
	v_bfe_u32 v3, v44, 16, 1
	v_add3_u32 v3, v44, v3, s15
	s_waitcnt lgkmcnt(2)
	v_bfe_u32 v4, v46, 16, 1
	v_lshrrev_b32_e32 v3, 16, v3
	v_add3_u32 v4, v46, v4, s15
	v_and_or_b32 v34, v4, s16, v3
	s_waitcnt lgkmcnt(1)
	v_bfe_u32 v3, v48, 16, 1
	v_add3_u32 v3, v48, v3, s15
	s_waitcnt lgkmcnt(0)
	v_bfe_u32 v4, v50, 16, 1
	v_lshrrev_b32_e32 v3, 16, v3
	v_add3_u32 v4, v50, v4, s15
	v_and_or_b32 v35, v4, s16, v3
	v_or_b32_e32 v3, s22, v30
	v_lshlrev_b32_e32 v4, 11, v3
	v_bfe_u32 v3, v25, 16, 1
	v_lshl_add_u64 v[52:53], v[36:37], 0, v[4:5]
	v_add3_u32 v3, v25, v3, s15
	v_bfe_u32 v4, v39, 16, 1
	v_lshrrev_b32_e32 v3, 16, v3
	v_add3_u32 v4, v39, v4, s15
	global_store_dwordx4 v[52:53], v[32:35], off sc1
	s_nop 1
	v_and_or_b32 v32, v4, s16, v3
	v_bfe_u32 v3, v41, 16, 1
	v_add3_u32 v3, v41, v3, s15
	v_bfe_u32 v4, v43, 16, 1
	v_lshrrev_b32_e32 v3, 16, v3
	v_add3_u32 v4, v43, v4, s15
	v_and_or_b32 v33, v4, s16, v3
	v_bfe_u32 v3, v45, 16, 1
	v_add3_u32 v3, v45, v3, s15
	v_bfe_u32 v4, v47, 16, 1
	v_lshrrev_b32_e32 v3, 16, v3
	v_add3_u32 v4, v47, v4, s15
	v_and_or_b32 v34, v4, s16, v3
	v_bfe_u32 v3, v49, 16, 1
	v_add3_u32 v3, v49, v3, s15
	v_bfe_u32 v4, v51, 16, 1
	v_lshrrev_b32_e32 v3, 16, v3
	v_add3_u32 v4, v51, v4, s15
	v_and_or_b32 v35, v4, s16, v3
	v_or_b32_e32 v3, s22, v31
	v_lshlrev_b32_e32 v4, 11, v3
	v_lshl_add_u64 v[24:25], v[36:37], 0, v[4:5]
	global_store_dwordx4 v[24:25], v[32:35], off sc1
	s_waitcnt lgkmcnt(0)

; __device__ __forceinline__ void p0_transpose_item(const float* W, int ld, int K, int ncols, bf16* WT, LAS float* scr, int item, int lane) {
;     const int nblk = ncols / 32, kb = item / nblk, nb = item % nblk, k0 = 64 * kb, n0 = 32 * nb;
; #pragma unroll 8
;     for (int i = 0; i < 32; ++i) { const int kk = 2 * i + (lane >> 5); scr[kk * 33 + (lane & 31)] = W[(size_t)(k0 + kk) * ld + n0 + (lane & 31)]; }
.LBB0_34:
	s_lshl_b32 s27, s23, 1
	s_lshl_b32 s28, s24, 1
	v_or_b32_e32 v4, s28, v26
	s_add_i32 s30, s27, 4
	s_add_i32 s31, s28, 4
	v_mov_b32_e32 v35, v5
	s_add_i32 s34, s28, 8
	v_lshlrev_b64 v[48:49], 12, v[4:5]
	v_or_b32_e32 v34, s30, v3
	v_or_b32_e32 v4, s31, v26
	v_mov_b32_e32 v33, v5
	v_or_b32_e32 v32, s27, v3
	s_add_i32 s36, s28, 12
	v_lshlrev_b64 v[34:35], 12, v[34:35]
	v_lshlrev_b64 v[50:51], 12, v[4:5]
	v_or_b32_e32 v4, s34, v26
	s_add_i32 s33, s27, 8
	s_add_i32 s35, s27, 12
	s_add_i32 s38, s28, 16
	v_lshlrev_b64 v[32:33], 12, v[32:33]
	v_lshl_add_u64 v[48:49], v[24:25], 0, v[48:49]
	v_lshl_add_u64 v[34:35], v[24:25], 0, v[34:35]
	v_lshlrev_b64 v[52:53], 12, v[4:5]
	v_or_b32_e32 v4, s36, v26
	v_mov_b32_e32 v37, v5
	v_mov_b32_e32 v39, v5
	s_add_i32 s40, s28, 20
	v_or_b32_e32 v36, s33, v3
	v_or_b32_e32 v38, s35, v3
	v_lshl_add_u64 v[32:33], v[24:25], 0, v[32:33]
	v_lshl_add_u64 v[50:51], v[24:25], 0, v[50:51]
	global_load_dword v21, v[48:49], off
	global_load_dword v23, v[32:33], off
	global_load_dword v64, v[50:51], off
	global_load_dword v65, v[34:35], off
	v_lshlrev_b64 v[34:35], 12, v[4:5]
	v_or_b32_e32 v4, s38, v26
	s_add_i32 s37, s27, 16
	s_add_i32 s39, s27, 20
	s_add_i32 s42, s28, 24
	v_lshlrev_b64 v[36:37], 12, v[36:37]
	v_lshlrev_b64 v[38:39], 12, v[38:39]
	v_lshl_add_u64 v[32:33], v[24:25], 0, v[52:53]
	v_lshl_add_u64 v[34:35], v[24:25], 0, v[34:35]
	v_lshlrev_b64 v[48:49], 12, v[4:5]
	v_or_b32_e32 v4, s40, v26
	v_mov_b32_e32 v41, v5
	v_mov_b32_e32 v43, v5
	s_add_i32 s41, s27, 24
	s_add_i32 s43, s27, 28
	s_add_i32 s44, s28, 28
	v_or_b32_e32 v40, s37, v3
	v_or_b32_e32 v42, s39, v3
	v_lshl_add_u64 v[36:37], v[24:25], 0, v[36:37]
	v_lshl_add_u64 v[38:39], v[24:25], 0, v[38:39]
	global_load_dword v66, v[32:33], off
	global_load_dword v67, v[36:37], off
	global_load_dword v68, v[34:35], off
	global_load_dword v69, v[38:39], off
	v_lshlrev_b64 v[34:35], 12, v[4:5]
	v_or_b32_e32 v4, s42, v26
	v_mov_b32_e32 v45, v5
	v_mov_b32_e32 v47, v5
	v_or_b32_e32 v44, s41, v3
	v_or_b32_e32 v46, s43, v3
	v_lshlrev_b64 v[40:41], 12, v[40:41]
	v_lshlrev_b64 v[42:43], 12, v[42:43]
	v_lshl_add_u64 v[32:33], v[24:25], 0, v[48:49]
	v_lshl_add_u64 v[34:35], v[24:25], 0, v[34:35]
	v_lshlrev_b64 v[36:37], 12, v[4:5]
	v_or_b32_e32 v4, s44, v26
	v_lshlrev_b64 v[44:45], 12, v[44:45]
	v_lshlrev_b64 v[46:47], 12, v[46:47]
	v_lshl_add_u64 v[40:41], v[24:25], 0, v[40:41]
	v_lshl_add_u64 v[42:43], v[24:25], 0, v[42:43]
	global_load_dword v70, v[32:33], off
	global_load_dword v71, v[40:41], off
	global_load_dword v72, v[34:35], off
	global_load_dword v73, v[42:43], off
	v_lshl_add_u64 v[32:33], v[24:25], 0, v[36:37]
	v_lshlrev_b64 v[34:35], 12, v[4:5]
	v_lshl_add_u64 v[44:45], v[24:25], 0, v[44:45]
	v_lshl_add_u64 v[46:47], v[24:25], 0, v[46:47]
	v_lshl_add_u64 v[34:35], v[24:25], 0, v[34:35]
	global_load_dword v4, v[32:33], off
	global_load_dword v74, v[44:45], off
	global_load_dword v75, v[34:35], off
	global_load_dword v76, v[46:47], off
	v_or_b32_e32 v34, s27, v1
	v_or_b32_e32 v32, s28, v2
	s_add_i32 s24, s24, 16
	s_add_i32 s23, s23, 16
	s_add_i32 s25, s25, -16
	v_mad_u64_u32 v[32:33], s[28:29], v32, s13, v[8:9]
	v_mad_u64_u32 v[34:35], s[28:29], v34, s13, v[8:9]
	v_or_b32_e32 v33, s30, v1
	v_or_b32_e32 v35, s31, v2
	v_or_b32_e32 v42, s33, v1
	v_or_b32_e32 v40, s34, v2
	v_or_b32_e32 v46, s35, v1
	v_or_b32_e32 v44, s36, v2
	v_or_b32_e32 v50, s37, v1
	v_or_b32_e32 v48, s38, v2
	v_or_b32_e32 v54, s39, v1
	v_or_b32_e32 v52, s40, v2
	v_or_b32_e32 v58, s41, v1
	v_or_b32_e32 v56, s42, v2
	v_or_b32_e32 v62, s43, v1
	v_or_b32_e32 v60, s44, v2
	s_cmp_lg_u32 s25, 0
	v_mad_u64_u32 v[36:37], s[28:29], v35, s13, v[8:9]
	v_mad_u64_u32 v[38:39], s[28:29], v33, s13, v[8:9]
	v_mad_u64_u32 v[40:41], s[28:29], v40, s13, v[8:9]
	v_mad_u64_u32 v[42:43], s[28:29], v42, s13, v[8:9]
	v_mad_u64_u32 v[44:45], s[28:29], v44, s13, v[8:9]
	v_mad_u64_u32 v[46:47], s[28:29], v46, s13, v[8:9]
	v_mad_u64_u32 v[48:49], s[28:29], v48, s13, v[8:9]
	v_mad_u64_u32 v[50:51], s[28:29], v50, s13, v[8:9]
	v_mad_u64_u32 v[52:53], s[28:29], v52, s13, v[8:9]
	v_mad_u64_u32 v[54:55], s[28:29], v54, s13, v[8:9]
	v_mad_u64_u32 v[56:57], s[28:29], v56, s13, v[8:9]
	v_mad_u64_u32 v[58:59], s[28:29], v58, s13, v[8:9]
	v_mad_u64_u32 v[60:61], s[28:29], v60, s13, v[8:9]
	v_mad_u64_u32 v[62:63], s[28:29], v62, s13, v[8:9]
	s_waitcnt vmcnt(15)
	ds_write_b32 v32, v21
	s_waitcnt vmcnt(14)
	ds_write_b32 v34, v23
	s_waitcnt vmcnt(13)
	ds_write_b32 v36, v64
	s_waitcnt vmcnt(12)
	ds_write_b32 v38, v65
	s_waitcnt vmcnt(11)
	ds_write_b32 v40, v66
	s_waitcnt vmcnt(10)
	ds_write_b32 v42, v67
	s_waitcnt vmcnt(9)
	ds_write_b32 v44, v68
	s_waitcnt vmcnt(8)
	ds_write_b32 v46, v69
	s_waitcnt vmcnt(7)
	ds_write_b32 v48, v70
	s_waitcnt vmcnt(6)
	ds_write_b32 v50, v71
	s_waitcnt vmcnt(5)
	ds_write_b32 v52, v72
	s_waitcnt vmcnt(4)
	ds_write_b32 v54, v73
	s_waitcnt vmcnt(3)
	ds_write_b32 v56, v4
	s_waitcnt vmcnt(2)
	ds_write_b32 v58, v74
	s_waitcnt vmcnt(1)
	ds_write_b32 v60, v75
	s_waitcnt vmcnt(0)
	ds_write_b32 v62, v76
	s_cbranch_scc1 .LBB0_34
; #define GAS __attribute__((address_space(1)))
; #define LAS __attribute__((address_space(3)))
; #define LDS_WAIT() asm volatile("s_waitcnt lgkmcnt(0)" ::: "memory")
; __device__ __forceinline__ unsigned f2bf(float f) { unsigned u = __builtin_bit_cast(unsigned, f); return (u + 0x7fffu + ((u >> 16) & 1u)) >> 16; }
; __device__ __forceinline__ unsigned pk2(float lo, float hi) { return f2bf(lo) | (f2bf(hi) << 16); }
; __device__ __forceinline__ void p0_transpose_item(const float* W, int ld, int K, int ncols, bf16* WT, LAS float* scr, int item, int lane) {
;     ...
;     const int c = lane & 7;
; #pragma unroll
;     for (int j = 0; j < 4; ++j) { const int n = (lane >> 3) + 8 * j; const LAS float* s = scr + (8 * c) * 33 + n;
;         v4u o; o.x = pk2(s[0 * 33], s[1 * 33]); o.y = pk2(s[2 * 33], s[3 * 33]); o.z = pk2(s[4 * 33], s[5 * 33]); o.w = pk2(s[6 * 33], s[7 * 33]);
;         *(GAS v4u*)(WT + (size_t)(n0 + n) * K + k0 + 8 * c) = o; }
;     LDS_WAIT(); asm volatile("" ::: "memory");
	s_waitcnt lgkmcnt(0)
	ds_read2_b32 v[24:25], v28 offset1:8
	ds_read2_b32 v[38:39], v28 offset0:33 offset1:41
	ds_read2_b32 v[40:41], v28 offset0:66 offset1:74
	ds_read2_b32 v[42:43], v28 offset0:99 offset1:107
	ds_read2_b32 v[44:45], v28 offset0:132 offset1:140
	ds_read2_b32 v[46:47], v28 offset0:165 offset1:173
	s_waitcnt lgkmcnt(5)
	v_bfe_u32 v3, v24, 16, 1
	v_add3_u32 v3, v24, v3, s15
	s_waitcnt lgkmcnt(4)
	v_bfe_u32 v4, v38, 16, 1
	v_lshrrev_b32_e32 v3, 16, v3
	v_add3_u32 v4, v38, v4, s15
	v_and_or_b32 v32, v4, s16, v3
	s_waitcnt lgkmcnt(3)
	v_bfe_u32 v3, v40, 16, 1
	v_add3_u32 v3, v40, v3, s15
	s_waitcnt lgkmcnt(2)
	v_bfe_u32 v4, v42, 16, 1
	ds_read2_b32 v[48:49], v28 offset0:198 offset1:206
	v_lshrrev_b32_e32 v3, 16, v3
	v_add3_u32 v4, v42, v4, s15
	ds_read2_b32 v[50:51], v28 offset0:231 offset1:239
	v_and_or_b32 v33, v4, s16, v3
	s_waitcnt lgkmcnt(3)
	v_bfe_u32 v3, v44, 16, 1
	v_add3_u32 v3, v44, v3, s15
	s_waitcnt lgkmcnt(2)
	v_bfe_u32 v4, v46, 16, 1
	v_lshrrev_b32_e32 v3, 16, v3
	v_add3_u32 v4, v46, v4, s15
	v_and_or_b32 v34, v4, s16, v3
	s_waitcnt lgkmcnt(1)
	v_bfe_u32 v3, v48, 16, 1
	v_add3_u32 v3, v48, v3, s15
	s_waitcnt lgkmcnt(0)
	v_bfe_u32 v4, v50, 16, 1
	v_lshrrev_b32_e32 v3, 16, v3
	v_add3_u32 v4, v50, v4, s15
	s_lshl_b32 s6, s6, 1
	v_and_or_b32 v35, v4, s16, v3
	v_or_b32_e32 v3, s22, v27
	v_lshl_add_u64 v[36:37], v[14:15], 0, s[6:7]
	v_lshlrev_b32_e32 v4, 11, v3
	v_bfe_u32 v3, v25, 16, 1
	v_lshl_add_u64 v[52:53], v[36:37], 0, v[4:5]
	v_add3_u32 v3, v25, v3, s15
	v_bfe_u32 v4, v39, 16, 1
	v_lshrrev_b32_e32 v3, 16, v3
	v_add3_u32 v4, v39, v4, s15
	global_store_dwordx4 v[52:53], v[32:35], off sc1
	ds_read2_b32 v[24:25], v28 offset0:16 offset1:24
	s_nop 0
	v_and_or_b32 v32, v4, s16, v3
	v_bfe_u32 v3, v41, 16, 1
	v_add3_u32 v3, v41, v3, s15
	v_bfe_u32 v4, v43, 16, 1
	v_lshrrev_b32_e32 v3, 16, v3
	v_add3_u32 v4, v43, v4, s15
	v_and_or_b32 v33, v4, s16, v3
	v_bfe_u32 v3, v45, 16, 1
	v_add3_u32 v3, v45, v3, s15
	v_bfe_u32 v4, v47, 16, 1
	v_lshrrev_b32_e32 v3, 16, v3
	v_add3_u32 v4, v47, v4, s15
	v_and_or_b32 v34, v4, s16, v3
	v_bfe_u32 v3, v49, 16, 1
	v_add3_u32 v3, v49, v3, s15
	v_bfe_u32 v4, v51, 16, 1
	v_lshrrev_b32_e32 v3, 16, v3
	v_add3_u32 v4, v51, v4, s15
	v_and_or_b32 v35, v4, s16, v3
	v_or_b32_e32 v3, s22, v29
	v_lshlrev_b32_e32 v4, 11, v3
	v_lshl_add_u64 v[38:39], v[36:37], 0, v[4:5]
	global_store_dwordx4 v[38:39], v[32:35], off sc1
	ds_read2_b32 v[38:39], v28 offset0:49 offset1:57
	ds_read2_b32 v[40:41], v28 offset0:82 offset1:90
	ds_read2_b32 v[42:43], v28 offset0:115 offset1:123
	s_waitcnt lgkmcnt(3)
	v_bfe_u32 v3, v24, 16, 1
	v_add3_u32 v3, v24, v3, s15
	s_waitcnt lgkmcnt(2)
	v_bfe_u32 v4, v38, 16, 1
	ds_read2_b32 v[44:45], v28 offset0:148 offset1:156
	v_lshrrev_b32_e32 v3, 16, v3
	v_add3_u32 v4, v38, v4, s15
	ds_read2_b32 v[46:47], v28 offset0:181 offset1:189
	v_and_or_b32 v32, v4, s16, v3
	s_waitcnt lgkmcnt(3)
	v_bfe_u32 v3, v40, 16, 1
	v_add3_u32 v3, v40, v3, s15
	s_waitcnt lgkmcnt(2)
	v_bfe_u32 v4, v42, 16, 1
	ds_read2_b32 v[48:49], v28 offset0:214 offset1:222
	v_lshrrev_b32_e32 v3, 16, v3
	v_add3_u32 v4, v42, v4, s15
	ds_read2_b32 v[50:51], v28 offset0:247 offset1:255
	v_and_or_b32 v33, v4, s16, v3
	s_waitcnt lgkmcnt(3)
	v_bfe_u32 v3, v44, 16, 1
	v_add3_u32 v3, v44, v3, s15
	s_waitcnt lgkmcnt(2)
	v_bfe_u32 v4, v46, 16, 1
	v_lshrrev_b32_e32 v3, 16, v3
	v_add3_u32 v4, v46, v4, s15
	v_and_or_b32 v34, v4, s16, v3
	s_waitcnt lgkmcnt(1)
	v_bfe_u32 v3, v48, 16, 1
	v_add3_u32 v3, v48, v3, s15
	s_waitcnt lgkmcnt(0)
	v_bfe_u32 v4, v50, 16, 1
	v_lshrrev_b32_e32 v3, 16, v3
	v_add3_u32 v4, v50, v4, s15
	v_and_or_b32 v35, v4, s16, v3
	v_or_b32_e32 v3, s22, v30
	v_lshlrev_b32_e32 v4, 11, v3
	v_bfe_u32 v3, v25, 16, 1
	v_lshl_add_u64 v[52:53], v[36:37], 0, v[4:5]
	v_add3_u32 v3, v25, v3, s15
	v_bfe_u32 v4, v39, 16, 1
	v_lshrrev_b32_e32 v3, 16, v3
	v_add3_u32 v4, v39, v4, s15
	global_store_dwordx4 v[52:53], v[32:35], off sc1
	s_nop 1
	v_and_or_b32 v32, v4, s16, v3
	v_bfe_u32 v3, v41, 16, 1
	v_add3_u32 v3, v41, v3, s15
	v_bfe_u32 v4, v43, 16, 1
	v_lshrrev_b32_e32 v3, 16, v3
	v_add3_u32 v4, v43, v4, s15
	v_and_or_b32 v33, v4, s16, v3
	v_bfe_u32 v3, v45, 16, 1
	v_add3_u32 v3, v45, v3, s15
	v_bfe_u32 v4, v47, 16, 1
	v_lshrrev_b32_e32 v3, 16, v3
	v_add3_u32 v4, v47, v4, s15
	v_and_or_b32 v34, v4, s16, v3
	v_bfe_u32 v3, v49, 16, 1
	v_add3_u32 v3, v49, v3, s15
	v_bfe_u32 v4, v51, 16, 1
	v_lshrrev_b32_e32 v3, 16, v3
	v_add3_u32 v4, v51, v4, s15
	v_and_or_b32 v35, v4, s16, v3
	v_or_b32_e32 v3, s22, v31
	v_lshlrev_b32_e32 v4, 11, v3
	v_lshl_add_u64 v[24:25], v[36:37], 0, v[4:5]
	global_store_dwordx4 v[24:25], v[32:35], off sc1
	s_waitcnt lgkmcnt(0)

; __device__ __forceinline__ void p0_transpose_item(const float* W, int ld, int K, int ncols, bf16* WT, LAS float* scr, int item, int lane) {
;     const int nblk = ncols / 32, kb = item / nblk, nb = item % nblk, k0 = 64 * kb, n0 = 32 * nb;
; #pragma unroll 8
;     for (int i = 0; i < 32; ++i) { const int kk = 2 * i + (lane >> 5); scr[kk * 33 + (lane & 31)] = W[(size_t)(k0 + kk) * ld + n0 + (lane & 31)]; }
.LBB0_39:
	s_lshl_b32 s27, s23, 1
	s_lshl_b32 s30, s24, 1
	v_or_b32_e32 v21, s27, v3
	v_or_b32_e32 v23, s30, v4
	s_add_i32 s31, s27, 4
	s_add_i32 s33, s30, 4
	s_add_i32 s34, s27, 8
	s_add_i32 s35, s30, 8
	s_add_i32 s36, s27, 12
	s_add_i32 s37, s30, 12
	s_add_i32 s38, s27, 16
	s_add_i32 s39, s30, 16
	s_add_i32 s40, s27, 20
	s_add_i32 s41, s30, 20
	s_add_i32 s42, s27, 24
	s_add_i32 s43, s30, 24
	s_add_i32 s44, s27, 28
	s_add_i32 s45, s30, 28
	v_mad_u64_u32 v[32:33], s[28:29], v23, s17, v[24:25]
	v_mad_u64_u32 v[34:35], s[28:29], v21, s17, v[24:25]
	v_or_b32_e32 v21, s31, v3
	v_or_b32_e32 v23, s33, v4
	v_or_b32_e32 v26, s34, v3
	v_or_b32_e32 v40, s35, v4
	v_or_b32_e32 v46, s36, v3
	v_or_b32_e32 v44, s37, v4
	v_or_b32_e32 v50, s38, v3
	v_or_b32_e32 v48, s39, v4
	v_or_b32_e32 v54, s40, v3
	v_or_b32_e32 v52, s41, v4
	v_or_b32_e32 v58, s42, v3
	v_or_b32_e32 v56, s43, v4
	v_or_b32_e32 v62, s44, v3
	v_or_b32_e32 v60, s45, v4
	v_mad_u64_u32 v[36:37], s[28:29], v23, s17, v[24:25]
	v_mad_u64_u32 v[38:39], s[28:29], v21, s17, v[24:25]
	v_mad_u64_u32 v[40:41], s[28:29], v40, s17, v[24:25]
	v_mad_u64_u32 v[42:43], s[28:29], v26, s17, v[24:25]
	v_mad_u64_u32 v[44:45], s[28:29], v44, s17, v[24:25]
	v_mad_u64_u32 v[46:47], s[28:29], v46, s17, v[24:25]
	v_mad_u64_u32 v[48:49], s[28:29], v48, s17, v[24:25]
	v_mad_u64_u32 v[50:51], s[28:29], v50, s17, v[24:25]
	v_mad_u64_u32 v[52:53], s[28:29], v52, s17, v[24:25]
	v_mad_u64_u32 v[54:55], s[28:29], v54, s17, v[24:25]
	v_mad_u64_u32 v[56:57], s[28:29], v56, s17, v[24:25]
	v_mad_u64_u32 v[58:59], s[28:29], v58, s17, v[24:25]
	v_mad_u64_u32 v[60:61], s[28:29], v60, s17, v[24:25]
	v_mad_u64_u32 v[62:63], s[28:29], v62, s17, v[24:25]
	global_load_dword v21, v[32:33], off
	global_load_dword v23, v[34:35], off
	global_load_dword v26, v[36:37], off
	global_load_dword v64, v[38:39], off
	global_load_dword v65, v[40:41], off
	global_load_dword v66, v[42:43], off
	global_load_dword v67, v[44:45], off
	global_load_dword v68, v[46:47], off
	global_load_dword v69, v[48:49], off
	global_load_dword v70, v[50:51], off
	global_load_dword v71, v[52:53], off
	global_load_dword v72, v[54:55], off
	global_load_dword v73, v[56:57], off
	global_load_dword v74, v[58:59], off
	global_load_dword v75, v[60:61], off
	global_load_dword v76, v[62:63], off
	v_or_b32_e32 v34, s27, v1
	v_or_b32_e32 v32, s30, v2
	s_add_i32 s24, s24, 16
	s_add_i32 s23, s23, 16
	s_add_i32 s25, s25, -16
	v_mad_u64_u32 v[32:33], s[28:29], v32, s13, v[8:9]
	v_mad_u64_u32 v[34:35], s[28:29], v34, s13, v[8:9]
	v_or_b32_e32 v33, s31, v1
	v_or_b32_e32 v35, s33, v2
	v_or_b32_e32 v42, s34, v1
	v_or_b32_e32 v40, s35, v2
	v_or_b32_e32 v46, s36, v1
	v_or_b32_e32 v44, s37, v2
	v_or_b32_e32 v50, s38, v1
	v_or_b32_e32 v48, s39, v2
	v_or_b32_e32 v54, s40, v1
	v_or_b32_e32 v52, s41, v2
	v_or_b32_e32 v58, s42, v1
	v_or_b32_e32 v56, s43, v2
	v_or_b32_e32 v62, s44, v1
	v_or_b32_e32 v60, s45, v2
	s_cmp_lg_u32 s25, 0
	v_mad_u64_u32 v[36:37], s[28:29], v35, s13, v[8:9]
	v_mad_u64_u32 v[38:39], s[28:29], v33, s13, v[8:9]
	v_mad_u64_u32 v[40:41], s[28:29], v40, s13, v[8:9]
	v_mad_u64_u32 v[42:43], s[28:29], v42, s13, v[8:9]
	v_mad_u64_u32 v[44:45], s[28:29], v44, s13, v[8:9]
	v_mad_u64_u32 v[46:47], s[28:29], v46, s13, v[8:9]
	v_mad_u64_u32 v[48:49], s[28:29], v48, s13, v[8:9]
	v_mad_u64_u32 v[50:51], s[28:29], v50, s13, v[8:9]
	v_mad_u64_u32 v[52:53], s[28:29], v52, s13, v[8:9]
	v_mad_u64_u32 v[54:55], s[28:29], v54, s13, v[8:9]
	v_mad_u64_u32 v[56:57], s[28:29], v56, s13, v[8:9]
	v_mad_u64_u32 v[58:59], s[28:29], v58, s13, v[8:9]
	v_mad_u64_u32 v[60:61], s[28:29], v60, s13, v[8:9]
	v_mad_u64_u32 v[62:63], s[28:29], v62, s13, v[8:9]
	s_waitcnt vmcnt(15)
	ds_write_b32 v32, v21
	s_waitcnt vmcnt(14)
	ds_write_b32 v34, v23
	s_waitcnt vmcnt(13)
	ds_write_b32 v36, v26
	s_waitcnt vmcnt(12)
	ds_write_b32 v38, v64
	s_waitcnt vmcnt(11)
	ds_write_b32 v40, v65
	s_waitcnt vmcnt(10)
	ds_write_b32 v42, v66
	s_waitcnt vmcnt(9)
	ds_write_b32 v44, v67
	s_waitcnt vmcnt(8)
	ds_write_b32 v46, v68
	s_waitcnt vmcnt(7)
	ds_write_b32 v48, v69
	s_waitcnt vmcnt(6)
	ds_write_b32 v50, v70
	s_waitcnt vmcnt(5)
	ds_write_b32 v52, v71
	s_waitcnt vmcnt(4)
	ds_write_b32 v54, v72
	s_waitcnt vmcnt(3)
	ds_write_b32 v56, v73
	s_waitcnt vmcnt(2)
	ds_write_b32 v58, v74
	s_waitcnt vmcnt(1)
	ds_write_b32 v60, v75
	s_waitcnt vmcnt(0)
	ds_write_b32 v62, v76
	s_cbranch_scc1 .LBB0_39
; #define GAS __attribute__((address_space(1)))
; #define LAS __attribute__((address_space(3)))
; #define LDS_WAIT() asm volatile("s_waitcnt lgkmcnt(0)" ::: "memory")
; __device__ __forceinline__ unsigned f2bf(float f) { unsigned u = __builtin_bit_cast(unsigned, f); return (u + 0x7fffu + ((u >> 16) & 1u)) >> 16; }
; __device__ __forceinline__ unsigned pk2(float lo, float hi) { return f2bf(lo) | (f2bf(hi) << 16); }
; __device__ __forceinline__ void p0_transpose_item(const float* W, int ld, int K, int ncols, bf16* WT, LAS float* scr, int item, int lane) {
;     ...
;     const int c = lane & 7;
; #pragma unroll
;     for (int j = 0; j < 4; ++j) { const int n = (lane >> 3) + 8 * j; const LAS float* s = scr + (8 * c) * 33 + n;
;         v4u o; o.x = pk2(s[0 * 33], s[1 * 33]); o.y = pk2(s[2 * 33], s[3 * 33]); o.z = pk2(s[4 * 33], s[5 * 33]); o.w = pk2(s[6 * 33], s[7 * 33]);
;         *(GAS v4u*)(WT + (size_t)(n0 + n) * K + k0 + 8 * c) = o; }
;     LDS_WAIT(); asm volatile("" ::: "memory");
	s_waitcnt lgkmcnt(0)
	ds_read2_b32 v[24:25], v28 offset1:8
	ds_read2_b32 v[38:39], v28 offset0:33 offset1:41
	ds_read2_b32 v[40:41], v28 offset0:66 offset1:74
	ds_read2_b32 v[42:43], v28 offset0:99 offset1:107
	ds_read2_b32 v[44:45], v28 offset0:132 offset1:140
	s_waitcnt lgkmcnt(4)
	v_bfe_u32 v3, v24, 16, 1
	v_add3_u32 v3, v24, v3, s15
	s_waitcnt lgkmcnt(3)
	v_bfe_u32 v4, v38, 16, 1
	v_lshrrev_b32_e32 v3, 16, v3
	v_add3_u32 v4, v38, v4, s15
	ds_read2_b32 v[46:47], v28 offset0:165 offset1:173
	v_and_or_b32 v32, v4, s16, v3
	s_waitcnt lgkmcnt(3)
	v_bfe_u32 v3, v40, 16, 1
	v_add3_u32 v3, v40, v3, s15
	s_waitcnt lgkmcnt(2)
	v_bfe_u32 v4, v42, 16, 1
	ds_read2_b32 v[48:49], v28 offset0:198 offset1:206
	v_lshrrev_b32_e32 v3, 16, v3
	v_add3_u32 v4, v42, v4, s15
	ds_read2_b32 v[50:51], v28 offset0:231 offset1:239
	v_and_or_b32 v33, v4, s16, v3
	s_waitcnt lgkmcnt(3)
	v_bfe_u32 v3, v44, 16, 1
	v_add3_u32 v3, v44, v3, s15
	s_waitcnt lgkmcnt(2)
	v_bfe_u32 v4, v46, 16, 1
	v_lshrrev_b32_e32 v3, 16, v3
	v_add3_u32 v4, v46, v4, s15
	v_and_or_b32 v34, v4, s16, v3
	s_waitcnt lgkmcnt(1)
	v_bfe_u32 v3, v48, 16, 1
	v_add3_u32 v3, v48, v3, s15
	s_waitcnt lgkmcnt(0)
	v_bfe_u32 v4, v50, 16, 1
	s_and_b32 s22, 0xffff, s22
	s_and_b32 s6, 0xffff, s6
	v_lshrrev_b32_e32 v3, 16, v3
	v_add3_u32 v4, v50, v4, s15
	s_lshl_b32 s6, s6, 1
	v_and_or_b32 v35, v4, s16, v3
	v_or_b32_e32 v3, s22, v27
	v_lshl_add_u64 v[36:37], v[16:17], 0, s[6:7]
	v_lshlrev_b32_e32 v4, 11, v3
	v_bfe_u32 v3, v25, 16, 1
	v_lshl_add_u64 v[52:53], v[36:37], 0, v[4:5]
	v_add3_u32 v3, v25, v3, s15
	v_bfe_u32 v4, v39, 16, 1
	v_lshrrev_b32_e32 v3, 16, v3
	v_add3_u32 v4, v39, v4, s15
	global_store_dwordx4 v[52:53], v[32:35], off sc1
	ds_read2_b32 v[24:25], v28 offset0:16 offset1:24
	s_nop 0
	v_and_or_b32 v32, v4, s16, v3
	v_bfe_u32 v3, v41, 16, 1
	v_add3_u32 v3, v41, v3, s15
	v_bfe_u32 v4, v43, 16, 1
	v_lshrrev_b32_e32 v3, 16, v3
	v_add3_u32 v4, v43, v4, s15
	v_and_or_b32 v33, v4, s16, v3
	v_bfe_u32 v3, v45, 16, 1
	v_add3_u32 v3, v45, v3, s15
	v_bfe_u32 v4, v47, 16, 1
	v_lshrrev_b32_e32 v3, 16, v3
	v_add3_u32 v4, v47, v4, s15
	v_and_or_b32 v34, v4, s16, v3
	v_bfe_u32 v3, v49, 16, 1
	v_add3_u32 v3, v49, v3, s15
	v_bfe_u32 v4, v51, 16, 1
	v_lshrrev_b32_e32 v3, 16, v3
	v_add3_u32 v4, v51, v4, s15
	v_and_or_b32 v35, v4, s16, v3
	v_or_b32_e32 v3, s22, v29
	v_lshlrev_b32_e32 v4, 11, v3
	v_lshl_add_u64 v[38:39], v[36:37], 0, v[4:5]
	global_store_dwordx4 v[38:39], v[32:35], off sc1
	ds_read2_b32 v[38:39], v28 offset0:49 offset1:57
	ds_read2_b32 v[40:41], v28 offset0:82 offset1:90
	ds_read2_b32 v[42:43], v28 offset0:115 offset1:123
	s_waitcnt lgkmcnt(3)
	v_bfe_u32 v3, v24, 16, 1
	v_add3_u32 v3, v24, v3, s15
	s_waitcnt lgkmcnt(2)
	v_bfe_u32 v4, v38, 16, 1
	ds_read2_b32 v[44:45], v28 offset0:148 offset1:156
	v_lshrrev_b32_e32 v3, 16, v3
	v_add3_u32 v4, v38, v4, s15
	ds_read2_b32 v[46:47], v28 offset0:181 offset1:189
	v_and_or_b32 v32, v4, s16, v3
	s_waitcnt lgkmcnt(3)
	v_bfe_u32 v3, v40, 16, 1
	v_add3_u32 v3, v40, v3, s15
	s_waitcnt lgkmcnt(2)
	v_bfe_u32 v4, v42, 16, 1
	ds_read2_b32 v[48:49], v28 offset0:214 offset1:222
	v_lshrrev_b32_e32 v3, 16, v3
	v_add3_u32 v4, v42, v4, s15
	ds_read2_b32 v[50:51], v28 offset0:247 offset1:255
	v_and_or_b32 v33, v4, s16, v3
	s_waitcnt lgkmcnt(3)
	v_bfe_u32 v3, v44, 16, 1
	v_add3_u32 v3, v44, v3, s15
	s_waitcnt lgkmcnt(2)
	v_bfe_u32 v4, v46, 16, 1
	v_lshrrev_b32_e32 v3, 16, v3
	v_add3_u32 v4, v46, v4, s15
	v_and_or_b32 v34, v4, s16, v3
	s_waitcnt lgkmcnt(1)
	v_bfe_u32 v3, v48, 16, 1
	v_add3_u32 v3, v48, v3, s15
	s_waitcnt lgkmcnt(0)
	v_bfe_u32 v4, v50, 16, 1
	v_lshrrev_b32_e32 v3, 16, v3
	v_add3_u32 v4, v50, v4, s15
	v_and_or_b32 v35, v4, s16, v3
	v_or_b32_e32 v3, s22, v30
	v_lshlrev_b32_e32 v4, 11, v3
	v_bfe_u32 v3, v25, 16, 1
	v_lshl_add_u64 v[52:53], v[36:37], 0, v[4:5]
	v_add3_u32 v3, v25, v3, s15
	v_bfe_u32 v4, v39, 16, 1
	v_lshrrev_b32_e32 v3, 16, v3
	v_add3_u32 v4, v39, v4, s15
	global_store_dwordx4 v[52:53], v[32:35], off sc1
	s_nop 1
	v_and_or_b32 v32, v4, s16, v3
	v_bfe_u32 v3, v41, 16, 1
	v_add3_u32 v3, v41, v3, s15
	v_bfe_u32 v4, v43, 16, 1
	v_lshrrev_b32_e32 v3, 16, v3
	v_add3_u32 v4, v43, v4, s15
	v_and_or_b32 v33, v4, s16, v3
	v_bfe_u32 v3, v45, 16, 1
	v_add3_u32 v3, v45, v3, s15
	v_bfe_u32 v4, v47, 16, 1
	v_lshrrev_b32_e32 v3, 16, v3
	v_add3_u32 v4, v47, v4, s15
	v_and_or_b32 v34, v4, s16, v3
	v_bfe_u32 v3, v49, 16, 1
	v_add3_u32 v3, v49, v3, s15
	v_bfe_u32 v4, v51, 16, 1
	v_lshrrev_b32_e32 v3, 16, v3
	v_add3_u32 v4, v51, v4, s15
	v_and_or_b32 v35, v4, s16, v3
	v_or_b32_e32 v3, s22, v31
	v_lshlrev_b32_e32 v4, 11, v3
	v_lshl_add_u64 v[24:25], v[36:37], 0, v[4:5]
	global_store_dwordx4 v[24:25], v[32:35], off sc1
	s_waitcnt lgkmcnt(0)

; __device__ __forceinline__ void p0_transpose_item(const float* W, int ld, int K, int ncols, bf16* WT, LAS float* scr, int item, int lane) {
;     const int nblk = ncols / 32, kb = item / nblk, nb = item % nblk, k0 = 64 * kb, n0 = 32 * nb;
; #pragma unroll 8
;     for (int i = 0; i < 32; ++i) { const int kk = 2 * i + (lane >> 5); scr[kk * 33 + (lane & 31)] = W[(size_t)(k0 + kk) * ld + n0 + (lane & 31)]; }
.LBB0_44:
	s_lshl_b32 s27, s6, 1
	s_lshl_b32 s30, s23, 1
	v_or_b32_e32 v21, s27, v3
	v_or_b32_e32 v23, s30, v4
	s_add_i32 s31, s27, 4
	s_add_i32 s33, s30, 4
	s_add_i32 s34, s27, 8
	s_add_i32 s35, s30, 8
	s_add_i32 s36, s27, 12
	s_add_i32 s37, s30, 12
	s_add_i32 s38, s27, 16
	s_add_i32 s39, s30, 16
	s_add_i32 s40, s27, 20
	s_add_i32 s41, s30, 20
	s_add_i32 s42, s27, 24
	s_add_i32 s43, s30, 24
	s_add_i32 s44, s27, 28
	s_add_i32 s45, s30, 28
	v_mad_i64_i32 v[32:33], s[28:29], v23, s17, v[24:25]
	v_mad_i64_i32 v[34:35], s[28:29], v21, s17, v[24:25]
	v_or_b32_e32 v21, s31, v3
	v_or_b32_e32 v23, s33, v4
	v_or_b32_e32 v26, s34, v3
	v_or_b32_e32 v40, s35, v4
	v_or_b32_e32 v46, s36, v3
	v_or_b32_e32 v44, s37, v4
	v_or_b32_e32 v50, s38, v3
	v_or_b32_e32 v48, s39, v4
	v_or_b32_e32 v54, s40, v3
	v_or_b32_e32 v52, s41, v4
	v_or_b32_e32 v58, s42, v3
	v_or_b32_e32 v56, s43, v4
	v_or_b32_e32 v62, s44, v3
	v_or_b32_e32 v60, s45, v4
	v_mad_i64_i32 v[36:37], s[28:29], v23, s17, v[24:25]
	v_mad_i64_i32 v[38:39], s[28:29], v21, s17, v[24:25]
	v_mad_i64_i32 v[40:41], s[28:29], v40, s17, v[24:25]
	v_mad_i64_i32 v[42:43], s[28:29], v26, s17, v[24:25]
	v_mad_i64_i32 v[44:45], s[28:29], v44, s17, v[24:25]
	v_mad_i64_i32 v[46:47], s[28:29], v46, s17, v[24:25]
	v_mad_i64_i32 v[48:49], s[28:29], v48, s17, v[24:25]
	v_mad_i64_i32 v[50:51], s[28:29], v50, s17, v[24:25]
	v_mad_i64_i32 v[52:53], s[28:29], v52, s17, v[24:25]
	v_mad_i64_i32 v[54:55], s[28:29], v54, s17, v[24:25]
	v_mad_i64_i32 v[56:57], s[28:29], v56, s17, v[24:25]
	v_mad_i64_i32 v[58:59], s[28:29], v58, s17, v[24:25]
	v_mad_i64_i32 v[60:61], s[28:29], v60, s17, v[24:25]
	v_mad_i64_i32 v[62:63], s[28:29], v62, s17, v[24:25]
	global_load_dword v21, v[32:33], off
	global_load_dword v23, v[34:35], off
	global_load_dword v26, v[36:37], off
	global_load_dword v64, v[38:39], off
	global_load_dword v65, v[40:41], off
	global_load_dword v66, v[42:43], off
	global_load_dword v67, v[44:45], off
	global_load_dword v68, v[46:47], off
	global_load_dword v69, v[48:49], off
	global_load_dword v70, v[50:51], off
	global_load_dword v71, v[52:53], off
	global_load_dword v72, v[54:55], off
	global_load_dword v73, v[56:57], off
	global_load_dword v74, v[58:59], off
	global_load_dword v75, v[60:61], off
	global_load_dword v76, v[62:63], off
	v_or_b32_e32 v34, s27, v1
	v_or_b32_e32 v32, s30, v2
	s_add_i32 s23, s23, 16
	s_add_i32 s6, s6, 16
	s_add_i32 s25, s25, -16
	v_mad_u64_u32 v[32:33], s[28:29], v32, s13, v[8:9]
	v_mad_u64_u32 v[34:35], s[28:29], v34, s13, v[8:9]
	v_or_b32_e32 v33, s31, v1
	v_or_b32_e32 v35, s33, v2
	v_or_b32_e32 v42, s34, v1
	v_or_b32_e32 v40, s35, v2
	v_or_b32_e32 v46, s36, v1
	v_or_b32_e32 v44, s37, v2
	v_or_b32_e32 v50, s38, v1
	v_or_b32_e32 v48, s39, v2
	v_or_b32_e32 v54, s40, v1
	v_or_b32_e32 v52, s41, v2
	v_or_b32_e32 v58, s42, v1
	v_or_b32_e32 v56, s43, v2
	v_or_b32_e32 v62, s44, v1
	v_or_b32_e32 v60, s45, v2
	s_cmp_lg_u32 s25, 0
	v_mad_u64_u32 v[36:37], s[28:29], v35, s13, v[8:9]
	v_mad_u64_u32 v[38:39], s[28:29], v33, s13, v[8:9]
	v_mad_u64_u32 v[40:41], s[28:29], v40, s13, v[8:9]
	v_mad_u64_u32 v[42:43], s[28:29], v42, s13, v[8:9]
	v_mad_u64_u32 v[44:45], s[28:29], v44, s13, v[8:9]
	v_mad_u64_u32 v[46:47], s[28:29], v46, s13, v[8:9]
	v_mad_u64_u32 v[48:49], s[28:29], v48, s13, v[8:9]
	v_mad_u64_u32 v[50:51], s[28:29], v50, s13, v[8:9]
	v_mad_u64_u32 v[52:53], s[28:29], v52, s13, v[8:9]
	v_mad_u64_u32 v[54:55], s[28:29], v54, s13, v[8:9]
	v_mad_u64_u32 v[56:57], s[28:29], v56, s13, v[8:9]
	v_mad_u64_u32 v[58:59], s[28:29], v58, s13, v[8:9]
	v_mad_u64_u32 v[60:61], s[28:29], v60, s13, v[8:9]
	v_mad_u64_u32 v[62:63], s[28:29], v62, s13, v[8:9]
	s_waitcnt vmcnt(15)
	ds_write_b32 v32, v21
	s_waitcnt vmcnt(14)
	ds_write_b32 v34, v23
	s_waitcnt vmcnt(13)
	ds_write_b32 v36, v26
	s_waitcnt vmcnt(12)
	ds_write_b32 v38, v64
	s_waitcnt vmcnt(11)
	ds_write_b32 v40, v65
	s_waitcnt vmcnt(10)
	ds_write_b32 v42, v66
	s_waitcnt vmcnt(9)
	ds_write_b32 v44, v67
	s_waitcnt vmcnt(8)
	ds_write_b32 v46, v68
	s_waitcnt vmcnt(7)
	ds_write_b32 v48, v69
	s_waitcnt vmcnt(6)
	ds_write_b32 v50, v70
	s_waitcnt vmcnt(5)
	ds_write_b32 v52, v71
	s_waitcnt vmcnt(4)
	ds_write_b32 v54, v72
	s_waitcnt vmcnt(3)
	ds_write_b32 v56, v73
	s_waitcnt vmcnt(2)
	ds_write_b32 v58, v74
	s_waitcnt vmcnt(1)
	ds_write_b32 v60, v75
	s_waitcnt vmcnt(0)
	ds_write_b32 v62, v76
	s_cbranch_scc1 .LBB0_44
; #define GAS __attribute__((address_space(1)))
; #define LAS __attribute__((address_space(3)))
; #define LDS_WAIT() asm volatile("s_waitcnt lgkmcnt(0)" ::: "memory")
; __device__ __forceinline__ unsigned f2bf(float f) { unsigned u = __builtin_bit_cast(unsigned, f); return (u + 0x7fffu + ((u >> 16) & 1u)) >> 16; }
; __device__ __forceinline__ unsigned pk2(float lo, float hi) { return f2bf(lo) | (f2bf(hi) << 16); }
; __device__ __forceinline__ void p0_transpose_item(const float* W, int ld, int K, int ncols, bf16* WT, LAS float* scr, int item, int lane) {
;     ...
;     const int c = lane & 7;
; #pragma unroll
;     for (int j = 0; j < 4; ++j) { const int n = (lane >> 3) + 8 * j; const LAS float* s = scr + (8 * c) * 33 + n;
;         v4u o; o.x = pk2(s[0 * 33], s[1 * 33]); o.y = pk2(s[2 * 33], s[3 * 33]); o.z = pk2(s[4 * 33], s[5 * 33]); o.w = pk2(s[6 * 33], s[7 * 33]);
;         *(GAS v4u*)(WT + (size_t)(n0 + n) * K + k0 + 8 * c) = o; }
;     LDS_WAIT(); asm volatile("" ::: "memory");
	s_waitcnt lgkmcnt(0)
	ds_read2_b32 v[24:25], v28 offset1:8
	ds_read2_b32 v[38:39], v28 offset0:33 offset1:41
	ds_read2_b32 v[40:41], v28 offset0:66 offset1:74
	ds_read2_b32 v[42:43], v28 offset0:99 offset1:107
	ds_read2_b32 v[44:45], v28 offset0:132 offset1:140
	ds_read2_b32 v[46:47], v28 offset0:165 offset1:173
	s_waitcnt lgkmcnt(5)
	v_bfe_u32 v3, v24, 16, 1
	v_add3_u32 v3, v24, v3, s15
	s_waitcnt lgkmcnt(4)
	v_bfe_u32 v4, v38, 16, 1
	v_lshrrev_b32_e32 v3, 16, v3
	v_add3_u32 v4, v38, v4, s15
	v_and_or_b32 v32, v4, s16, v3
	s_waitcnt lgkmcnt(3)
	v_bfe_u32 v3, v40, 16, 1
	v_add3_u32 v3, v40, v3, s15
	s_waitcnt lgkmcnt(2)
	v_bfe_u32 v4, v42, 16, 1
	ds_read2_b32 v[48:49], v28 offset0:198 offset1:206
	v_lshrrev_b32_e32 v3, 16, v3
	v_add3_u32 v4, v42, v4, s15
	ds_read2_b32 v[50:51], v28 offset0:231 offset1:239
	v_and_or_b32 v33, v4, s16, v3
	s_waitcnt lgkmcnt(3)
	v_bfe_u32 v3, v44, 16, 1
	v_add3_u32 v3, v44, v3, s15
	s_waitcnt lgkmcnt(2)
	v_bfe_u32 v4, v46, 16, 1
	v_lshrrev_b32_e32 v3, 16, v3
	v_add3_u32 v4, v46, v4, s15
	v_and_or_b32 v34, v4, s16, v3
	s_waitcnt lgkmcnt(1)
	v_bfe_u32 v3, v48, 16, 1
	v_add3_u32 v3, v48, v3, s15
	s_waitcnt lgkmcnt(0)
	v_bfe_u32 v4, v50, 16, 1
	v_lshrrev_b32_e32 v3, 16, v3
	v_add3_u32 v4, v50, v4, s15
	v_or_b32_e32 v52, s22, v27
	s_ashr_i32 s25, s24, 31
	v_and_or_b32 v35, v4, s16, v3
	v_ashrrev_i32_e32 v53, 31, v52
	v_bfe_u32 v3, v25, 16, 1
	v_lshl_add_u64 v[36:37], s[24:25], 1, v[18:19]
	v_lshlrev_b64 v[52:53], 11, v[52:53]
	v_add3_u32 v3, v25, v3, s15
	v_bfe_u32 v4, v39, 16, 1
	v_lshl_add_u64 v[52:53], v[36:37], 0, v[52:53]
	v_lshrrev_b32_e32 v3, 16, v3
	v_add3_u32 v4, v39, v4, s15
	global_store_dwordx4 v[52:53], v[32:35], off sc1
	v_or_b32_e32 v24, s22, v29
	v_ashrrev_i32_e32 v25, 31, v24
	v_and_or_b32 v32, v4, s16, v3
	v_bfe_u32 v3, v41, 16, 1
	v_add3_u32 v3, v41, v3, s15
	v_bfe_u32 v4, v43, 16, 1
	v_lshrrev_b32_e32 v3, 16, v3
	v_add3_u32 v4, v43, v4, s15
	v_and_or_b32 v33, v4, s16, v3
	v_bfe_u32 v3, v45, 16, 1
	v_add3_u32 v3, v45, v3, s15
	v_bfe_u32 v4, v47, 16, 1
	v_lshrrev_b32_e32 v3, 16, v3
	v_add3_u32 v4, v47, v4, s15
	v_and_or_b32 v34, v4, s16, v3
	v_bfe_u32 v3, v49, 16, 1
	v_add3_u32 v3, v49, v3, s15
	v_bfe_u32 v4, v51, 16, 1
	v_lshrrev_b32_e32 v3, 16, v3
	v_add3_u32 v4, v51, v4, s15
	v_lshlrev_b64 v[24:25], 11, v[24:25]
	v_and_or_b32 v35, v4, s16, v3
	ds_read2_b32 v[38:39], v28 offset0:16 offset1:24
	v_lshl_add_u64 v[24:25], v[36:37], 0, v[24:25]
	global_store_dwordx4 v[24:25], v[32:35], off sc1
	ds_read2_b32 v[24:25], v28 offset0:49 offset1:57
	ds_read2_b32 v[40:41], v28 offset0:82 offset1:90
	ds_read2_b32 v[42:43], v28 offset0:115 offset1:123
	s_waitcnt lgkmcnt(3)
	v_bfe_u32 v3, v38, 16, 1
	v_add3_u32 v3, v38, v3, s15
	s_waitcnt lgkmcnt(2)
	v_bfe_u32 v4, v24, 16, 1
	ds_read2_b32 v[44:45], v28 offset0:148 offset1:156
	v_lshrrev_b32_e32 v3, 16, v3
	v_add3_u32 v4, v24, v4, s15
	ds_read2_b32 v[46:47], v28 offset0:181 offset1:189
	v_and_or_b32 v32, v4, s16, v3
	s_waitcnt lgkmcnt(3)
	v_bfe_u32 v3, v40, 16, 1
	v_add3_u32 v3, v40, v3, s15
	s_waitcnt lgkmcnt(2)
	v_bfe_u32 v4, v42, 16, 1
	ds_read2_b32 v[48:49], v28 offset0:214 offset1:222
	v_lshrrev_b32_e32 v3, 16, v3
	v_add3_u32 v4, v42, v4, s15
	ds_read2_b32 v[50:51], v28 offset0:247 offset1:255
	v_and_or_b32 v33, v4, s16, v3
	s_waitcnt lgkmcnt(3)
	v_bfe_u32 v3, v44, 16, 1
	v_add3_u32 v3, v44, v3, s15
	s_waitcnt lgkmcnt(2)
	v_bfe_u32 v4, v46, 16, 1
	v_lshrrev_b32_e32 v3, 16, v3
	v_add3_u32 v4, v46, v4, s15
	v_and_or_b32 v34, v4, s16, v3
	s_waitcnt lgkmcnt(1)
	v_bfe_u32 v3, v48, 16, 1
	v_add3_u32 v3, v48, v3, s15
	s_waitcnt lgkmcnt(0)
	v_bfe_u32 v4, v50, 16, 1
	v_lshrrev_b32_e32 v3, 16, v3
	v_add3_u32 v4, v50, v4, s15
	v_or_b32_e32 v52, s22, v30
	v_and_or_b32 v35, v4, s16, v3
	v_ashrrev_i32_e32 v53, 31, v52
	v_bfe_u32 v3, v39, 16, 1
	v_lshlrev_b64 v[52:53], 11, v[52:53]
	v_add3_u32 v3, v39, v3, s15
	v_bfe_u32 v4, v25, 16, 1
	v_lshl_add_u64 v[52:53], v[36:37], 0, v[52:53]
	v_lshrrev_b32_e32 v3, 16, v3
	v_add3_u32 v4, v25, v4, s15
	global_store_dwordx4 v[52:53], v[32:35], off sc1
	v_or_b32_e32 v24, s22, v31
	v_ashrrev_i32_e32 v25, 31, v24
	v_and_or_b32 v32, v4, s16, v3
	v_bfe_u32 v3, v41, 16, 1
	v_add3_u32 v3, v41, v3, s15
	v_bfe_u32 v4, v43, 16, 1
	v_lshrrev_b32_e32 v3, 16, v3
	v_add3_u32 v4, v43, v4, s15
	v_and_or_b32 v33, v4, s16, v3
	v_bfe_u32 v3, v45, 16, 1
	v_add3_u32 v3, v45, v3, s15
	v_bfe_u32 v4, v47, 16, 1
	v_lshrrev_b32_e32 v3, 16, v3
	v_add3_u32 v4, v47, v4, s15
	v_and_or_b32 v34, v4, s16, v3
	v_bfe_u32 v3, v49, 16, 1
	v_add3_u32 v3, v49, v3, s15
	v_bfe_u32 v4, v51, 16, 1
	v_lshrrev_b32_e32 v3, 16, v3
	v_add3_u32 v4, v51, v4, s15
	v_lshlrev_b64 v[24:25], 11, v[24:25]
	v_and_or_b32 v35, v4, s16, v3
	v_lshl_add_u64 v[24:25], v[36:37], 0, v[24:25]
	global_store_dwordx4 v[24:25], v[32:35], off sc1
	s_waitcnt lgkmcnt(0)
	s_branch .LBB0_13

; __device__ __forceinline__ unsigned pk2(float lo, float hi) { return f2bf(lo) | (f2bf(hi) << 16); }
; __global__ void __launch_bounds__(NWAVES * 64, 2) hybrid_fwd(Args args) {
;     ...
;         for (int e = gt; e < 256 * 128; e += NGT) { const int row = e >> 7, k8 = (e & 127) * 8; v4u o = (v4u){0u, 0u, 0u, 0u};
;             if (row < 16) { const float* s = args->w_in + (size_t)k8 * IN_COLS + 5120 + row;
;                 o.x = pk2(s[0], s[IN_COLS]); o.y = pk2(s[2 * IN_COLS], s[3 * IN_COLS]); o.z = pk2(s[4 * IN_COLS], s[5 * IN_COLS]); o.w = pk2(s[6 * IN_COLS], s[7 * IN_COLS]); }
;             *(v4u*)(WinT + (size_t)(NZC + row) * D + k8) = o; }
.LBB0_48:
	s_or_b64 exec, exec, s[24:25]
	v_lshlrev_b64 v[12:13], 11, v[12:13]
	v_lshl_add_u64 v[12:13], s[4:5], 0, v[12:13]
	v_lshlrev_b32_e32 v10, 1, v14
	v_lshl_add_u64 v[12:13], v[12:13], 0, v[10:11]
	v_add_co_u32_e32 v12, vcc, 0x1600000, v12
	v_add_u32_e32 v9, s6, v9
	s_nop 0
	v_addc_co_u32_e32 v13, vcc, 0, v13, vcc
	v_cmp_lt_i32_e32 vcc, s3, v9
	s_or_b64 s[22:23], vcc, s[22:23]
	v_add_u32_e32 v1, s2, v1
	global_store_dwordx4 v[12:13], v[2:5], off sc1
	s_andn2_b64 exec, exec, s[22:23]
	s_cbranch_execz .LBB0_51

; __device__ __forceinline__ unsigned pk2(float lo, float hi) { return f2bf(lo) | (f2bf(hi) << 16); }
; __global__ void __launch_bounds__(NWAVES * 64, 2) hybrid_fwd(Args args) {
;     ...
;         for (int e = gt; e < 16 * 2 * 2 * 4 * 64; e += NGT) { const int ln = e & 63, ks = (e >> 6) & 3, rb = (e >> 8) & 1, mat = (e >> 9) & 1, gg = e >> 10;
;             const float* Wm = (mat ? args->w_lru_i : args->w_lru_r) + (size_t)gg * 64 * 64; const int j = 32 * rb + (ln & 31), hh = ln >> 5;
;             float f[8];
; #pragma unroll
;             for (int q = 0; q < 8; ++q) { const int k = 8 * (2 * ks + (q >> 2)) + 4 * hh + (q & 3); f[q] = Wm[k * 64 + j]; }
;             v4u o; o.x = pk2(f[0], f[1]); o.y = pk2(f[2], f[3]); o.z = pk2(f[4], f[5]); o.w = pk2(f[6], f[7]);
;             *(v4u*)((bf16*)(ws + WS_WRF) + (size_t)e * 8) = o; }
.LBB0_53:
	v_and_b32_e32 v4, 0x200, v1
	v_cmp_eq_u32_e32 vcc, 0, v4
	v_ashrrev_i32_e32 v12, 10, v1
	v_lshlrev_b32_e32 v14, 3, v1
	v_cndmask_b32_e64 v4, 64, 48, vcc
	v_lshl_add_u64 v[10:11], s[20:21], 0, v[4:5]
	global_load_dwordx2 v[10:11], v[10:11], off
	v_lshrrev_b32_e32 v4, 3, v1
	v_lshlrev_b32_e32 v15, 4, v1
	v_ashrrev_i32_e32 v13, 31, v12
	v_and_or_b32 v4, v4, 32, v6
	v_and_b32_e32 v14, 0x100, v14
	v_and_b32_e32 v15, 0xc00, v15
	v_lshlrev_b64 v[12:13], 14, v[12:13]
	v_or3_b32 v4, v15, v14, v4
	v_lshlrev_b32_e32 v4, 2, v4
	v_add_u32_e32 v1, s6, v1
	v_cmp_lt_i32_e32 vcc, s7, v1
	s_or_b64 s[22:23], vcc, s[22:23]
	s_waitcnt vmcnt(0)
	v_lshl_add_u64 v[10:11], v[10:11], 0, v[12:13]
	v_lshl_add_u64 v[10:11], v[10:11], 0, v[4:5]
	global_load_dword v4, v[10:11], off
	global_load_dword v12, v[10:11], off offset:256
	global_load_dword v13, v[10:11], off offset:512
	global_load_dword v14, v[10:11], off offset:768
	global_load_dword v15, v[10:11], off offset:2048
	global_load_dword v16, v[10:11], off offset:2304
	global_load_dword v17, v[10:11], off offset:2560
	global_load_dword v18, v[10:11], off offset:2816
	s_waitcnt vmcnt(7)
	v_bfe_u32 v10, v4, 16, 1
	s_waitcnt vmcnt(6)
	v_bfe_u32 v11, v12, 16, 1
	s_waitcnt vmcnt(5)
	v_bfe_u32 v19, v13, 16, 1
	s_waitcnt vmcnt(4)
	v_bfe_u32 v20, v14, 16, 1
	s_waitcnt vmcnt(3)
	v_bfe_u32 v21, v15, 16, 1
	s_waitcnt vmcnt(2)
	v_bfe_u32 v22, v16, 16, 1
	s_waitcnt vmcnt(1)
	v_bfe_u32 v23, v17, 16, 1
	s_waitcnt vmcnt(0)
	v_bfe_u32 v24, v18, 16, 1
	v_add3_u32 v4, v4, v10, s2
	v_add3_u32 v10, v12, v11, s2
	v_add3_u32 v11, v13, v19, s2
	v_add3_u32 v13, v15, v21, s2
	v_add3_u32 v15, v17, v23, s2
	v_add3_u32 v12, v14, v20, s2
	v_add3_u32 v14, v16, v22, s2
	v_add3_u32 v16, v18, v24, s2
	v_lshrrev_b32_e32 v4, 16, v4
	v_lshrrev_b32_e32 v11, 16, v11
	v_lshrrev_b32_e32 v13, 16, v13
	v_lshrrev_b32_e32 v15, 16, v15
	v_and_or_b32 v10, v10, s3, v4
	v_and_or_b32 v11, v12, s3, v11
	v_and_or_b32 v12, v14, s3, v13
	v_and_or_b32 v13, v16, s3, v15
	global_store_dwordx4 v[2:3], v[10:13], off sc1
	v_lshl_add_u64 v[2:3], v[2:3], 0, s[8:9]
	s_andn2_b64 exec, exec, s[22:23]
	s_cbranch_execnz .LBB0_53

; __global__ void __launch_bounds__(NWAVES * 64, 2) hybrid_fwd(Args args) {
;     ...
;         for (int e = gt; e < D; e += NGT) { const float x = -args->lru_lambda[e]; const float sp = fmaxf(x, 0.f) + log1pf(expf(-fabsf(x))); ((float*)(ws + WS_COEF))[e] = -8.f * sp * LOG2E; }
.LBB0_56:
	s_waitcnt lgkmcnt(0)
	v_lshl_add_u64 v[10:11], s[8:9], 0, v[2:3]
	global_load_dword v5, v[10:11], off
	v_add_u32_e32 v8, s6, v8
	v_cmp_lt_i32_e32 vcc, s29, v8
	s_or_b64 s[26:27], vcc, s[26:27]
	v_lshl_add_u64 v[10:11], s[22:23], 0, v[2:3]
	v_lshl_add_u64 v[2:3], v[2:3], 0, s[24:25]
	s_waitcnt vmcnt(0)
	v_mul_f32_e64 v12, |v5|, s2
	v_fma_f32 v13, |v5|, s2, -v12
	v_rndne_f32_e32 v14, v12
	v_fma_f32 v13, |v5|, s3, v13
	v_sub_f32_e32 v12, v12, v14
	v_add_f32_e32 v12, v12, v13
	v_cvt_i32_f32_e32 v14, v14
	v_exp_f32_e32 v12, v12
	v_cmp_ngt_f32_e64 vcc, |v5|, s7
	v_max_f32_e64 v9, -v5, -v5
	v_max_f32_e32 v9, 0, v9
	v_ldexp_f32 v12, v12, v14
	v_cndmask_b32_e32 v12, 0, v12, vcc
	v_cmp_nlt_f32_e64 vcc, |v5|, s13
	s_nop 1
	v_cndmask_b32_e32 v26, v1, v12, vcc
	v_add_f32_e32 v5, 1.0, v26
	v_add_f32_e32 v14, -1.0, v5
	v_frexp_mant_f32_e32 v15, v5
	v_cvt_f64_f32_e32 v[12:13], v5
	v_sub_f32_e32 v16, v14, v5
	v_frexp_exp_i32_f64_e32 v12, v[12:13]
	v_cmp_gt_f32_e32 vcc, s16, v15
	v_sub_f32_e32 v14, v26, v14
	v_add_f32_e32 v13, 1.0, v16
	v_subbrev_co_u32_e32 v12, vcc, 0, v12, vcc
	v_add_f32_e32 v13, v14, v13
	v_sub_u32_e32 v14, 0, v12
	v_ldexp_f32 v5, v5, v14
	v_ldexp_f32 v13, v13, v14
	v_add_f32_e32 v14, -1.0, v5
	v_add_f32_e32 v16, 1.0, v5
	v_add_f32_e32 v15, 1.0, v14
	v_add_f32_e32 v17, -1.0, v16
	v_sub_f32_e32 v15, v5, v15
	v_sub_f32_e32 v5, v5, v17
	v_add_f32_e32 v5, v13, v5
	v_add_f32_e32 v17, v13, v15
	v_add_f32_e32 v13, v16, v5
	v_rcp_f32_e32 v20, v13
	v_add_f32_e32 v15, v14, v17
	v_sub_f32_e32 v16, v16, v13
	v_add_f32_e32 v5, v5, v16
	v_mul_f32_e32 v22, v15, v20
	v_mul_f32_e32 v16, v13, v22
	v_fma_f32 v18, v22, v13, -v16
	v_sub_f32_e32 v14, v14, v15
	v_fmac_f32_e32 v18, v22, v5
	v_add_f32_e32 v21, v17, v14
	v_add_f32_e32 v14, v16, v18
	v_sub_f32_e32 v17, v15, v14
	v_mov_b32_e32 v19, v14
	v_pk_add_f32 v[14:15], v[14:15], v[16:17] neg_lo:[0,1] neg_hi:[0,1]
	v_cvt_f32_i32_e32 v12, v12
	v_pk_add_f32 v[14:15], v[14:15], v[18:19] neg_lo:[0,1] neg_hi:[0,1]
	v_cmp_neq_f32_e32 vcc, s15, v26
	v_add_f32_e32 v15, v21, v15
	v_add_f32_e32 v14, v14, v15
	v_add_f32_e32 v15, v17, v14
	v_mul_f32_e32 v19, v20, v15
	v_mul_f32_e32 v16, v13, v19
	v_fma_f32 v18, v19, v13, -v16
	v_sub_f32_e32 v17, v17, v15
	v_fmac_f32_e32 v18, v19, v5
	v_add_f32_e32 v21, v14, v17
	v_add_f32_e32 v23, v22, v19
	v_add_f32_e32 v14, v16, v18
	v_sub_f32_e32 v13, v23, v22
	v_sub_f32_e32 v17, v15, v14
	v_sub_f32_e32 v5, v19, v13
	v_mov_b32_e32 v19, v14
	v_pk_add_f32 v[14:15], v[14:15], v[16:17] neg_lo:[0,1] neg_hi:[0,1]
	s_nop 0
	v_pk_add_f32 v[14:15], v[14:15], v[18:19] neg_lo:[0,1] neg_hi:[0,1]
	s_nop 0
	v_add_f32_e32 v13, v21, v15
	v_add_f32_e32 v13, v14, v13
	v_add_f32_e32 v13, v17, v13
	v_mul_f32_e32 v13, v20, v13
	v_add_f32_e32 v5, v5, v13
	v_add_f32_e32 v13, v23, v5
	v_mul_f32_e32 v14, v13, v13
	v_sub_f32_e32 v16, v13, v23
	v_fmamk_f32 v17, v14, 0x3e9b6dac, v6
	v_ldexp_f32 v15, v13, 1
	v_sub_f32_e32 v16, v5, v16
	v_mul_f32_e32 v13, v13, v14
	v_fmaak_f32 v5, v14, v17, 0x3f2aaada
	v_ldexp_f32 v19, v16, 1
	v_pk_mul_f32 v[16:17], v[12:13], v[4:5]
	s_nop 0
	v_fma_f32 v14, v12, s17, -v16
	v_fmac_f32_e32 v14, 0xb102e308, v12
	v_pk_add_f32 v[12:13], v[16:17], v[14:15]
	v_mov_b32_e32 v18, v16
	v_sub_f32_e32 v5, v13, v15
	v_sub_f32_e32 v5, v17, v5
	v_add_f32_e32 v19, v19, v5
	v_pk_add_f32 v[20:21], v[12:13], v[16:17] neg_lo:[0,1] neg_hi:[0,1]
	v_pk_add_f32 v[16:17], v[12:13], v[18:19]
	v_mov_b32_e32 v15, v12
	v_mov_b32_e32 v21, v17
	v_pk_add_f32 v[24:25], v[14:15], v[20:21] neg_lo:[0,1] neg_hi:[0,1]
	v_pk_add_f32 v[14:15], v[14:15], v[20:21]
	v_mov_b32_e32 v23, v12
	v_pk_add_f32 v[20:21], v[14:15], v[12:13] op_sel:[1,0] op_sel_hi:[0,1] neg_lo:[0,1] neg_hi:[0,1]
	v_mov_b32_e32 v22, v19
	v_mov_b32_e32 v18, v17
	v_mov_b32_e32 v19, v15
	v_pk_mov_b32 v[12:13], v[12:13], v[20:21] op_sel:[1,0]
	v_pk_add_f32 v[16:17], v[16:17], v[20:21] op_sel_hi:[1,0] neg_lo:[0,1] neg_hi:[0,1]
	v_pk_add_f32 v[12:13], v[18:19], v[12:13] neg_lo:[0,1] neg_hi:[0,1]
	v_mov_b32_e32 v16, v24
	v_pk_add_f32 v[12:13], v[22:23], v[12:13] neg_lo:[0,1] neg_hi:[0,1]
	v_mov_b32_e32 v25, v15
	v_pk_add_f32 v[16:17], v[16:17], v[12:13]
	s_nop 0
	v_pk_add_f32 v[18:19], v[16:17], v[16:17] op_sel:[0,1] op_sel_hi:[1,0]
	s_nop 0
	v_pk_add_f32 v[14:15], v[14:15], v[18:19] op_sel:[1,0] op_sel_hi:[0,1]
	v_mov_b32_e32 v17, v14
	v_mov_b32_e32 v13, v18
	v_pk_add_f32 v[18:19], v[16:17], v[24:25] neg_lo:[0,1] neg_hi:[0,1]
	s_nop 0
	v_sub_f32_e32 v5, v16, v18
	v_pk_add_f32 v[12:13], v[12:13], v[18:19] neg_lo:[0,1] neg_hi:[0,1]
	v_sub_f32_e32 v5, v24, v5
	v_add_f32_e32 v5, v12, v5
	v_add_f32_e32 v5, v5, v13
	v_add_f32_e32 v5, v14, v5
	v_cndmask_b32_e32 v5, v1, v5, vcc
	v_cmp_lt_f32_e64 vcc, |v26|, s28
	s_nop 1
	v_cndmask_b32_e32 v5, v5, v26, vcc
	v_add_f32_e32 v5, v9, v5
	v_mul_f32_e32 v5, 0xc1000000, v5
	v_mul_f32_e32 v5, 0x3fb8aa3b, v5
	global_store_dword v[10:11], v5, off sc1
	s_andn2_b64 exec, exec, s[26:27]
	s_cbranch_execnz .LBB0_56

; #define GAS __attribute__((address_space(1)))
; __device__ __forceinline__ float wave_sum(float v, int lane) {
; #pragma unroll
;     for (int o = 1; o < 64; o <<= 1) v += __builtin_bit_cast(float, __builtin_amdgcn_ds_bpermute((lane ^ o) << 2, __builtin_bit_cast(int, v)));
;     return v;
; __device__ __forceinline__ void rms_rows4_to_bf16(const float* xrow, const float* g, bf16* orow, int lane) {
;     const GAS f32x4* xr = (const GAS f32x4*)xrow + lane; const GAS f32x4* gr = (const GAS f32x4*)g + lane;
;     f32x4 v[4][4]; float s[4] = {0.f, 0.f, 0.f, 0.f};
; #pragma unroll
;     for (int r = 0; r < 4; ++r)
; #pragma unroll
;         for (int j = 0; j < 4; ++j) v[r][j] = xr[r * (D / 4) + 64 * j];
; #pragma unroll
;     for (int r = 0; r < 4; ++r)
; #pragma unroll
;         for (int j = 0; j < 4; ++j) s[r] += (v[r][j].x * v[r][j].x + v[r][j].y * v[r][j].y) + (v[r][j].z * v[r][j].z + v[r][j].w * v[r][j].w);
; #pragma unroll
;     for (int r = 0; r < 4; ++r) { const float rs = 1.f / sqrtf(wave_sum(s[r], lane) * (1.f / D) + RMS_EPS);
.LBB0_59:
	global_load_dwordx4 v[14:17], v[76:77], off
	global_load_dwordx4 v[10:13], v[76:77], off offset:1024
	global_load_dwordx4 v[6:9], v[76:77], off offset:2048
	global_load_dwordx4 v[2:5], v[76:77], off offset:3072
	v_add_co_u32_e32 v22, vcc, 0x1000, v76
	global_load_dwordx4 v[18:21], v[74:75], off
	s_nop 0
	v_addc_co_u32_e32 v23, vcc, 0, v77, vcc
	v_add_co_u32_e32 v24, vcc, 0x2000, v76
	global_load_dwordx4 v[66:69], v[22:23], off
	global_load_dwordx4 v[62:65], v[22:23], off offset:1024
	global_load_dwordx4 v[58:61], v[22:23], off offset:2048
	global_load_dwordx4 v[54:57], v[22:23], off offset:3072
	v_addc_co_u32_e32 v25, vcc, 0, v77, vcc
	global_load_dwordx4 v[50:53], v[24:25], off
	global_load_dwordx4 v[46:49], v[24:25], off offset:1024
	global_load_dwordx4 v[42:45], v[24:25], off offset:2048
	global_load_dwordx4 v[38:41], v[24:25], off offset:3072
	v_add_co_u32_e32 v88, vcc, 0x3000, v76
	v_add_co_u32_e64 v80, s[4:5], s2, v78
	s_nop 0
	v_addc_co_u32_e32 v89, vcc, 0, v77, vcc
	global_load_dwordx4 v[34:37], v[88:89], off
	global_load_dwordx4 v[30:33], v[88:89], off offset:1024
	global_load_dwordx4 v[26:29], v[88:89], off offset:2048
	global_load_dwordx4 v[22:25], v[88:89], off offset:3072
	v_addc_co_u32_e64 v81, s[4:5], 0, v79, s[4:5]
	s_add_i32 s22, s22, s24
	s_cmp_gt_i32 s22, 0xffff
	v_lshl_add_u64 v[76:77], v[76:77], 0, s[26:27]
	s_waitcnt vmcnt(16)
	v_mul_f32_e32 v88, v15, v15
	v_mul_f32_e32 v89, v17, v17
	s_waitcnt vmcnt(15)
	v_mul_f32_e32 v90, v11, v11
	v_mul_f32_e32 v91, v13, v13
	s_waitcnt vmcnt(14)
	v_mul_f32_e32 v92, v7, v7
	v_mul_f32_e32 v93, v9, v9
	s_waitcnt vmcnt(13)
	v_mul_f32_e32 v94, v3, v3
	v_mul_f32_e32 v95, v5, v5
	v_fmac_f32_e32 v88, v14, v14
	v_fmac_f32_e32 v89, v16, v16
	v_fmac_f32_e32 v90, v10, v10
	v_fmac_f32_e32 v91, v12, v12
	v_fmac_f32_e32 v92, v6, v6
	v_fmac_f32_e32 v93, v8, v8
	v_fmac_f32_e32 v94, v2, v2
	v_fmac_f32_e32 v95, v4, v4
	v_add_f32_e32 v88, v88, v89
	v_add_f32_e32 v89, v90, v91
	v_add_f32_e32 v90, v92, v93
	v_add_f32_e32 v91, v94, v95
	s_waitcnt vmcnt(11)
	v_mul_f32_e32 v92, v67, v67
	v_mul_f32_e32 v93, v69, v69
	s_waitcnt vmcnt(10)
	v_mul_f32_e32 v94, v63, v63
	v_mul_f32_e32 v95, v65, v65
	v_add_f32_e32 v88, v88, v89
	s_waitcnt vmcnt(9)
	v_mul_f32_e32 v96, v59, v59
	v_mul_f32_e32 v97, v61, v61
	v_fmac_f32_e32 v92, v66, v66
	v_fmac_f32_e32 v93, v68, v68
	v_fmac_f32_e32 v94, v62, v62
	v_fmac_f32_e32 v95, v64, v64
	s_waitcnt vmcnt(6)
	v_mul_f32_e32 v101, v47, v47
	v_mul_f32_e32 v102, v49, v49
	v_add_f32_e32 v88, v88, v90
	v_mul_f32_e32 v98, v55, v55
	v_mul_f32_e32 v99, v57, v57
	v_fmac_f32_e32 v96, v58, v58
	v_fmac_f32_e32 v97, v60, v60
	v_mul_f32_e32 v89, v51, v51
	v_mul_f32_e32 v100, v53, v53
	v_add_f32_e32 v90, v92, v93
	v_add_f32_e32 v92, v94, v95
	v_fmac_f32_e32 v101, v46, v46
	v_fmac_f32_e32 v102, v48, v48
	v_add_f32_e32 v88, v88, v91
	v_fmac_f32_e32 v98, v54, v54
	v_fmac_f32_e32 v99, v56, v56
	s_waitcnt vmcnt(5)
	v_mul_f32_e32 v103, v43, v43
	v_mul_f32_e32 v104, v45, v45
	v_add_f32_e32 v93, v96, v97
	v_fmac_f32_e32 v89, v50, v50
	v_fmac_f32_e32 v100, v52, v52
	v_add_f32_e32 v90, v90, v92
	v_add_f32_e32 v91, v101, v102
	ds_bpermute_b32 v101, v82, v88
	s_waitcnt vmcnt(4)
	v_mul_f32_e32 v105, v39, v39
	v_mul_f32_e32 v106, v41, v41
	v_add_f32_e32 v94, v98, v99
	v_fmac_f32_e32 v103, v42, v42
	v_fmac_f32_e32 v104, v44, v44
	s_waitcnt vmcnt(3)
	v_mul_f32_e32 v95, v35, v35
	v_mul_f32_e32 v96, v37, v37
	s_waitcnt vmcnt(2)
	v_mul_f32_e32 v97, v31, v31
	v_mul_f32_e32 v98, v33, v33
	v_add_f32_e32 v89, v89, v100
	v_add_f32_e32 v90, v90, v93
	v_fmac_f32_e32 v105, v38, v38
	v_fmac_f32_e32 v106, v40, v40
	s_waitcnt vmcnt(1)
	v_mul_f32_e32 v99, v27, v27
	v_mul_f32_e32 v107, v29, v29
	v_add_f32_e32 v92, v103, v104
	v_fmac_f32_e32 v95, v34, v34
	v_fmac_f32_e32 v96, v36, v36
	v_fmac_f32_e32 v97, v30, v30
	v_fmac_f32_e32 v98, v32, v32
	v_add_f32_e32 v89, v89, v91
	v_add_f32_e32 v90, v90, v94
	s_waitcnt vmcnt(0)
	v_mul_f32_e32 v108, v23, v23
	v_mul_f32_e32 v109, v25, v25
	v_add_f32_e32 v100, v105, v106
	v_fmac_f32_e32 v99, v26, v26
	v_fmac_f32_e32 v107, v28, v28
	v_add_f32_e32 v91, v95, v96
	v_add_f32_e32 v93, v97, v98
	v_add_f32_e32 v89, v89, v92
	ds_bpermute_b32 v92, v82, v90
	v_fmac_f32_e32 v108, v22, v22
	v_fmac_f32_e32 v109, v24, v24
	v_add_f32_e32 v95, v99, v107
	v_add_f32_e32 v91, v91, v93
	v_add_f32_e32 v89, v89, v100
	v_add_f32_e32 v96, v108, v109
	v_add_f32_e32 v91, v91, v95
	ds_bpermute_b32 v93, v82, v89
	s_waitcnt lgkmcnt(2)
	v_add_f32_e32 v88, v88, v101
	v_add_f32_e32 v91, v91, v96
	ds_bpermute_b32 v95, v83, v88
	ds_bpermute_b32 v94, v82, v91
	s_waitcnt lgkmcnt(3)
	v_add_f32_e32 v90, v90, v92
	ds_bpermute_b32 v92, v83, v90
	s_waitcnt lgkmcnt(3)
	v_add_f32_e32 v89, v89, v93
	ds_bpermute_b32 v93, v83, v89
	s_waitcnt lgkmcnt(3)
	v_add_f32_e32 v88, v88, v95
	s_waitcnt lgkmcnt(2)
	v_add_f32_e32 v91, v91, v94
	ds_bpermute_b32 v94, v84, v88
	s_waitcnt lgkmcnt(2)
	v_add_f32_e32 v90, v90, v92
	ds_bpermute_b32 v92, v84, v90
	s_waitcnt lgkmcnt(2)
	v_add_f32_e32 v89, v89, v93
	ds_bpermute_b32 v93, v84, v89
	s_waitcnt lgkmcnt(2)
	v_add_f32_e32 v88, v88, v94
	ds_bpermute_b32 v94, v85, v88
	s_waitcnt lgkmcnt(2)
	v_add_f32_e32 v90, v90, v92
	ds_bpermute_b32 v92, v85, v90
	s_waitcnt lgkmcnt(2)
	v_add_f32_e32 v89, v89, v93
	ds_bpermute_b32 v93, v85, v89
	s_waitcnt lgkmcnt(2)
	v_add_f32_e32 v88, v88, v94
	ds_bpermute_b32 v94, v86, v88
	s_waitcnt lgkmcnt(2)
	v_add_f32_e32 v90, v90, v92
	ds_bpermute_b32 v92, v86, v90
	s_waitcnt lgkmcnt(2)
	v_add_f32_e32 v89, v89, v93
	ds_bpermute_b32 v93, v86, v89
	s_waitcnt lgkmcnt(2)
	v_add_f32_e32 v88, v88, v94
	ds_bpermute_b32 v94, v87, v88
	s_waitcnt lgkmcnt(2)
; #define GAS __attribute__((address_space(1)))
; __device__ __forceinline__ unsigned f2bf(float f) { unsigned u = __builtin_bit_cast(unsigned, f); return (u + 0x7fffu + ((u >> 16) & 1u)) >> 16; }
; __device__ __forceinline__ unsigned pk2(float lo, float hi) { return f2bf(lo) | (f2bf(hi) << 16); }
; __device__ __forceinline__ void rms_rows4_to_bf16(const float* xrow, const float* g, bf16* orow, int lane) {
;     ...
;     for (int r = 0; r < 4; ++r) { const float rs = 1.f / sqrtf(wave_sum(s[r], lane) * (1.f / D) + RMS_EPS);
;         GAS unsigned long long* o8 = (GAS unsigned long long*)(orow + (size_t)r * D) + lane;
; #pragma unroll
;         for (int j = 0; j < 4; ++j) { const f32x4 gg = gr[64 * j];
;             o8[64 * j] = (unsigned long long)pk2(v[r][j].x * rs * gg.x, v[r][j].y * rs * gg.y) | ((unsigned long long)pk2(v[r][j].z * rs * gg.z, v[r][j].w * rs * gg.w) << 32); } }
	v_add_f32_e32 v90, v90, v92
	ds_bpermute_b32 v92, v87, v90
	s_waitcnt lgkmcnt(2)
	v_add_f32_e32 v89, v89, v93
	ds_bpermute_b32 v93, v87, v89
	s_waitcnt lgkmcnt(2)
	v_add_f32_e32 v88, v88, v94
	v_fmamk_f32 v88, v88, 0x3a800000, v71
	v_mul_f32_e32 v94, 0x4f800000, v88
	v_cmp_gt_f32_e32 vcc, s3, v88
	s_waitcnt lgkmcnt(1)
	v_add_f32_e32 v90, v90, v92
	v_fmamk_f32 v90, v90, 0x3a800000, v71
	v_cndmask_b32_e32 v88, v88, v94, vcc
	v_sqrt_f32_e32 v92, v88
	s_waitcnt lgkmcnt(0)
	v_add_f32_e32 v89, v89, v93
	v_mul_f32_e32 v93, 0x4f800000, v90
	v_cmp_gt_f32_e64 s[4:5], s3, v90
	v_fmamk_f32 v89, v89, 0x3a800000, v71
	v_cmp_gt_f32_e64 s[6:7], s3, v89
	v_cndmask_b32_e64 v90, v90, v93, s[4:5]
	v_mul_f32_e32 v93, 0x4f800000, v89
	v_sqrt_f32_e32 v94, v90
	v_cndmask_b32_e64 v89, v89, v93, s[6:7]
	v_add_u32_e32 v95, -1, v92
	v_sqrt_f32_e32 v93, v89
	v_add_u32_e32 v96, 1, v92
	v_fma_f32 v97, -v95, v92, v88
	v_fma_f32 v98, -v96, v92, v88
	v_cmp_ge_f32_e64 s[8:9], 0, v97
	v_add_u32_e32 v97, 1, v94
	v_add_u32_e32 v99, -1, v93
	v_cndmask_b32_e64 v92, v92, v95, s[8:9]
	v_add_u32_e32 v95, -1, v94
	v_cmp_lt_f32_e64 s[8:9], 0, v98
	v_fma_f32 v98, -v97, v94, v90
	v_add_u32_e32 v100, 1, v93
	v_cndmask_b32_e64 v92, v92, v96, s[8:9]
	v_fma_f32 v96, -v95, v94, v90
	v_cmp_ge_f32_e64 s[8:9], 0, v96
	v_mul_f32_e32 v101, 0x37800000, v92
	v_fma_f32 v96, -v100, v93, v89
	v_cndmask_b32_e64 v94, v94, v95, s[8:9]
	v_cmp_lt_f32_e64 s[8:9], 0, v98
	v_fma_f32 v95, -v99, v93, v89
	v_cndmask_b32_e32 v92, v92, v101, vcc
	v_cndmask_b32_e64 v94, v94, v97, s[8:9]
	v_cmp_ge_f32_e32 vcc, 0, v95
	v_cmp_class_f32_e64 s[8:9], v88, v73
	s_nop 0
	v_cndmask_b32_e32 v93, v93, v99, vcc
	v_cmp_lt_f32_e32 vcc, 0, v96
	v_cndmask_b32_e64 v88, v92, v88, s[8:9]
	v_mul_f32_e32 v92, 0x37800000, v94
	v_cndmask_b32_e32 v93, v93, v100, vcc
	v_div_scale_f32 v95, s[8:9], v88, v88, 1.0
	v_cndmask_b32_e64 v92, v94, v92, s[4:5]
	v_cmp_class_f32_e64 s[4:5], v90, v73
	v_mul_f32_e32 v94, 0x37800000, v93
	v_rcp_f32_e32 v97, v95
	v_cndmask_b32_e64 v90, v92, v90, s[4:5]
	v_cndmask_b32_e64 v92, v93, v94, s[6:7]
	v_cmp_class_f32_e64 s[4:5], v89, v73
	v_div_scale_f32 v93, s[6:7], v90, v90, 1.0
	s_nop 0
	v_cndmask_b32_e64 v89, v92, v89, s[4:5]
	v_rcp_f32_e32 v92, v93
	v_div_scale_f32 v98, s[4:5], v89, v89, 1.0
	v_fma_f32 v101, -v95, v97, 1.0
	v_div_scale_f32 v96, vcc, 1.0, v88, 1.0
	v_rcp_f32_e32 v100, v98
	v_fmac_f32_e32 v97, v101, v97
	v_mul_f32_e32 v101, v96, v97
	v_fma_f32 v102, -v93, v92, 1.0
	v_div_scale_f32 v94, s[6:7], 1.0, v90, 1.0
	v_fma_f32 v103, -v95, v101, v96
	v_fmac_f32_e32 v92, v102, v92
	v_fmac_f32_e32 v101, v103, v97
	v_mul_f32_e32 v103, v94, v92
	v_fma_f32 v102, -v98, v100, 1.0
	v_fma_f32 v95, -v95, v101, v96
	v_fma_f32 v96, -v93, v103, v94
	v_div_scale_f32 v99, s[4:5], 1.0, v89, 1.0
	v_fmac_f32_e32 v100, v102, v100
	v_div_fmas_f32 v95, v95, v97, v101
	v_fmac_f32_e32 v103, v96, v92
	v_mul_f32_e32 v102, v99, v100
	v_div_fixup_f32 v88, v95, v88, 1.0
	v_fma_f32 v93, -v93, v103, v94
	s_mov_b64 vcc, s[6:7]
	v_fma_f32 v96, -v98, v102, v99
	v_mul_f32_e32 v14, v14, v88
	v_mul_f32_e32 v16, v16, v88
	v_mul_f32_e32 v94, v2, v88
	v_div_fmas_f32 v2, v93, v92, v103
	v_fmac_f32_e32 v102, v96, v100
	v_mul_f32_e32 v15, v15, v88
	v_mul_f32_e32 v17, v17, v88
	v_mul_f32_e32 v96, v4, v88
	v_mul_f32_e32 v4, v18, v14
	v_mul_f32_e32 v14, v20, v16
	v_div_fixup_f32 v2, v2, v90, 1.0
	v_mul_f32_e32 v10, v10, v88
	v_mul_f32_e32 v11, v11, v88
	v_mul_f32_e32 v12, v12, v88
	v_mul_f32_e32 v13, v13, v88
	v_mul_f32_e32 v6, v6, v88
	v_mul_f32_e32 v7, v7, v88
	v_mul_f32_e32 v8, v8, v88
	v_mul_f32_e32 v9, v9, v88
	v_mul_f32_e32 v95, v3, v88
	v_mul_f32_e32 v88, v5, v88
	v_fma_f32 v3, -v98, v102, v99
	v_mul_f32_e32 v5, v19, v15
	v_mul_f32_e32 v15, v21, v17
	s_mov_b64 vcc, s[4:5]
	v_mul_f32_e32 v16, v66, v2
	v_mul_f32_e32 v17, v67, v2
	v_mul_f32_e32 v18, v68, v2
	v_mul_f32_e32 v19, v69, v2
	v_mul_f32_e32 v20, v62, v2
	v_mul_f32_e32 v21, v63, v2
	v_mul_f32_e32 v62, v64, v2
	v_mul_f32_e32 v63, v65, v2
	v_mul_f32_e32 v58, v58, v2
	v_mul_f32_e32 v59, v59, v2
	v_mul_f32_e32 v60, v60, v2
	v_mul_f32_e32 v61, v61, v2
	v_mul_f32_e32 v54, v54, v2
	v_mul_f32_e32 v55, v55, v2
	v_mul_f32_e32 v56, v56, v2
	v_mul_f32_e32 v57, v57, v2
	v_bfe_u32 v2, v4, 16, 1
	v_bfe_u32 v65, v14, 16, 1
	v_div_fmas_f32 v3, v3, v100, v102
	v_bfe_u32 v64, v5, 16, 1
	v_bfe_u32 v66, v15, 16, 1
	v_add3_u32 v2, v4, v2, s13
	v_add3_u32 v4, v14, v65, s13
	v_div_fixup_f32 v67, v3, v89, 1.0
	v_add3_u32 v3, v5, v64, s13
	v_add3_u32 v5, v15, v66, s13
	v_lshrrev_b32_e32 v2, 16, v2
	v_lshrrev_b32_e32 v4, 16, v4
	v_and_or_b32 v2, v3, s15, v2
	v_and_or_b32 v3, v5, s15, v4
	global_store_dwordx2 v[78:79], v[2:3], off sc1
	global_load_dwordx4 v[2:5], v[74:75], off offset:1024
	v_mul_f32_e32 v14, v50, v67
	v_mul_f32_e32 v50, v52, v67
	v_mul_f32_e32 v15, v51, v67
	v_mul_f32_e32 v51, v53, v67
	v_mul_f32_e32 v46, v46, v67
	v_mul_f32_e32 v47, v47, v67
	s_waitcnt vmcnt(0)
	v_mul_f32_e32 v2, v2, v10
	v_mul_f32_e32 v4, v4, v12
	v_mul_f32_e32 v3, v3, v11
	v_mul_f32_e32 v5, v5, v13
	v_bfe_u32 v10, v2, 16, 1
	v_bfe_u32 v12, v4, 16, 1
	v_bfe_u32 v11, v3, 16, 1
	v_bfe_u32 v13, v5, 16, 1
	v_add3_u32 v2, v2, v10, s13
	v_add3_u32 v4, v4, v12, s13
	v_add3_u32 v3, v3, v11, s13
	v_add3_u32 v5, v5, v13, s13
	v_lshrrev_b32_e32 v2, 16, v2
	v_lshrrev_b32_e32 v4, 16, v4
	v_and_or_b32 v2, v3, s15, v2
	v_and_or_b32 v3, v5, s15, v4
	global_store_dwordx2 v[78:79], v[2:3], off offset:512 sc1
	global_load_dwordx4 v[2:5], v[74:75], off offset:2048
	v_mul_f32_e32 v10, v45, v67
	s_waitcnt vmcnt(0)
; #define GAS __attribute__((address_space(1)))
; __device__ __forceinline__ unsigned f2bf(float f) { unsigned u = __builtin_bit_cast(unsigned, f); return (u + 0x7fffu + ((u >> 16) & 1u)) >> 16; }
; __device__ __forceinline__ unsigned pk2(float lo, float hi) { return f2bf(lo) | (f2bf(hi) << 16); }
; __device__ __forceinline__ void rms_rows4_to_bf16(const float* xrow, const float* g, bf16* orow, int lane) {
;     ...
;     for (int r = 0; r < 4; ++r) { const float rs = 1.f / sqrtf(wave_sum(s[r], lane) * (1.f / D) + RMS_EPS);
;         GAS unsigned long long* o8 = (GAS unsigned long long*)(orow + (size_t)r * D) + lane;
; #pragma unroll
;         for (int j = 0; j < 4; ++j) { const f32x4 gg = gr[64 * j];
;             o8[64 * j] = (unsigned long long)pk2(v[r][j].x * rs * gg.x, v[r][j].y * rs * gg.y) | ((unsigned long long)pk2(v[r][j].z * rs * gg.z, v[r][j].w * rs * gg.w) << 32); } }
	v_mul_f32_e32 v2, v2, v6
	v_mul_f32_e32 v4, v4, v8
	v_mul_f32_e32 v3, v3, v7
	v_mul_f32_e32 v5, v5, v9
	v_bfe_u32 v6, v2, 16, 1
	v_bfe_u32 v8, v4, 16, 1
	v_bfe_u32 v7, v3, 16, 1
	v_bfe_u32 v9, v5, 16, 1
	v_add3_u32 v2, v2, v6, s13
	v_add3_u32 v4, v4, v8, s13
	v_add3_u32 v3, v3, v7, s13
	v_add3_u32 v5, v5, v9, s13
	v_lshrrev_b32_e32 v2, 16, v2
	v_lshrrev_b32_e32 v4, 16, v4
	v_and_or_b32 v2, v3, s15, v2
	v_and_or_b32 v3, v5, s15, v4
	global_store_dwordx2 v[78:79], v[2:3], off offset:1024 sc1
	global_load_dwordx4 v[2:5], v[74:75], off offset:3072
	s_waitcnt vmcnt(0)
	v_mul_f32_e32 v2, v94, v2
	v_mul_f32_e32 v4, v96, v4
	v_mul_f32_e32 v3, v95, v3
	v_mul_f32_e32 v5, v88, v5
	v_bfe_u32 v6, v2, 16, 1
	v_bfe_u32 v8, v4, 16, 1
	v_bfe_u32 v7, v3, 16, 1
	v_bfe_u32 v9, v5, 16, 1
	v_add3_u32 v2, v2, v6, s13
	v_add3_u32 v4, v4, v8, s13
	v_add3_u32 v3, v3, v7, s13
	v_add3_u32 v5, v5, v9, s13
	v_lshrrev_b32_e32 v2, 16, v2
	v_lshrrev_b32_e32 v4, 16, v4
	v_and_or_b32 v2, v3, s15, v2
	v_and_or_b32 v3, v5, s15, v4
	global_store_dwordx2 v[78:79], v[2:3], off offset:1536 sc1
	global_load_dwordx4 v[2:5], v[74:75], off
	s_waitcnt vmcnt(0)
	v_mul_f32_e32 v2, v2, v16
	v_mul_f32_e32 v4, v4, v18
	v_mul_f32_e32 v3, v3, v17
	v_mul_f32_e32 v5, v5, v19
	v_bfe_u32 v6, v2, 16, 1
	v_bfe_u32 v8, v4, 16, 1
	v_bfe_u32 v7, v3, 16, 1
	v_bfe_u32 v9, v5, 16, 1
	v_add3_u32 v2, v2, v6, s13
	v_add3_u32 v4, v4, v8, s13
	v_add3_u32 v3, v3, v7, s13
	v_add3_u32 v5, v5, v9, s13
	v_lshrrev_b32_e32 v2, 16, v2
	v_lshrrev_b32_e32 v4, 16, v4
	v_and_or_b32 v2, v3, s15, v2
	v_and_or_b32 v3, v5, s15, v4
	global_store_dwordx2 v[78:79], v[2:3], off offset:2048 sc1
	global_load_dwordx4 v[2:5], v[74:75], off offset:1024
	s_waitcnt vmcnt(0)
	v_mul_f32_e32 v2, v2, v20
	v_mul_f32_e32 v4, v4, v62
	v_mul_f32_e32 v3, v3, v21
	v_mul_f32_e32 v5, v5, v63
	v_bfe_u32 v6, v2, 16, 1
	v_bfe_u32 v8, v4, 16, 1
	v_bfe_u32 v7, v3, 16, 1
	v_bfe_u32 v9, v5, 16, 1
	v_add3_u32 v2, v2, v6, s13
	v_add3_u32 v4, v4, v8, s13
	v_add3_u32 v3, v3, v7, s13
	v_add3_u32 v5, v5, v9, s13
	v_lshrrev_b32_e32 v2, 16, v2
	v_lshrrev_b32_e32 v4, 16, v4
	v_and_or_b32 v2, v3, s15, v2
	v_and_or_b32 v3, v5, s15, v4
	global_store_dwordx2 v[78:79], v[2:3], off offset:2560 sc1
	global_load_dwordx4 v[2:5], v[74:75], off offset:2048
	s_waitcnt vmcnt(0)
	v_mul_f32_e32 v2, v2, v58
	v_mul_f32_e32 v4, v4, v60
	v_mul_f32_e32 v3, v3, v59
	v_mul_f32_e32 v5, v5, v61
	v_bfe_u32 v6, v2, 16, 1
	v_bfe_u32 v8, v4, 16, 1
	v_bfe_u32 v7, v3, 16, 1
	v_bfe_u32 v9, v5, 16, 1
	v_add3_u32 v2, v2, v6, s13
	v_add3_u32 v4, v4, v8, s13
	v_add3_u32 v3, v3, v7, s13
	v_add3_u32 v5, v5, v9, s13
	v_lshrrev_b32_e32 v2, 16, v2
	v_lshrrev_b32_e32 v4, 16, v4
	v_and_or_b32 v2, v3, s15, v2
	v_and_or_b32 v3, v5, s15, v4
	global_store_dwordx2 v[78:79], v[2:3], off offset:3072 sc1
	global_load_dwordx4 v[2:5], v[74:75], off offset:3072
	s_waitcnt vmcnt(0)
	v_mul_f32_e32 v2, v54, v2
	v_mul_f32_e32 v4, v56, v4
	v_mul_f32_e32 v3, v55, v3
	v_mul_f32_e32 v5, v57, v5
	v_bfe_u32 v6, v2, 16, 1
	v_bfe_u32 v8, v4, 16, 1
	v_bfe_u32 v7, v3, 16, 1
	v_bfe_u32 v9, v5, 16, 1
	v_add3_u32 v2, v2, v6, s13
	v_add3_u32 v4, v4, v8, s13
	v_add3_u32 v3, v3, v7, s13
	v_add3_u32 v5, v5, v9, s13
	v_lshrrev_b32_e32 v2, 16, v2
	v_lshrrev_b32_e32 v4, 16, v4
	v_and_or_b32 v2, v3, s15, v2
	v_and_or_b32 v3, v5, s15, v4
	global_store_dwordx2 v[78:79], v[2:3], off offset:3584 sc1
	global_load_dwordx4 v[2:5], v[74:75], off
	v_lshl_add_u64 v[78:79], v[78:79], 0, s[28:29]
	s_waitcnt vmcnt(0)
	v_mul_f32_e32 v2, v2, v14
	v_mul_f32_e32 v4, v4, v50
	v_mul_f32_e32 v3, v3, v15
	v_mul_f32_e32 v5, v5, v51
	v_bfe_u32 v6, v2, 16, 1
	v_bfe_u32 v8, v4, 16, 1
	v_bfe_u32 v7, v3, 16, 1
	v_bfe_u32 v9, v5, 16, 1
	v_add3_u32 v2, v2, v6, s13
	v_add3_u32 v4, v4, v8, s13
	v_add3_u32 v3, v3, v7, s13
	v_add3_u32 v5, v5, v9, s13
	v_lshrrev_b32_e32 v2, 16, v2
	v_lshrrev_b32_e32 v4, 16, v4
	v_and_or_b32 v2, v3, s15, v2
	v_and_or_b32 v3, v5, s15, v4
	global_store_dwordx2 v[80:81], v[2:3], off sc1
	global_load_dwordx4 v[2:5], v[74:75], off offset:1024
	v_mul_f32_e32 v6, v48, v67
	v_mul_f32_e32 v7, v49, v67
	s_waitcnt vmcnt(0)
	v_mul_f32_e32 v2, v2, v46
	v_mul_f32_e32 v4, v4, v6
	v_mul_f32_e32 v3, v3, v47
	v_mul_f32_e32 v5, v5, v7
	v_bfe_u32 v6, v2, 16, 1
	v_bfe_u32 v8, v4, 16, 1
	v_bfe_u32 v7, v3, 16, 1
	v_bfe_u32 v9, v5, 16, 1
	v_add3_u32 v2, v2, v6, s13
	v_add3_u32 v4, v4, v8, s13
	v_add3_u32 v3, v3, v7, s13
	v_add3_u32 v5, v5, v9, s13
	v_lshrrev_b32_e32 v2, 16, v2
	v_lshrrev_b32_e32 v4, 16, v4
	v_and_or_b32 v2, v3, s15, v2
	v_and_or_b32 v3, v5, s15, v4
	global_store_dwordx2 v[80:81], v[2:3], off offset:512 sc1
	global_load_dwordx4 v[2:5], v[74:75], off offset:2048
	ds_bpermute_b32 v6, v83, v91
	v_mul_f32_e32 v9, v44, v67
	v_mul_f32_e32 v8, v43, v67
	s_waitcnt lgkmcnt(0)
	v_add_f32_e32 v6, v91, v6
	ds_bpermute_b32 v7, v84, v6
	s_waitcnt lgkmcnt(0)
	v_add_f32_e32 v6, v6, v7
	v_mul_f32_e32 v7, v42, v67
	s_waitcnt vmcnt(0)
; #define GAS __attribute__((address_space(1)))
; __device__ __forceinline__ unsigned pk2(float lo, float hi) { return f2bf(lo) | (f2bf(hi) << 16); }
; __device__ __forceinline__ float wave_sum(float v, int lane) {
; #pragma unroll
;     for (int o = 1; o < 64; o <<= 1) v += __builtin_bit_cast(float, __builtin_amdgcn_ds_bpermute((lane ^ o) << 2, __builtin_bit_cast(int, v)));
;     return v;
; __device__ __forceinline__ void rms_rows4_to_bf16(const float* xrow, const float* g, bf16* orow, int lane) {
;     ...
;     for (int r = 0; r < 4; ++r) { const float rs = 1.f / sqrtf(wave_sum(s[r], lane) * (1.f / D) + RMS_EPS);
;         GAS unsigned long long* o8 = (GAS unsigned long long*)(orow + (size_t)r * D) + lane;
; #pragma unroll
;         for (int j = 0; j < 4; ++j) { const f32x4 gg = gr[64 * j];
;             o8[64 * j] = (unsigned long long)pk2(v[r][j].x * rs * gg.x, v[r][j].y * rs * gg.y) | ((unsigned long long)pk2(v[r][j].z * rs * gg.z, v[r][j].w * rs * gg.w) << 32); } }
	v_mul_f32_e32 v2, v2, v7
	v_mul_f32_e32 v4, v4, v9
	v_mul_f32_e32 v3, v3, v8
	v_mul_f32_e32 v5, v5, v10
	v_bfe_u32 v7, v2, 16, 1
	v_bfe_u32 v9, v4, 16, 1
	v_bfe_u32 v8, v3, 16, 1
	v_bfe_u32 v10, v5, 16, 1
	v_add3_u32 v2, v2, v7, s13
	v_add3_u32 v4, v4, v9, s13
	v_add3_u32 v3, v3, v8, s13
	v_add3_u32 v5, v5, v10, s13
	v_lshrrev_b32_e32 v2, 16, v2
	v_lshrrev_b32_e32 v4, 16, v4
	v_and_or_b32 v2, v3, s15, v2
	v_and_or_b32 v3, v5, s15, v4
	global_store_dwordx2 v[80:81], v[2:3], off offset:1024 sc1
	global_load_dwordx4 v[2:5], v[74:75], off offset:3072
	ds_bpermute_b32 v7, v85, v6
	v_mul_f32_e32 v9, v40, v67
	v_mul_f32_e32 v8, v39, v67
	v_mul_f32_e32 v10, v41, v67
	s_waitcnt lgkmcnt(0)
	v_add_f32_e32 v6, v6, v7
	ds_bpermute_b32 v7, v86, v6
	s_waitcnt lgkmcnt(0)
	v_add_f32_e32 v6, v6, v7
	ds_bpermute_b32 v7, v87, v6
	s_waitcnt lgkmcnt(0)
	v_add_f32_e32 v6, v6, v7
	v_fmamk_f32 v6, v6, 0x3a800000, v71
	v_mul_f32_e32 v7, 0x4f800000, v6
	v_cmp_gt_f32_e32 vcc, s3, v6
	s_waitcnt vmcnt(0)
	v_mul_f32_e32 v4, v9, v4
	v_cndmask_b32_e32 v6, v6, v7, vcc
	v_mul_f32_e32 v7, v38, v67
	v_mul_f32_e32 v2, v7, v2
	v_mul_f32_e32 v3, v8, v3
	v_mul_f32_e32 v5, v10, v5
	v_bfe_u32 v7, v2, 16, 1
	v_bfe_u32 v9, v4, 16, 1
	v_bfe_u32 v8, v3, 16, 1
	v_bfe_u32 v10, v5, 16, 1
	v_add3_u32 v2, v2, v7, s13
	v_add3_u32 v4, v4, v9, s13
	v_add3_u32 v3, v3, v8, s13
	v_add3_u32 v5, v5, v10, s13
	v_lshrrev_b32_e32 v2, 16, v2
	v_lshrrev_b32_e32 v4, 16, v4
	v_and_or_b32 v2, v3, s15, v2
	v_and_or_b32 v3, v5, s15, v4
	global_store_dwordx2 v[80:81], v[2:3], off offset:1536 sc1
	global_load_dwordx4 v[2:5], v[74:75], off
	v_sqrt_f32_e32 v7, v6
	s_nop 0
	v_add_u32_e32 v8, -1, v7
	v_add_u32_e32 v9, 1, v7
	v_fma_f32 v10, -v8, v7, v6
	v_fma_f32 v11, -v9, v7, v6
	v_cmp_ge_f32_e64 s[4:5], 0, v10
	s_nop 1
	v_cndmask_b32_e64 v7, v7, v8, s[4:5]
	v_cmp_lt_f32_e64 s[4:5], 0, v11
	s_nop 1
	v_cndmask_b32_e64 v7, v7, v9, s[4:5]
	v_mul_f32_e32 v8, 0x37800000, v7
	v_cndmask_b32_e32 v7, v7, v8, vcc
	v_cmp_class_f32_e32 vcc, v6, v73
	s_nop 1
	v_cndmask_b32_e32 v6, v7, v6, vcc
	v_div_scale_f32 v7, s[4:5], v6, v6, 1.0
	v_rcp_f32_e32 v9, v7
	v_div_scale_f32 v8, vcc, 1.0, v6, 1.0
	v_fma_f32 v10, -v7, v9, 1.0
	v_fmac_f32_e32 v9, v10, v9
	v_mul_f32_e32 v10, v8, v9
	v_fma_f32 v11, -v7, v10, v8
	v_fmac_f32_e32 v10, v11, v9
	v_fma_f32 v7, -v7, v10, v8
	v_div_fmas_f32 v7, v7, v9, v10
	v_div_fixup_f32 v6, v7, v6, 1.0
	v_mul_f32_e32 v7, v34, v6
	v_mul_f32_e32 v9, v36, v6
	v_mul_f32_e32 v8, v35, v6
	v_mul_f32_e32 v10, v37, v6
	s_waitcnt vmcnt(0)
	v_mul_f32_e32 v2, v2, v7
	v_mul_f32_e32 v4, v4, v9
	v_mul_f32_e32 v3, v3, v8
	v_mul_f32_e32 v5, v5, v10
	v_bfe_u32 v7, v2, 16, 1
	v_bfe_u32 v9, v4, 16, 1
	v_bfe_u32 v8, v3, 16, 1
	v_bfe_u32 v10, v5, 16, 1
	v_add3_u32 v2, v2, v7, s13
	v_add3_u32 v4, v4, v9, s13
	v_add3_u32 v3, v3, v8, s13
	v_add3_u32 v5, v5, v10, s13
	v_lshrrev_b32_e32 v2, 16, v2
	v_lshrrev_b32_e32 v4, 16, v4
	v_and_or_b32 v2, v3, s15, v2
	v_and_or_b32 v3, v5, s15, v4
	global_store_dwordx2 v[80:81], v[2:3], off offset:2048 sc1
	global_load_dwordx4 v[2:5], v[74:75], off offset:1024
	v_mul_f32_e32 v7, v30, v6
	v_mul_f32_e32 v9, v32, v6
	v_mul_f32_e32 v8, v31, v6
	v_mul_f32_e32 v10, v33, v6
	s_waitcnt vmcnt(0)
	v_mul_f32_e32 v2, v2, v7
	v_mul_f32_e32 v4, v4, v9
	v_mul_f32_e32 v3, v3, v8
	v_mul_f32_e32 v5, v5, v10
	v_bfe_u32 v7, v2, 16, 1
	v_bfe_u32 v9, v4, 16, 1
	v_bfe_u32 v8, v3, 16, 1
	v_bfe_u32 v10, v5, 16, 1
	v_add3_u32 v2, v2, v7, s13
	v_add3_u32 v4, v4, v9, s13
	v_add3_u32 v3, v3, v8, s13
	v_add3_u32 v5, v5, v10, s13
	v_lshrrev_b32_e32 v2, 16, v2
	v_lshrrev_b32_e32 v4, 16, v4
	v_and_or_b32 v2, v3, s15, v2
	v_and_or_b32 v3, v5, s15, v4
	global_store_dwordx2 v[80:81], v[2:3], off offset:2560 sc1
	global_load_dwordx4 v[2:5], v[74:75], off offset:2048
	v_mul_f32_e32 v7, v26, v6
	v_mul_f32_e32 v9, v28, v6
	v_mul_f32_e32 v8, v27, v6
	v_mul_f32_e32 v10, v29, v6
	s_waitcnt vmcnt(0)
	v_mul_f32_e32 v2, v2, v7
	v_mul_f32_e32 v4, v4, v9
	v_mul_f32_e32 v3, v3, v8
	v_mul_f32_e32 v5, v5, v10
	v_bfe_u32 v7, v2, 16, 1
	v_bfe_u32 v9, v4, 16, 1
	v_bfe_u32 v8, v3, 16, 1
	v_bfe_u32 v10, v5, 16, 1
	v_add3_u32 v2, v2, v7, s13
	v_add3_u32 v4, v4, v9, s13
	v_add3_u32 v3, v3, v8, s13
	v_add3_u32 v5, v5, v10, s13
	v_lshrrev_b32_e32 v2, 16, v2
	v_lshrrev_b32_e32 v4, 16, v4
	v_and_or_b32 v2, v3, s15, v2
	v_and_or_b32 v3, v5, s15, v4
	global_store_dwordx2 v[80:81], v[2:3], off offset:3072 sc1
	global_load_dwordx4 v[2:5], v[74:75], off offset:3072
	v_mul_f32_e32 v7, v22, v6
	v_mul_f32_e32 v9, v24, v6
	v_mul_f32_e32 v8, v23, v6
	v_mul_f32_e32 v6, v25, v6
	s_waitcnt vmcnt(0)
	v_mul_f32_e32 v2, v7, v2
	v_mul_f32_e32 v4, v9, v4
	v_mul_f32_e32 v3, v8, v3
	v_mul_f32_e32 v5, v6, v5
	v_bfe_u32 v6, v2, 16, 1
	v_bfe_u32 v8, v4, 16, 1
	v_bfe_u32 v7, v3, 16, 1
	v_bfe_u32 v9, v5, 16, 1
	v_add3_u32 v2, v2, v6, s13
	v_add3_u32 v4, v4, v8, s13
	v_add3_u32 v3, v3, v7, s13
	v_add3_u32 v5, v5, v9, s13
	v_lshrrev_b32_e32 v2, 16, v2
	v_lshrrev_b32_e32 v4, 16, v4
	v_and_or_b32 v2, v3, s15, v2
	v_and_or_b32 v3, v5, s15, v4
	global_store_dwordx2 v[80:81], v[2:3], off offset:3584 sc1
	s_cbranch_scc0 .LBB0_59

; #define GAS __attribute__((address_space(1)))
; __device__ __forceinline__ unsigned pk2(float lo, float hi) { return f2bf(lo) | (f2bf(hi) << 16); }
; __device__ __forceinline__ void rms_row_to_bf16(const float* xrow, const float* g, bf16* orow, int lane) {
;     const GAS f32x4* xr = (const GAS f32x4*)xrow + lane; const GAS f32x4* gr = (const GAS f32x4*)g + lane;
;     f32x4 v[4]; float s = 0.f;
; #pragma unroll
;     for (int j = 0; j < 4; ++j) { v[j] = xr[64 * j]; s += (v[j].x * v[j].x + v[j].y * v[j].y) + (v[j].z * v[j].z + v[j].w * v[j].w); }
;     const float rs = 1.f / sqrtf(wave_sum(s, lane) * (1.f / D) + RMS_EPS);
;     GAS unsigned long long* o8 = (GAS unsigned long long*)orow + lane;
; #pragma unroll
;     for (int j = 0; j < 4; ++j) { const f32x4 gg = gr[64 * j];
;         o8[64 * j] = (unsigned long long)pk2(v[j].x * rs * gg.x, v[j].y * rs * gg.y) | ((unsigned long long)pk2(v[j].z * rs * gg.z, v[j].w * rs * gg.w) << 32); }
; }
; __global__ void __launch_bounds__(NWAVES * 64, 2) hybrid_fwd(Args args) {
;     ...
;         for (int m = gw; m < NB * MEMLEN; m += NGW) rms_row_to_bf16(args->mem + (size_t)m * D, args->g_mem, MN + (size_t)m * D, lane);
.LBB0_62:
	global_load_dwordx4 v[20:23], v[10:11], off offset:-3072
	global_load_dwordx4 v[24:27], v[10:11], off offset:-2048
	global_load_dwordx4 v[28:31], v[10:11], off offset:-1024
	global_load_dwordx4 v[2:5], v[10:11], off
	global_load_dwordx4 v[32:35], v[6:7], off
	s_add_i32 s14, s14, s12
	v_lshl_add_u64 v[10:11], v[10:11], 0, s[8:9]
	s_cmpk_gt_i32 s14, 0x7ff
	s_waitcnt vmcnt(4)
	v_mul_f32_e32 v19, v21, v21
	v_mul_f32_e32 v36, v23, v23
	s_waitcnt vmcnt(3)
	v_mul_f32_e32 v37, v25, v25
	v_mul_f32_e32 v38, v27, v27
	s_waitcnt vmcnt(2)
	v_mul_f32_e32 v39, v29, v29
	v_mul_f32_e32 v40, v31, v31
	v_fmac_f32_e32 v19, v20, v20
	v_fmac_f32_e32 v36, v22, v22
	v_fmac_f32_e32 v37, v24, v24
	v_fmac_f32_e32 v38, v26, v26
	s_waitcnt vmcnt(1)
	v_mul_f32_e32 v41, v3, v3
	v_mul_f32_e32 v42, v5, v5
	v_fmac_f32_e32 v39, v28, v28
	v_fmac_f32_e32 v40, v30, v30
	v_add_f32_e32 v19, v19, v36
	v_add_f32_e32 v36, v37, v38
	v_fmac_f32_e32 v41, v2, v2
	v_fmac_f32_e32 v42, v4, v4
	v_add_f32_e32 v37, v39, v40
	v_add_f32_e32 v19, v19, v36
	v_add_f32_e32 v38, v41, v42
	v_add_f32_e32 v19, v19, v37
	v_add_f32_e32 v19, v19, v38
	ds_bpermute_b32 v36, v12, v19
	s_waitcnt lgkmcnt(0)
	v_add_f32_e32 v19, v19, v36
	ds_bpermute_b32 v36, v13, v19
	s_waitcnt lgkmcnt(0)
	v_add_f32_e32 v19, v19, v36
	ds_bpermute_b32 v36, v14, v19
	s_waitcnt lgkmcnt(0)
	v_add_f32_e32 v19, v19, v36
	ds_bpermute_b32 v36, v15, v19
	s_waitcnt lgkmcnt(0)
	v_add_f32_e32 v19, v19, v36
	ds_bpermute_b32 v36, v16, v19
	s_waitcnt lgkmcnt(0)
	v_add_f32_e32 v19, v19, v36
	ds_bpermute_b32 v36, v1, v19
	s_waitcnt lgkmcnt(0)
	v_add_f32_e32 v19, v19, v36
	v_fmamk_f32 v19, v19, 0x3a800000, v17
	v_mul_f32_e32 v36, 0x4f800000, v19
	v_cmp_gt_f32_e32 vcc, s2, v19
	s_nop 1
	v_cndmask_b32_e32 v19, v19, v36, vcc
	v_sqrt_f32_e32 v36, v19
	s_nop 0
	v_add_u32_e32 v37, -1, v36
	v_add_u32_e32 v38, 1, v36
	v_fma_f32 v39, -v37, v36, v19
	v_fma_f32 v40, -v38, v36, v19
	v_cmp_ge_f32_e64 s[4:5], 0, v39
	s_nop 1
	v_cndmask_b32_e64 v36, v36, v37, s[4:5]
	v_cmp_lt_f32_e64 s[4:5], 0, v40
	s_nop 1
	v_cndmask_b32_e64 v36, v36, v38, s[4:5]
	v_mul_f32_e32 v37, 0x37800000, v36
	v_cndmask_b32_e32 v36, v36, v37, vcc
	v_cmp_class_f32_e32 vcc, v19, v18
	s_nop 1
	v_cndmask_b32_e32 v19, v36, v19, vcc
	v_div_scale_f32 v36, s[4:5], v19, v19, 1.0
	v_rcp_f32_e32 v38, v36
	v_div_scale_f32 v37, vcc, 1.0, v19, 1.0
	v_fma_f32 v39, -v36, v38, 1.0
	v_fmac_f32_e32 v38, v39, v38
	v_mul_f32_e32 v39, v37, v38
	v_fma_f32 v40, -v36, v39, v37
	v_fmac_f32_e32 v39, v40, v38
	v_fma_f32 v36, -v36, v39, v37
	v_div_fmas_f32 v36, v36, v38, v39
	v_div_fixup_f32 v19, v36, v19, 1.0
	v_mul_f32_e32 v20, v20, v19
	v_mul_f32_e32 v22, v22, v19
	v_mul_f32_e32 v21, v21, v19
	v_mul_f32_e32 v23, v23, v19
	s_waitcnt vmcnt(0)
	v_mul_f32_e32 v20, v32, v20
	v_mul_f32_e32 v22, v34, v22
	v_mul_f32_e32 v21, v33, v21
	v_mul_f32_e32 v23, v35, v23
	v_bfe_u32 v32, v20, 16, 1
	v_bfe_u32 v34, v22, 16, 1
	v_bfe_u32 v33, v21, 16, 1
	v_bfe_u32 v35, v23, 16, 1
	v_add3_u32 v20, v20, v32, s3
	v_add3_u32 v22, v22, v34, s3
	v_add3_u32 v21, v21, v33, s3
	v_add3_u32 v23, v23, v35, s3
	v_lshrrev_b32_e32 v20, 16, v20
	v_lshrrev_b32_e32 v22, 16, v22
	v_and_or_b32 v20, v21, s13, v20
	v_and_or_b32 v21, v23, s13, v22
	global_store_dwordx2 v[8:9], v[20:21], off sc1
	global_load_dwordx4 v[20:23], v[6:7], off offset:1024
	v_mul_f32_e32 v24, v24, v19
	v_mul_f32_e32 v26, v26, v19
	v_mul_f32_e32 v25, v25, v19
	v_mul_f32_e32 v27, v27, v19
	v_mul_f32_e32 v2, v2, v19
	v_mul_f32_e32 v4, v4, v19
	v_mul_f32_e32 v3, v3, v19
	v_mul_f32_e32 v5, v5, v19
	s_waitcnt vmcnt(0)
	v_mul_f32_e32 v20, v20, v24
	v_mul_f32_e32 v22, v22, v26
	v_mul_f32_e32 v21, v21, v25
	v_mul_f32_e32 v23, v23, v27
	v_bfe_u32 v24, v20, 16, 1
	v_bfe_u32 v26, v22, 16, 1
	v_bfe_u32 v25, v21, 16, 1
	v_bfe_u32 v27, v23, 16, 1
	v_add3_u32 v20, v20, v24, s3
	v_add3_u32 v22, v22, v26, s3
	v_add3_u32 v21, v21, v25, s3
	v_add3_u32 v23, v23, v27, s3
	v_lshrrev_b32_e32 v20, 16, v20
	v_lshrrev_b32_e32 v22, 16, v22
	v_and_or_b32 v20, v21, s13, v20
	v_and_or_b32 v21, v23, s13, v22
	global_store_dwordx2 v[8:9], v[20:21], off offset:512 sc1
	global_load_dwordx4 v[20:23], v[6:7], off offset:2048
	v_mul_f32_e32 v24, v28, v19
	v_mul_f32_e32 v26, v30, v19
	v_mul_f32_e32 v25, v29, v19
	v_mul_f32_e32 v27, v31, v19
	s_waitcnt vmcnt(0)
	v_mul_f32_e32 v20, v20, v24
	v_mul_f32_e32 v22, v22, v26
	v_mul_f32_e32 v21, v21, v25
	v_mul_f32_e32 v23, v23, v27
	v_bfe_u32 v24, v20, 16, 1
	v_bfe_u32 v26, v22, 16, 1
	v_bfe_u32 v25, v21, 16, 1
	v_bfe_u32 v27, v23, 16, 1
	v_add3_u32 v20, v20, v24, s3
	v_add3_u32 v22, v22, v26, s3
	v_add3_u32 v21, v21, v25, s3
	v_add3_u32 v23, v23, v27, s3
	v_lshrrev_b32_e32 v20, 16, v20
	v_lshrrev_b32_e32 v22, 16, v22
	v_and_or_b32 v20, v21, s13, v20
	v_and_or_b32 v21, v23, s13, v22
	global_store_dwordx2 v[8:9], v[20:21], off offset:1024 sc1
	global_load_dwordx4 v[20:23], v[6:7], off offset:3072
	s_waitcnt vmcnt(0)
	v_mul_f32_e32 v2, v20, v2
	v_mul_f32_e32 v4, v22, v4
	v_mul_f32_e32 v3, v21, v3
	v_mul_f32_e32 v5, v23, v5
	v_bfe_u32 v19, v2, 16, 1
	v_bfe_u32 v21, v4, 16, 1
	v_bfe_u32 v20, v3, 16, 1
	v_bfe_u32 v22, v5, 16, 1
	v_add3_u32 v2, v2, v19, s3
	v_add3_u32 v4, v4, v21, s3
	v_add3_u32 v3, v3, v20, s3
	v_add3_u32 v5, v5, v22, s3
	v_lshrrev_b32_e32 v2, 16, v2
	v_lshrrev_b32_e32 v4, 16, v4
	v_and_or_b32 v2, v3, s13, v2
	v_and_or_b32 v3, v5, s13, v4
	global_store_dwordx2 v[8:9], v[2:3], off offset:1536 sc1
	v_lshl_add_u64 v[8:9], v[8:9], 0, s[6:7]
	s_cbranch_scc0 .LBB0_62

; __device__ __forceinline__ unsigned xb_ld(unsigned* p)              { return __hip_atomic_load(p, __ATOMIC_RELAXED, __HIP_MEMORY_SCOPE_AGENT); }
; __device__ __forceinline__ unsigned xb_add(unsigned* p, unsigned v) { return __hip_atomic_fetch_add(p, v, __ATOMIC_RELAXED, __HIP_MEMORY_SCOPE_AGENT); }
; #define XB_SPIN(cond, bar) do { unsigned _sp = 0; while (cond) { __builtin_amdgcn_s_sleep(1); \
;     if ((++_sp & 255u) == 0u) { if (xb_ld(&(bar)[XB_TMO])) break; if (_sp > XB_SPIN_CAP) { atomicAdd(&(bar)[XB_TMO], 1u); break; } } } } while (0)
; __device__ __forceinline__ void xcd_barrier(const XcdBarrier& b) {
;     ...
;         if (old + 1u == (gen + 1u) * nloc) {
;             __builtin_amdgcn_fence(__ATOMIC_RELEASE, "agent");
;             asm volatile("s_waitcnt vmcnt(0)" ::: "memory");
;             const unsigned og = xb_add(&bar[XB_TOP], 1u);
;             const unsigned tg = og / nx;
;             if (og + 1u == (tg + 1u) * nx) xb_add(&bar[XB_TOPGEN], 1u);
;             else XB_SPIN(xb_ld(&bar[XB_TOPGEN]) == tg, bar);
.LBB0_107:
	s_andn2_saveexec_b64 s[2:3], s[14:15]
	s_cbranch_execz .LBB0_127
	s_mov_b64 s[14:15], exec
	s_waitcnt lgkmcnt(0)
	s_waitcnt vmcnt(0)
	buffer_inv sc1
	v_mbcnt_lo_u32_b32 v1, s14, 0
	v_mbcnt_hi_u32_b32 v1, s15, v1
	v_cmp_eq_u32_e32 vcc, 0, v1
	s_and_saveexec_b64 s[18:19], vcc
	s_cbranch_execz .LBB0_110
	s_bcnt1_i32_b64 s2, s[14:15]
	v_mov_b32_e32 v2, 0x7000
	v_mov_b32_e32 v3, s2
	global_atomic_add v2, v2, v3, s[6:7] offset:1024 sc0

; #define GAS __attribute__((address_space(1)))
; __global__ void __launch_bounds__(NWAVES * 64, 2) hybrid_fwd(Args args) {
;     ...
;         for (int it = kvcu ? MTOK : cc * NWAVES + wv; it < MTOK / 32; it += GG * NWAVES) {
;             const GAS bf16* ap = XNg + (size_t)(it * 32 + r32) * D + 8 * hi; const GAS bf16* bp = Wf + (size_t)r32 * D + 8 * hi;
;             f32x16 acc = f32x16{};
; #pragma unroll 8
;             for (int ks = 0; ks < 64; ++ks) { const bf16x8 af = __builtin_bit_cast(bf16x8, *(const GAS v4u*)(ap + 16 * ks)), bfv = __builtin_bit_cast(bf16x8, *(const GAS v4u*)(bp + 16 * ks));
;                 acc = __builtin_amdgcn_mfma_f32_32x32x16_bf16(af, bfv, acc, 0, 0, 0); }
;             if (r32 < 16) { const float bb = bfg[r32]; const int tok = it * 32, bg = tok >> 13, t = tok & (T - 1);
; #pragma unroll
;                 for (int g4 = 0; g4 < 4; ++g4) { f32x4 o;
; #pragma unroll
;                     for (int e = 0; e < 4; ++e) { const float x = acc[4 * g4 + e] + bb; o[e] = fminf(x, 0.f) - log1pf(__expf(-fabsf(x))); }
.LBB0_131:
	v_lshl_add_u64 v[28:29], v[26:27], 0, s[34:35]
	v_add_co_u32_e64 v28, s[4:5], s23, v28
	v_lshl_add_u64 v[34:35], v[24:25], 0, s[34:35]
	s_nop 0
	v_addc_co_u32_e64 v29, s[4:5], 0, v29, s[4:5]
	v_add_co_u32_e64 v54, s[4:5], s25, v34
	s_add_u32 s34, s34, 0x100
	s_nop 0
	v_addc_co_u32_e64 v55, s[4:5], 0, v35, s[4:5]
	global_load_dwordx4 v[34:37], v[28:29], off
	global_load_dwordx4 v[38:41], v[54:55], off
	global_load_dwordx4 v[42:45], v[28:29], off offset:32
	global_load_dwordx4 v[46:49], v[54:55], off offset:32
	global_load_dwordx4 v[50:53], v[28:29], off offset:64
	s_addc_u32 s35, s35, 0
	s_cmpk_eq_i32 s34, 0x800
	s_waitcnt vmcnt(3)
	v_mfma_f32_32x32x16_bf16 v[0:15], v[34:37], v[38:41], v[0:15]
	global_load_dwordx4 v[34:37], v[54:55], off offset:64
	global_load_dwordx4 v[38:41], v[28:29], off offset:96
	s_waitcnt vmcnt(3)
	v_mfma_f32_32x32x16_bf16 v[0:15], v[42:45], v[46:49], v[0:15]
	global_load_dwordx4 v[42:45], v[54:55], off offset:96
	global_load_dwordx4 v[46:49], v[28:29], off offset:128
	s_waitcnt vmcnt(3)
	v_mfma_f32_32x32x16_bf16 v[0:15], v[50:53], v[34:37], v[0:15]
	global_load_dwordx4 v[34:37], v[54:55], off offset:128
	global_load_dwordx4 v[50:53], v[28:29], off offset:160
	s_waitcnt vmcnt(3)
	v_mfma_f32_32x32x16_bf16 v[0:15], v[38:41], v[42:45], v[0:15]
	global_load_dwordx4 v[38:41], v[54:55], off offset:160
	global_load_dwordx4 v[42:45], v[28:29], off offset:192
	s_waitcnt vmcnt(3)
	v_mfma_f32_32x32x16_bf16 v[0:15], v[46:49], v[34:37], v[0:15]
	global_load_dwordx4 v[34:37], v[54:55], off offset:192
	global_load_dwordx4 v[46:49], v[28:29], off offset:224
	s_waitcnt vmcnt(3)
	v_mfma_f32_32x32x16_bf16 v[0:15], v[50:53], v[38:41], v[0:15]
	global_load_dwordx4 v[38:41], v[54:55], off offset:224
	s_waitcnt vmcnt(2)
	v_mfma_f32_32x32x16_bf16 v[0:15], v[42:45], v[34:37], v[0:15]
	s_waitcnt vmcnt(0)
	v_mfma_f32_32x32x16_bf16 v[0:15], v[46:49], v[38:41], v[0:15]
	s_cbranch_scc0 .LBB0_131
	s_and_saveexec_b64 s[34:35], vcc
	s_cbranch_execz .LBB0_129
	global_load_dword v23, v[18:19], off
	s_ashr_i32 s4, s3, 4
	s_lshl_b32 s5, s3, 7
	v_and_or_b32 v26, s4, -16, v30
	s_and_b32 s12, s5, 0x7f80
	v_mov_b64_e32 v[28:29], s[22:23]
	v_ashrrev_i32_e32 v27, 31, v26
	v_lshlrev_b64 v[26:27], 15, v[26:27]
	v_lshl_add_u64 v[26:27], s[20:21], 0, v[26:27]
	v_lshl_add_u64 v[26:27], v[26:27], 0, s[12:13]
	v_lshl_add_u64 v[26:27], v[26:27], 0, v[16:17]
	s_waitcnt vmcnt(0)
	v_add_f32_e32 v0, v23, v0
	v_mul_f32_e64 v34, |v0|, s27
	v_add_f32_e32 v1, v23, v1
	v_exp_f32_e32 v70, v34
	v_mul_f32_e64 v35, |v1|, s27
	v_exp_f32_e32 v71, v35
	v_add_f32_e32 v2, v23, v2
	v_add_f32_e32 v38, 1.0, v70
	v_frexp_mant_f32_e32 v41, v38
	v_cvt_f64_f32_e32 v[34:35], v38
	v_add_f32_e32 v39, 1.0, v71
	v_frexp_exp_i32_f64_e32 v34, v[34:35]
	v_cmp_gt_f32_e64 s[4:5], s29, v41
	v_add_f32_e32 v40, -1.0, v38
	v_add_f32_e32 v42, -1.0, v39
	v_frexp_mant_f32_e32 v43, v39
	v_cvt_f64_f32_e32 v[36:37], v39
	v_subbrev_co_u32_e64 v34, s[4:5], 0, v34, s[4:5]
	v_sub_f32_e32 v44, v40, v38
	v_sub_f32_e32 v35, v42, v39
	v_frexp_exp_i32_f64_e32 v36, v[36:37]
	v_cmp_gt_f32_e64 s[4:5], s29, v43
	v_sub_f32_e32 v40, v70, v40
	v_sub_f32_e32 v42, v71, v42
	v_add_f32_e32 v37, 1.0, v44
	v_add_f32_e32 v35, 1.0, v35
	v_subbrev_co_u32_e64 v36, s[4:5], 0, v36, s[4:5]
	v_add_f32_e32 v37, v40, v37
	v_sub_u32_e32 v40, 0, v34
	v_add_f32_e32 v41, v42, v35
	v_sub_u32_e32 v42, 0, v36
	v_cvt_f32_i32_e32 v35, v36
	v_cvt_f32_i32_e32 v34, v34
	v_ldexp_f32 v36, v38, v40
	v_ldexp_f32 v38, v37, v40
	v_ldexp_f32 v37, v39, v42
	v_ldexp_f32 v39, v41, v42
	v_pk_add_f32 v[40:41], v[36:37], 1.0 op_sel_hi:[1,0]
	v_pk_add_f32 v[42:43], v[36:37], -1.0 op_sel_hi:[1,0]
	v_pk_add_f32 v[44:45], v[40:41], -1.0 op_sel_hi:[1,0]
	v_pk_add_f32 v[46:47], v[42:43], 1.0 op_sel_hi:[1,0]
	v_pk_add_f32 v[44:45], v[36:37], v[44:45] neg_lo:[0,1] neg_hi:[0,1]
	v_pk_add_f32 v[36:37], v[36:37], v[46:47] neg_lo:[0,1] neg_hi:[0,1]
	v_pk_mul_f32 v[46:47], v[34:35], s[28:29] op_sel_hi:[1,0]
	v_pk_add_f32 v[44:45], v[38:39], v[44:45]
	v_pk_add_f32 v[36:37], v[38:39], v[36:37]
	v_pk_fma_f32 v[38:39], v[34:35], s[28:29], v[46:47] op_sel_hi:[1,0,1] neg_lo:[0,0,1] neg_hi:[0,0,1]
	v_pk_add_f32 v[52:53], v[40:41], v[44:45]
	v_pk_fma_f32 v[34:35], v[34:35], s[30:31], v[38:39] op_sel_hi:[1,0,1]
	v_rcp_f32_e32 v38, v52
	v_rcp_f32_e32 v39, v53
	v_pk_add_f32 v[54:55], v[42:43], v[36:37]
	v_pk_add_f32 v[40:41], v[52:53], v[40:41] neg_lo:[0,1] neg_hi:[0,1]
	v_pk_add_f32 v[42:43], v[54:55], v[42:43] neg_lo:[0,1] neg_hi:[0,1]
	v_pk_add_f32 v[40:41], v[44:45], v[40:41] neg_lo:[0,1] neg_hi:[0,1]
	v_pk_mul_f32 v[44:45], v[54:55], v[38:39]
	v_pk_add_f32 v[36:37], v[36:37], v[42:43] neg_lo:[0,1] neg_hi:[0,1]
	v_pk_mul_f32 v[62:63], v[52:53], v[44:45]
	v_pk_add_f32 v[56:57], v[46:47], v[34:35]
	v_pk_fma_f32 v[64:65], v[44:45], v[52:53], v[62:63] neg_lo:[0,0,1] neg_hi:[0,0,1]
	v_mov_b32_e32 v48, v46
	v_pk_fma_f32 v[64:65], v[44:45], v[40:41], v[64:65]
	v_mov_b32_e32 v58, v34
	v_pk_add_f32 v[66:67], v[62:63], v[64:65]
	v_mov_b32_e32 v51, v47
	v_pk_add_f32 v[68:69], v[54:55], v[66:67] neg_lo:[0,1] neg_hi:[0,1]
	v_pk_add_f32 v[62:63], v[66:67], v[62:63] neg_lo:[0,1] neg_hi:[0,1]
	v_pk_add_f32 v[54:55], v[54:55], v[68:69] neg_lo:[0,1] neg_hi:[0,1]
	v_pk_add_f32 v[62:63], v[62:63], v[64:65] neg_lo:[0,1] neg_hi:[0,1]
	v_pk_add_f32 v[54:55], v[54:55], v[66:67] neg_lo:[0,1] neg_hi:[0,1]
	v_mov_b32_e32 v43, v57
	v_pk_add_f32 v[36:37], v[36:37], v[54:55]
	v_mov_b32_e32 v50, v56
	v_pk_add_f32 v[36:37], v[62:63], v[36:37]
	v_mov_b32_e32 v61, v35
	v_pk_add_f32 v[54:55], v[68:69], v[36:37]
	v_cmp_neq_f32_e64 s[4:5], s31, v70
	v_pk_mul_f32 v[62:63], v[38:39], v[54:55]
; #define GAS __attribute__((address_space(1)))
; __global__ void __launch_bounds__(NWAVES * 64, 2) hybrid_fwd(Args args) {
;     ...
;             if (r32 < 16) { const float bb = bfg[r32]; const int tok = it * 32, bg = tok >> 13, t = tok & (T - 1);
; #pragma unroll
;                 for (int g4 = 0; g4 < 4; ++g4) { f32x4 o;
; #pragma unroll
;                     for (int e = 0; e < 4; ++e) { const float x = acc[4 * g4 + e] + bb; o[e] = fminf(x, 0.f) - log1pf(__expf(-fabsf(x))); }
;                     *(GAS f32x4*)(LFt + (size_t)(bg * 16 + r32) * T + t + 8 * g4 + 4 * hi) = o; } }
	v_pk_add_f32 v[64:65], v[68:69], v[54:55] neg_lo:[0,1] neg_hi:[0,1]
	v_pk_mul_f32 v[66:67], v[52:53], v[62:63]
	v_pk_add_f32 v[36:37], v[36:37], v[64:65]
	v_pk_fma_f32 v[52:53], v[62:63], v[52:53], v[66:67] neg_lo:[0,0,1] neg_hi:[0,0,1]
	v_pk_add_f32 v[64:65], v[44:45], v[62:63]
	v_pk_fma_f32 v[40:41], v[62:63], v[40:41], v[52:53]
	v_pk_add_f32 v[44:45], v[64:65], v[44:45] neg_lo:[0,1] neg_hi:[0,1]
	v_pk_add_f32 v[52:53], v[66:67], v[40:41]
	v_pk_add_f32 v[44:45], v[62:63], v[44:45] neg_lo:[0,1] neg_hi:[0,1]
	v_pk_add_f32 v[62:63], v[52:53], v[66:67] neg_lo:[0,1] neg_hi:[0,1]
	v_pk_add_f32 v[66:67], v[54:55], v[52:53] neg_lo:[0,1] neg_hi:[0,1]
	v_pk_add_f32 v[40:41], v[62:63], v[40:41] neg_lo:[0,1] neg_hi:[0,1]
	v_pk_add_f32 v[54:55], v[54:55], v[66:67] neg_lo:[0,1] neg_hi:[0,1]
	v_min_f32_e32 v0, 0, v0
	v_pk_add_f32 v[52:53], v[54:55], v[52:53] neg_lo:[0,1] neg_hi:[0,1]
	v_min_f32_e32 v1, 0, v1
	v_pk_add_f32 v[36:37], v[36:37], v[52:53]
	v_add_f32_e32 v3, v23, v3
	v_pk_add_f32 v[36:37], v[40:41], v[36:37]
	v_add_f32_e32 v4, v23, v4
	v_pk_add_f32 v[36:37], v[66:67], v[36:37]
	v_add_f32_e32 v5, v23, v5
	v_pk_mul_f32 v[36:37], v[38:39], v[36:37]
	v_add_f32_e32 v7, v23, v7
	v_pk_add_f32 v[36:37], v[44:45], v[36:37]
	s_nop 0
	v_pk_add_f32 v[38:39], v[64:65], v[36:37]
	s_nop 0
	v_pk_add_f32 v[40:41], v[38:39], v[64:65] neg_lo:[0,1] neg_hi:[0,1]
	v_pk_mul_f32 v[52:53], v[38:39], v[38:39]
	v_pk_add_f32 v[36:37], v[36:37], v[40:41] neg_lo:[0,1] neg_hi:[0,1]
	v_pk_fma_f32 v[40:41], v[52:53], s[24:25], v[28:29] op_sel_hi:[1,0,0]
	v_ldexp_f32 v44, v38, 1
	v_ldexp_f32 v45, v39, 1
	v_pk_mul_f32 v[38:39], v[38:39], v[52:53]
	v_pk_fma_f32 v[40:41], v[52:53], v[40:41], s[26:27] op_sel_hi:[1,1,0]
	v_ldexp_f32 v59, v37, 1
	v_pk_mul_f32 v[38:39], v[38:39], v[40:41]
	v_ldexp_f32 v36, v36, 1
	v_pk_add_f32 v[40:41], v[44:45], v[38:39]
	v_mov_b32_e32 v37, v59
	v_pk_add_f32 v[44:45], v[40:41], v[44:45] neg_lo:[0,1] neg_hi:[0,1]
	s_nop 0
	v_pk_add_f32 v[38:39], v[38:39], v[44:45] neg_lo:[0,1] neg_hi:[0,1]
	s_nop 0
	v_pk_add_f32 v[44:45], v[36:37], v[38:39]
	v_mov_b32_e32 v49, v39
	v_mov_b32_e32 v39, v41
	v_mov_b32_e32 v37, v45
	v_pk_add_f32 v[52:53], v[40:41], v[44:45]
	v_pk_add_f32 v[36:37], v[36:37], v[38:39]
	v_pk_add_f32 v[38:39], v[56:57], v[52:53]
	v_pk_add_f32 v[48:49], v[48:49], v[58:59]
	v_mov_b32_e32 v54, v52
	v_mov_b32_e32 v55, v39
	v_mov_b32_e32 v58, v40
	v_mov_b32_e32 v59, v57
	v_pk_add_f32 v[54:55], v[54:55], v[58:59] neg_lo:[0,1] neg_hi:[0,1]
	v_mov_b32_e32 v42, v38
	v_mov_b32_e32 v58, v56
	v_mov_b32_e32 v59, v39
	v_mov_b32_e32 v47, v55
	v_mov_b32_e32 v60, v52
	v_pk_add_f32 v[42:43], v[42:43], v[50:51] neg_lo:[0,1] neg_hi:[0,1]
	v_pk_add_f32 v[46:47], v[58:59], v[46:47] neg_lo:[0,1] neg_hi:[0,1]
	v_pk_add_f32 v[50:51], v[60:61], v[42:43] neg_lo:[0,1] neg_hi:[0,1]
	v_mov_b32_e32 v58, v46
	v_mov_b32_e32 v59, v43
	v_mov_b32_e32 v60, v38
	v_mov_b32_e32 v61, v53
	v_mov_b32_e32 v43, v41
	v_pk_add_f32 v[58:59], v[34:35], v[58:59] neg_lo:[0,1] neg_hi:[0,1]
	v_pk_add_f32 v[42:43], v[60:61], v[42:43] neg_lo:[0,1] neg_hi:[0,1]
	v_mov_b32_e32 v35, v57
	v_pk_add_f32 v[40:41], v[52:53], v[40:41] neg_lo:[0,1] neg_hi:[0,1]
	v_pk_add_f32 v[42:43], v[48:49], v[42:43] neg_lo:[0,1] neg_hi:[0,1]
	v_pk_add_f32 v[34:35], v[34:35], v[46:47] neg_lo:[0,1] neg_hi:[0,1]
	v_pk_add_f32 v[36:37], v[36:37], v[54:55] neg_lo:[0,1] neg_hi:[0,1]
	v_pk_add_f32 v[40:41], v[44:45], v[40:41] neg_lo:[0,1] neg_hi:[0,1]
	v_pk_add_f32 v[44:45], v[36:37], v[34:35]
	v_mov_b32_e32 v35, v51
	v_mov_b32_e32 v37, v43
	v_pk_add_f32 v[46:47], v[50:51], v[42:43]
	v_pk_add_f32 v[36:37], v[34:35], v[36:37]
	v_mov_b32_e32 v42, v44
	v_pk_add_f32 v[36:37], v[36:37], v[58:59] neg_lo:[0,1] neg_hi:[0,1]
	v_mov_b32_e32 v43, v47
	v_pk_add_f32 v[42:43], v[42:43], v[36:37] neg_lo:[0,1] neg_hi:[0,1]
	v_pk_add_f32 v[36:37], v[40:41], v[36:37] neg_lo:[0,1] neg_hi:[0,1]
	v_pk_add_f32 v[34:35], v[34:35], v[42:43] neg_lo:[0,1] neg_hi:[0,1]
	s_nop 0
	v_pk_add_f32 v[34:35], v[36:37], v[34:35]
	v_pk_add_f32 v[36:37], v[46:47], v[44:45]
	s_nop 0
	v_pk_add_f32 v[40:41], v[38:39], v[36:37]
	s_nop 0
	v_pk_add_f32 v[38:39], v[40:41], v[38:39] neg_lo:[0,1] neg_hi:[0,1]
	s_nop 0
	v_pk_add_f32 v[36:37], v[36:37], v[38:39] neg_lo:[0,1] neg_hi:[0,1]
	s_nop 0
	v_pk_add_f32 v[34:35], v[34:35], v[36:37]
	v_mul_f32_e64 v36, |v2|, s27
	v_pk_add_f32 v[34:35], v[40:41], v[34:35]
	v_exp_f32_e32 v62, v36
	v_cndmask_b32_e64 v34, v31, v34, s[4:5]
	v_cmp_neq_f32_e64 s[4:5], s31, v71
	v_min_f32_e32 v2, 0, v2
	v_add_f32_e32 v36, 1.0, v62
	v_cndmask_b32_e64 v35, v31, v35, s[4:5]
	v_cmp_ngt_f32_e64 s[4:5], -1.0, v71
	v_frexp_mant_f32_e32 v38, v36
	s_nop 0
	v_cndmask_b32_e64 v35, v32, v35, s[4:5]
	v_cmp_ngt_f32_e64 s[4:5], -1.0, v70
	s_nop 1
	v_cndmask_b32_e64 v34, v32, v34, s[4:5]
	v_cmp_neq_f32_e64 s[4:5], -1.0, v70
	s_nop 1
	v_cndmask_b32_e64 v34, v33, v34, s[4:5]
	v_cmp_neq_f32_e64 s[4:5], -1.0, v71
	s_nop 1
	v_cndmask_b32_e64 v35, v33, v35, s[4:5]
	v_cmp_lt_f32_e64 s[4:5], |v71|, s33
	s_nop 1
	v_cndmask_b32_e64 v35, v35, v71, s[4:5]
	v_cmp_lt_f32_e64 s[4:5], |v70|, s33
	s_nop 1
	v_cndmask_b32_e64 v34, v34, v70, s[4:5]
	v_pk_add_f32 v[0:1], v[0:1], v[34:35] neg_lo:[0,1] neg_hi:[0,1]
	v_add_f32_e32 v34, -1.0, v36
	v_sub_f32_e32 v35, v34, v36
	v_add_f32_e32 v35, 1.0, v35
	v_sub_f32_e32 v34, v62, v34
	v_add_f32_e32 v37, v34, v35
	v_cvt_f64_f32_e32 v[34:35], v36
	v_frexp_exp_i32_f64_e32 v34, v[34:35]
	v_cmp_gt_f32_e64 s[4:5], s29, v38
	s_nop 1
	v_subbrev_co_u32_e64 v54, s[4:5], 0, v34, s[4:5]
	v_mul_f32_e64 v34, |v3|, s27
	v_exp_f32_e32 v63, v34
	v_sub_u32_e32 v35, 0, v54
	v_ldexp_f32 v34, v36, v35
	v_ldexp_f32 v36, v37, v35
	v_add_f32_e32 v35, 1.0, v63
; #define GAS __attribute__((address_space(1)))
; __global__ void __launch_bounds__(NWAVES * 64, 2) hybrid_fwd(Args args) {
;     ...
;             if (r32 < 16) { const float bb = bfg[r32]; const int tok = it * 32, bg = tok >> 13, t = tok & (T - 1);
; #pragma unroll
;                 for (int g4 = 0; g4 < 4; ++g4) { f32x4 o;
; #pragma unroll
;                     for (int e = 0; e < 4; ++e) { const float x = acc[4 * g4 + e] + bb; o[e] = fminf(x, 0.f) - log1pf(__expf(-fabsf(x))); }
;                     *(GAS f32x4*)(LFt + (size_t)(bg * 16 + r32) * T + t + 8 * g4 + 4 * hi) = o; } }
	v_add_f32_e32 v37, -1.0, v35
	v_sub_f32_e32 v38, v37, v35
	v_add_f32_e32 v38, 1.0, v38
	v_sub_f32_e32 v37, v63, v37
	v_add_f32_e32 v37, v37, v38
	v_frexp_mant_f32_e32 v40, v35
	v_cvt_f64_f32_e32 v[38:39], v35
	v_frexp_exp_i32_f64_e32 v38, v[38:39]
	v_cmp_gt_f32_e64 s[4:5], s29, v40
	v_min_f32_e32 v3, 0, v3
	s_nop 0
	v_subbrev_co_u32_e64 v55, s[4:5], 0, v38, s[4:5]
	v_sub_u32_e32 v38, 0, v55
	v_ldexp_f32 v35, v35, v38
	v_ldexp_f32 v37, v37, v38
	v_pk_add_f32 v[38:39], v[34:35], 1.0 op_sel_hi:[1,0]
	v_pk_add_f32 v[46:47], v[34:35], -1.0 op_sel_hi:[1,0]
	v_pk_add_f32 v[40:41], v[38:39], -1.0 op_sel_hi:[1,0]
	v_pk_add_f32 v[48:49], v[46:47], 1.0 op_sel_hi:[1,0]
	v_pk_add_f32 v[40:41], v[34:35], v[40:41] neg_lo:[0,1] neg_hi:[0,1]
	v_pk_add_f32 v[34:35], v[34:35], v[48:49] neg_lo:[0,1] neg_hi:[0,1]
	v_pk_add_f32 v[40:41], v[36:37], v[40:41]
	v_pk_add_f32 v[34:35], v[36:37], v[34:35]
	v_pk_add_f32 v[42:43], v[38:39], v[40:41]
	v_pk_add_f32 v[36:37], v[46:47], v[34:35]
	v_rcp_f32_e32 v44, v42
	v_rcp_f32_e32 v45, v43
	v_pk_add_f32 v[38:39], v[42:43], v[38:39] neg_lo:[0,1] neg_hi:[0,1]
	v_pk_add_f32 v[46:47], v[36:37], v[46:47] neg_lo:[0,1] neg_hi:[0,1]
	v_pk_add_f32 v[38:39], v[40:41], v[38:39] neg_lo:[0,1] neg_hi:[0,1]
	v_pk_mul_f32 v[40:41], v[36:37], v[44:45]
	v_pk_add_f32 v[34:35], v[34:35], v[46:47] neg_lo:[0,1] neg_hi:[0,1]
	v_pk_mul_f32 v[46:47], v[42:43], v[40:41]
	v_cmp_neq_f32_e64 s[4:5], s31, v62
	v_pk_fma_f32 v[48:49], v[40:41], v[42:43], v[46:47] neg_lo:[0,0,1] neg_hi:[0,0,1]
	s_nop 0
	v_pk_fma_f32 v[48:49], v[40:41], v[38:39], v[48:49]
	s_nop 0
	v_pk_add_f32 v[50:51], v[46:47], v[48:49]
	s_nop 0
	v_pk_add_f32 v[52:53], v[36:37], v[50:51] neg_lo:[0,1] neg_hi:[0,1]
	v_pk_add_f32 v[46:47], v[50:51], v[46:47] neg_lo:[0,1] neg_hi:[0,1]
	v_pk_add_f32 v[36:37], v[36:37], v[52:53] neg_lo:[0,1] neg_hi:[0,1]
	s_nop 0
	v_pk_add_f32 v[36:37], v[36:37], v[50:51] neg_lo:[0,1] neg_hi:[0,1]
	s_nop 0
	v_pk_add_f32 v[34:35], v[34:35], v[36:37]
	v_pk_add_f32 v[36:37], v[46:47], v[48:49] neg_lo:[0,1] neg_hi:[0,1]
	s_nop 0
	v_pk_add_f32 v[34:35], v[36:37], v[34:35]
	s_nop 0
	v_pk_add_f32 v[36:37], v[52:53], v[34:35]
	s_nop 0
	v_pk_mul_f32 v[46:47], v[44:45], v[36:37]
	s_nop 0
	v_pk_mul_f32 v[48:49], v[42:43], v[46:47]
	s_nop 0
	v_pk_fma_f32 v[42:43], v[46:47], v[42:43], v[48:49] neg_lo:[0,0,1] neg_hi:[0,0,1]
	s_nop 0
	v_pk_fma_f32 v[38:39], v[46:47], v[38:39], v[42:43]
	v_pk_add_f32 v[42:43], v[52:53], v[36:37] neg_lo:[0,1] neg_hi:[0,1]
	s_nop 0
	v_pk_add_f32 v[34:35], v[34:35], v[42:43]
	v_pk_add_f32 v[42:43], v[48:49], v[38:39]
	s_nop 0
	v_pk_add_f32 v[50:51], v[36:37], v[42:43] neg_lo:[0,1] neg_hi:[0,1]
	v_pk_add_f32 v[48:49], v[42:43], v[48:49] neg_lo:[0,1] neg_hi:[0,1]
	v_pk_add_f32 v[36:37], v[36:37], v[50:51] neg_lo:[0,1] neg_hi:[0,1]
	s_nop 0
	v_pk_add_f32 v[36:37], v[36:37], v[42:43] neg_lo:[0,1] neg_hi:[0,1]
	s_nop 0
	v_pk_add_f32 v[34:35], v[34:35], v[36:37]
	v_pk_add_f32 v[36:37], v[48:49], v[38:39] neg_lo:[0,1] neg_hi:[0,1]
	s_nop 0
	v_pk_add_f32 v[34:35], v[36:37], v[34:35]
	v_pk_add_f32 v[36:37], v[40:41], v[46:47]
	v_pk_add_f32 v[34:35], v[50:51], v[34:35]
	v_pk_add_f32 v[38:39], v[36:37], v[40:41] neg_lo:[0,1] neg_hi:[0,1]
	v_pk_mul_f32 v[34:35], v[44:45], v[34:35]
	v_pk_add_f32 v[38:39], v[46:47], v[38:39] neg_lo:[0,1] neg_hi:[0,1]
	v_cvt_f32_i32_e32 v45, v55
	v_pk_add_f32 v[34:35], v[38:39], v[34:35]
	v_cvt_f32_i32_e32 v44, v54
	v_pk_add_f32 v[38:39], v[36:37], v[34:35]
	s_nop 0
	v_pk_mul_f32 v[40:41], v[38:39], v[38:39]
	v_pk_add_f32 v[36:37], v[38:39], v[36:37] neg_lo:[0,1] neg_hi:[0,1]
	v_pk_fma_f32 v[42:43], v[40:41], s[24:25], v[28:29] op_sel_hi:[1,0,0]
	v_pk_add_f32 v[34:35], v[34:35], v[36:37] neg_lo:[0,1] neg_hi:[0,1]
	v_ldexp_f32 v36, v38, 1
	v_pk_fma_f32 v[42:43], v[40:41], v[42:43], s[26:27] op_sel_hi:[1,1,0]
	v_ldexp_f32 v37, v39, 1
	v_pk_mul_f32 v[38:39], v[38:39], v[40:41]
	v_pk_mul_f32 v[40:41], v[44:45], s[28:29] op_sel_hi:[1,0]
	v_pk_mul_f32 v[38:39], v[38:39], v[42:43]
	v_pk_fma_f32 v[48:49], v[44:45], s[28:29], v[40:41] op_sel_hi:[1,0,1] neg_lo:[0,0,1] neg_hi:[0,0,1]
	v_pk_add_f32 v[42:43], v[36:37], v[38:39]
	v_ldexp_f32 v47, v35, 1
	v_pk_add_f32 v[36:37], v[42:43], v[36:37] neg_lo:[0,1] neg_hi:[0,1]
	v_pk_fma_f32 v[44:45], v[44:45], s[30:31], v[48:49] op_sel_hi:[1,0,1]
	v_pk_add_f32 v[36:37], v[38:39], v[36:37] neg_lo:[0,1] neg_hi:[0,1]
	v_ldexp_f32 v34, v34, 1
	v_mov_b32_e32 v38, v40
	v_mov_b32_e32 v39, v37
	v_mov_b32_e32 v46, v44
	v_mov_b32_e32 v35, v47
	v_pk_add_f32 v[38:39], v[38:39], v[46:47]
	v_pk_add_f32 v[46:47], v[34:35], v[36:37]
	v_mov_b32_e32 v37, v43
	v_mov_b32_e32 v35, v47
	v_pk_add_f32 v[48:49], v[40:41], v[44:45]
	v_pk_add_f32 v[34:35], v[34:35], v[36:37]
	v_pk_add_f32 v[36:37], v[42:43], v[46:47]
	v_mov_b32_e32 v58, v42
	v_pk_add_f32 v[50:51], v[48:49], v[36:37]
	v_mov_b32_e32 v56, v36
	v_mov_b32_e32 v57, v51
	v_mov_b32_e32 v59, v49
	v_pk_add_f32 v[56:57], v[56:57], v[58:59] neg_lo:[0,1] neg_hi:[0,1]
	v_mov_b32_e32 v52, v50
	v_mov_b32_e32 v53, v49
	v_mov_b32_e32 v54, v48
	v_mov_b32_e32 v55, v41
	v_mov_b32_e32 v58, v48
	v_mov_b32_e32 v59, v51
	v_mov_b32_e32 v41, v57
	v_pk_add_f32 v[52:53], v[52:53], v[54:55] neg_lo:[0,1] neg_hi:[0,1]
	v_mov_b32_e32 v54, v36
	v_mov_b32_e32 v55, v45
	v_pk_add_f32 v[40:41], v[58:59], v[40:41] neg_lo:[0,1] neg_hi:[0,1]
	v_pk_add_f32 v[54:55], v[54:55], v[52:53] neg_lo:[0,1] neg_hi:[0,1]
	v_mov_b32_e32 v58, v40
	v_mov_b32_e32 v59, v53
	v_mov_b32_e32 v60, v50
	v_mov_b32_e32 v61, v37
	v_mov_b32_e32 v53, v43
	v_pk_add_f32 v[58:59], v[44:45], v[58:59] neg_lo:[0,1] neg_hi:[0,1]
	v_pk_add_f32 v[52:53], v[60:61], v[52:53] neg_lo:[0,1] neg_hi:[0,1]
	v_mov_b32_e32 v45, v49
; #define GAS __attribute__((address_space(1)))
; __global__ void __launch_bounds__(NWAVES * 64, 2) hybrid_fwd(Args args) {
;     ...
;             if (r32 < 16) { const float bb = bfg[r32]; const int tok = it * 32, bg = tok >> 13, t = tok & (T - 1);
; #pragma unroll
;                 for (int g4 = 0; g4 < 4; ++g4) { f32x4 o;
; #pragma unroll
;                     for (int e = 0; e < 4; ++e) { const float x = acc[4 * g4 + e] + bb; o[e] = fminf(x, 0.f) - log1pf(__expf(-fabsf(x))); }
;                     *(GAS f32x4*)(LFt + (size_t)(bg * 16 + r32) * T + t + 8 * g4 + 4 * hi) = o; } }
	v_pk_add_f32 v[38:39], v[38:39], v[52:53] neg_lo:[0,1] neg_hi:[0,1]
	v_pk_add_f32 v[40:41], v[44:45], v[40:41] neg_lo:[0,1] neg_hi:[0,1]
	v_pk_add_f32 v[34:35], v[34:35], v[56:57] neg_lo:[0,1] neg_hi:[0,1]
	v_pk_add_f32 v[36:37], v[36:37], v[42:43] neg_lo:[0,1] neg_hi:[0,1]
	v_pk_add_f32 v[42:43], v[34:35], v[40:41]
	v_mov_b32_e32 v41, v55
	v_mov_b32_e32 v35, v39
	v_pk_add_f32 v[44:45], v[54:55], v[38:39]
	v_pk_add_f32 v[34:35], v[40:41], v[34:35]
	v_mov_b32_e32 v38, v42
	v_pk_add_f32 v[34:35], v[34:35], v[58:59] neg_lo:[0,1] neg_hi:[0,1]
	v_mov_b32_e32 v39, v45
	v_pk_add_f32 v[36:37], v[46:47], v[36:37] neg_lo:[0,1] neg_hi:[0,1]
	v_pk_add_f32 v[38:39], v[38:39], v[34:35] neg_lo:[0,1] neg_hi:[0,1]
	v_pk_add_f32 v[34:35], v[36:37], v[34:35] neg_lo:[0,1] neg_hi:[0,1]
	v_pk_add_f32 v[38:39], v[40:41], v[38:39] neg_lo:[0,1] neg_hi:[0,1]
	v_pk_add_f32 v[36:37], v[44:45], v[42:43]
	v_pk_add_f32 v[34:35], v[34:35], v[38:39]
	v_pk_add_f32 v[38:39], v[50:51], v[36:37]
	s_nop 0
	v_pk_add_f32 v[40:41], v[38:39], v[50:51] neg_lo:[0,1] neg_hi:[0,1]
	s_nop 0
	v_pk_add_f32 v[36:37], v[36:37], v[40:41] neg_lo:[0,1] neg_hi:[0,1]
	s_nop 0
	v_pk_add_f32 v[34:35], v[34:35], v[36:37]
	v_mul_f32_e64 v36, |v4|, s27
	v_pk_add_f32 v[34:35], v[38:39], v[34:35]
	v_exp_f32_e32 v58, v36
	v_cndmask_b32_e64 v34, v31, v34, s[4:5]
	v_cmp_neq_f32_e64 s[4:5], s31, v63
	s_nop 1
	v_cndmask_b32_e64 v35, v31, v35, s[4:5]
	v_cmp_ngt_f32_e64 s[4:5], -1.0, v63
	s_nop 1
	v_cndmask_b32_e64 v35, v32, v35, s[4:5]
	v_cmp_ngt_f32_e64 s[4:5], -1.0, v62
	s_nop 1
	v_cndmask_b32_e64 v34, v32, v34, s[4:5]
	v_cmp_neq_f32_e64 s[4:5], -1.0, v62
	s_nop 1
	v_cndmask_b32_e64 v34, v33, v34, s[4:5]
	v_cmp_neq_f32_e64 s[4:5], -1.0, v63
	s_nop 1
	v_cndmask_b32_e64 v35, v33, v35, s[4:5]
	v_cmp_lt_f32_e64 s[4:5], |v63|, s33
	s_nop 1
	v_cndmask_b32_e64 v35, v35, v63, s[4:5]
	v_cmp_lt_f32_e64 s[4:5], |v62|, s33
	s_nop 1
	v_cndmask_b32_e64 v34, v34, v62, s[4:5]
	v_pk_add_f32 v[2:3], v[2:3], v[34:35] neg_lo:[0,1] neg_hi:[0,1]
	global_store_dwordx4 v[26:27], v[0:3], off sc1
	s_nop 1
	v_add_f32_e32 v1, 1.0, v58
	v_add_f32_e32 v2, -1.0, v1
	v_sub_f32_e32 v3, v2, v1
	v_add_f32_e32 v3, 1.0, v3
	v_sub_f32_e32 v2, v58, v2
	v_min_f32_e32 v0, 0, v4
	v_add_f32_e32 v4, v2, v3
	v_frexp_mant_f32_e32 v34, v1
	v_cvt_f64_f32_e32 v[2:3], v1
	v_frexp_exp_i32_f64_e32 v2, v[2:3]
	v_cmp_gt_f32_e64 s[4:5], s29, v34
	s_nop 1
	v_subbrev_co_u32_e64 v50, s[4:5], 0, v2, s[4:5]
	v_mul_f32_e64 v2, |v5|, s27
	v_exp_f32_e32 v59, v2
	v_sub_u32_e32 v3, 0, v50
	v_ldexp_f32 v2, v1, v3
	v_ldexp_f32 v4, v4, v3
	v_add_f32_e32 v3, 1.0, v59
	v_min_f32_e32 v1, 0, v5
	v_add_f32_e32 v5, -1.0, v3
	v_sub_f32_e32 v34, v5, v3
	v_add_f32_e32 v34, 1.0, v34
	v_sub_f32_e32 v5, v59, v5
	v_add_f32_e32 v5, v5, v34
	v_frexp_mant_f32_e32 v36, v3
	v_cvt_f64_f32_e32 v[34:35], v3
	v_frexp_exp_i32_f64_e32 v34, v[34:35]
	v_cmp_gt_f32_e64 s[4:5], s29, v36
	s_nop 1
	v_subbrev_co_u32_e64 v51, s[4:5], 0, v34, s[4:5]
	v_sub_u32_e32 v34, 0, v51
	v_ldexp_f32 v3, v3, v34
	v_ldexp_f32 v5, v5, v34
	v_pk_add_f32 v[34:35], v[2:3], 1.0 op_sel_hi:[1,0]
	v_pk_add_f32 v[42:43], v[2:3], -1.0 op_sel_hi:[1,0]
	v_pk_add_f32 v[36:37], v[34:35], -1.0 op_sel_hi:[1,0]
	v_pk_add_f32 v[44:45], v[42:43], 1.0 op_sel_hi:[1,0]
	v_pk_add_f32 v[36:37], v[2:3], v[36:37] neg_lo:[0,1] neg_hi:[0,1]
	v_pk_add_f32 v[2:3], v[2:3], v[44:45] neg_lo:[0,1] neg_hi:[0,1]
	v_pk_add_f32 v[36:37], v[4:5], v[36:37]
	v_pk_add_f32 v[2:3], v[4:5], v[2:3]
	v_pk_add_f32 v[38:39], v[34:35], v[36:37]
	v_pk_add_f32 v[4:5], v[42:43], v[2:3]
	v_rcp_f32_e32 v40, v38
	v_rcp_f32_e32 v41, v39
	v_pk_add_f32 v[34:35], v[38:39], v[34:35] neg_lo:[0,1] neg_hi:[0,1]
	v_pk_add_f32 v[42:43], v[4:5], v[42:43] neg_lo:[0,1] neg_hi:[0,1]
	v_pk_add_f32 v[34:35], v[36:37], v[34:35] neg_lo:[0,1] neg_hi:[0,1]
	v_pk_mul_f32 v[36:37], v[4:5], v[40:41]
	v_pk_add_f32 v[2:3], v[2:3], v[42:43] neg_lo:[0,1] neg_hi:[0,1]
	v_pk_mul_f32 v[42:43], v[38:39], v[36:37]
	v_cmp_neq_f32_e64 s[4:5], s31, v58
	v_pk_fma_f32 v[44:45], v[36:37], v[38:39], v[42:43] neg_lo:[0,0,1] neg_hi:[0,0,1]
	s_nop 0
	v_pk_fma_f32 v[44:45], v[36:37], v[34:35], v[44:45]
	s_nop 0
	v_pk_add_f32 v[46:47], v[42:43], v[44:45]
	s_nop 0
	v_pk_add_f32 v[48:49], v[4:5], v[46:47] neg_lo:[0,1] neg_hi:[0,1]
	v_pk_add_f32 v[42:43], v[46:47], v[42:43] neg_lo:[0,1] neg_hi:[0,1]
	v_pk_add_f32 v[4:5], v[4:5], v[48:49] neg_lo:[0,1] neg_hi:[0,1]
	s_nop 0
	v_pk_add_f32 v[4:5], v[4:5], v[46:47] neg_lo:[0,1] neg_hi:[0,1]
	s_nop 0
	v_pk_add_f32 v[2:3], v[2:3], v[4:5]
	v_pk_add_f32 v[4:5], v[42:43], v[44:45] neg_lo:[0,1] neg_hi:[0,1]
	s_nop 0
	v_pk_add_f32 v[2:3], v[4:5], v[2:3]
	s_nop 0
	v_pk_add_f32 v[4:5], v[48:49], v[2:3]
	s_nop 0
	v_pk_mul_f32 v[42:43], v[40:41], v[4:5]
	s_nop 0
	v_pk_mul_f32 v[44:45], v[38:39], v[42:43]
	s_nop 0
	v_pk_fma_f32 v[38:39], v[42:43], v[38:39], v[44:45] neg_lo:[0,0,1] neg_hi:[0,0,1]
	s_nop 0
	v_pk_fma_f32 v[34:35], v[42:43], v[34:35], v[38:39]
	v_pk_add_f32 v[38:39], v[48:49], v[4:5] neg_lo:[0,1] neg_hi:[0,1]
	s_nop 0
	v_pk_add_f32 v[2:3], v[2:3], v[38:39]
	v_pk_add_f32 v[38:39], v[44:45], v[34:35]
	s_nop 0
	v_pk_add_f32 v[46:47], v[4:5], v[38:39] neg_lo:[0,1] neg_hi:[0,1]
	v_pk_add_f32 v[44:45], v[38:39], v[44:45] neg_lo:[0,1] neg_hi:[0,1]
	v_pk_add_f32 v[4:5], v[4:5], v[46:47] neg_lo:[0,1] neg_hi:[0,1]
	s_nop 0
	v_pk_add_f32 v[4:5], v[4:5], v[38:39] neg_lo:[0,1] neg_hi:[0,1]
	s_nop 0
	v_pk_add_f32 v[2:3], v[2:3], v[4:5]
	v_pk_add_f32 v[4:5], v[44:45], v[34:35] neg_lo:[0,1] neg_hi:[0,1]
	s_nop 0
	v_pk_add_f32 v[2:3], v[4:5], v[2:3]
	v_pk_add_f32 v[4:5], v[36:37], v[42:43]
	v_pk_add_f32 v[2:3], v[46:47], v[2:3]
	v_pk_add_f32 v[34:35], v[4:5], v[36:37] neg_lo:[0,1] neg_hi:[0,1]
; #define GAS __attribute__((address_space(1)))
; __global__ void __launch_bounds__(NWAVES * 64, 2) hybrid_fwd(Args args) {
;     ...
;             if (r32 < 16) { const float bb = bfg[r32]; const int tok = it * 32, bg = tok >> 13, t = tok & (T - 1);
; #pragma unroll
;                 for (int g4 = 0; g4 < 4; ++g4) { f32x4 o;
; #pragma unroll
;                     for (int e = 0; e < 4; ++e) { const float x = acc[4 * g4 + e] + bb; o[e] = fminf(x, 0.f) - log1pf(__expf(-fabsf(x))); }
;                     *(GAS f32x4*)(LFt + (size_t)(bg * 16 + r32) * T + t + 8 * g4 + 4 * hi) = o; } }
	v_pk_mul_f32 v[2:3], v[40:41], v[2:3]
	v_pk_add_f32 v[34:35], v[42:43], v[34:35] neg_lo:[0,1] neg_hi:[0,1]
	v_cvt_f32_i32_e32 v41, v51
	v_pk_add_f32 v[2:3], v[34:35], v[2:3]
	v_cvt_f32_i32_e32 v40, v50
	v_pk_add_f32 v[34:35], v[4:5], v[2:3]
	s_nop 0
	v_pk_mul_f32 v[36:37], v[34:35], v[34:35]
	v_pk_add_f32 v[4:5], v[34:35], v[4:5] neg_lo:[0,1] neg_hi:[0,1]
	v_pk_fma_f32 v[38:39], v[36:37], s[24:25], v[28:29] op_sel_hi:[1,0,0]
	v_pk_add_f32 v[2:3], v[2:3], v[4:5] neg_lo:[0,1] neg_hi:[0,1]
	v_ldexp_f32 v4, v34, 1
	v_pk_fma_f32 v[38:39], v[36:37], v[38:39], s[26:27] op_sel_hi:[1,1,0]
	v_ldexp_f32 v5, v35, 1
	v_pk_mul_f32 v[34:35], v[34:35], v[36:37]
	v_pk_mul_f32 v[36:37], v[40:41], s[28:29] op_sel_hi:[1,0]
	v_pk_mul_f32 v[34:35], v[34:35], v[38:39]
	v_pk_fma_f32 v[44:45], v[40:41], s[28:29], v[36:37] op_sel_hi:[1,0,1] neg_lo:[0,0,1] neg_hi:[0,0,1]
	v_pk_add_f32 v[38:39], v[4:5], v[34:35]
	v_ldexp_f32 v43, v3, 1
	v_pk_add_f32 v[4:5], v[38:39], v[4:5] neg_lo:[0,1] neg_hi:[0,1]
	v_pk_fma_f32 v[40:41], v[40:41], s[30:31], v[44:45] op_sel_hi:[1,0,1]
	v_pk_add_f32 v[4:5], v[34:35], v[4:5] neg_lo:[0,1] neg_hi:[0,1]
	v_ldexp_f32 v2, v2, 1
	v_mov_b32_e32 v34, v36
	v_mov_b32_e32 v35, v5
	v_mov_b32_e32 v42, v40
	v_mov_b32_e32 v3, v43
	v_pk_add_f32 v[34:35], v[34:35], v[42:43]
	v_pk_add_f32 v[42:43], v[2:3], v[4:5]
	v_mov_b32_e32 v5, v39
	v_mov_b32_e32 v3, v43
	v_pk_add_f32 v[44:45], v[36:37], v[40:41]
	v_pk_add_f32 v[2:3], v[2:3], v[4:5]
	v_pk_add_f32 v[4:5], v[38:39], v[42:43]
	v_mov_b32_e32 v54, v38
	v_pk_add_f32 v[46:47], v[44:45], v[4:5]
	v_mov_b32_e32 v52, v4
	v_mov_b32_e32 v53, v47
	v_mov_b32_e32 v55, v45
	v_pk_add_f32 v[52:53], v[52:53], v[54:55] neg_lo:[0,1] neg_hi:[0,1]
	v_mov_b32_e32 v48, v46
	v_mov_b32_e32 v49, v45
	v_mov_b32_e32 v50, v44
	v_mov_b32_e32 v51, v37
	v_mov_b32_e32 v54, v44
	v_mov_b32_e32 v55, v47
	v_mov_b32_e32 v37, v53
	v_pk_add_f32 v[48:49], v[48:49], v[50:51] neg_lo:[0,1] neg_hi:[0,1]
	v_mov_b32_e32 v50, v4
	v_mov_b32_e32 v51, v41
	v_pk_add_f32 v[36:37], v[54:55], v[36:37] neg_lo:[0,1] neg_hi:[0,1]
	v_pk_add_f32 v[50:51], v[50:51], v[48:49] neg_lo:[0,1] neg_hi:[0,1]
	v_mov_b32_e32 v54, v36
	v_mov_b32_e32 v55, v49
	v_mov_b32_e32 v56, v46
	v_mov_b32_e32 v57, v5
	v_mov_b32_e32 v49, v39
	v_pk_add_f32 v[54:55], v[40:41], v[54:55] neg_lo:[0,1] neg_hi:[0,1]
	v_pk_add_f32 v[48:49], v[56:57], v[48:49] neg_lo:[0,1] neg_hi:[0,1]
	v_mov_b32_e32 v41, v45
	v_pk_add_f32 v[34:35], v[34:35], v[48:49] neg_lo:[0,1] neg_hi:[0,1]
	v_pk_add_f32 v[36:37], v[40:41], v[36:37] neg_lo:[0,1] neg_hi:[0,1]
	v_pk_add_f32 v[2:3], v[2:3], v[52:53] neg_lo:[0,1] neg_hi:[0,1]
	v_pk_add_f32 v[4:5], v[4:5], v[38:39] neg_lo:[0,1] neg_hi:[0,1]
	v_pk_add_f32 v[38:39], v[2:3], v[36:37]
	v_mov_b32_e32 v37, v51
	v_mov_b32_e32 v3, v35
	v_pk_add_f32 v[40:41], v[50:51], v[34:35]
	v_pk_add_f32 v[2:3], v[36:37], v[2:3]
	v_mov_b32_e32 v34, v38
	v_pk_add_f32 v[2:3], v[2:3], v[54:55] neg_lo:[0,1] neg_hi:[0,1]
	v_mov_b32_e32 v35, v41
	v_pk_add_f32 v[4:5], v[42:43], v[4:5] neg_lo:[0,1] neg_hi:[0,1]
	v_pk_add_f32 v[34:35], v[34:35], v[2:3] neg_lo:[0,1] neg_hi:[0,1]
	v_pk_add_f32 v[2:3], v[4:5], v[2:3] neg_lo:[0,1] neg_hi:[0,1]
	v_pk_add_f32 v[34:35], v[36:37], v[34:35] neg_lo:[0,1] neg_hi:[0,1]
	v_pk_add_f32 v[4:5], v[40:41], v[38:39]
	v_pk_add_f32 v[2:3], v[2:3], v[34:35]
	v_pk_add_f32 v[34:35], v[46:47], v[4:5]
	s_nop 0
	v_pk_add_f32 v[36:37], v[34:35], v[46:47] neg_lo:[0,1] neg_hi:[0,1]
	s_nop 0
	v_pk_add_f32 v[4:5], v[4:5], v[36:37] neg_lo:[0,1] neg_hi:[0,1]
	s_nop 0
	v_pk_add_f32 v[2:3], v[2:3], v[4:5]
	v_add_f32_e32 v4, v23, v6
	v_pk_add_f32 v[2:3], v[34:35], v[2:3]
	v_mul_f32_e64 v5, |v4|, s27
	v_cndmask_b32_e64 v2, v31, v2, s[4:5]
	v_cmp_neq_f32_e64 s[4:5], s31, v59
	s_nop 1
	v_cndmask_b32_e64 v3, v31, v3, s[4:5]
	v_cmp_ngt_f32_e64 s[4:5], -1.0, v59
	s_nop 1
	v_cndmask_b32_e64 v3, v32, v3, s[4:5]
	v_cmp_ngt_f32_e64 s[4:5], -1.0, v58
	s_nop 1
	v_cndmask_b32_e64 v2, v32, v2, s[4:5]
	v_cmp_neq_f32_e64 s[4:5], -1.0, v58
	s_nop 1
	v_cndmask_b32_e64 v2, v33, v2, s[4:5]
	v_cmp_neq_f32_e64 s[4:5], -1.0, v59
	s_nop 1
	v_cndmask_b32_e64 v3, v33, v3, s[4:5]
	v_cmp_lt_f32_e64 s[4:5], |v59|, s33
	s_nop 1
	v_cndmask_b32_e64 v3, v3, v59, s[4:5]
	v_exp_f32_e32 v59, v5
	v_cmp_lt_f32_e64 s[4:5], |v58|, s33
	s_nop 1
	v_cndmask_b32_e64 v2, v2, v58, s[4:5]
	v_pk_add_f32 v[0:1], v[0:1], v[2:3] neg_lo:[0,1] neg_hi:[0,1]
	v_add_f32_e32 v3, 1.0, v59
	v_min_f32_e32 v2, 0, v4
	v_add_f32_e32 v4, -1.0, v3
	v_sub_f32_e32 v5, v4, v3
	v_add_f32_e32 v5, 1.0, v5
	v_sub_f32_e32 v4, v59, v4
	v_add_f32_e32 v6, v4, v5
	v_frexp_mant_f32_e32 v34, v3
	v_cvt_f64_f32_e32 v[4:5], v3
	v_frexp_exp_i32_f64_e32 v4, v[4:5]
	v_cmp_gt_f32_e64 s[4:5], s29, v34
	s_nop 1
	v_subbrev_co_u32_e64 v50, s[4:5], 0, v4, s[4:5]
	v_mul_f32_e64 v4, |v7|, s27
	v_exp_f32_e32 v58, v4
	v_sub_u32_e32 v5, 0, v50
	v_ldexp_f32 v4, v3, v5
	v_ldexp_f32 v6, v6, v5
	v_add_f32_e32 v5, 1.0, v58
	v_min_f32_e32 v3, 0, v7
	v_add_f32_e32 v7, -1.0, v5
	v_sub_f32_e32 v34, v7, v5
	v_add_f32_e32 v34, 1.0, v34
	v_sub_f32_e32 v7, v58, v7
	v_add_f32_e32 v7, v7, v34
	v_frexp_mant_f32_e32 v36, v5
	v_cvt_f64_f32_e32 v[34:35], v5
	v_frexp_exp_i32_f64_e32 v34, v[34:35]
	v_cmp_gt_f32_e64 s[4:5], s29, v36
	s_nop 1
	v_subbrev_co_u32_e64 v51, s[4:5], 0, v34, s[4:5]
	v_sub_u32_e32 v34, 0, v51
	v_ldexp_f32 v5, v5, v34
	v_ldexp_f32 v7, v7, v34
	v_pk_add_f32 v[34:35], v[4:5], 1.0 op_sel_hi:[1,0]
	v_pk_add_f32 v[42:43], v[4:5], -1.0 op_sel_hi:[1,0]
	v_pk_add_f32 v[36:37], v[34:35], -1.0 op_sel_hi:[1,0]
	v_pk_add_f32 v[44:45], v[42:43], 1.0 op_sel_hi:[1,0]
	v_pk_add_f32 v[36:37], v[4:5], v[36:37] neg_lo:[0,1] neg_hi:[0,1]
	v_pk_add_f32 v[4:5], v[4:5], v[44:45] neg_lo:[0,1] neg_hi:[0,1]
; #define GAS __attribute__((address_space(1)))
; __global__ void __launch_bounds__(NWAVES * 64, 2) hybrid_fwd(Args args) {
;     ...
;             if (r32 < 16) { const float bb = bfg[r32]; const int tok = it * 32, bg = tok >> 13, t = tok & (T - 1);
; #pragma unroll
;                 for (int g4 = 0; g4 < 4; ++g4) { f32x4 o;
; #pragma unroll
;                     for (int e = 0; e < 4; ++e) { const float x = acc[4 * g4 + e] + bb; o[e] = fminf(x, 0.f) - log1pf(__expf(-fabsf(x))); }
;                     *(GAS f32x4*)(LFt + (size_t)(bg * 16 + r32) * T + t + 8 * g4 + 4 * hi) = o; } }
	v_pk_add_f32 v[36:37], v[6:7], v[36:37]
	v_pk_add_f32 v[4:5], v[6:7], v[4:5]
	v_pk_add_f32 v[38:39], v[34:35], v[36:37]
	v_pk_add_f32 v[6:7], v[42:43], v[4:5]
	v_rcp_f32_e32 v40, v38
	v_rcp_f32_e32 v41, v39
	v_pk_add_f32 v[34:35], v[38:39], v[34:35] neg_lo:[0,1] neg_hi:[0,1]
	v_pk_add_f32 v[42:43], v[6:7], v[42:43] neg_lo:[0,1] neg_hi:[0,1]
	v_pk_add_f32 v[34:35], v[36:37], v[34:35] neg_lo:[0,1] neg_hi:[0,1]
	v_pk_mul_f32 v[36:37], v[6:7], v[40:41]
	v_pk_add_f32 v[4:5], v[4:5], v[42:43] neg_lo:[0,1] neg_hi:[0,1]
	v_pk_mul_f32 v[42:43], v[38:39], v[36:37]
	v_cmp_neq_f32_e64 s[4:5], s31, v59
	v_pk_fma_f32 v[44:45], v[36:37], v[38:39], v[42:43] neg_lo:[0,0,1] neg_hi:[0,0,1]
	s_nop 0
	v_pk_fma_f32 v[44:45], v[36:37], v[34:35], v[44:45]
	s_nop 0
	v_pk_add_f32 v[46:47], v[42:43], v[44:45]
	s_nop 0
	v_pk_add_f32 v[48:49], v[6:7], v[46:47] neg_lo:[0,1] neg_hi:[0,1]
	v_pk_add_f32 v[42:43], v[46:47], v[42:43] neg_lo:[0,1] neg_hi:[0,1]
	v_pk_add_f32 v[6:7], v[6:7], v[48:49] neg_lo:[0,1] neg_hi:[0,1]
	s_nop 0
	v_pk_add_f32 v[6:7], v[6:7], v[46:47] neg_lo:[0,1] neg_hi:[0,1]
	s_nop 0
	v_pk_add_f32 v[4:5], v[4:5], v[6:7]
	v_pk_add_f32 v[6:7], v[42:43], v[44:45] neg_lo:[0,1] neg_hi:[0,1]
	s_nop 0
	v_pk_add_f32 v[4:5], v[6:7], v[4:5]
	s_nop 0
	v_pk_add_f32 v[6:7], v[48:49], v[4:5]
	s_nop 0
	v_pk_mul_f32 v[42:43], v[40:41], v[6:7]
	s_nop 0
	v_pk_mul_f32 v[44:45], v[38:39], v[42:43]
	s_nop 0
	v_pk_fma_f32 v[38:39], v[42:43], v[38:39], v[44:45] neg_lo:[0,0,1] neg_hi:[0,0,1]
	s_nop 0
	v_pk_fma_f32 v[34:35], v[42:43], v[34:35], v[38:39]
	v_pk_add_f32 v[38:39], v[48:49], v[6:7] neg_lo:[0,1] neg_hi:[0,1]
	s_nop 0
	v_pk_add_f32 v[4:5], v[4:5], v[38:39]
	v_pk_add_f32 v[38:39], v[44:45], v[34:35]
	s_nop 0
	v_pk_add_f32 v[46:47], v[6:7], v[38:39] neg_lo:[0,1] neg_hi:[0,1]
	v_pk_add_f32 v[44:45], v[38:39], v[44:45] neg_lo:[0,1] neg_hi:[0,1]
	v_pk_add_f32 v[6:7], v[6:7], v[46:47] neg_lo:[0,1] neg_hi:[0,1]
	s_nop 0
	v_pk_add_f32 v[6:7], v[6:7], v[38:39] neg_lo:[0,1] neg_hi:[0,1]
	s_nop 0
	v_pk_add_f32 v[4:5], v[4:5], v[6:7]
	v_pk_add_f32 v[6:7], v[44:45], v[34:35] neg_lo:[0,1] neg_hi:[0,1]
	s_nop 0
	v_pk_add_f32 v[4:5], v[6:7], v[4:5]
	v_pk_add_f32 v[6:7], v[36:37], v[42:43]
	v_pk_add_f32 v[4:5], v[46:47], v[4:5]
	v_pk_add_f32 v[34:35], v[6:7], v[36:37] neg_lo:[0,1] neg_hi:[0,1]
	v_pk_mul_f32 v[4:5], v[40:41], v[4:5]
	v_pk_add_f32 v[34:35], v[42:43], v[34:35] neg_lo:[0,1] neg_hi:[0,1]
	v_cvt_f32_i32_e32 v41, v51
	v_pk_add_f32 v[4:5], v[34:35], v[4:5]
	v_cvt_f32_i32_e32 v40, v50
	v_pk_add_f32 v[34:35], v[6:7], v[4:5]
	s_nop 0
	v_pk_mul_f32 v[36:37], v[34:35], v[34:35]
	v_pk_add_f32 v[6:7], v[34:35], v[6:7] neg_lo:[0,1] neg_hi:[0,1]
	v_pk_fma_f32 v[38:39], v[36:37], s[24:25], v[28:29] op_sel_hi:[1,0,0]
	v_pk_add_f32 v[4:5], v[4:5], v[6:7] neg_lo:[0,1] neg_hi:[0,1]
	v_ldexp_f32 v6, v34, 1
	v_pk_fma_f32 v[38:39], v[36:37], v[38:39], s[26:27] op_sel_hi:[1,1,0]
	v_ldexp_f32 v7, v35, 1
	v_pk_mul_f32 v[34:35], v[34:35], v[36:37]
	v_pk_mul_f32 v[36:37], v[40:41], s[28:29] op_sel_hi:[1,0]
	v_pk_mul_f32 v[34:35], v[34:35], v[38:39]
	v_pk_fma_f32 v[44:45], v[40:41], s[28:29], v[36:37] op_sel_hi:[1,0,1] neg_lo:[0,0,1] neg_hi:[0,0,1]
	v_pk_add_f32 v[38:39], v[6:7], v[34:35]
	v_ldexp_f32 v43, v5, 1
	v_pk_add_f32 v[6:7], v[38:39], v[6:7] neg_lo:[0,1] neg_hi:[0,1]
	v_pk_fma_f32 v[40:41], v[40:41], s[30:31], v[44:45] op_sel_hi:[1,0,1]
	v_pk_add_f32 v[6:7], v[34:35], v[6:7] neg_lo:[0,1] neg_hi:[0,1]
	v_ldexp_f32 v4, v4, 1
	v_mov_b32_e32 v34, v36
	v_mov_b32_e32 v35, v7
	v_mov_b32_e32 v42, v40
	v_mov_b32_e32 v5, v43
	v_pk_add_f32 v[34:35], v[34:35], v[42:43]
	v_pk_add_f32 v[42:43], v[4:5], v[6:7]
	v_mov_b32_e32 v7, v39
	v_mov_b32_e32 v5, v43
	v_pk_add_f32 v[44:45], v[36:37], v[40:41]
	v_pk_add_f32 v[4:5], v[4:5], v[6:7]
	v_pk_add_f32 v[6:7], v[38:39], v[42:43]
	v_mov_b32_e32 v54, v38
	v_pk_add_f32 v[46:47], v[44:45], v[6:7]
	v_mov_b32_e32 v52, v6
	v_mov_b32_e32 v53, v47
	v_mov_b32_e32 v55, v45
	v_pk_add_f32 v[52:53], v[52:53], v[54:55] neg_lo:[0,1] neg_hi:[0,1]
	v_mov_b32_e32 v48, v46
	v_mov_b32_e32 v49, v45
	v_mov_b32_e32 v50, v44
	v_mov_b32_e32 v51, v37
	v_mov_b32_e32 v54, v44
	v_mov_b32_e32 v55, v47
	v_mov_b32_e32 v37, v53
	v_pk_add_f32 v[48:49], v[48:49], v[50:51] neg_lo:[0,1] neg_hi:[0,1]
	v_mov_b32_e32 v50, v6
	v_mov_b32_e32 v51, v41
	v_pk_add_f32 v[36:37], v[54:55], v[36:37] neg_lo:[0,1] neg_hi:[0,1]
	v_pk_add_f32 v[50:51], v[50:51], v[48:49] neg_lo:[0,1] neg_hi:[0,1]
	v_mov_b32_e32 v54, v36
	v_mov_b32_e32 v55, v49
	v_mov_b32_e32 v56, v46
	v_mov_b32_e32 v57, v7
	v_mov_b32_e32 v49, v39
	v_pk_add_f32 v[54:55], v[40:41], v[54:55] neg_lo:[0,1] neg_hi:[0,1]
	v_pk_add_f32 v[48:49], v[56:57], v[48:49] neg_lo:[0,1] neg_hi:[0,1]
	v_mov_b32_e32 v41, v45
	v_pk_add_f32 v[34:35], v[34:35], v[48:49] neg_lo:[0,1] neg_hi:[0,1]
	v_pk_add_f32 v[36:37], v[40:41], v[36:37] neg_lo:[0,1] neg_hi:[0,1]
	v_pk_add_f32 v[4:5], v[4:5], v[52:53] neg_lo:[0,1] neg_hi:[0,1]
	v_pk_add_f32 v[6:7], v[6:7], v[38:39] neg_lo:[0,1] neg_hi:[0,1]
	v_pk_add_f32 v[38:39], v[4:5], v[36:37]
	v_mov_b32_e32 v37, v51
	v_mov_b32_e32 v5, v35
	v_pk_add_f32 v[40:41], v[50:51], v[34:35]
	v_pk_add_f32 v[4:5], v[36:37], v[4:5]
	v_mov_b32_e32 v34, v38
	v_pk_add_f32 v[4:5], v[4:5], v[54:55] neg_lo:[0,1] neg_hi:[0,1]
	v_mov_b32_e32 v35, v41
	v_pk_add_f32 v[6:7], v[42:43], v[6:7] neg_lo:[0,1] neg_hi:[0,1]
	v_pk_add_f32 v[34:35], v[34:35], v[4:5] neg_lo:[0,1] neg_hi:[0,1]
	v_pk_add_f32 v[4:5], v[6:7], v[4:5] neg_lo:[0,1] neg_hi:[0,1]
	v_pk_add_f32 v[34:35], v[36:37], v[34:35] neg_lo:[0,1] neg_hi:[0,1]
	v_pk_add_f32 v[6:7], v[40:41], v[38:39]
	v_pk_add_f32 v[4:5], v[4:5], v[34:35]
	v_pk_add_f32 v[34:35], v[46:47], v[6:7]
	s_nop 0
; #define GAS __attribute__((address_space(1)))
; __global__ void __launch_bounds__(NWAVES * 64, 2) hybrid_fwd(Args args) {
;     ...
;             if (r32 < 16) { const float bb = bfg[r32]; const int tok = it * 32, bg = tok >> 13, t = tok & (T - 1);
; #pragma unroll
;                 for (int g4 = 0; g4 < 4; ++g4) { f32x4 o;
; #pragma unroll
;                     for (int e = 0; e < 4; ++e) { const float x = acc[4 * g4 + e] + bb; o[e] = fminf(x, 0.f) - log1pf(__expf(-fabsf(x))); }
;                     *(GAS f32x4*)(LFt + (size_t)(bg * 16 + r32) * T + t + 8 * g4 + 4 * hi) = o; } }
	v_pk_add_f32 v[36:37], v[34:35], v[46:47] neg_lo:[0,1] neg_hi:[0,1]
	s_nop 0
	v_pk_add_f32 v[6:7], v[6:7], v[36:37] neg_lo:[0,1] neg_hi:[0,1]
	s_nop 0
	v_pk_add_f32 v[4:5], v[4:5], v[6:7]
	v_add_f32_e32 v6, v23, v8
	v_pk_add_f32 v[4:5], v[34:35], v[4:5]
	v_mul_f32_e64 v7, |v6|, s27
	v_cndmask_b32_e64 v4, v31, v4, s[4:5]
	v_cmp_neq_f32_e64 s[4:5], s31, v58
	v_exp_f32_e32 v54, v7
	s_nop 0
	v_cndmask_b32_e64 v5, v31, v5, s[4:5]
	v_cmp_ngt_f32_e64 s[4:5], -1.0, v58
	s_nop 1
	v_cndmask_b32_e64 v5, v32, v5, s[4:5]
	v_cmp_ngt_f32_e64 s[4:5], -1.0, v59
	s_nop 1
	v_cndmask_b32_e64 v4, v32, v4, s[4:5]
	v_cmp_neq_f32_e64 s[4:5], -1.0, v59
	s_nop 1
	v_cndmask_b32_e64 v4, v33, v4, s[4:5]
	v_cmp_neq_f32_e64 s[4:5], -1.0, v58
	s_nop 1
	v_cndmask_b32_e64 v5, v33, v5, s[4:5]
	v_cmp_lt_f32_e64 s[4:5], |v58|, s33
	s_nop 1
	v_cndmask_b32_e64 v5, v5, v58, s[4:5]
	v_cmp_lt_f32_e64 s[4:5], |v59|, s33
	s_nop 1
	v_cndmask_b32_e64 v4, v4, v59, s[4:5]
	v_pk_add_f32 v[2:3], v[2:3], v[4:5] neg_lo:[0,1] neg_hi:[0,1]
	global_store_dwordx4 v[26:27], v[0:3], off offset:32 sc1
	s_nop 1
	v_add_f32_e32 v1, 1.0, v54
	v_add_f32_e32 v2, -1.0, v1
	v_sub_f32_e32 v3, v2, v1
	v_add_f32_e32 v3, 1.0, v3
	v_sub_f32_e32 v2, v54, v2
	v_add_f32_e32 v4, v2, v3
	v_frexp_mant_f32_e32 v5, v1
	v_cvt_f64_f32_e32 v[2:3], v1
	v_frexp_exp_i32_f64_e32 v2, v[2:3]
	v_cmp_gt_f32_e64 s[4:5], s29, v5
	v_add_f32_e32 v5, v23, v9
	v_min_f32_e32 v0, 0, v6
	v_subbrev_co_u32_e64 v46, s[4:5], 0, v2, s[4:5]
	v_mul_f32_e64 v2, |v5|, s27
	v_exp_f32_e32 v55, v2
	v_sub_u32_e32 v3, 0, v46
	v_ldexp_f32 v2, v1, v3
	v_ldexp_f32 v4, v4, v3
	v_add_f32_e32 v3, 1.0, v55
	v_min_f32_e32 v1, 0, v5
	v_add_f32_e32 v5, -1.0, v3
	v_sub_f32_e32 v6, v5, v3
	v_add_f32_e32 v6, 1.0, v6
	v_sub_f32_e32 v5, v55, v5
	v_add_f32_e32 v5, v5, v6
	v_frexp_mant_f32_e32 v8, v3
	v_cvt_f64_f32_e32 v[6:7], v3
	v_frexp_exp_i32_f64_e32 v6, v[6:7]
	v_cmp_gt_f32_e64 s[4:5], s29, v8
	s_nop 1
	v_subbrev_co_u32_e64 v47, s[4:5], 0, v6, s[4:5]
	v_sub_u32_e32 v6, 0, v47
	v_ldexp_f32 v3, v3, v6
	v_ldexp_f32 v5, v5, v6
	v_pk_add_f32 v[6:7], v[2:3], 1.0 op_sel_hi:[1,0]
	v_pk_add_f32 v[38:39], v[2:3], -1.0 op_sel_hi:[1,0]
	v_pk_add_f32 v[8:9], v[6:7], -1.0 op_sel_hi:[1,0]
	v_pk_add_f32 v[40:41], v[38:39], 1.0 op_sel_hi:[1,0]
	v_pk_add_f32 v[8:9], v[2:3], v[8:9] neg_lo:[0,1] neg_hi:[0,1]
	v_pk_add_f32 v[2:3], v[2:3], v[40:41] neg_lo:[0,1] neg_hi:[0,1]
	v_pk_add_f32 v[8:9], v[4:5], v[8:9]
	v_pk_add_f32 v[2:3], v[4:5], v[2:3]
	v_pk_add_f32 v[34:35], v[6:7], v[8:9]
	v_pk_add_f32 v[4:5], v[38:39], v[2:3]
	v_rcp_f32_e32 v36, v34
	v_rcp_f32_e32 v37, v35
	v_pk_add_f32 v[6:7], v[34:35], v[6:7] neg_lo:[0,1] neg_hi:[0,1]
	v_pk_add_f32 v[38:39], v[4:5], v[38:39] neg_lo:[0,1] neg_hi:[0,1]
	v_pk_add_f32 v[6:7], v[8:9], v[6:7] neg_lo:[0,1] neg_hi:[0,1]
	v_pk_mul_f32 v[8:9], v[4:5], v[36:37]
	v_pk_add_f32 v[2:3], v[2:3], v[38:39] neg_lo:[0,1] neg_hi:[0,1]
	v_pk_mul_f32 v[38:39], v[34:35], v[8:9]
	v_cmp_neq_f32_e64 s[4:5], s31, v54
	v_pk_fma_f32 v[40:41], v[8:9], v[34:35], v[38:39] neg_lo:[0,0,1] neg_hi:[0,0,1]
	s_nop 0
	v_pk_fma_f32 v[40:41], v[8:9], v[6:7], v[40:41]
	s_nop 0
	v_pk_add_f32 v[42:43], v[38:39], v[40:41]
	s_nop 0
	v_pk_add_f32 v[44:45], v[4:5], v[42:43] neg_lo:[0,1] neg_hi:[0,1]
	v_pk_add_f32 v[38:39], v[42:43], v[38:39] neg_lo:[0,1] neg_hi:[0,1]
	v_pk_add_f32 v[4:5], v[4:5], v[44:45] neg_lo:[0,1] neg_hi:[0,1]
	s_nop 0
	v_pk_add_f32 v[4:5], v[4:5], v[42:43] neg_lo:[0,1] neg_hi:[0,1]
	s_nop 0
	v_pk_add_f32 v[2:3], v[2:3], v[4:5]
	v_pk_add_f32 v[4:5], v[38:39], v[40:41] neg_lo:[0,1] neg_hi:[0,1]
	s_nop 0
	v_pk_add_f32 v[2:3], v[4:5], v[2:3]
	s_nop 0
	v_pk_add_f32 v[4:5], v[44:45], v[2:3]
	s_nop 0
	v_pk_mul_f32 v[38:39], v[36:37], v[4:5]
	s_nop 0
	v_pk_mul_f32 v[40:41], v[34:35], v[38:39]
	s_nop 0
	v_pk_fma_f32 v[34:35], v[38:39], v[34:35], v[40:41] neg_lo:[0,0,1] neg_hi:[0,0,1]
	s_nop 0
	v_pk_fma_f32 v[6:7], v[38:39], v[6:7], v[34:35]
	v_pk_add_f32 v[34:35], v[44:45], v[4:5] neg_lo:[0,1] neg_hi:[0,1]
	s_nop 0
	v_pk_add_f32 v[2:3], v[2:3], v[34:35]
	v_pk_add_f32 v[34:35], v[40:41], v[6:7]
	s_nop 0
	v_pk_add_f32 v[42:43], v[4:5], v[34:35] neg_lo:[0,1] neg_hi:[0,1]
	v_pk_add_f32 v[40:41], v[34:35], v[40:41] neg_lo:[0,1] neg_hi:[0,1]
	v_pk_add_f32 v[4:5], v[4:5], v[42:43] neg_lo:[0,1] neg_hi:[0,1]
	s_nop 0
	v_pk_add_f32 v[4:5], v[4:5], v[34:35] neg_lo:[0,1] neg_hi:[0,1]
	s_nop 0
	v_pk_add_f32 v[2:3], v[2:3], v[4:5]
	v_pk_add_f32 v[4:5], v[40:41], v[6:7] neg_lo:[0,1] neg_hi:[0,1]
	s_nop 0
	v_pk_add_f32 v[2:3], v[4:5], v[2:3]
	v_pk_add_f32 v[4:5], v[8:9], v[38:39]
	v_pk_add_f32 v[2:3], v[42:43], v[2:3]
	v_pk_add_f32 v[6:7], v[4:5], v[8:9] neg_lo:[0,1] neg_hi:[0,1]
	v_pk_mul_f32 v[2:3], v[36:37], v[2:3]
	v_pk_add_f32 v[6:7], v[38:39], v[6:7] neg_lo:[0,1] neg_hi:[0,1]
	v_cvt_f32_i32_e32 v37, v47
	v_pk_add_f32 v[2:3], v[6:7], v[2:3]
	v_cvt_f32_i32_e32 v36, v46
	v_pk_add_f32 v[6:7], v[4:5], v[2:3]
	s_nop 0
	v_pk_mul_f32 v[8:9], v[6:7], v[6:7]
	v_pk_add_f32 v[4:5], v[6:7], v[4:5] neg_lo:[0,1] neg_hi:[0,1]
	v_pk_fma_f32 v[34:35], v[8:9], s[24:25], v[28:29] op_sel_hi:[1,0,0]
	v_pk_add_f32 v[2:3], v[2:3], v[4:5] neg_lo:[0,1] neg_hi:[0,1]
	v_ldexp_f32 v4, v6, 1
	v_pk_fma_f32 v[34:35], v[8:9], v[34:35], s[26:27] op_sel_hi:[1,1,0]
	v_ldexp_f32 v5, v7, 1
	v_pk_mul_f32 v[6:7], v[6:7], v[8:9]
	v_pk_mul_f32 v[8:9], v[36:37], s[28:29] op_sel_hi:[1,0]
	v_pk_mul_f32 v[6:7], v[6:7], v[34:35]
	v_pk_fma_f32 v[40:41], v[36:37], s[28:29], v[8:9] op_sel_hi:[1,0,1] neg_lo:[0,0,1] neg_hi:[0,0,1]
	v_pk_add_f32 v[34:35], v[4:5], v[6:7]
	v_ldexp_f32 v39, v3, 1
	v_pk_add_f32 v[4:5], v[34:35], v[4:5] neg_lo:[0,1] neg_hi:[0,1]
	v_pk_fma_f32 v[36:37], v[36:37], s[30:31], v[40:41] op_sel_hi:[1,0,1]
; #define GAS __attribute__((address_space(1)))
; __global__ void __launch_bounds__(NWAVES * 64, 2) hybrid_fwd(Args args) {
;     ...
;             if (r32 < 16) { const float bb = bfg[r32]; const int tok = it * 32, bg = tok >> 13, t = tok & (T - 1);
; #pragma unroll
;                 for (int g4 = 0; g4 < 4; ++g4) { f32x4 o;
; #pragma unroll
;                     for (int e = 0; e < 4; ++e) { const float x = acc[4 * g4 + e] + bb; o[e] = fminf(x, 0.f) - log1pf(__expf(-fabsf(x))); }
;                     *(GAS f32x4*)(LFt + (size_t)(bg * 16 + r32) * T + t + 8 * g4 + 4 * hi) = o; } }
	v_pk_add_f32 v[4:5], v[6:7], v[4:5] neg_lo:[0,1] neg_hi:[0,1]
	v_ldexp_f32 v2, v2, 1
	v_mov_b32_e32 v6, v8
	v_mov_b32_e32 v7, v5
	v_mov_b32_e32 v38, v36
	v_mov_b32_e32 v3, v39
	v_pk_add_f32 v[6:7], v[6:7], v[38:39]
	v_pk_add_f32 v[38:39], v[2:3], v[4:5]
	v_mov_b32_e32 v5, v35
	v_mov_b32_e32 v3, v39
	v_pk_add_f32 v[40:41], v[8:9], v[36:37]
	v_pk_add_f32 v[2:3], v[2:3], v[4:5]
	v_pk_add_f32 v[4:5], v[34:35], v[38:39]
	v_mov_b32_e32 v50, v34
	v_pk_add_f32 v[42:43], v[40:41], v[4:5]
	v_mov_b32_e32 v48, v4
	v_mov_b32_e32 v49, v43
	v_mov_b32_e32 v51, v41
	v_pk_add_f32 v[48:49], v[48:49], v[50:51] neg_lo:[0,1] neg_hi:[0,1]
	v_mov_b32_e32 v44, v42
	v_mov_b32_e32 v45, v41
	v_mov_b32_e32 v46, v40
	v_mov_b32_e32 v47, v9
	v_mov_b32_e32 v50, v40
	v_mov_b32_e32 v51, v43
	v_mov_b32_e32 v9, v49
	v_pk_add_f32 v[44:45], v[44:45], v[46:47] neg_lo:[0,1] neg_hi:[0,1]
	v_mov_b32_e32 v46, v4
	v_mov_b32_e32 v47, v37
	v_pk_add_f32 v[8:9], v[50:51], v[8:9] neg_lo:[0,1] neg_hi:[0,1]
	v_pk_add_f32 v[46:47], v[46:47], v[44:45] neg_lo:[0,1] neg_hi:[0,1]
	v_mov_b32_e32 v50, v8
	v_mov_b32_e32 v51, v45
	v_mov_b32_e32 v52, v42
	v_mov_b32_e32 v53, v5
	v_mov_b32_e32 v45, v35
	v_pk_add_f32 v[50:51], v[36:37], v[50:51] neg_lo:[0,1] neg_hi:[0,1]
	v_pk_add_f32 v[44:45], v[52:53], v[44:45] neg_lo:[0,1] neg_hi:[0,1]
	v_mov_b32_e32 v37, v41
	v_pk_add_f32 v[6:7], v[6:7], v[44:45] neg_lo:[0,1] neg_hi:[0,1]
	v_pk_add_f32 v[8:9], v[36:37], v[8:9] neg_lo:[0,1] neg_hi:[0,1]
	v_pk_add_f32 v[2:3], v[2:3], v[48:49] neg_lo:[0,1] neg_hi:[0,1]
	v_pk_add_f32 v[4:5], v[4:5], v[34:35] neg_lo:[0,1] neg_hi:[0,1]
	v_pk_add_f32 v[34:35], v[2:3], v[8:9]
	v_mov_b32_e32 v9, v47
	v_mov_b32_e32 v3, v7
	v_pk_add_f32 v[36:37], v[46:47], v[6:7]
	v_pk_add_f32 v[2:3], v[8:9], v[2:3]
	v_mov_b32_e32 v6, v34
	v_pk_add_f32 v[2:3], v[2:3], v[50:51] neg_lo:[0,1] neg_hi:[0,1]
	v_mov_b32_e32 v7, v37
	v_pk_add_f32 v[4:5], v[38:39], v[4:5] neg_lo:[0,1] neg_hi:[0,1]
	v_pk_add_f32 v[6:7], v[6:7], v[2:3] neg_lo:[0,1] neg_hi:[0,1]
	v_pk_add_f32 v[2:3], v[4:5], v[2:3] neg_lo:[0,1] neg_hi:[0,1]
	v_pk_add_f32 v[6:7], v[8:9], v[6:7] neg_lo:[0,1] neg_hi:[0,1]
	v_pk_add_f32 v[4:5], v[36:37], v[34:35]
	v_pk_add_f32 v[2:3], v[2:3], v[6:7]
	v_pk_add_f32 v[6:7], v[42:43], v[4:5]
	s_nop 0
	v_pk_add_f32 v[8:9], v[6:7], v[42:43] neg_lo:[0,1] neg_hi:[0,1]
	s_nop 0
	v_pk_add_f32 v[4:5], v[4:5], v[8:9] neg_lo:[0,1] neg_hi:[0,1]
	s_nop 0
	v_pk_add_f32 v[2:3], v[2:3], v[4:5]
	v_add_f32_e32 v4, v23, v10
	v_pk_add_f32 v[2:3], v[6:7], v[2:3]
	v_mul_f32_e64 v5, |v4|, s27
	v_cndmask_b32_e64 v2, v31, v2, s[4:5]
	v_cmp_neq_f32_e64 s[4:5], s31, v55
	s_nop 1
	v_cndmask_b32_e64 v3, v31, v3, s[4:5]
	v_cmp_ngt_f32_e64 s[4:5], -1.0, v55
	s_nop 1
	v_cndmask_b32_e64 v3, v32, v3, s[4:5]
	v_cmp_ngt_f32_e64 s[4:5], -1.0, v54
	s_nop 1
	v_cndmask_b32_e64 v2, v32, v2, s[4:5]
	v_cmp_neq_f32_e64 s[4:5], -1.0, v54
	s_nop 1
	v_cndmask_b32_e64 v2, v33, v2, s[4:5]
	v_cmp_neq_f32_e64 s[4:5], -1.0, v55
	s_nop 1
	v_cndmask_b32_e64 v3, v33, v3, s[4:5]
	v_cmp_lt_f32_e64 s[4:5], |v55|, s33
	s_nop 1
	v_cndmask_b32_e64 v3, v3, v55, s[4:5]
	v_exp_f32_e32 v55, v5
	v_cmp_lt_f32_e64 s[4:5], |v54|, s33
	s_nop 1
	v_cndmask_b32_e64 v2, v2, v54, s[4:5]
	v_pk_add_f32 v[0:1], v[0:1], v[2:3] neg_lo:[0,1] neg_hi:[0,1]
	v_add_f32_e32 v3, 1.0, v55
	v_min_f32_e32 v2, 0, v4
	v_add_f32_e32 v4, -1.0, v3
	v_sub_f32_e32 v5, v4, v3
	v_add_f32_e32 v5, 1.0, v5
	v_sub_f32_e32 v4, v55, v4
	v_add_f32_e32 v6, v4, v5
	v_frexp_mant_f32_e32 v7, v3
	v_cvt_f64_f32_e32 v[4:5], v3
	v_frexp_exp_i32_f64_e32 v4, v[4:5]
	v_cmp_gt_f32_e64 s[4:5], s29, v7
	v_add_f32_e32 v7, v23, v11
	s_nop 0
	v_subbrev_co_u32_e64 v46, s[4:5], 0, v4, s[4:5]
	v_mul_f32_e64 v4, |v7|, s27
	v_exp_f32_e32 v54, v4
	v_sub_u32_e32 v5, 0, v46
	v_ldexp_f32 v4, v3, v5
	v_ldexp_f32 v6, v6, v5
	v_add_f32_e32 v5, 1.0, v54
	v_min_f32_e32 v3, 0, v7
	v_add_f32_e32 v7, -1.0, v5
	v_sub_f32_e32 v8, v7, v5
	v_add_f32_e32 v8, 1.0, v8
	v_sub_f32_e32 v7, v54, v7
	v_add_f32_e32 v7, v7, v8
	v_frexp_mant_f32_e32 v10, v5
	v_cvt_f64_f32_e32 v[8:9], v5
	v_frexp_exp_i32_f64_e32 v8, v[8:9]
	v_cmp_gt_f32_e64 s[4:5], s29, v10
	s_nop 1
	v_subbrev_co_u32_e64 v47, s[4:5], 0, v8, s[4:5]
	v_sub_u32_e32 v8, 0, v47
	v_ldexp_f32 v5, v5, v8
	v_ldexp_f32 v7, v7, v8
	v_pk_add_f32 v[8:9], v[4:5], 1.0 op_sel_hi:[1,0]
	v_pk_add_f32 v[38:39], v[4:5], -1.0 op_sel_hi:[1,0]
	v_pk_add_f32 v[10:11], v[8:9], -1.0 op_sel_hi:[1,0]
	v_pk_add_f32 v[40:41], v[38:39], 1.0 op_sel_hi:[1,0]
	v_pk_add_f32 v[10:11], v[4:5], v[10:11] neg_lo:[0,1] neg_hi:[0,1]
	v_pk_add_f32 v[4:5], v[4:5], v[40:41] neg_lo:[0,1] neg_hi:[0,1]
	v_pk_add_f32 v[10:11], v[6:7], v[10:11]
	v_pk_add_f32 v[4:5], v[6:7], v[4:5]
	v_pk_add_f32 v[34:35], v[8:9], v[10:11]
	v_pk_add_f32 v[6:7], v[38:39], v[4:5]
	v_rcp_f32_e32 v36, v34
	v_rcp_f32_e32 v37, v35
	v_pk_add_f32 v[8:9], v[34:35], v[8:9] neg_lo:[0,1] neg_hi:[0,1]
	v_pk_add_f32 v[38:39], v[6:7], v[38:39] neg_lo:[0,1] neg_hi:[0,1]
	v_pk_add_f32 v[8:9], v[10:11], v[8:9] neg_lo:[0,1] neg_hi:[0,1]
	v_pk_mul_f32 v[10:11], v[6:7], v[36:37]
	v_pk_add_f32 v[4:5], v[4:5], v[38:39] neg_lo:[0,1] neg_hi:[0,1]
	v_pk_mul_f32 v[38:39], v[34:35], v[10:11]
	v_cmp_neq_f32_e64 s[4:5], s31, v55
	v_pk_fma_f32 v[40:41], v[10:11], v[34:35], v[38:39] neg_lo:[0,0,1] neg_hi:[0,0,1]
	s_nop 0
	v_pk_fma_f32 v[40:41], v[10:11], v[8:9], v[40:41]
	s_nop 0
	v_pk_add_f32 v[42:43], v[38:39], v[40:41]
	s_nop 0
	v_pk_add_f32 v[44:45], v[6:7], v[42:43] neg_lo:[0,1] neg_hi:[0,1]
	v_pk_add_f32 v[38:39], v[42:43], v[38:39] neg_lo:[0,1] neg_hi:[0,1]
	v_pk_add_f32 v[6:7], v[6:7], v[44:45] neg_lo:[0,1] neg_hi:[0,1]
	s_nop 0
	v_pk_add_f32 v[6:7], v[6:7], v[42:43] neg_lo:[0,1] neg_hi:[0,1]
	s_nop 0
; #define GAS __attribute__((address_space(1)))
; __global__ void __launch_bounds__(NWAVES * 64, 2) hybrid_fwd(Args args) {
;     ...
;             if (r32 < 16) { const float bb = bfg[r32]; const int tok = it * 32, bg = tok >> 13, t = tok & (T - 1);
; #pragma unroll
;                 for (int g4 = 0; g4 < 4; ++g4) { f32x4 o;
; #pragma unroll
;                     for (int e = 0; e < 4; ++e) { const float x = acc[4 * g4 + e] + bb; o[e] = fminf(x, 0.f) - log1pf(__expf(-fabsf(x))); }
;                     *(GAS f32x4*)(LFt + (size_t)(bg * 16 + r32) * T + t + 8 * g4 + 4 * hi) = o; } }
	v_pk_add_f32 v[4:5], v[4:5], v[6:7]
	v_pk_add_f32 v[6:7], v[38:39], v[40:41] neg_lo:[0,1] neg_hi:[0,1]
	s_nop 0
	v_pk_add_f32 v[4:5], v[6:7], v[4:5]
	s_nop 0
	v_pk_add_f32 v[6:7], v[44:45], v[4:5]
	s_nop 0
	v_pk_mul_f32 v[38:39], v[36:37], v[6:7]
	s_nop 0
	v_pk_mul_f32 v[40:41], v[34:35], v[38:39]
	s_nop 0
	v_pk_fma_f32 v[34:35], v[38:39], v[34:35], v[40:41] neg_lo:[0,0,1] neg_hi:[0,0,1]
	s_nop 0
	v_pk_fma_f32 v[8:9], v[38:39], v[8:9], v[34:35]
	v_pk_add_f32 v[34:35], v[44:45], v[6:7] neg_lo:[0,1] neg_hi:[0,1]
	s_nop 0
	v_pk_add_f32 v[4:5], v[4:5], v[34:35]
	v_pk_add_f32 v[34:35], v[40:41], v[8:9]
	s_nop 0
	v_pk_add_f32 v[42:43], v[6:7], v[34:35] neg_lo:[0,1] neg_hi:[0,1]
	v_pk_add_f32 v[40:41], v[34:35], v[40:41] neg_lo:[0,1] neg_hi:[0,1]
	v_pk_add_f32 v[6:7], v[6:7], v[42:43] neg_lo:[0,1] neg_hi:[0,1]
	s_nop 0
	v_pk_add_f32 v[6:7], v[6:7], v[34:35] neg_lo:[0,1] neg_hi:[0,1]
	s_nop 0
	v_pk_add_f32 v[4:5], v[4:5], v[6:7]
	v_pk_add_f32 v[6:7], v[40:41], v[8:9] neg_lo:[0,1] neg_hi:[0,1]
	s_nop 0
	v_pk_add_f32 v[4:5], v[6:7], v[4:5]
	v_pk_add_f32 v[6:7], v[10:11], v[38:39]
	v_pk_add_f32 v[4:5], v[42:43], v[4:5]
	v_pk_add_f32 v[8:9], v[6:7], v[10:11] neg_lo:[0,1] neg_hi:[0,1]
	v_pk_mul_f32 v[4:5], v[36:37], v[4:5]
	v_pk_add_f32 v[8:9], v[38:39], v[8:9] neg_lo:[0,1] neg_hi:[0,1]
	v_cvt_f32_i32_e32 v37, v47
	v_pk_add_f32 v[4:5], v[8:9], v[4:5]
	v_cvt_f32_i32_e32 v36, v46
	v_pk_add_f32 v[8:9], v[6:7], v[4:5]
	s_nop 0
	v_pk_mul_f32 v[10:11], v[8:9], v[8:9]
	v_pk_add_f32 v[6:7], v[8:9], v[6:7] neg_lo:[0,1] neg_hi:[0,1]
	v_pk_fma_f32 v[34:35], v[10:11], s[24:25], v[28:29] op_sel_hi:[1,0,0]
	v_pk_add_f32 v[4:5], v[4:5], v[6:7] neg_lo:[0,1] neg_hi:[0,1]
	v_ldexp_f32 v6, v8, 1
	v_pk_fma_f32 v[34:35], v[10:11], v[34:35], s[26:27] op_sel_hi:[1,1,0]
	v_ldexp_f32 v7, v9, 1
	v_pk_mul_f32 v[8:9], v[8:9], v[10:11]
	v_pk_mul_f32 v[10:11], v[36:37], s[28:29] op_sel_hi:[1,0]
	v_pk_mul_f32 v[8:9], v[8:9], v[34:35]
	v_pk_fma_f32 v[40:41], v[36:37], s[28:29], v[10:11] op_sel_hi:[1,0,1] neg_lo:[0,0,1] neg_hi:[0,0,1]
	v_pk_add_f32 v[34:35], v[6:7], v[8:9]
	v_ldexp_f32 v39, v5, 1
	v_pk_add_f32 v[6:7], v[34:35], v[6:7] neg_lo:[0,1] neg_hi:[0,1]
	v_pk_fma_f32 v[36:37], v[36:37], s[30:31], v[40:41] op_sel_hi:[1,0,1]
	v_pk_add_f32 v[6:7], v[8:9], v[6:7] neg_lo:[0,1] neg_hi:[0,1]
	v_ldexp_f32 v4, v4, 1
	v_mov_b32_e32 v8, v10
	v_mov_b32_e32 v9, v7
	v_mov_b32_e32 v38, v36
	v_mov_b32_e32 v5, v39
	v_pk_add_f32 v[8:9], v[8:9], v[38:39]
	v_pk_add_f32 v[38:39], v[4:5], v[6:7]
	v_mov_b32_e32 v7, v35
	v_mov_b32_e32 v5, v39
	v_pk_add_f32 v[40:41], v[10:11], v[36:37]
	v_pk_add_f32 v[4:5], v[4:5], v[6:7]
	v_pk_add_f32 v[6:7], v[34:35], v[38:39]
	v_mov_b32_e32 v50, v34
	v_pk_add_f32 v[42:43], v[40:41], v[6:7]
	v_mov_b32_e32 v48, v6
	v_mov_b32_e32 v49, v43
	v_mov_b32_e32 v51, v41
	v_pk_add_f32 v[48:49], v[48:49], v[50:51] neg_lo:[0,1] neg_hi:[0,1]
	v_mov_b32_e32 v44, v42
	v_mov_b32_e32 v45, v41
	v_mov_b32_e32 v46, v40
	v_mov_b32_e32 v47, v11
	v_mov_b32_e32 v50, v40
	v_mov_b32_e32 v51, v43
	v_mov_b32_e32 v11, v49
	v_pk_add_f32 v[44:45], v[44:45], v[46:47] neg_lo:[0,1] neg_hi:[0,1]
	v_mov_b32_e32 v46, v6
	v_mov_b32_e32 v47, v37
	v_pk_add_f32 v[10:11], v[50:51], v[10:11] neg_lo:[0,1] neg_hi:[0,1]
	v_pk_add_f32 v[46:47], v[46:47], v[44:45] neg_lo:[0,1] neg_hi:[0,1]
	v_mov_b32_e32 v50, v10
	v_mov_b32_e32 v51, v45
	v_mov_b32_e32 v52, v42
	v_mov_b32_e32 v53, v7
	v_mov_b32_e32 v45, v35
	v_pk_add_f32 v[50:51], v[36:37], v[50:51] neg_lo:[0,1] neg_hi:[0,1]
	v_pk_add_f32 v[44:45], v[52:53], v[44:45] neg_lo:[0,1] neg_hi:[0,1]
	v_mov_b32_e32 v37, v41
	v_pk_add_f32 v[8:9], v[8:9], v[44:45] neg_lo:[0,1] neg_hi:[0,1]
	v_pk_add_f32 v[10:11], v[36:37], v[10:11] neg_lo:[0,1] neg_hi:[0,1]
	v_pk_add_f32 v[4:5], v[4:5], v[48:49] neg_lo:[0,1] neg_hi:[0,1]
	v_pk_add_f32 v[6:7], v[6:7], v[34:35] neg_lo:[0,1] neg_hi:[0,1]
	v_pk_add_f32 v[34:35], v[4:5], v[10:11]
	v_mov_b32_e32 v11, v47
	v_mov_b32_e32 v5, v9
	v_pk_add_f32 v[36:37], v[46:47], v[8:9]
	v_pk_add_f32 v[4:5], v[10:11], v[4:5]
	v_mov_b32_e32 v8, v34
	v_pk_add_f32 v[4:5], v[4:5], v[50:51] neg_lo:[0,1] neg_hi:[0,1]
	v_mov_b32_e32 v9, v37
	v_pk_add_f32 v[6:7], v[38:39], v[6:7] neg_lo:[0,1] neg_hi:[0,1]
	v_pk_add_f32 v[8:9], v[8:9], v[4:5] neg_lo:[0,1] neg_hi:[0,1]
	v_pk_add_f32 v[4:5], v[6:7], v[4:5] neg_lo:[0,1] neg_hi:[0,1]
	v_pk_add_f32 v[8:9], v[10:11], v[8:9] neg_lo:[0,1] neg_hi:[0,1]
	v_pk_add_f32 v[6:7], v[36:37], v[34:35]
	v_pk_add_f32 v[4:5], v[4:5], v[8:9]
	v_pk_add_f32 v[8:9], v[42:43], v[6:7]
	s_nop 0
	v_pk_add_f32 v[10:11], v[8:9], v[42:43] neg_lo:[0,1] neg_hi:[0,1]
	s_nop 0
	v_pk_add_f32 v[6:7], v[6:7], v[10:11] neg_lo:[0,1] neg_hi:[0,1]
	s_nop 0
	v_pk_add_f32 v[4:5], v[4:5], v[6:7]
	v_add_f32_e32 v6, v23, v12
	v_pk_add_f32 v[4:5], v[8:9], v[4:5]
	v_mul_f32_e64 v7, |v6|, s27
	v_cndmask_b32_e64 v4, v31, v4, s[4:5]
	v_cmp_neq_f32_e64 s[4:5], s31, v54
	v_exp_f32_e32 v50, v7
	s_nop 0
	v_cndmask_b32_e64 v5, v31, v5, s[4:5]
	v_cmp_ngt_f32_e64 s[4:5], -1.0, v54
	s_nop 1
	v_cndmask_b32_e64 v5, v32, v5, s[4:5]
	v_cmp_ngt_f32_e64 s[4:5], -1.0, v55
	s_nop 1
	v_cndmask_b32_e64 v4, v32, v4, s[4:5]
	v_cmp_neq_f32_e64 s[4:5], -1.0, v55
	s_nop 1
	v_cndmask_b32_e64 v4, v33, v4, s[4:5]
	v_cmp_neq_f32_e64 s[4:5], -1.0, v54
	s_nop 1
	v_cndmask_b32_e64 v5, v33, v5, s[4:5]
	v_cmp_lt_f32_e64 s[4:5], |v54|, s33
	s_nop 1
	v_cndmask_b32_e64 v5, v5, v54, s[4:5]
	v_cmp_lt_f32_e64 s[4:5], |v55|, s33
	s_nop 1
	v_cndmask_b32_e64 v4, v4, v55, s[4:5]
	v_pk_add_f32 v[2:3], v[2:3], v[4:5] neg_lo:[0,1] neg_hi:[0,1]
	global_store_dwordx4 v[26:27], v[0:3], off offset:64 sc1
	s_nop 1
	v_add_f32_e32 v1, 1.0, v50
	v_add_f32_e32 v2, -1.0, v1
	v_sub_f32_e32 v3, v2, v1
; #define GAS __attribute__((address_space(1)))
; __global__ void __launch_bounds__(NWAVES * 64, 2) hybrid_fwd(Args args) {
;     ...
;             if (r32 < 16) { const float bb = bfg[r32]; const int tok = it * 32, bg = tok >> 13, t = tok & (T - 1);
; #pragma unroll
;                 for (int g4 = 0; g4 < 4; ++g4) { f32x4 o;
; #pragma unroll
;                     for (int e = 0; e < 4; ++e) { const float x = acc[4 * g4 + e] + bb; o[e] = fminf(x, 0.f) - log1pf(__expf(-fabsf(x))); }
;                     *(GAS f32x4*)(LFt + (size_t)(bg * 16 + r32) * T + t + 8 * g4 + 4 * hi) = o; } }
	v_add_f32_e32 v3, 1.0, v3
	v_sub_f32_e32 v2, v50, v2
	v_add_f32_e32 v4, v2, v3
	v_frexp_mant_f32_e32 v5, v1
	v_cvt_f64_f32_e32 v[2:3], v1
	v_frexp_exp_i32_f64_e32 v2, v[2:3]
	v_cmp_gt_f32_e64 s[4:5], s29, v5
	v_add_f32_e32 v5, v23, v13
	v_min_f32_e32 v0, 0, v6
	v_subbrev_co_u32_e64 v42, s[4:5], 0, v2, s[4:5]
	v_mul_f32_e64 v2, |v5|, s27
	v_exp_f32_e32 v51, v2
	v_sub_u32_e32 v3, 0, v42
	v_ldexp_f32 v2, v1, v3
	v_ldexp_f32 v4, v4, v3
	v_add_f32_e32 v3, 1.0, v51
	v_min_f32_e32 v1, 0, v5
	v_add_f32_e32 v5, -1.0, v3
	v_sub_f32_e32 v6, v5, v3
	v_add_f32_e32 v6, 1.0, v6
	v_sub_f32_e32 v5, v51, v5
	v_add_f32_e32 v5, v5, v6
	v_frexp_mant_f32_e32 v8, v3
	v_cvt_f64_f32_e32 v[6:7], v3
	v_frexp_exp_i32_f64_e32 v6, v[6:7]
	v_cmp_gt_f32_e64 s[4:5], s29, v8
	s_nop 1
	v_subbrev_co_u32_e64 v43, s[4:5], 0, v6, s[4:5]
	v_sub_u32_e32 v6, 0, v43
	v_ldexp_f32 v3, v3, v6
	v_ldexp_f32 v5, v5, v6
	v_pk_add_f32 v[6:7], v[2:3], 1.0 op_sel_hi:[1,0]
	v_pk_add_f32 v[34:35], v[2:3], -1.0 op_sel_hi:[1,0]
	v_pk_add_f32 v[8:9], v[6:7], -1.0 op_sel_hi:[1,0]
	v_pk_add_f32 v[36:37], v[34:35], 1.0 op_sel_hi:[1,0]
	v_pk_add_f32 v[8:9], v[2:3], v[8:9] neg_lo:[0,1] neg_hi:[0,1]
	v_pk_add_f32 v[2:3], v[2:3], v[36:37] neg_lo:[0,1] neg_hi:[0,1]
	v_pk_add_f32 v[8:9], v[4:5], v[8:9]
	v_pk_add_f32 v[2:3], v[4:5], v[2:3]
	v_pk_add_f32 v[10:11], v[6:7], v[8:9]
	v_pk_add_f32 v[4:5], v[34:35], v[2:3]
	v_rcp_f32_e32 v12, v10
	v_rcp_f32_e32 v13, v11
	v_pk_add_f32 v[6:7], v[10:11], v[6:7] neg_lo:[0,1] neg_hi:[0,1]
	v_pk_add_f32 v[34:35], v[4:5], v[34:35] neg_lo:[0,1] neg_hi:[0,1]
	v_pk_add_f32 v[6:7], v[8:9], v[6:7] neg_lo:[0,1] neg_hi:[0,1]
	v_pk_mul_f32 v[8:9], v[4:5], v[12:13]
	v_pk_add_f32 v[2:3], v[2:3], v[34:35] neg_lo:[0,1] neg_hi:[0,1]
	v_pk_mul_f32 v[34:35], v[10:11], v[8:9]
	v_cmp_neq_f32_e64 s[4:5], s31, v50
	v_pk_fma_f32 v[36:37], v[8:9], v[10:11], v[34:35] neg_lo:[0,0,1] neg_hi:[0,0,1]
	s_nop 0
	v_pk_fma_f32 v[36:37], v[8:9], v[6:7], v[36:37]
	s_nop 0
	v_pk_add_f32 v[38:39], v[34:35], v[36:37]
	s_nop 0
	v_pk_add_f32 v[40:41], v[4:5], v[38:39] neg_lo:[0,1] neg_hi:[0,1]
	v_pk_add_f32 v[34:35], v[38:39], v[34:35] neg_lo:[0,1] neg_hi:[0,1]
	v_pk_add_f32 v[4:5], v[4:5], v[40:41] neg_lo:[0,1] neg_hi:[0,1]
	s_nop 0
	v_pk_add_f32 v[4:5], v[4:5], v[38:39] neg_lo:[0,1] neg_hi:[0,1]
	s_nop 0
	v_pk_add_f32 v[2:3], v[2:3], v[4:5]
	v_pk_add_f32 v[4:5], v[34:35], v[36:37] neg_lo:[0,1] neg_hi:[0,1]
	s_nop 0
	v_pk_add_f32 v[2:3], v[4:5], v[2:3]
	s_nop 0
	v_pk_add_f32 v[4:5], v[40:41], v[2:3]
	s_nop 0
	v_pk_mul_f32 v[34:35], v[12:13], v[4:5]
	s_nop 0
	v_pk_mul_f32 v[36:37], v[10:11], v[34:35]
	s_nop 0
	v_pk_fma_f32 v[10:11], v[34:35], v[10:11], v[36:37] neg_lo:[0,0,1] neg_hi:[0,0,1]
	s_nop 0
	v_pk_fma_f32 v[6:7], v[34:35], v[6:7], v[10:11]
	v_pk_add_f32 v[10:11], v[40:41], v[4:5] neg_lo:[0,1] neg_hi:[0,1]
	s_nop 0
	v_pk_add_f32 v[2:3], v[2:3], v[10:11]
	v_pk_add_f32 v[10:11], v[36:37], v[6:7]
	s_nop 0
	v_pk_add_f32 v[38:39], v[4:5], v[10:11] neg_lo:[0,1] neg_hi:[0,1]
	v_pk_add_f32 v[36:37], v[10:11], v[36:37] neg_lo:[0,1] neg_hi:[0,1]
	v_pk_add_f32 v[4:5], v[4:5], v[38:39] neg_lo:[0,1] neg_hi:[0,1]
	s_nop 0
	v_pk_add_f32 v[4:5], v[4:5], v[10:11] neg_lo:[0,1] neg_hi:[0,1]
	s_nop 0
	v_pk_add_f32 v[2:3], v[2:3], v[4:5]
	v_pk_add_f32 v[4:5], v[36:37], v[6:7] neg_lo:[0,1] neg_hi:[0,1]
	s_nop 0
	v_pk_add_f32 v[2:3], v[4:5], v[2:3]
	v_pk_add_f32 v[4:5], v[8:9], v[34:35]
	v_pk_add_f32 v[2:3], v[38:39], v[2:3]
	v_pk_add_f32 v[6:7], v[4:5], v[8:9] neg_lo:[0,1] neg_hi:[0,1]
	v_pk_mul_f32 v[2:3], v[12:13], v[2:3]
	v_pk_add_f32 v[6:7], v[34:35], v[6:7] neg_lo:[0,1] neg_hi:[0,1]
	v_cvt_f32_i32_e32 v13, v43
	v_pk_add_f32 v[2:3], v[6:7], v[2:3]
	v_cvt_f32_i32_e32 v12, v42
	v_pk_add_f32 v[6:7], v[4:5], v[2:3]
	s_nop 0
	v_pk_mul_f32 v[8:9], v[6:7], v[6:7]
	v_pk_add_f32 v[4:5], v[6:7], v[4:5] neg_lo:[0,1] neg_hi:[0,1]
	v_pk_fma_f32 v[10:11], v[8:9], s[24:25], v[28:29] op_sel_hi:[1,0,0]
	v_pk_add_f32 v[2:3], v[2:3], v[4:5] neg_lo:[0,1] neg_hi:[0,1]
	v_ldexp_f32 v4, v6, 1
	v_pk_fma_f32 v[10:11], v[8:9], v[10:11], s[26:27] op_sel_hi:[1,1,0]
	v_ldexp_f32 v5, v7, 1
	v_pk_mul_f32 v[6:7], v[6:7], v[8:9]
	v_pk_mul_f32 v[8:9], v[12:13], s[28:29] op_sel_hi:[1,0]
	v_pk_mul_f32 v[6:7], v[6:7], v[10:11]
	v_pk_fma_f32 v[36:37], v[12:13], s[28:29], v[8:9] op_sel_hi:[1,0,1] neg_lo:[0,0,1] neg_hi:[0,0,1]
	v_pk_add_f32 v[10:11], v[4:5], v[6:7]
	v_ldexp_f32 v35, v3, 1
	v_pk_add_f32 v[4:5], v[10:11], v[4:5] neg_lo:[0,1] neg_hi:[0,1]
	v_pk_fma_f32 v[12:13], v[12:13], s[30:31], v[36:37] op_sel_hi:[1,0,1]
	v_pk_add_f32 v[4:5], v[6:7], v[4:5] neg_lo:[0,1] neg_hi:[0,1]
	v_ldexp_f32 v2, v2, 1
	v_mov_b32_e32 v6, v8
	v_mov_b32_e32 v7, v5
	v_mov_b32_e32 v34, v12
	v_mov_b32_e32 v3, v35
	v_pk_add_f32 v[6:7], v[6:7], v[34:35]
	v_pk_add_f32 v[34:35], v[2:3], v[4:5]
	v_mov_b32_e32 v5, v11
	v_mov_b32_e32 v3, v35
	v_pk_add_f32 v[36:37], v[8:9], v[12:13]
	v_pk_add_f32 v[2:3], v[2:3], v[4:5]
	v_pk_add_f32 v[4:5], v[10:11], v[34:35]
	v_mov_b32_e32 v46, v10
	v_pk_add_f32 v[38:39], v[36:37], v[4:5]
	v_mov_b32_e32 v44, v4
	v_mov_b32_e32 v45, v39
	v_mov_b32_e32 v47, v37
	v_pk_add_f32 v[44:45], v[44:45], v[46:47] neg_lo:[0,1] neg_hi:[0,1]
	v_mov_b32_e32 v40, v38
	v_mov_b32_e32 v41, v37
	v_mov_b32_e32 v42, v36
	v_mov_b32_e32 v43, v9
	v_mov_b32_e32 v46, v36
	v_mov_b32_e32 v47, v39
	v_mov_b32_e32 v9, v45
	v_pk_add_f32 v[40:41], v[40:41], v[42:43] neg_lo:[0,1] neg_hi:[0,1]
	v_mov_b32_e32 v42, v4
	v_mov_b32_e32 v43, v13
	v_pk_add_f32 v[8:9], v[46:47], v[8:9] neg_lo:[0,1] neg_hi:[0,1]
	v_pk_add_f32 v[42:43], v[42:43], v[40:41] neg_lo:[0,1] neg_hi:[0,1]
	v_mov_b32_e32 v46, v8
	v_mov_b32_e32 v47, v41
	v_mov_b32_e32 v48, v38
	v_mov_b32_e32 v49, v5
	v_mov_b32_e32 v41, v11
; #define GAS __attribute__((address_space(1)))
; __global__ void __launch_bounds__(NWAVES * 64, 2) hybrid_fwd(Args args) {
;     ...
;             if (r32 < 16) { const float bb = bfg[r32]; const int tok = it * 32, bg = tok >> 13, t = tok & (T - 1);
; #pragma unroll
;                 for (int g4 = 0; g4 < 4; ++g4) { f32x4 o;
; #pragma unroll
;                     for (int e = 0; e < 4; ++e) { const float x = acc[4 * g4 + e] + bb; o[e] = fminf(x, 0.f) - log1pf(__expf(-fabsf(x))); }
;                     *(GAS f32x4*)(LFt + (size_t)(bg * 16 + r32) * T + t + 8 * g4 + 4 * hi) = o; } }
	v_pk_add_f32 v[46:47], v[12:13], v[46:47] neg_lo:[0,1] neg_hi:[0,1]
	v_pk_add_f32 v[40:41], v[48:49], v[40:41] neg_lo:[0,1] neg_hi:[0,1]
	v_mov_b32_e32 v13, v37
	v_pk_add_f32 v[6:7], v[6:7], v[40:41] neg_lo:[0,1] neg_hi:[0,1]
	v_pk_add_f32 v[8:9], v[12:13], v[8:9] neg_lo:[0,1] neg_hi:[0,1]
	v_pk_add_f32 v[2:3], v[2:3], v[44:45] neg_lo:[0,1] neg_hi:[0,1]
	v_pk_add_f32 v[4:5], v[4:5], v[10:11] neg_lo:[0,1] neg_hi:[0,1]
	v_pk_add_f32 v[10:11], v[2:3], v[8:9]
	v_mov_b32_e32 v9, v43
	v_mov_b32_e32 v3, v7
	v_pk_add_f32 v[12:13], v[42:43], v[6:7]
	v_pk_add_f32 v[2:3], v[8:9], v[2:3]
	v_mov_b32_e32 v6, v10
	v_pk_add_f32 v[2:3], v[2:3], v[46:47] neg_lo:[0,1] neg_hi:[0,1]
	v_mov_b32_e32 v7, v13
	v_pk_add_f32 v[4:5], v[34:35], v[4:5] neg_lo:[0,1] neg_hi:[0,1]
	v_pk_add_f32 v[6:7], v[6:7], v[2:3] neg_lo:[0,1] neg_hi:[0,1]
	v_pk_add_f32 v[2:3], v[4:5], v[2:3] neg_lo:[0,1] neg_hi:[0,1]
	v_pk_add_f32 v[6:7], v[8:9], v[6:7] neg_lo:[0,1] neg_hi:[0,1]
	v_pk_add_f32 v[4:5], v[12:13], v[10:11]
	v_pk_add_f32 v[2:3], v[2:3], v[6:7]
	v_pk_add_f32 v[6:7], v[38:39], v[4:5]
	s_nop 0
	v_pk_add_f32 v[8:9], v[6:7], v[38:39] neg_lo:[0,1] neg_hi:[0,1]
	s_nop 0
	v_pk_add_f32 v[4:5], v[4:5], v[8:9] neg_lo:[0,1] neg_hi:[0,1]
	s_nop 0
	v_pk_add_f32 v[2:3], v[2:3], v[4:5]
	v_add_f32_e32 v4, v23, v14
	v_pk_add_f32 v[2:3], v[6:7], v[2:3]
	v_mul_f32_e64 v5, |v4|, s27
	v_cndmask_b32_e64 v2, v31, v2, s[4:5]
	v_cmp_neq_f32_e64 s[4:5], s31, v51
	v_exp_f32_e32 v48, v5
	s_nop 0
	v_cndmask_b32_e64 v3, v31, v3, s[4:5]
	v_cmp_ngt_f32_e64 s[4:5], -1.0, v51
	s_nop 1
	v_cndmask_b32_e64 v3, v32, v3, s[4:5]
	v_cmp_ngt_f32_e64 s[4:5], -1.0, v50
	s_nop 1
	v_cndmask_b32_e64 v2, v32, v2, s[4:5]
	v_cmp_neq_f32_e64 s[4:5], -1.0, v50
	s_nop 1
	v_cndmask_b32_e64 v2, v33, v2, s[4:5]
	v_cmp_neq_f32_e64 s[4:5], -1.0, v51
	s_nop 1
	v_cndmask_b32_e64 v3, v33, v3, s[4:5]
	v_cmp_lt_f32_e64 s[4:5], |v51|, s33
	s_nop 1
	v_cndmask_b32_e64 v3, v3, v51, s[4:5]
	v_cmp_lt_f32_e64 s[4:5], |v50|, s33
	s_nop 1
	v_cndmask_b32_e64 v2, v2, v50, s[4:5]
	v_pk_add_f32 v[0:1], v[0:1], v[2:3] neg_lo:[0,1] neg_hi:[0,1]
	v_add_f32_e32 v3, 1.0, v48
	v_min_f32_e32 v2, 0, v4
	v_add_f32_e32 v4, -1.0, v3
	v_sub_f32_e32 v5, v4, v3
	v_add_f32_e32 v5, 1.0, v5
	v_sub_f32_e32 v4, v48, v4
	v_add_f32_e32 v6, v4, v5
	v_frexp_mant_f32_e32 v7, v3
	v_cvt_f64_f32_e32 v[4:5], v3
	v_frexp_exp_i32_f64_e32 v4, v[4:5]
	v_cmp_gt_f32_e64 s[4:5], s29, v7
	v_add_f32_e32 v7, v23, v15
	s_nop 0
	v_subbrev_co_u32_e64 v42, s[4:5], 0, v4, s[4:5]
	v_mul_f32_e64 v4, |v7|, s27
	v_exp_f32_e32 v23, v4
	v_sub_u32_e32 v5, 0, v42
	v_ldexp_f32 v4, v3, v5
	v_ldexp_f32 v6, v6, v5
	v_add_f32_e32 v5, 1.0, v23
	v_min_f32_e32 v3, 0, v7
	v_add_f32_e32 v7, -1.0, v5
	v_sub_f32_e32 v8, v7, v5
	v_add_f32_e32 v8, 1.0, v8
	v_sub_f32_e32 v7, v23, v7
	v_add_f32_e32 v7, v7, v8
	v_frexp_mant_f32_e32 v10, v5
	v_cvt_f64_f32_e32 v[8:9], v5
	v_frexp_exp_i32_f64_e32 v8, v[8:9]
	v_cmp_gt_f32_e64 s[4:5], s29, v10
	s_nop 1
	v_subbrev_co_u32_e64 v43, s[4:5], 0, v8, s[4:5]
	v_sub_u32_e32 v8, 0, v43
	v_ldexp_f32 v5, v5, v8
	v_ldexp_f32 v7, v7, v8
	v_pk_add_f32 v[8:9], v[4:5], 1.0 op_sel_hi:[1,0]
	v_pk_add_f32 v[34:35], v[4:5], -1.0 op_sel_hi:[1,0]
	v_pk_add_f32 v[10:11], v[8:9], -1.0 op_sel_hi:[1,0]
	v_pk_add_f32 v[36:37], v[34:35], 1.0 op_sel_hi:[1,0]
	v_pk_add_f32 v[10:11], v[4:5], v[10:11] neg_lo:[0,1] neg_hi:[0,1]
	v_pk_add_f32 v[4:5], v[4:5], v[36:37] neg_lo:[0,1] neg_hi:[0,1]
	v_pk_add_f32 v[10:11], v[6:7], v[10:11]
	v_pk_add_f32 v[4:5], v[6:7], v[4:5]
	v_pk_add_f32 v[12:13], v[8:9], v[10:11]
	v_pk_add_f32 v[6:7], v[34:35], v[4:5]
	v_rcp_f32_e32 v14, v12
	v_rcp_f32_e32 v15, v13
	v_pk_add_f32 v[8:9], v[12:13], v[8:9] neg_lo:[0,1] neg_hi:[0,1]
	v_pk_add_f32 v[34:35], v[6:7], v[34:35] neg_lo:[0,1] neg_hi:[0,1]
	v_pk_add_f32 v[8:9], v[10:11], v[8:9] neg_lo:[0,1] neg_hi:[0,1]
	v_pk_mul_f32 v[10:11], v[6:7], v[14:15]
	v_pk_add_f32 v[4:5], v[4:5], v[34:35] neg_lo:[0,1] neg_hi:[0,1]
	v_pk_mul_f32 v[34:35], v[12:13], v[10:11]
	v_cmp_neq_f32_e64 s[4:5], s31, v48
	v_pk_fma_f32 v[36:37], v[10:11], v[12:13], v[34:35] neg_lo:[0,0,1] neg_hi:[0,0,1]
	s_nop 0
	v_pk_fma_f32 v[36:37], v[10:11], v[8:9], v[36:37]
	s_nop 0
	v_pk_add_f32 v[38:39], v[34:35], v[36:37]
	s_nop 0
	v_pk_add_f32 v[40:41], v[6:7], v[38:39] neg_lo:[0,1] neg_hi:[0,1]
	v_pk_add_f32 v[34:35], v[38:39], v[34:35] neg_lo:[0,1] neg_hi:[0,1]
	v_pk_add_f32 v[6:7], v[6:7], v[40:41] neg_lo:[0,1] neg_hi:[0,1]
	s_nop 0
	v_pk_add_f32 v[6:7], v[6:7], v[38:39] neg_lo:[0,1] neg_hi:[0,1]
	s_nop 0
	v_pk_add_f32 v[4:5], v[4:5], v[6:7]
	v_pk_add_f32 v[6:7], v[34:35], v[36:37] neg_lo:[0,1] neg_hi:[0,1]
	s_nop 0
	v_pk_add_f32 v[4:5], v[6:7], v[4:5]
	s_nop 0
	v_pk_add_f32 v[6:7], v[40:41], v[4:5]
	s_nop 0
	v_pk_mul_f32 v[34:35], v[14:15], v[6:7]
	s_nop 0
	v_pk_mul_f32 v[36:37], v[12:13], v[34:35]
	s_nop 0
	v_pk_fma_f32 v[12:13], v[34:35], v[12:13], v[36:37] neg_lo:[0,0,1] neg_hi:[0,0,1]
	s_nop 0
	v_pk_fma_f32 v[8:9], v[34:35], v[8:9], v[12:13]
	v_pk_add_f32 v[12:13], v[40:41], v[6:7] neg_lo:[0,1] neg_hi:[0,1]
; #define GAS __attribute__((address_space(1)))
; __global__ void __launch_bounds__(NWAVES * 64, 2) hybrid_fwd(Args args) {
;     ...
;             if (r32 < 16) { const float bb = bfg[r32]; const int tok = it * 32, bg = tok >> 13, t = tok & (T - 1);
; #pragma unroll
;                 for (int g4 = 0; g4 < 4; ++g4) { f32x4 o;
; #pragma unroll
;                     for (int e = 0; e < 4; ++e) { const float x = acc[4 * g4 + e] + bb; o[e] = fminf(x, 0.f) - log1pf(__expf(-fabsf(x))); }
;                     *(GAS f32x4*)(LFt + (size_t)(bg * 16 + r32) * T + t + 8 * g4 + 4 * hi) = o; } }
	s_nop 0
	v_pk_add_f32 v[4:5], v[4:5], v[12:13]
	v_pk_add_f32 v[12:13], v[36:37], v[8:9]
	s_nop 0
	v_pk_add_f32 v[38:39], v[6:7], v[12:13] neg_lo:[0,1] neg_hi:[0,1]
	v_pk_add_f32 v[36:37], v[12:13], v[36:37] neg_lo:[0,1] neg_hi:[0,1]
	v_pk_add_f32 v[6:7], v[6:7], v[38:39] neg_lo:[0,1] neg_hi:[0,1]
	s_nop 0
	v_pk_add_f32 v[6:7], v[6:7], v[12:13] neg_lo:[0,1] neg_hi:[0,1]
	s_nop 0
	v_pk_add_f32 v[4:5], v[4:5], v[6:7]
	v_pk_add_f32 v[6:7], v[36:37], v[8:9] neg_lo:[0,1] neg_hi:[0,1]
	s_nop 0
	v_pk_add_f32 v[4:5], v[6:7], v[4:5]
	v_pk_add_f32 v[6:7], v[10:11], v[34:35]
	v_pk_add_f32 v[4:5], v[38:39], v[4:5]
	v_pk_add_f32 v[8:9], v[6:7], v[10:11] neg_lo:[0,1] neg_hi:[0,1]
	v_pk_mul_f32 v[4:5], v[14:15], v[4:5]
	v_pk_add_f32 v[8:9], v[34:35], v[8:9] neg_lo:[0,1] neg_hi:[0,1]
	v_cvt_f32_i32_e32 v15, v43
	v_pk_add_f32 v[4:5], v[8:9], v[4:5]
	v_cvt_f32_i32_e32 v14, v42
	v_pk_add_f32 v[8:9], v[6:7], v[4:5]
	s_nop 0
	v_pk_mul_f32 v[10:11], v[8:9], v[8:9]
	v_pk_add_f32 v[6:7], v[8:9], v[6:7] neg_lo:[0,1] neg_hi:[0,1]
	v_pk_fma_f32 v[12:13], v[10:11], s[24:25], v[28:29] op_sel_hi:[1,0,0]
	v_pk_add_f32 v[4:5], v[4:5], v[6:7] neg_lo:[0,1] neg_hi:[0,1]
	v_ldexp_f32 v6, v8, 1
	v_pk_fma_f32 v[12:13], v[10:11], v[12:13], s[26:27] op_sel_hi:[1,1,0]
	v_ldexp_f32 v7, v9, 1
	v_pk_mul_f32 v[8:9], v[8:9], v[10:11]
	v_pk_mul_f32 v[10:11], v[14:15], s[28:29] op_sel_hi:[1,0]
	v_pk_mul_f32 v[8:9], v[8:9], v[12:13]
	v_pk_fma_f32 v[34:35], v[14:15], s[28:29], v[10:11] op_sel_hi:[1,0,1] neg_lo:[0,0,1] neg_hi:[0,0,1]
	v_pk_add_f32 v[12:13], v[6:7], v[8:9]
	v_ldexp_f32 v29, v5, 1
	v_pk_add_f32 v[6:7], v[12:13], v[6:7] neg_lo:[0,1] neg_hi:[0,1]
	v_pk_fma_f32 v[14:15], v[14:15], s[30:31], v[34:35] op_sel_hi:[1,0,1]
	v_pk_add_f32 v[6:7], v[8:9], v[6:7] neg_lo:[0,1] neg_hi:[0,1]
	v_ldexp_f32 v4, v4, 1
	v_mov_b32_e32 v8, v10
	v_mov_b32_e32 v9, v7
	v_mov_b32_e32 v28, v14
	v_mov_b32_e32 v5, v29
	v_pk_add_f32 v[8:9], v[8:9], v[28:29]
	v_pk_add_f32 v[28:29], v[4:5], v[6:7]
	v_mov_b32_e32 v7, v13
	v_mov_b32_e32 v5, v29
	v_pk_add_f32 v[34:35], v[10:11], v[14:15]
	v_pk_add_f32 v[4:5], v[4:5], v[6:7]
	v_pk_add_f32 v[6:7], v[12:13], v[28:29]
	v_mov_b32_e32 v44, v12
	v_pk_add_f32 v[36:37], v[34:35], v[6:7]
	v_mov_b32_e32 v42, v6
	v_mov_b32_e32 v43, v37
	v_mov_b32_e32 v45, v35
	v_pk_add_f32 v[42:43], v[42:43], v[44:45] neg_lo:[0,1] neg_hi:[0,1]
	v_mov_b32_e32 v38, v36
	v_mov_b32_e32 v39, v35
	v_mov_b32_e32 v40, v34
	v_mov_b32_e32 v41, v11
	v_mov_b32_e32 v44, v34
	v_mov_b32_e32 v45, v37
	v_mov_b32_e32 v11, v43
	v_pk_add_f32 v[38:39], v[38:39], v[40:41] neg_lo:[0,1] neg_hi:[0,1]
	v_mov_b32_e32 v40, v6
	v_mov_b32_e32 v41, v15
	v_pk_add_f32 v[10:11], v[44:45], v[10:11] neg_lo:[0,1] neg_hi:[0,1]
	v_pk_add_f32 v[40:41], v[40:41], v[38:39] neg_lo:[0,1] neg_hi:[0,1]
	v_mov_b32_e32 v44, v10
	v_mov_b32_e32 v45, v39
	v_mov_b32_e32 v46, v36
	v_mov_b32_e32 v47, v7
	v_mov_b32_e32 v39, v13
	v_pk_add_f32 v[44:45], v[14:15], v[44:45] neg_lo:[0,1] neg_hi:[0,1]
	v_pk_add_f32 v[38:39], v[46:47], v[38:39] neg_lo:[0,1] neg_hi:[0,1]
	v_mov_b32_e32 v15, v35
	v_pk_add_f32 v[8:9], v[8:9], v[38:39] neg_lo:[0,1] neg_hi:[0,1]
	v_pk_add_f32 v[10:11], v[14:15], v[10:11] neg_lo:[0,1] neg_hi:[0,1]
	v_pk_add_f32 v[4:5], v[4:5], v[42:43] neg_lo:[0,1] neg_hi:[0,1]
	v_pk_add_f32 v[6:7], v[6:7], v[12:13] neg_lo:[0,1] neg_hi:[0,1]
	v_pk_add_f32 v[12:13], v[4:5], v[10:11]
	v_mov_b32_e32 v11, v41
	v_mov_b32_e32 v5, v9
	v_pk_add_f32 v[14:15], v[40:41], v[8:9]
	v_pk_add_f32 v[4:5], v[10:11], v[4:5]
	v_mov_b32_e32 v8, v12
	v_pk_add_f32 v[4:5], v[4:5], v[44:45] neg_lo:[0,1] neg_hi:[0,1]
	v_mov_b32_e32 v9, v15
	v_pk_add_f32 v[6:7], v[28:29], v[6:7] neg_lo:[0,1] neg_hi:[0,1]
	v_pk_add_f32 v[8:9], v[8:9], v[4:5] neg_lo:[0,1] neg_hi:[0,1]
	v_pk_add_f32 v[4:5], v[6:7], v[4:5] neg_lo:[0,1] neg_hi:[0,1]
	v_pk_add_f32 v[8:9], v[10:11], v[8:9] neg_lo:[0,1] neg_hi:[0,1]
	v_pk_add_f32 v[6:7], v[14:15], v[12:13]
	v_pk_add_f32 v[4:5], v[4:5], v[8:9]
	v_pk_add_f32 v[8:9], v[36:37], v[6:7]
	s_nop 0
	v_pk_add_f32 v[10:11], v[8:9], v[36:37] neg_lo:[0,1] neg_hi:[0,1]
	s_nop 0
	v_pk_add_f32 v[6:7], v[6:7], v[10:11] neg_lo:[0,1] neg_hi:[0,1]
	s_nop 0
	v_pk_add_f32 v[4:5], v[4:5], v[6:7]
	s_nop 0
	v_pk_add_f32 v[4:5], v[8:9], v[4:5]
	s_nop 0
	v_cndmask_b32_e64 v4, v31, v4, s[4:5]
	v_cmp_neq_f32_e64 s[4:5], s31, v23
	s_nop 1
	v_cndmask_b32_e64 v5, v31, v5, s[4:5]
	v_cmp_ngt_f32_e64 s[4:5], -1.0, v23
	s_nop 1
	v_cndmask_b32_e64 v5, v32, v5, s[4:5]
	v_cmp_ngt_f32_e64 s[4:5], -1.0, v48
	s_nop 1
	v_cndmask_b32_e64 v4, v32, v4, s[4:5]
	v_cmp_neq_f32_e64 s[4:5], -1.0, v48
	s_nop 1
	v_cndmask_b32_e64 v4, v33, v4, s[4:5]
	v_cmp_neq_f32_e64 s[4:5], -1.0, v23
	s_nop 1
	v_cndmask_b32_e64 v5, v33, v5, s[4:5]
	v_cmp_lt_f32_e64 s[4:5], |v23|, s33
	s_nop 1
	v_cndmask_b32_e64 v5, v5, v23, s[4:5]
	v_cmp_lt_f32_e64 s[4:5], |v48|, s33
	s_nop 1
	v_cndmask_b32_e64 v4, v4, v48, s[4:5]
	v_pk_add_f32 v[2:3], v[2:3], v[4:5] neg_lo:[0,1] neg_hi:[0,1]
	global_store_dwordx4 v[26:27], v[0:3], off offset:96 sc1
	s_branch .LBB0_129

; #define PG8_WAIT_V(n) asm volatile("s_waitcnt vmcnt(" #n ")" ::: "memory")
; #define PG8_BAR __builtin_amdgcn_s_barrier()
; __device__ __forceinline__ u32x4 pack8(const f32x4 v0, const f32x4 v1) { u32x4 w; w.x = cvt_pk_bf16(v0[0], v0[1]); w.y = cvt_pk_bf16(v0[2], v0[3]); w.z = cvt_pk_bf16(v1[0], v1[1]); w.w = cvt_pk_bf16(v1[2], v1[3]); return w; }
; template <class Epi, class Sched>
; __device__ __forceinline__ void gemm_phase(PG8_LAS unsigned char* lds, const Gemm g, const Sched& S, const Epi& E) {
;     ...
;     PG8_WAIT_V(0);
;     PG8_BAR;
;     __device__ __forceinline__ void operator()(f32x4 (&acc)[2][2][4][2], const Unit& u, int wr, int wc, int fr, int fq) const {
;     ...
;         bf16_t* base = u.O + (size_t)(wr * 64 + fr) * u.ldo + wc * 32 + 8 * fq;
; #pragma unroll
;         for (int ai = 0; ai < 2; ++ai)
; #pragma unroll
;             for (int m = 0; m < 4; ++m) { bf16_t* rowp = base + (size_t)(ai * HALF + m * 16) * u.ldo;
; #pragma unroll
;                 for (int bj = 0; bj < 2; ++bj) *(u32x4*)(rowp + bj * HALF) = pack8(acc[ai][bj][m][0], acc[ai][bj][m][1]); }
.LBB0_146:
	s_lshl_b32 s6, s25, 1
	v_add_u32_e32 v128, s24, v141
	v_mad_i64_i32 v[128:129], s[2:3], s4, v128, 0
	v_lshl_add_u64 v[128:129], v[128:129], 1, s[12:13]
	s_mov_b32 s7, 0
	v_lshlrev_b32_e32 v130, 3, v140
	v_lshl_add_u64 v[128:129], v[128:129], 0, s[6:7]
	v_ashrrev_i32_e32 v131, 31, v130
	v_lshl_add_u64 v[128:129], v[130:131], 1, v[128:129]
	v_cvt_pk_bf16_f32 v124, v124, v125
	v_cvt_pk_bf16_f32 v125, v126, v127
	v_cvt_pk_bf16_f32 v126, v120, v121
	v_cvt_pk_bf16_f32 v127, v122, v123
	global_store_dwordx4 v[128:129], v[124:127], off sc1
	v_cvt_pk_bf16_f32 v112, v112, v113
	v_cvt_pk_bf16_f32 v113, v114, v115
	s_lshl_b32 s6, s4, 5
	v_cvt_pk_bf16_f32 v114, v104, v105
	v_cvt_pk_bf16_f32 v115, v106, v107
	global_store_dwordx4 v[128:129], v[112:115], off offset:256 sc1
	v_cvt_pk_bf16_f32 v104, v116, v117
	v_cvt_pk_bf16_f32 v105, v118, v119
	v_cvt_pk_bf16_f32 v106, v108, v109
	v_cvt_pk_bf16_f32 v107, v110, v111
	s_mul_i32 s2, s4, 0xa0
	s_nop 0
	v_lshl_add_u64 v[112:113], v[128:129], 0, s[6:7]
	global_store_dwordx4 v[112:113], v[104:107], off sc1
	v_cvt_pk_bf16_f32 v96, v96, v97
	v_cvt_pk_bf16_f32 v97, v98, v99
	v_cvt_pk_bf16_f32 v98, v88, v89
	v_cvt_pk_bf16_f32 v99, v90, v91
	global_store_dwordx4 v[112:113], v[96:99], off offset:256 sc1
	v_cvt_pk_bf16_f32 v88, v100, v101
	v_cvt_pk_bf16_f32 v89, v102, v103
	v_cvt_pk_bf16_f32 v90, v92, v93
	v_cvt_pk_bf16_f32 v91, v94, v95
	s_mov_b32 s3, s7
	s_nop 0
	v_lshl_add_u64 v[96:97], v[112:113], 0, s[6:7]
	global_store_dwordx4 v[96:97], v[88:91], off sc1
	v_cvt_pk_bf16_f32 v80, v80, v81
	v_cvt_pk_bf16_f32 v81, v82, v83
	v_cvt_pk_bf16_f32 v82, v72, v73
	v_cvt_pk_bf16_f32 v83, v74, v75
	global_store_dwordx4 v[96:97], v[80:83], off offset:256 sc1
	v_cvt_pk_bf16_f32 v72, v84, v85
	v_cvt_pk_bf16_f32 v73, v86, v87
	v_cvt_pk_bf16_f32 v74, v76, v77
	v_cvt_pk_bf16_f32 v75, v78, v79
	s_nop 1
	v_lshl_add_u64 v[80:81], v[96:97], 0, s[6:7]
	global_store_dwordx4 v[80:81], v[72:75], off sc1
	v_cvt_pk_bf16_f32 v68, v68, v69
	v_cvt_pk_bf16_f32 v69, v70, v71
	v_cvt_pk_bf16_f32 v70, v64, v65
	v_lshl_add_u64 v[64:65], v[80:81], 0, s[2:3]
	v_cvt_pk_bf16_f32 v71, v66, v67
	global_store_dwordx4 v[80:81], v[68:71], off offset:256 sc1
	v_cvt_pk_bf16_f32 v60, v60, v61
	v_cvt_pk_bf16_f32 v61, v62, v63
	v_cvt_pk_bf16_f32 v62, v56, v57
	v_cvt_pk_bf16_f32 v63, v58, v59
	global_store_dwordx4 v[64:65], v[60:63], off sc1
	v_cvt_pk_bf16_f32 v48, v48, v49
	v_cvt_pk_bf16_f32 v49, v50, v51
	v_cvt_pk_bf16_f32 v50, v40, v41
	v_cvt_pk_bf16_f32 v51, v42, v43
	global_store_dwordx4 v[64:65], v[48:51], off offset:256 sc1
	v_cvt_pk_bf16_f32 v40, v52, v53
	v_cvt_pk_bf16_f32 v41, v54, v55
	v_cvt_pk_bf16_f32 v42, v44, v45
	v_cvt_pk_bf16_f32 v43, v46, v47
	s_nop 1
	v_lshl_add_u64 v[48:49], v[64:65], 0, s[6:7]
	global_store_dwordx4 v[48:49], v[40:43], off sc1
	v_cvt_pk_bf16_f32 v32, v32, v33
	v_cvt_pk_bf16_f32 v33, v34, v35
	v_cvt_pk_bf16_f32 v34, v24, v25
	v_cvt_pk_bf16_f32 v35, v26, v27
	global_store_dwordx4 v[48:49], v[32:35], off offset:256 sc1
	v_cvt_pk_bf16_f32 v24, v36, v37
	v_cvt_pk_bf16_f32 v25, v38, v39
	v_cvt_pk_bf16_f32 v26, v28, v29
	v_cvt_pk_bf16_f32 v27, v30, v31
	s_nop 1
	v_lshl_add_u64 v[32:33], v[48:49], 0, s[6:7]
	global_store_dwordx4 v[32:33], v[24:27], off sc1
	v_cvt_pk_bf16_f32 v16, v16, v17
	v_cvt_pk_bf16_f32 v17, v18, v19
	v_cvt_pk_bf16_f32 v18, v8, v9
	v_cvt_pk_bf16_f32 v19, v10, v11
	global_store_dwordx4 v[32:33], v[16:19], off offset:256 sc1
	v_cvt_pk_bf16_f32 v8, v20, v21
	v_cvt_pk_bf16_f32 v9, v22, v23
	v_cvt_pk_bf16_f32 v10, v12, v13
	v_cvt_pk_bf16_f32 v11, v14, v15
	s_nop 1
	v_lshl_add_u64 v[16:17], v[32:33], 0, s[6:7]
	global_store_dwordx4 v[16:17], v[8:11], off sc1
	v_cvt_pk_bf16_f32 v4, v4, v5
	v_cvt_pk_bf16_f32 v5, v6, v7
	v_cvt_pk_bf16_f32 v6, v0, v1
	v_cvt_pk_bf16_f32 v7, v2, v3
	global_store_dwordx4 v[16:17], v[4:7], off offset:256 sc1
	s_waitcnt vmcnt(0)
	s_barrier

;     __device__ __forceinline__ void operator()(f32x4 (&acc)[2][2][4][2], const Unit& u, int wr, int wc, int fr, int fq) const {
;     ...
;                     if (lane_ == 0) { const int head = (pn & 3) * 4 + 2 * bj + (wc >> 1), half = wc & 1;
;                         unsigned* w = (pn < 12) ? NRM + 1024 + ((bg * 16 + head) * 32 + qb) * 2 + half : NRM + (bg * 16 + head) * 2 + half;
;                         __hip_atomic_fetch_max(w, __builtin_bit_cast(unsigned, mx * sc2 * 1.02f), __ATOMIC_RELAXED, __HIP_MEMORY_SCOPE_AGENT); } }
.LBB0_333:
	s_ff1_i32_b64 s53, s[56:57]
	v_readlane_b32 s75, v70, s53
	s_lshl_b64 s[84:85], 1, s53
	s_max_u32 s74, s74, s75
	s_andn2_b64 s[56:57], s[56:57], s[84:85]
	s_cmp_lg_u64 s[56:57], 0
	s_cbranch_scc1 .LBB0_333
	v_mbcnt_lo_u32_b32 v70, exec_lo, 0
	v_mbcnt_hi_u32_b32 v70, exec_hi, v70
	v_cmp_eq_u32_e32 vcc, 0, v70
	s_and_saveexec_b64 s[56:57], vcc
	s_xor_b64 s[56:57], exec, s[56:57]
	s_cbranch_execz .LBB0_336
	s_add_u32 s54, s36, s54
	s_addc_u32 s55, s37, s55
	s_ashr_i32 s53, s52, 31
	s_lshl_b64 s[52:53], s[52:53], 2
	s_add_u32 s52, s54, s52
	s_addc_u32 s53, s55, s53
	s_mov_b32 s54, 0
	v_mov_b32_e32 v70, s54
	v_mov_b32_e32 v71, s74
	global_atomic_umax v70, v71, s[52:53] sc1

;     __device__ __forceinline__ void operator()(f32x4 (&acc)[2][2][4][2], const Unit& u, int wr, int wc, int fr, int fq) const {
;     ...
;                     if (lane_ == 0) { const int head = (pn & 3) * 4 + 2 * bj + (wc >> 1), half = wc & 1;
;                         unsigned* w = (pn < 12) ? NRM + 1024 + ((bg * 16 + head) * 32 + qb) * 2 + half : NRM + (bg * 16 + head) * 2 + half;
;                         __hip_atomic_fetch_max(w, __builtin_bit_cast(unsigned, mx * sc2 * 1.02f), __ATOMIC_RELAXED, __HIP_MEMORY_SCOPE_AGENT); } }
.LBB0_342:
	s_ff1_i32_b64 s7, s[52:53]
	v_readlane_b32 s18, v2, s7
	s_lshl_b64 s[54:55], 1, s7
	s_max_u32 s2, s2, s18
	s_andn2_b64 s[52:53], s[52:53], s[54:55]
	s_cmp_lg_u64 s[52:53], 0
	s_cbranch_scc1 .LBB0_342
	v_mbcnt_lo_u32_b32 v2, exec_lo, 0
	v_mbcnt_hi_u32_b32 v2, exec_hi, v2
	v_cmp_eq_u32_e32 vcc, 0, v2
	s_and_saveexec_b64 s[52:53], vcc
	s_xor_b64 s[52:53], exec, s[52:53]
	s_cbranch_execz .LBB0_345
	s_add_u32 s18, s36, s50
	s_addc_u32 s39, s37, s51
	s_ashr_i32 s7, s6, 31
	s_lshl_b64 s[6:7], s[6:7], 2
	s_add_u32 s6, s18, s6
	s_addc_u32 s7, s39, s7
	s_mov_b32 s18, 4
	v_mov_b32_e32 v2, s18
	v_mov_b32_e32 v3, s2
	global_atomic_umax v2, v3, s[6:7] sc1

; __device__ __forceinline__ unsigned xb_add(unsigned* p, unsigned v) { return __hip_atomic_fetch_add(p, v, __ATOMIC_RELAXED, __HIP_MEMORY_SCOPE_AGENT); }
; __device__ __forceinline__ void xcd_barrier(const XcdBarrier& b) {
;     ...
;         const unsigned old = xb_add(&bar[XB_XSUB(b.x)], 1u);
;         const unsigned gen = old / nloc;
;         if (old + 1u == (gen + 1u) * nloc) {
;             __builtin_amdgcn_fence(__ATOMIC_RELEASE, "agent");
;             asm volatile("s_waitcnt vmcnt(0)" ::: "memory");
;             const unsigned og = xb_add(&bar[XB_TOP], 1u);
;             const unsigned tg = og / nx;
;             if (og + 1u == (tg + 1u) * nx) xb_add(&bar[XB_TOPGEN], 1u);
.LBB0_382:
	s_andn2_saveexec_b64 s[12:13], s[12:13]
	s_cbranch_execz .LBB0_402
	s_mov_b64 s[12:13], exec
	s_waitcnt lgkmcnt(0)
	s_waitcnt vmcnt(0)
	buffer_inv sc1
	v_mbcnt_lo_u32_b32 v2, s12, 0
	v_mbcnt_hi_u32_b32 v2, s13, v2
	v_cmp_eq_u32_e32 vcc, 0, v2
	s_and_saveexec_b64 s[14:15], vcc
	s_cbranch_execz .LBB0_385
	s_bcnt1_i32_b64 s2, s[12:13]
	v_mov_b32_e32 v3, s2
	v_mov_b32_e32 v4, 0x7000
	global_atomic_add v3, v4, v3, s[6:7] offset:1024 sc0

; __device__ __forceinline__ void cumsum_unit(float* CBh, LAS unsigned char* lds) {
;     ...
;     for (int j = 0; j < 4; ++j) { f32x4 o;
; #pragma unroll
;         for (int e = 0; e < 4; ++e) o[e] = -(off + v[j][e]) * LOG2E;
;         *(f32x4*)(CBh + tid * 16 + 4 * j) = o; }
;     __syncthreads();
.LBB0_418:
	s_or_b64 exec, exec, s[4:5]
	v_pk_add_f32 v[20:21], v[18:19], v[0:1] op_sel_hi:[1,0]
	v_pk_add_f32 v[16:17], v[16:17], v[0:1] op_sel_hi:[1,0]
	v_pk_add_f32 v[12:13], v[12:13], v[0:1] op_sel_hi:[1,0]
	v_pk_mul_f32 v[18:19], v[16:17], s[24:25] op_sel_hi:[1,0]
	v_pk_mul_f32 v[16:17], v[20:21], s[24:25] op_sel_hi:[1,0]
	global_store_dwordx4 v[2:3], v[16:19], off sc1
	v_pk_add_f32 v[8:9], v[8:9], v[0:1] op_sel_hi:[1,0]
	v_pk_add_f32 v[4:5], v[4:5], v[0:1] op_sel_hi:[1,0]
	v_pk_add_f32 v[16:17], v[14:15], v[0:1] op_sel_hi:[1,0]
	v_pk_mul_f32 v[14:15], v[12:13], s[24:25] op_sel_hi:[1,0]
	v_pk_mul_f32 v[12:13], v[16:17], s[24:25] op_sel_hi:[1,0]
	global_store_dwordx4 v[2:3], v[12:15], off offset:16 sc1
	s_mov_b64 s[4:5], 0
	s_nop 0
	v_pk_add_f32 v[12:13], v[10:11], v[0:1] op_sel_hi:[1,0]
	v_pk_mul_f32 v[10:11], v[8:9], s[24:25] op_sel_hi:[1,0]
	v_pk_mul_f32 v[8:9], v[12:13], s[24:25] op_sel_hi:[1,0]
	global_store_dwordx4 v[2:3], v[8:11], off offset:32 sc1
	s_nop 1
	v_pk_add_f32 v[8:9], v[6:7], v[0:1] op_sel_hi:[1,0]
	v_pk_mul_f32 v[6:7], v[4:5], s[24:25] op_sel_hi:[1,0]
	v_pk_mul_f32 v[4:5], v[8:9], s[24:25] op_sel_hi:[1,0]
	global_store_dwordx4 v[2:3], v[4:7], off offset:48 sc1
	s_barrier

; #define GAS __attribute__((address_space(1)))
; #define LAS __attribute__((address_space(3)))
; template <int PASS>
; __device__ __forceinline__ void lru_unit(const LruPtrs& args, LAS unsigned char* lds, int chunk, int bl, int g, int ck) {
;     ...
;           PRM[w * 64 + lane] = ((const GAS float*)src)[g * 64 + lane]; }
;         LAS bf16* XT = (LAS bf16*)(lds + RING_OFF + 32768 + w * 4864);
;         {
;             const int tl0 = ck * 256 + w * 32;
;             v4u xv[5];
; #pragma unroll
;             for (int i = 0; i < 5; ++i) { const int idx = lane + 64 * i, r = idx >> 3, ch = idx & 7; const int ts = tl0 - 3 + r;
;                 xv[i] = (v4u){0u, 0u, 0u, 0u};
;                 if (r < 35 && ts >= 0) xv[i] = *(const GAS v4u*)(Z + ((size_t)bl * T + ts) * LDZ + ZC_AX + g * 64 + ch * 8); }
; #pragma unroll
;             for (int i = 0; i < 5; ++i) { const int idx = lane + 64 * i, r = idx >> 3, ch = idx & 7;
;                 if (r < 35) { *(LAS v2u*)(XT + r * 68 + ch * 8) = (v2u){xv[i].x, xv[i].y}; *(LAS v2u*)(XT + r * 68 + ch * 8 + 4) = (v2u){xv[i].z, xv[i].w}; } }
;         }
;         __syncthreads();
;         v2u xw[4][8];
; #pragma unroll
;         for (int k = 0; k < 4; ++k)
; #pragma unroll
;             for (int q = 0; q < 8; ++q) xw[k][q] = *(const LAS v2u*)(XT + (n + k) * 68 + 8 * q + 4 * hi);
;         float xc[8][4];
; #pragma unroll
;         for (int q = 0; q < 8; ++q) { const f32x4 bb = *(const LAS f32x4*)(PRM + 4 * 64 + 8 * q + 4 * hi);
; #pragma unroll
;             for (int p = 0; p < 4; ++p) xc[q][p] = bb[p]; }
; #pragma unroll
;         for (int k = 0; k < 4; ++k) {
; #pragma unroll
;             for (int q = 0; q < 8; ++q) { const f32x4 cw = *(const LAS f32x4*)(PRM + k * 64 + 8 * q + 4 * hi);
;                 xc[q][0] += cw[0] * pg8::bf_lo(xw[k][q].x); xc[q][1] += cw[1] * pg8::bf_hi(xw[k][q].x); xc[q][2] += cw[2] * pg8::bf_lo(xw[k][q].y); xc[q][3] += cw[3] * pg8::bf_hi(xw[k][q].y); }
.LBB0_443:
	s_or_b64 exec, exec, s[4:5]
	s_mul_i32 s4, s48, 0x1300
	s_add_i32 s50, s4, 0
	v_lshl_add_u32 v0, v26, 1, s50
	s_movk_i32 s4, 0x88
	v_mad_u32_u24 v22, v25, s4, v0
	v_add_u32_e32 v23, 0x8000, v22
	s_waitcnt vmcnt(0)
	ds_write_b32 v179, v178 offset:12288
	ds_write2_b64 v23, v[6:7], v[8:9] offset1:1
	v_add_u32_e32 v6, 0x8440, v22
	ds_write2_b64 v6, v[2:3], v[4:5] offset1:1
	v_add_u32_e32 v2, 0x8880, v22
	ds_write2_b64 v2, v[14:15], v[16:17] offset1:1
	v_add_u32_e32 v2, 0x8cc0, v22
	ds_write2_b64 v2, v[10:11], v[12:13] offset1:1
	s_and_saveexec_b64 s[4:5], vcc
	v_mul_u32_u24_e32 v2, 0x88, v27
	v_add3_u32 v0, v0, v2, s79
	ds_write2_b64 v0, v[18:19], v[20:21] offset1:1
	s_or_b64 exec, exec, s[4:5]
	v_lshrrev_b32_e32 v2, 3, v24
	v_and_b32_e32 v87, 31, v24
	v_and_b32_e32 v88, 4, v2
	v_lshlrev_b32_e32 v2, 1, v88
	v_mul_u32_u24_e32 v3, 0x88, v87
	v_add3_u32 v2, s50, v2, v3
	v_add_u32_e32 v10, 0x8000, v2
	v_lshl_add_u32 v89, v88, 2, 0
	s_waitcnt lgkmcnt(0)
	s_barrier
	ds_read2_b64 v[90:93], v10 offset1:2
	ds_read2_b64 v[82:85], v10 offset0:4 offset1:6
	ds_read2_b64 v[50:53], v10 offset0:8 offset1:10
	ds_read2_b64 v[2:5], v10 offset0:12 offset1:14
	ds_read2_b64 v[94:97], v10 offset0:17 offset1:19
	ds_read2_b64 v[98:101], v10 offset0:21 offset1:23
	ds_read2_b64 v[54:57], v10 offset0:25 offset1:27
	ds_read2_b64 v[6:9], v10 offset0:29 offset1:31
	ds_read2_b64 v[34:37], v10 offset0:34 offset1:36
	ds_read2_b64 v[26:29], v10 offset0:38 offset1:40
	ds_read2_b64 v[18:21], v10 offset0:42 offset1:44
	ds_read2_b64 v[66:69], v10 offset0:46 offset1:48
	ds_read2_b64 v[38:41], v10 offset0:51 offset1:53
	ds_read2_b64 v[30:33], v10 offset0:55 offset1:57
	ds_read2_b64 v[22:25], v10 offset0:59 offset1:61
	ds_read2_b64 v[70:73], v10 offset0:63 offset1:65
	ds_read_b128 v[102:105], v89 offset:13312
	ds_read_b128 v[106:109], v89 offset:13344
	ds_read_b128 v[110:113], v89 offset:13376
	ds_read_b128 v[114:117], v89 offset:13408
	ds_read_b128 v[74:77], v89 offset:13440
	ds_read_b128 v[58:61], v89 offset:13472
	ds_read_b128 v[42:45], v89 offset:13504
	ds_read_b128 v[10:13], v89 offset:13536
	ds_read_b128 v[118:121], v89 offset:12288
	ds_read_b128 v[122:125], v89 offset:12320
	ds_read_b128 v[126:129], v89 offset:12352
	ds_read_b128 v[130:133], v89 offset:12384
	ds_read_b128 v[78:81], v89 offset:12416
	ds_read_b128 v[62:65], v89 offset:12448
	ds_read_b128 v[46:49], v89 offset:12480
	ds_read_b128 v[14:17], v89 offset:12512
	ds_read_b128 v[134:137], v89 offset:12544
	s_waitcnt lgkmcnt(14)
	v_lshlrev_b32_e32 v143, 16, v94
	v_lshlrev_b32_e32 v142, 16, v90
	s_waitcnt lgkmcnt(8)
	v_mov_b32_e32 v144, v118
	ds_read_b128 v[138:141], v89 offset:12576
	s_waitcnt lgkmcnt(1)
	v_mov_b32_e32 v145, v134
	v_pk_mul_f32 v[142:143], v[144:145], v[142:143]
	v_mov_b32_e32 v134, v119
	v_add_f32_e32 v102, v102, v142
	v_add_f32_e32 v144, v102, v143
	v_and_b32_e32 v143, 0xffff0000, v94
	v_and_b32_e32 v142, 0xffff0000, v90
	v_pk_mul_f32 v[118:119], v[134:135], v[142:143]
	v_lshlrev_b32_e32 v102, 16, v91
	v_add_f32_e32 v90, v103, v118
	v_add_f32_e32 v134, v90, v119
	v_lshlrev_b32_e32 v103, 16, v95
	v_mov_b32_e32 v118, v120
	v_mov_b32_e32 v119, v136
	v_pk_mul_f32 v[102:103], v[118:119], v[102:103]
	v_and_b32_e32 v95, 0xffff0000, v95
	v_add_f32_e32 v90, v104, v102
	v_and_b32_e32 v94, 0xffff0000, v91
	v_mov_b32_e32 v136, v121
	v_add_f32_e32 v135, v90, v103
	v_pk_mul_f32 v[90:91], v[136:137], v[94:95]
	v_mov_b32_e32 v94, v122
	v_add_f32_e32 v90, v105, v90
	v_add_f32_e32 v136, v90, v91
	v_lshlrev_b32_e32 v91, 16, v96
	v_lshlrev_b32_e32 v90, 16, v92
	s_waitcnt lgkmcnt(0)
	v_mov_b32_e32 v95, v138
	v_pk_mul_f32 v[90:91], v[94:95], v[90:91]
	v_mov_b32_e32 v138, v123
	v_add_f32_e32 v90, v106, v90
	v_add_f32_e32 v122, v90, v91
	v_and_b32_e32 v91, 0xffff0000, v96
	v_and_b32_e32 v90, 0xffff0000, v92
	v_pk_mul_f32 v[90:91], v[138:139], v[90:91]
	v_mov_b32_e32 v94, v124
	v_add_f32_e32 v90, v107, v90
	v_add_f32_e32 v123, v90, v91
	v_lshlrev_b32_e32 v91, 16, v97
	v_lshlrev_b32_e32 v90, 16, v93
	v_mov_b32_e32 v95, v140
	v_pk_mul_f32 v[90:91], v[94:95], v[90:91]
	v_mov_b32_e32 v140, v125
	v_add_f32_e32 v90, v108, v90
	v_add_f32_e32 v108, v90, v91
	v_and_b32_e32 v91, 0xffff0000, v97
	v_and_b32_e32 v90, 0xffff0000, v93
	v_pk_mul_f32 v[90:91], v[140:141], v[90:91]
	v_lshlrev_b32_e32 v103, 16, v98
	v_add_f32_e32 v90, v109, v90
	v_add_f32_e32 v124, v90, v91
	ds_read_b128 v[90:93], v89 offset:12608
	ds_read_b128 v[94:97], v89 offset:12640
	v_lshlrev_b32_e32 v102, 16, v82
	v_mov_b32_e32 v104, v126
	s_and_b32 s4, s49, 0x1ffffe00
	s_waitcnt lgkmcnt(1)
	v_mov_b32_e32 v105, v90
	v_pk_mul_f32 v[102:103], v[104:105], v[102:103]
	s_lshl_b32 s5, s2, 5
	v_add_f32_e32 v90, v110, v102
	v_add_f32_e32 v125, v90, v103
	v_and_b32_e32 v103, 0xffff0000, v98
	v_and_b32_e32 v102, 0xffff0000, v82
	v_mov_b32_e32 v90, v127
	v_pk_mul_f32 v[90:91], v[90:91], v[102:103]
	v_mov_b32_e32 v102, v128
	v_add_f32_e32 v82, v111, v90
	v_add_f32_e32 v126, v82, v91
	v_lshlrev_b32_e32 v91, 16, v99
	v_lshlrev_b32_e32 v90, 16, v83
	v_mov_b32_e32 v103, v92
	v_pk_mul_f32 v[90:91], v[102:103], v[90:91]
	v_mov_b32_e32 v92, v129
	v_add_f32_e32 v82, v112, v90
	v_add_f32_e32 v127, v82, v91
	v_and_b32_e32 v91, 0xffff0000, v99
	v_and_b32_e32 v90, 0xffff0000, v83
	v_pk_mul_f32 v[82:83], v[92:93], v[90:91]
	v_mov_b32_e32 v90, v130
	v_add_f32_e32 v82, v113, v82
	v_add_f32_e32 v128, v82, v83
	v_lshlrev_b32_e32 v83, 16, v100
	v_lshlrev_b32_e32 v82, 16, v84
	s_waitcnt lgkmcnt(0)
; #define LAS __attribute__((address_space(3)))
; template <int PASS>
; __device__ __forceinline__ void lru_unit(const LruPtrs& args, LAS unsigned char* lds, int chunk, int bl, int g, int ck) {
;     ...
;         for (int k = 0; k < 4; ++k) {
; #pragma unroll
;             for (int q = 0; q < 8; ++q) { const f32x4 cw = *(const LAS f32x4*)(PRM + k * 64 + 8 * q + 4 * hi);
;                 xc[q][0] += cw[0] * pg8::bf_lo(xw[k][q].x); xc[q][1] += cw[1] * pg8::bf_hi(xw[k][q].x); xc[q][2] += cw[2] * pg8::bf_lo(xw[k][q].y); xc[q][3] += cw[3] * pg8::bf_hi(xw[k][q].y); }
;         }
	v_mov_b32_e32 v91, v94
	v_pk_mul_f32 v[82:83], v[90:91], v[82:83]
	v_mov_b32_e32 v94, v131
	v_add_f32_e32 v82, v114, v82
	v_add_f32_e32 v129, v82, v83
	v_and_b32_e32 v83, 0xffff0000, v100
	v_and_b32_e32 v82, 0xffff0000, v84
	v_pk_mul_f32 v[82:83], v[94:95], v[82:83]
	v_mov_b32_e32 v90, v132
	v_add_f32_e32 v82, v115, v82
	v_add_f32_e32 v130, v82, v83
	v_lshlrev_b32_e32 v83, 16, v101
	v_lshlrev_b32_e32 v82, 16, v85
	v_mov_b32_e32 v91, v96
	v_pk_mul_f32 v[82:83], v[90:91], v[82:83]
	v_mov_b32_e32 v96, v133
	v_add_f32_e32 v82, v116, v82
	v_add_f32_e32 v131, v82, v83
	v_and_b32_e32 v83, 0xffff0000, v101
	v_and_b32_e32 v82, 0xffff0000, v85
	v_pk_mul_f32 v[82:83], v[96:97], v[82:83]
	v_lshlrev_b32_e32 v91, 16, v54
	v_add_f32_e32 v82, v117, v82
	v_add_f32_e32 v117, v82, v83
	ds_read_b128 v[82:85], v89 offset:12672
	ds_read_b128 v[94:97], v89 offset:12704
	v_lshlrev_b32_e32 v90, 16, v50
	v_mov_b32_e32 v92, v78
	s_or_b32 s4, s5, s4
	s_waitcnt lgkmcnt(1)
	v_mov_b32_e32 v93, v82
	v_pk_mul_f32 v[90:91], v[92:93], v[90:91]
	v_mov_b32_e32 v82, v79
	v_add_f32_e32 v74, v74, v90
	v_add_f32_e32 v132, v74, v91
	v_and_b32_e32 v91, 0xffff0000, v54
	v_and_b32_e32 v90, 0xffff0000, v50
	v_pk_mul_f32 v[78:79], v[82:83], v[90:91]
	v_lshlrev_b32_e32 v74, 16, v51
	v_add_f32_e32 v50, v75, v78
	v_add_f32_e32 v133, v50, v79
	v_lshlrev_b32_e32 v75, 16, v55
	v_mov_b32_e32 v78, v80
	v_mov_b32_e32 v79, v84
	v_pk_mul_f32 v[74:75], v[78:79], v[74:75]
	v_and_b32_e32 v55, 0xffff0000, v55
	v_add_f32_e32 v50, v76, v74
	v_and_b32_e32 v54, 0xffff0000, v51
	v_mov_b32_e32 v84, v81
	v_add_f32_e32 v92, v50, v75
	v_pk_mul_f32 v[50:51], v[84:85], v[54:55]
	v_mov_b32_e32 v74, v62
	v_add_f32_e32 v50, v77, v50
	v_add_f32_e32 v54, v50, v51
	v_lshlrev_b32_e32 v51, 16, v56
	v_lshlrev_b32_e32 v50, 16, v52
	s_waitcnt lgkmcnt(0)
	v_mov_b32_e32 v75, v94
	v_pk_mul_f32 v[50:51], v[74:75], v[50:51]
	v_and_b32_e32 v75, 0xffff0000, v56
	v_and_b32_e32 v74, 0xffff0000, v52
	v_mov_b32_e32 v94, v63
	v_add_f32_e32 v50, v58, v50
	v_pk_mul_f32 v[62:63], v[94:95], v[74:75]
	v_add_f32_e32 v51, v50, v51
	v_add_f32_e32 v50, v59, v62
	v_add_f32_e32 v52, v50, v63
	v_lshlrev_b32_e32 v59, 16, v57
	v_lshlrev_b32_e32 v58, 16, v53
	v_mov_b32_e32 v62, v64
	v_mov_b32_e32 v63, v96
	v_and_b32_e32 v57, 0xffff0000, v57
	v_and_b32_e32 v56, 0xffff0000, v53
	v_mov_b32_e32 v96, v65
	v_pk_mul_f32 v[58:59], v[62:63], v[58:59]
	v_pk_mul_f32 v[56:57], v[96:97], v[56:57]
	v_add_f32_e32 v50, v60, v58
	v_add_f32_e32 v53, v61, v56
	v_add_f32_e32 v50, v50, v59
	v_add_f32_e32 v53, v53, v57
	ds_read_b128 v[56:59], v89 offset:12736
	ds_read_b128 v[74:77], v89 offset:12768
	v_lshlrev_b32_e32 v61, 16, v6
	v_lshlrev_b32_e32 v60, 16, v2
	v_mov_b32_e32 v62, v46
	s_waitcnt lgkmcnt(1)
	v_mov_b32_e32 v63, v56
	v_pk_mul_f32 v[60:61], v[62:63], v[60:61]
	v_mov_b32_e32 v56, v47
	v_add_f32_e32 v42, v42, v60
	v_add_f32_e32 v94, v42, v61
	v_and_b32_e32 v61, 0xffff0000, v6
	v_and_b32_e32 v60, 0xffff0000, v2
	v_pk_mul_f32 v[46:47], v[56:57], v[60:61]
	v_lshlrev_b32_e32 v42, 16, v3
	v_add_f32_e32 v2, v43, v46
	v_add_f32_e32 v93, v2, v47
	v_lshlrev_b32_e32 v43, 16, v7
	v_mov_b32_e32 v46, v48
	v_mov_b32_e32 v47, v58
	v_pk_mul_f32 v[42:43], v[46:47], v[42:43]
	v_and_b32_e32 v7, 0xffff0000, v7
	v_add_f32_e32 v2, v44, v42
	v_and_b32_e32 v6, 0xffff0000, v3
	v_mov_b32_e32 v58, v49
	v_add_f32_e32 v116, v2, v43
	v_pk_mul_f32 v[2:3], v[58:59], v[6:7]
	v_lshlrev_b32_e32 v7, 16, v38
	v_add_f32_e32 v2, v45, v2
	ds_read_b128 v[56:59], v89 offset:12800
	ds_read_b128 v[60:63], v89 offset:12832
	ds_read_b128 v[96:99], v89 offset:12864
	ds_read_b128 v[118:121], v89 offset:12896
	ds_read_b128 v[46:49], v89 offset:12928
	ds_read_b128 v[42:45], v89 offset:12960
	ds_read_b128 v[82:85], v89 offset:12992
	ds_read_b128 v[78:81], v89 offset:13024
	ds_read_b128 v[100:103], v89 offset:13056
	v_lshlrev_b32_e32 v6, 16, v34
	s_waitcnt lgkmcnt(8)
	v_mov_b32_e32 v64, v56
	v_mov_b32_e32 v56, v58
	ds_read_b128 v[104:107], v89 offset:13088
	s_waitcnt lgkmcnt(1)
	v_mov_b32_e32 v65, v100
	v_pk_mul_f32 v[6:7], v[64:65], v[6:7]
	v_mov_b32_e32 v100, v57
	v_add_f32_e32 v6, v144, v6
	v_add_f32_e32 v115, v6, v7
	v_and_b32_e32 v7, 0xffff0000, v38
	v_and_b32_e32 v6, 0xffff0000, v34
	v_pk_mul_f32 v[6:7], v[100:101], v[6:7]
	v_mov_b32_e32 v57, v102
	v_add_f32_e32 v6, v134, v6
	v_add_f32_e32 v114, v6, v7
	v_lshlrev_b32_e32 v7, 16, v39
	v_lshlrev_b32_e32 v6, 16, v35
	v_pk_mul_f32 v[6:7], v[56:57], v[6:7]
	v_mov_b32_e32 v102, v59
	v_add_f32_e32 v6, v135, v6
	v_add_f32_e32 v113, v6, v7
	v_and_b32_e32 v7, 0xffff0000, v39
	v_and_b32_e32 v6, 0xffff0000, v35
	v_pk_mul_f32 v[6:7], v[102:103], v[6:7]
	v_mov_b32_e32 v34, v60
	v_add_f32_e32 v6, v136, v6
	v_add_f32_e32 v112, v6, v7
	v_lshlrev_b32_e32 v7, 16, v40
	v_lshlrev_b32_e32 v6, 16, v36
	s_waitcnt lgkmcnt(0)
	v_mov_b32_e32 v35, v104
	v_pk_mul_f32 v[6:7], v[34:35], v[6:7]
	v_mov_b32_e32 v104, v61
	v_add_f32_e32 v6, v122, v6
	v_add_f32_e32 v111, v6, v7
	v_and_b32_e32 v7, 0xffff0000, v40
	v_and_b32_e32 v6, 0xffff0000, v36
	v_pk_mul_f32 v[6:7], v[104:105], v[6:7]
	v_mov_b32_e32 v34, v62
	v_add_f32_e32 v6, v123, v6
	v_add_f32_e32 v110, v6, v7
	v_lshlrev_b32_e32 v7, 16, v41
	v_lshlrev_b32_e32 v6, 16, v37
	v_mov_b32_e32 v35, v106
	v_pk_mul_f32 v[6:7], v[34:35], v[6:7]
	v_mov_b32_e32 v106, v63
	v_add_f32_e32 v6, v108, v6
	v_add_f32_e32 v109, v6, v7
	v_and_b32_e32 v6, 0xffff0000, v37
	ds_read_b128 v[34:37], v89 offset:13120
	v_and_b32_e32 v7, 0xffff0000, v41
	v_pk_mul_f32 v[6:7], v[106:107], v[6:7]
	v_mov_b32_e32 v56, v96
	v_add_f32_e32 v6, v124, v6
	v_add_f32_e32 v100, v6, v7
	v_lshlrev_b32_e32 v7, 16, v30
	v_lshlrev_b32_e32 v6, 16, v26
	ds_read_b128 v[38:41], v89 offset:13152
	s_waitcnt lgkmcnt(1)
; __device__ __forceinline__ unsigned cvt_pk_bf16(float lo, float hi) { unsigned r; asm volatile("v_cvt_pk_bf16_f32 %0, %1, %2" : "=v"(r) : "v"(lo), "v"(hi)); return r; }
; #define GAS __attribute__((address_space(1)))
; #define LAS __attribute__((address_space(3)))
; template <int PASS>
; __device__ __forceinline__ void lru_unit(const LruPtrs& args, LAS unsigned char* lds, int chunk, int bl, int g, int ck) {
;     ...
;         for (int k = 0; k < 4; ++k) {
; #pragma unroll
;             for (int q = 0; q < 8; ++q) { const f32x4 cw = *(const LAS f32x4*)(PRM + k * 64 + 8 * q + 4 * hi);
;                 xc[q][0] += cw[0] * pg8::bf_lo(xw[k][q].x); xc[q][1] += cw[1] * pg8::bf_hi(xw[k][q].x); xc[q][2] += cw[2] * pg8::bf_lo(xw[k][q].y); xc[q][3] += cw[3] * pg8::bf_hi(xw[k][q].y); }
;         }
;         f32x16 ar[2], ai_[2];
; #pragma unroll
;         for (int rb = 0; rb < 2; ++rb) { ar[rb] = f32x16{}; ai_[rb] = f32x16{}; }
;         const GAS bf16* wrf = (const GAS bf16*)(ws + WS_WRF) + (size_t)g * (2 * 2 * 4 * 64 * 8) + lane * 8;
; #pragma unroll
;         for (int ks = 0; ks < 4; ++ks) {
;             v4u bw; bw.x = pg8::cvt_pk_bf16(xc[2 * ks][0], xc[2 * ks][1]); bw.y = pg8::cvt_pk_bf16(xc[2 * ks][2], xc[2 * ks][3]); bw.z = pg8::cvt_pk_bf16(xc[2 * ks + 1][0], xc[2 * ks + 1][1]); bw.w = pg8::cvt_pk_bf16(xc[2 * ks + 1][2], xc[2 * ks + 1][3]);
;             const bf16x8 bfr = __builtin_bit_cast(bf16x8, bw);
; #pragma unroll
;             for (int rb = 0; rb < 2; ++rb) {
;                 const bf16x8 wr_ = __builtin_bit_cast(bf16x8, *(const GAS v4u*)(wrf + ((0 * 2 + rb) * 4 + ks) * 512));
	v_mov_b32_e32 v57, v34
	v_pk_mul_f32 v[6:7], v[56:57], v[6:7]
	v_mov_b32_e32 v34, v97
	v_add_f32_e32 v6, v125, v6
	v_add_f32_e32 v106, v6, v7
	v_and_b32_e32 v7, 0xffff0000, v30
	v_and_b32_e32 v6, 0xffff0000, v26
	v_pk_mul_f32 v[6:7], v[34:35], v[6:7]
	v_mov_b32_e32 v34, v98
	v_add_f32_e32 v6, v126, v6
	v_add_f32_e32 v103, v6, v7
	v_lshlrev_b32_e32 v7, 16, v31
	v_lshlrev_b32_e32 v6, 16, v27
	v_mov_b32_e32 v35, v36
	v_pk_mul_f32 v[6:7], v[34:35], v[6:7]
	v_mov_b32_e32 v36, v99
	v_add_f32_e32 v6, v127, v6
	v_add_f32_e32 v102, v6, v7
	v_and_b32_e32 v7, 0xffff0000, v31
	v_and_b32_e32 v6, 0xffff0000, v27
	v_pk_mul_f32 v[6:7], v[36:37], v[6:7]
	v_mov_b32_e32 v26, v118
	v_add_f32_e32 v6, v128, v6
	v_add_f32_e32 v99, v6, v7
	v_lshlrev_b32_e32 v7, 16, v32
	v_lshlrev_b32_e32 v6, 16, v28
	s_waitcnt lgkmcnt(0)
	v_mov_b32_e32 v27, v38
	v_pk_mul_f32 v[6:7], v[26:27], v[6:7]
	v_mov_b32_e32 v38, v119
	v_add_f32_e32 v6, v129, v6
	v_add_f32_e32 v97, v6, v7
	v_and_b32_e32 v7, 0xffff0000, v32
	v_and_b32_e32 v6, 0xffff0000, v28
	v_pk_mul_f32 v[6:7], v[38:39], v[6:7]
	v_mov_b32_e32 v26, v120
	v_add_f32_e32 v6, v130, v6
	v_add_f32_e32 v96, v6, v7
	v_lshlrev_b32_e32 v7, 16, v33
	v_lshlrev_b32_e32 v6, 16, v29
	v_mov_b32_e32 v27, v40
	v_pk_mul_f32 v[6:7], v[26:27], v[6:7]
	v_mov_b32_e32 v40, v121
	v_add_f32_e32 v6, v131, v6
	v_add_f32_e32 v95, v6, v7
	v_and_b32_e32 v6, 0xffff0000, v29
	ds_read_b128 v[26:29], v89 offset:13184
	v_and_b32_e32 v7, 0xffff0000, v33
	v_pk_mul_f32 v[6:7], v[40:41], v[6:7]
	v_mov_b32_e32 v34, v46
	v_add_f32_e32 v6, v117, v6
	v_add_f32_e32 v90, v6, v7
	v_lshlrev_b32_e32 v7, 16, v22
	v_lshlrev_b32_e32 v6, 16, v18
	ds_read_b128 v[30:33], v89 offset:13216
	s_waitcnt lgkmcnt(1)
	v_mov_b32_e32 v35, v26
	v_pk_mul_f32 v[6:7], v[34:35], v[6:7]
	v_mov_b32_e32 v26, v47
	v_add_f32_e32 v6, v132, v6
	v_add_f32_e32 v91, v6, v7
	v_and_b32_e32 v7, 0xffff0000, v22
	v_and_b32_e32 v6, 0xffff0000, v18
	v_pk_mul_f32 v[6:7], v[26:27], v[6:7]
	v_mov_b32_e32 v26, v48
	v_add_f32_e32 v6, v133, v6
	v_add_f32_e32 v107, v6, v7
	v_lshlrev_b32_e32 v7, 16, v23
	v_lshlrev_b32_e32 v6, 16, v19
	v_mov_b32_e32 v27, v28
	v_pk_mul_f32 v[6:7], v[26:27], v[6:7]
	v_mov_b32_e32 v28, v49
	v_add_f32_e32 v6, v92, v6
	v_add_f32_e32 v108, v6, v7
	v_and_b32_e32 v7, 0xffff0000, v23
	v_and_b32_e32 v6, 0xffff0000, v19
	s_or_b32 s4, s4, s45
	v_pk_mul_f32 v[6:7], v[28:29], v[6:7]
	s_lshl_b32 s4, s4, 3
	s_ashr_i32 s5, s48, 31
	v_add_f32_e32 v6, v54, v6
	s_add_u32 s4, s48, s4
	v_add_f32_e32 v105, v6, v7
	v_lshlrev_b32_e32 v7, 16, v24
	v_lshlrev_b32_e32 v6, 16, v20
	v_mov_b32_e32 v18, v42
	s_waitcnt lgkmcnt(0)
	v_mov_b32_e32 v19, v30
	s_addc_u32 s5, s5, 0
	v_pk_mul_f32 v[6:7], v[18:19], v[6:7]
	s_lshl_b64 s[4:5], s[4:5], 13
	v_add_f32_e32 v6, v51, v6
	s_add_u32 s4, s42, s4
	v_add_f32_e32 v104, v6, v7
	v_and_b32_e32 v7, 0xffff0000, v24
	v_and_b32_e32 v6, 0xffff0000, v20
	v_mov_b32_e32 v30, v43
	s_addc_u32 s5, s43, s5
	s_lshl_b32 s2, s2, 14
	v_pk_mul_f32 v[6:7], v[30:31], v[6:7]
	s_add_u32 s48, s42, s2
	v_add_f32_e32 v6, v52, v6
	v_lshlrev_b32_e32 v0, 4, v86
	s_addc_u32 s49, s43, 0
	v_add_f32_e32 v101, v6, v7
	v_lshlrev_b32_e32 v7, 16, v25
	v_lshlrev_b32_e32 v6, 16, v21
	v_mov_b32_e32 v18, v44
	v_mov_b32_e32 v19, v32
	v_lshl_add_u64 v[38:39], s[48:49], 0, v[0:1]
	s_mov_b32 s2, 0x2501000
	v_pk_mul_f32 v[6:7], v[18:19], v[6:7]
	v_add_co_u32_e32 v166, vcc, s2, v38
	v_add_f32_e32 v6, v50, v6
	s_nop 0
	v_addc_co_u32_e32 v167, vcc, 0, v39, vcc
	v_add_f32_e32 v98, v6, v7
	v_and_b32_e32 v7, 0xffff0000, v25
	v_and_b32_e32 v6, 0xffff0000, v21
	v_mov_b32_e32 v32, v45
	ds_read_b128 v[118:121], v89 offset:13248
	ds_read_b128 v[122:125], v89 offset:13280
	v_cvt_pk_bf16_f32 v126, v115, v114
	v_cvt_pk_bf16_f32 v127, v113, v112
	v_cvt_pk_bf16_f32 v128, v111, v110
	v_cvt_pk_bf16_f32 v129, v109, v100
	global_load_dwordx4 v[34:37], v[166:167], off offset:-4096
	global_load_dwordx4 v[130:133], v[166:167], off
	v_pk_mul_f32 v[6:7], v[32:33], v[6:7]
	v_add_f32_e32 v117, v2, v3
	v_add_f32_e32 v6, v53, v6
	v_add_f32_e32 v92, v6, v7
	v_lshlrev_b32_e32 v3, 16, v8
	v_lshlrev_b32_e32 v2, 16, v4
	v_mov_b32_e32 v6, v14
	v_mov_b32_e32 v7, v74
	v_pk_mul_f32 v[2:3], v[6:7], v[2:3]
	s_mov_b32 s2, 0x2503000
	v_add_f32_e32 v2, v10, v2
	v_add_f32_e32 v174, v2, v3
	v_and_b32_e32 v3, 0xffff0000, v8
	v_and_b32_e32 v2, 0xffff0000, v4
	v_mov_b32_e32 v74, v15
	v_add_co_u32_e32 v168, vcc, s2, v38
	v_pk_mul_f32 v[2:3], v[74:75], v[2:3]
	v_lshlrev_b32_e32 v19, 16, v70
	v_lshlrev_b32_e32 v18, 16, v66
	v_mov_b32_e32 v20, v82
	s_waitcnt lgkmcnt(1)
	v_mov_b32_e32 v21, v118
	v_addc_co_u32_e32 v169, vcc, 0, v39, vcc
	v_add_f32_e32 v2, v11, v2
	v_pk_mul_f32 v[18:19], v[20:21], v[18:19]
	global_load_dwordx4 v[56:59], v[168:169], off offset:-4096
	global_load_dwordx4 v[26:29], v[168:169], off
	v_cvt_pk_bf16_f32 v134, v106, v103
	v_cvt_pk_bf16_f32 v135, v102, v99
	v_cvt_pk_bf16_f32 v136, v97, v96
	v_cvt_pk_bf16_f32 v137, v95, v90
	global_load_dwordx4 v[146:149], v[166:167], off offset:1024
	global_load_dwordx4 v[150:153], v[168:169], off offset:1024
	v_add_f32_e32 v175, v2, v3
	v_lshlrev_b32_e32 v3, 16, v9
	v_lshlrev_b32_e32 v2, 16, v5
	v_mov_b32_e32 v6, v16
	v_mov_b32_e32 v7, v76
	v_add_f32_e32 v18, v94, v18
	v_pk_mul_f32 v[2:3], v[6:7], v[2:3]
	v_add_f32_e32 v94, v18, v19
	v_and_b32_e32 v19, 0xffff0000, v70
	v_and_b32_e32 v18, 0xffff0000, v66
	v_mov_b32_e32 v118, v83
	v_add_f32_e32 v2, v12, v2
	v_pk_mul_f32 v[74:75], v[118:119], v[18:19]
	v_add_f32_e32 v176, v2, v3
	v_and_b32_e32 v3, 0xffff0000, v9
	v_and_b32_e32 v2, 0xffff0000, v5
	v_mov_b32_e32 v76, v17
	v_add_f32_e32 v66, v93, v74
	v_pk_mul_f32 v[2:3], v[76:77], v[2:3]
	v_add_f32_e32 v93, v66, v75
	v_lshlrev_b32_e32 v75, 16, v71
	v_lshlrev_b32_e32 v74, 16, v67
	v_mov_b32_e32 v76, v84
	v_mov_b32_e32 v77, v120
	s_mov_b32 s2, 0x2502000
	v_pk_mul_f32 v[74:75], v[76:77], v[74:75]
	s_mov_b64 s[48:49], 0x2500000
	v_add_co_u32_e32 v172, vcc, s2, v38
	v_add_f32_e32 v66, v116, v74
	v_and_b32_e32 v71, 0xffff0000, v71
	v_and_b32_e32 v70, 0xffff0000, v67
	v_mov_b32_e32 v120, v85
	v_lshl_add_u64 v[170:171], v[38:39], 0, s[48:49]
	v_addc_co_u32_e32 v173, vcc, 0, v39, vcc
	v_add_f32_e32 v83, v66, v75
	v_pk_mul_f32 v[66:67], v[120:121], v[70:71]
	global_load_dwordx4 v[138:141], v[170:171], off offset:1024
	global_load_dwordx4 v[142:145], v[172:173], off offset:1024
	v_cvt_pk_bf16_f32 v154, v91, v107
	v_cvt_pk_bf16_f32 v155, v108, v105
	v_cvt_pk_bf16_f32 v156, v104, v101
	v_cvt_pk_bf16_f32 v157, v98, v92
	v_add_f32_e32 v66, v117, v66
	global_load_dwordx4 v[116:119], v[166:167], off offset:2048
	v_add_f32_e32 v82, v66, v67
	v_lshlrev_b32_e32 v67, 16, v72
	v_lshlrev_b32_e32 v66, 16, v68
	v_mov_b32_e32 v70, v78
	s_waitcnt lgkmcnt(0)
; __device__ __forceinline__ unsigned cvt_pk_bf16(float lo, float hi) { unsigned r; asm volatile("v_cvt_pk_bf16_f32 %0, %1, %2" : "=v"(r) : "v"(lo), "v"(hi)); return r; }
; __device__ __forceinline__ float sigm(float x) { return __builtin_amdgcn_rcpf(1.f + __expf(-x)); }
; #define GAS __attribute__((address_space(1)))
; #define LAS __attribute__((address_space(3)))
; template <int PASS>
; __device__ __forceinline__ void lru_unit(const LruPtrs& args, LAS unsigned char* lds, int chunk, int bl, int g, int ck) {
;     ...
;         for (int ks = 0; ks < 4; ++ks) {
;             v4u bw; bw.x = pg8::cvt_pk_bf16(xc[2 * ks][0], xc[2 * ks][1]); bw.y = pg8::cvt_pk_bf16(xc[2 * ks][2], xc[2 * ks][3]); bw.z = pg8::cvt_pk_bf16(xc[2 * ks + 1][0], xc[2 * ks + 1][1]); bw.w = pg8::cvt_pk_bf16(xc[2 * ks + 1][2], xc[2 * ks + 1][3]);
;             const bf16x8 bfr = __builtin_bit_cast(bf16x8, bw);
; #pragma unroll
;             for (int rb = 0; rb < 2; ++rb) {
;                 const bf16x8 wr_ = __builtin_bit_cast(bf16x8, *(const GAS v4u*)(wrf + ((0 * 2 + rb) * 4 + ks) * 512));
;                 const bf16x8 wi_ = __builtin_bit_cast(bf16x8, *(const GAS v4u*)(wrf + ((1 * 2 + rb) * 4 + ks) * 512));
;                 ar[rb] = __builtin_amdgcn_mfma_f32_32x32x16_bf16(wr_, bfr, ar[rb], 0, 0, 0);
;                 ai_[rb] = __builtin_amdgcn_mfma_f32_32x32x16_bf16(wi_, bfr, ai_[rb], 0, 0, 0);
;             }
;         }
; #pragma unroll
;         for (int q = 0; q < 8; ++q) {
;             const f32x4 br = *(const LAS f32x4*)(PRM + 5 * 64 + 8 * q + 4 * hi), bi = *(const LAS f32x4*)(PRM + 6 * 64 + 8 * q + 4 * hi), cf = *(const LAS f32x4*)(PRM + 7 * 64 + 8 * q + 4 * hi);
; #pragma unroll
;             for (int p = 0; p < 4; ++p) { const int rb = q >> 2, r = (q & 3) * 4 + p;
;                 const float rr = pg8::sigm(ar[rb][r] + br[p]), ii = pg8::sigm(ai_[rb][r] + bi[p]);
;                 const float a0 = __builtin_amdgcn_exp2f(cf[p] * rr);
;                 av[q][p] = a0; uv[q][p] = __builtin_amdgcn_sqrtf(fmaxf(1.f - a0 * a0, 0.f)) * (ii * xc[q][p]); }
	v_mov_b32_e32 v71, v122
	v_pk_mul_f32 v[66:67], v[70:71], v[66:67]
	v_mov_b32_e32 v122, v79
	v_add_f32_e32 v66, v174, v66
	v_add_f32_e32 v77, v66, v67
	v_and_b32_e32 v67, 0xffff0000, v72
	v_and_b32_e32 v66, 0xffff0000, v68
	v_pk_mul_f32 v[66:67], v[122:123], v[66:67]
	global_load_dwordx4 v[120:123], v[168:169], off offset:2048
	global_load_dwordx4 v[158:161], v[170:171], off offset:2048
	global_load_dwordx4 v[162:165], v[172:173], off offset:2048
	v_add_f32_e32 v66, v175, v66
	v_add_f32_e32 v76, v66, v67
	v_lshlrev_b32_e32 v67, 16, v73
	v_lshlrev_b32_e32 v66, 16, v69
	v_mov_b32_e32 v70, v80
	v_mov_b32_e32 v71, v124
	v_pk_mul_f32 v[66:67], v[70:71], v[66:67]
	v_add_f32_e32 v2, v13, v2
	v_add_f32_e32 v66, v176, v66
	v_add_f32_e32 v74, v66, v67
	v_and_b32_e32 v67, 0xffff0000, v73
	v_and_b32_e32 v66, 0xffff0000, v69
	v_mov_b32_e32 v124, v81
	v_add_f32_e32 v177, v2, v3
	s_waitcnt vmcnt(10)
	v_mfma_f32_32x32x16_bf16 v[2:17], v[130:133], v[126:129], 0
	v_mul_f32_e64 v66, v124, v66
	v_mul_f32_e64 v67, v125, v67
	v_cvt_pk_bf16_f32 v78, v94, v93
	v_cvt_pk_bf16_f32 v79, v83, v82
	v_cvt_pk_bf16_f32 v80, v77, v76
	s_mov_b32 s2, 0x29c01000
	v_add_f32_e32 v66, v177, v66
	v_add_f32_e32 v75, v66, v67
	v_cvt_pk_bf16_f32 v81, v74, v75
	global_load_dwordx4 v[66:69], v[170:171], off offset:3072
	global_load_dwordx4 v[70:73], v[172:173], off offset:3072
	s_waitcnt vmcnt(9)
	v_mfma_f32_32x32x16_bf16 v[2:17], v[146:149], v[134:137], v[2:17]
	s_waitcnt vmcnt(5)
	v_mfma_f32_32x32x16_bf16 v[2:17], v[116:119], v[154:157], v[2:17]
	global_load_dwordx4 v[116:119], v[166:167], off offset:3072
	v_mfma_f32_32x32x16_bf16 v[18:33], v[26:29], v[126:129], 0
	v_mfma_f32_32x32x16_bf16 v[34:49], v[34:37], v[126:129], 0
	v_mfma_f32_32x32x16_bf16 v[18:33], v[150:153], v[134:137], v[18:33]
	v_mfma_f32_32x32x16_bf16 v[50:65], v[56:59], v[126:129], 0
	ds_read_b128 v[124:127], v89 offset:13568
	ds_read_b128 v[128:131], v89 offset:13600
	v_mfma_f32_32x32x16_bf16 v[34:49], v[138:141], v[134:137], v[34:49]
	s_waitcnt vmcnt(5)
	v_mfma_f32_32x32x16_bf16 v[18:33], v[120:123], v[154:157], v[18:33]
	global_load_dwordx4 v[120:123], v[168:169], off offset:3072
	v_mfma_f32_32x32x16_bf16 v[50:65], v[142:145], v[134:137], v[50:65]
	s_waitcnt vmcnt(5)
	v_mfma_f32_32x32x16_bf16 v[34:49], v[158:161], v[154:157], v[34:49]
	s_waitcnt vmcnt(4)
	v_mfma_f32_32x32x16_bf16 v[50:65], v[162:165], v[154:157], v[50:65]
	s_waitcnt vmcnt(3)
	v_mfma_f32_32x32x16_bf16 v[34:49], v[66:69], v[78:81], v[34:49]
	s_waitcnt vmcnt(2)
	v_mfma_f32_32x32x16_bf16 v[50:65], v[70:73], v[78:81], v[50:65]
	v_lshl_add_u64 v[72:73], s[4:5], 0, v[0:1]
	s_waitcnt lgkmcnt(1)
	s_nop 7
	v_add_f32_e32 v0, v34, v124
	v_mul_f32_e32 v0, 0xbfb8aa3b, v0
	v_exp_f32_e32 v0, v0
	v_add_f32_e32 v35, v35, v125
	v_mul_f32_e32 v35, 0xbfb8aa3b, v35
	v_exp_f32_e32 v35, v35
	s_waitcnt vmcnt(1)
	v_mfma_f32_32x32x16_bf16 v[2:17], v[116:119], v[78:81], v[2:17]
	ds_read_b128 v[116:119], v89 offset:13824
	ds_read_b128 v[132:135], v89 offset:14080
	v_add_f32_e32 v0, 1.0, v0
	v_rcp_f32_e32 v0, v0
	v_add_f32_e32 v35, 1.0, v35
	s_waitcnt lgkmcnt(1)
	v_add_f32_e32 v34, v50, v116
	v_mul_f32_e32 v34, 0xbfb8aa3b, v34
	s_waitcnt lgkmcnt(0)
	v_mul_f32_e32 v0, v132, v0
	v_exp_f32_e32 v34, v34
	v_exp_f32_e32 v66, v0
	v_rcp_f32_e32 v35, v35
	v_add_f32_e32 v50, v51, v117
	v_add_f32_e32 v0, 1.0, v34
	v_fma_f32 v34, -v66, v66, 1.0
	v_rcp_f32_e32 v0, v0
	v_max_f32_e32 v34, 0, v34
	v_mul_f32_e32 v50, 0xbfb8aa3b, v50
	v_mul_f32_e32 v35, v133, v35
	v_sqrt_f32_e32 v34, v34
	v_exp_f32_e32 v50, v50
	v_exp_f32_e32 v68, v35
	v_mul_f32_e32 v0, v115, v0
	v_mul_f32_e32 v67, v0, v34
	v_add_f32_e32 v0, 1.0, v50
	v_fma_f32 v34, -v68, v68, 1.0
	v_add_f32_e32 v35, v36, v126
	v_rcp_f32_e32 v0, v0
	v_mul_f32_e32 v35, 0xbfb8aa3b, v35
	v_max_f32_e32 v34, 0, v34
	v_exp_f32_e32 v35, v35
	v_sqrt_f32_e32 v36, v34
	v_mul_f32_e32 v0, v114, v0
	v_add_f32_e32 v38, v38, v128
	v_add_f32_e32 v34, 1.0, v35
	v_mul_f32_e32 v69, v0, v36
	v_add_f32_e32 v36, v37, v127
	v_rcp_f32_e32 v34, v34
	v_mul_f32_e32 v36, 0xbfb8aa3b, v36
	v_exp_f32_e32 v36, v36
	v_add_f32_e32 v35, v52, v118
	v_mul_f32_e32 v35, 0xbfb8aa3b, v35
	v_mul_f32_e32 v34, v134, v34
	v_exp_f32_e32 v35, v35
	v_exp_f32_e32 v34, v34
	v_add_f32_e32 v36, 1.0, v36
	v_rcp_f32_e32 v36, v36
	v_mul_f32_e32 v38, 0xbfb8aa3b, v38
	v_exp_f32_e32 v38, v38
	v_add_f32_e32 v0, 1.0, v35
	v_fma_f32 v35, -v34, v34, 1.0
	v_add_f32_e32 v37, v53, v119
	ds_read_b128 v[136:139], v89 offset:13856
	ds_read_b128 v[140:143], v89 offset:14112
	v_rcp_f32_e32 v0, v0
	v_max_f32_e32 v35, 0, v35
	v_mul_f32_e32 v37, 0xbfb8aa3b, v37
	v_mul_f32_e32 v36, v135, v36
	v_sqrt_f32_e32 v35, v35
	v_exp_f32_e32 v37, v37
	v_exp_f32_e32 v36, v36
	v_add_f32_e32 v38, 1.0, v38
	v_add_f32_e32 v39, v39, v129
	v_rcp_f32_e32 v38, v38
	v_mul_f32_e32 v39, 0xbfb8aa3b, v39
	v_exp_f32_e32 v39, v39
	v_mul_f32_e32 v0, v113, v0
	v_mul_f32_e32 v35, v0, v35
	v_add_f32_e32 v0, 1.0, v37
	v_fma_f32 v37, -v36, v36, 1.0
	s_waitcnt lgkmcnt(1)
	v_add_f32_e32 v50, v54, v136
	v_rcp_f32_e32 v0, v0
	v_max_f32_e32 v37, 0, v37
	v_mul_f32_e32 v50, 0xbfb8aa3b, v50
	s_waitcnt lgkmcnt(0)
	v_mul_f32_e32 v38, v140, v38
	v_sqrt_f32_e32 v37, v37
	v_exp_f32_e32 v51, v50
	v_exp_f32_e32 v50, v38
	v_add_f32_e32 v39, 1.0, v39
	v_rcp_f32_e32 v39, v39
	v_mul_f32_e32 v0, v112, v0
	v_mul_f32_e32 v37, v0, v37
	v_add_f32_e32 v0, 1.0, v51
	v_fma_f32 v38, -v50, v50, 1.0
	v_rcp_f32_e32 v0, v0
	v_max_f32_e32 v38, 0, v38
	v_add_f32_e32 v51, v55, v137
	v_mul_f32_e32 v39, v141, v39
	v_sqrt_f32_e32 v38, v38
	v_mul_f32_e32 v51, 0xbfb8aa3b, v51
	v_exp_f32_e32 v52, v39
	v_add_f32_e32 v39, v40, v130
	v_exp_f32_e32 v53, v51
	v_mul_f32_e32 v39, 0xbfb8aa3b, v39
	v_exp_f32_e32 v39, v39
	v_mul_f32_e32 v0, v111, v0
	v_mul_f32_e32 v51, v0, v38
	v_fma_f32 v38, -v52, v52, 1.0
	v_add_f32_e32 v0, 1.0, v53
	v_max_f32_e32 v38, 0, v38
	v_rcp_f32_e32 v0, v0
	v_sqrt_f32_e32 v40, v38
	v_add_f32_e32 v38, 1.0, v39
	v_rcp_f32_e32 v38, v38
	v_mul_f32_e32 v0, v110, v0
	v_add_f32_e32 v39, v56, v138
	v_mul_f32_e32 v39, 0xbfb8aa3b, v39
	v_mul_f32_e32 v38, v142, v38
	v_mul_f32_e32 v53, v0, v40
	v_add_f32_e32 v40, v41, v131
	s_waitcnt vmcnt(0)
; __device__ __forceinline__ float sigm(float x) { return __builtin_amdgcn_rcpf(1.f + __expf(-x)); }
; #define LAS __attribute__((address_space(3)))
; template <int PASS>
; __device__ __forceinline__ void lru_unit(const LruPtrs& args, LAS unsigned char* lds, int chunk, int bl, int g, int ck) {
;     ...
; #pragma unroll
;         for (int q = 0; q < 8; ++q) {
;             const f32x4 br = *(const LAS f32x4*)(PRM + 5 * 64 + 8 * q + 4 * hi), bi = *(const LAS f32x4*)(PRM + 6 * 64 + 8 * q + 4 * hi), cf = *(const LAS f32x4*)(PRM + 7 * 64 + 8 * q + 4 * hi);
; #pragma unroll
;             for (int p = 0; p < 4; ++p) { const int rb = q >> 2, r = (q & 3) * 4 + p;
;                 const float rr = pg8::sigm(ar[rb][r] + br[p]), ii = pg8::sigm(ai_[rb][r] + bi[p]);
;                 const float a0 = __builtin_amdgcn_exp2f(cf[p] * rr);
;                 av[q][p] = a0; uv[q][p] = __builtin_amdgcn_sqrtf(fmaxf(1.f - a0 * a0, 0.f)) * (ii * xc[q][p]); }
	v_mfma_f32_32x32x16_bf16 v[18:33], v[120:123], v[78:81], v[18:33]
	v_exp_f32_e32 v39, v39
	v_exp_f32_e32 v38, v38
	v_mul_f32_e32 v40, 0xbfb8aa3b, v40
	ds_read_b128 v[78:81], v89 offset:13632
	ds_read_b128 v[110:113], v89 offset:13664
	v_exp_f32_e32 v40, v40
	v_add_f32_e32 v0, 1.0, v39
	v_fma_f32 v39, -v38, v38, 1.0
	v_rcp_f32_e32 v0, v0
	v_max_f32_e32 v39, 0, v39
	v_add_f32_e32 v40, 1.0, v40
	s_waitcnt lgkmcnt(1)
	v_add_f32_e32 v42, v42, v78
	v_sqrt_f32_e32 v39, v39
	v_rcp_f32_e32 v40, v40
	v_mul_f32_e32 v42, 0xbfb8aa3b, v42
	v_exp_f32_e32 v42, v42
	v_mul_f32_e32 v0, v109, v0
	v_add_f32_e32 v41, v57, v139
	v_mul_f32_e32 v41, 0xbfb8aa3b, v41
	v_mul_f32_e32 v39, v0, v39
	v_mul_f32_e32 v0, v143, v40
	v_exp_f32_e32 v41, v41
	v_exp_f32_e32 v40, v0
	ds_read_b128 v[114:117], v89 offset:13888
	ds_read_b128 v[118:121], v89 offset:14144
	v_add_f32_e32 v42, 1.0, v42
	v_add_f32_e32 v43, v43, v79
	v_rcp_f32_e32 v42, v42
	v_mul_f32_e32 v43, 0xbfb8aa3b, v43
	v_exp_f32_e32 v43, v43
	v_add_f32_e32 v0, 1.0, v41
	v_fma_f32 v41, -v40, v40, 1.0
	s_waitcnt lgkmcnt(1)
	v_add_f32_e32 v54, v58, v114
	v_rcp_f32_e32 v0, v0
	v_max_f32_e32 v41, 0, v41
	v_mul_f32_e32 v54, 0xbfb8aa3b, v54
	s_waitcnt lgkmcnt(0)
	v_mul_f32_e32 v42, v118, v42
	v_sqrt_f32_e32 v41, v41
	v_exp_f32_e32 v55, v54
	v_exp_f32_e32 v54, v42
	v_add_f32_e32 v43, 1.0, v43
	v_rcp_f32_e32 v43, v43
	v_mul_f32_e32 v0, v100, v0
	v_mul_f32_e32 v41, v0, v41
	v_add_f32_e32 v0, 1.0, v55
	v_fma_f32 v42, -v54, v54, 1.0
	v_add_f32_e32 v55, v59, v115
	v_rcp_f32_e32 v0, v0
	v_max_f32_e32 v42, 0, v42
	v_mul_f32_e32 v55, 0xbfb8aa3b, v55
	v_mul_f32_e32 v43, v119, v43
	v_sqrt_f32_e32 v42, v42
	v_exp_f32_e32 v57, v55
	v_exp_f32_e32 v56, v43
	v_mul_f32_e32 v0, v106, v0
	v_mul_f32_e32 v55, v0, v42
	v_add_f32_e32 v0, 1.0, v57
	v_fma_f32 v42, -v56, v56, 1.0
	v_add_f32_e32 v43, v44, v80
	v_rcp_f32_e32 v0, v0
	v_mul_f32_e32 v43, 0xbfb8aa3b, v43
	v_max_f32_e32 v42, 0, v42
	v_exp_f32_e32 v43, v43
	v_sqrt_f32_e32 v44, v42
	v_mul_f32_e32 v0, v103, v0
	v_add_f32_e32 v46, v46, v110
	v_add_f32_e32 v42, 1.0, v43
	v_mul_f32_e32 v57, v0, v44
	v_add_f32_e32 v44, v45, v81
	v_rcp_f32_e32 v42, v42
	v_mul_f32_e32 v44, 0xbfb8aa3b, v44
	v_exp_f32_e32 v44, v44
	v_add_f32_e32 v43, v60, v116
	v_mul_f32_e32 v43, 0xbfb8aa3b, v43
	v_mul_f32_e32 v42, v120, v42
	v_exp_f32_e32 v43, v43
	v_exp_f32_e32 v42, v42
	v_add_f32_e32 v44, 1.0, v44
	v_rcp_f32_e32 v44, v44
	v_mul_f32_e32 v46, 0xbfb8aa3b, v46
	v_exp_f32_e32 v46, v46
	v_add_f32_e32 v0, 1.0, v43
	v_fma_f32 v43, -v42, v42, 1.0
	v_add_f32_e32 v45, v61, v117
	ds_read_b128 v[122:125], v89 offset:13920
	ds_read_b128 v[126:129], v89 offset:14176
	v_rcp_f32_e32 v0, v0
	v_max_f32_e32 v43, 0, v43
	v_mul_f32_e32 v45, 0xbfb8aa3b, v45
	v_mul_f32_e32 v44, v121, v44
	v_sqrt_f32_e32 v43, v43
	v_exp_f32_e32 v45, v45
	v_exp_f32_e32 v44, v44
	v_add_f32_e32 v46, 1.0, v46
	v_add_f32_e32 v47, v47, v111
	v_rcp_f32_e32 v46, v46
	v_mul_f32_e32 v47, 0xbfb8aa3b, v47
	v_exp_f32_e32 v47, v47
	v_mul_f32_e32 v0, v102, v0
	v_mul_f32_e32 v43, v0, v43
	v_add_f32_e32 v0, 1.0, v45
	v_fma_f32 v45, -v44, v44, 1.0
	s_waitcnt lgkmcnt(1)
	v_add_f32_e32 v58, v62, v122
	v_rcp_f32_e32 v0, v0
	v_max_f32_e32 v45, 0, v45
	v_mul_f32_e32 v58, 0xbfb8aa3b, v58
	s_waitcnt lgkmcnt(0)
	v_mul_f32_e32 v46, v126, v46
	v_sqrt_f32_e32 v45, v45
	v_exp_f32_e32 v59, v58
	v_exp_f32_e32 v58, v46
	v_add_f32_e32 v47, 1.0, v47
	v_rcp_f32_e32 v47, v47
	v_mul_f32_e32 v0, v99, v0
	v_mul_f32_e32 v45, v0, v45
	v_add_f32_e32 v0, 1.0, v59
	v_fma_f32 v46, -v58, v58, 1.0
	v_rcp_f32_e32 v0, v0
	v_max_f32_e32 v46, 0, v46
	v_add_f32_e32 v59, v63, v123
	v_mul_f32_e32 v47, v127, v47
	v_sqrt_f32_e32 v46, v46
	v_mul_f32_e32 v59, 0xbfb8aa3b, v59
	v_exp_f32_e32 v60, v47
	v_add_f32_e32 v47, v48, v112
	v_exp_f32_e32 v61, v59
	v_mul_f32_e32 v47, 0xbfb8aa3b, v47
	v_exp_f32_e32 v47, v47
	v_mul_f32_e32 v0, v97, v0
	v_mul_f32_e32 v59, v0, v46
	v_fma_f32 v46, -v60, v60, 1.0
	v_add_f32_e32 v0, 1.0, v61
	v_max_f32_e32 v46, 0, v46
	v_rcp_f32_e32 v0, v0
	v_sqrt_f32_e32 v48, v46
	v_add_f32_e32 v46, 1.0, v47
	v_rcp_f32_e32 v46, v46
	v_mul_f32_e32 v0, v96, v0
	v_add_f32_e32 v47, v64, v124
	v_mul_f32_e32 v47, 0xbfb8aa3b, v47
	v_mul_f32_e32 v46, v128, v46
	v_mul_f32_e32 v61, v0, v48
	v_add_f32_e32 v48, v49, v113
	v_exp_f32_e32 v47, v47
	v_exp_f32_e32 v46, v46
	v_mul_f32_e32 v48, 0xbfb8aa3b, v48
	ds_read_b128 v[78:81], v89 offset:13696
	ds_read_b128 v[110:113], v89 offset:13728
	v_exp_f32_e32 v48, v48
	v_add_f32_e32 v0, 1.0, v47
	v_fma_f32 v47, -v46, v46, 1.0
	v_rcp_f32_e32 v0, v0
	v_max_f32_e32 v47, 0, v47
	v_add_f32_e32 v48, 1.0, v48
	s_waitcnt lgkmcnt(1)
	v_add_f32_e32 v2, v2, v78
	v_sqrt_f32_e32 v47, v47
	v_rcp_f32_e32 v48, v48
	v_mul_f32_e32 v2, 0xbfb8aa3b, v2
	v_exp_f32_e32 v2, v2
	v_mul_f32_e32 v0, v95, v0
	v_add_f32_e32 v49, v65, v125
	v_mul_f32_e32 v49, 0xbfb8aa3b, v49
	v_mul_f32_e32 v47, v0, v47
	v_mul_f32_e32 v0, v129, v48
	v_exp_f32_e32 v49, v49
	v_exp_f32_e32 v48, v0
	ds_read_b128 v[114:117], v89 offset:13952
	ds_read_b128 v[118:121], v89 offset:14208
	v_add_f32_e32 v2, 1.0, v2
	v_add_f32_e32 v3, v3, v79
	v_rcp_f32_e32 v2, v2
	v_mul_f32_e32 v3, 0xbfb8aa3b, v3
	v_exp_f32_e32 v3, v3
	v_add_f32_e32 v0, 1.0, v49
	v_fma_f32 v49, -v48, v48, 1.0
	s_waitcnt lgkmcnt(1)
	v_add_f32_e32 v18, v18, v114
	v_rcp_f32_e32 v0, v0
	v_max_f32_e32 v49, 0, v49
	v_mul_f32_e32 v18, 0xbfb8aa3b, v18
	s_waitcnt lgkmcnt(0)
; __device__ __forceinline__ float sigm(float x) { return __builtin_amdgcn_rcpf(1.f + __expf(-x)); }
; #define LAS __attribute__((address_space(3)))
; template <int PASS>
; __device__ __forceinline__ void lru_unit(const LruPtrs& args, LAS unsigned char* lds, int chunk, int bl, int g, int ck) {
;     ...
; #pragma unroll
;         for (int q = 0; q < 8; ++q) {
;             const f32x4 br = *(const LAS f32x4*)(PRM + 5 * 64 + 8 * q + 4 * hi), bi = *(const LAS f32x4*)(PRM + 6 * 64 + 8 * q + 4 * hi), cf = *(const LAS f32x4*)(PRM + 7 * 64 + 8 * q + 4 * hi);
; #pragma unroll
;             for (int p = 0; p < 4; ++p) { const int rb = q >> 2, r = (q & 3) * 4 + p;
;                 const float rr = pg8::sigm(ar[rb][r] + br[p]), ii = pg8::sigm(ai_[rb][r] + bi[p]);
;                 const float a0 = __builtin_amdgcn_exp2f(cf[p] * rr);
;                 av[q][p] = a0; uv[q][p] = __builtin_amdgcn_sqrtf(fmaxf(1.f - a0 * a0, 0.f)) * (ii * xc[q][p]); }
	v_mul_f32_e32 v2, v118, v2
	v_sqrt_f32_e32 v49, v49
	v_exp_f32_e32 v18, v18
	v_exp_f32_e32 v62, v2
	v_add_f32_e32 v3, 1.0, v3
	v_rcp_f32_e32 v3, v3
	v_mul_f32_e32 v0, v90, v0
	v_mul_f32_e32 v49, v0, v49
	v_add_f32_e32 v0, 1.0, v18
	v_fma_f32 v2, -v62, v62, 1.0
	v_add_f32_e32 v18, v19, v115
	v_rcp_f32_e32 v0, v0
	v_max_f32_e32 v2, 0, v2
	v_mul_f32_e32 v18, 0xbfb8aa3b, v18
	v_mul_f32_e32 v3, v119, v3
	v_sqrt_f32_e32 v2, v2
	v_exp_f32_e32 v18, v18
	v_exp_f32_e32 v64, v3
	v_mul_f32_e32 v0, v91, v0
	v_mul_f32_e32 v63, v0, v2
	v_add_f32_e32 v0, 1.0, v18
	v_fma_f32 v2, -v64, v64, 1.0
	v_add_f32_e32 v3, v4, v80
	v_rcp_f32_e32 v0, v0
	v_mul_f32_e32 v3, 0xbfb8aa3b, v3
	v_max_f32_e32 v2, 0, v2
	v_exp_f32_e32 v3, v3
	v_sqrt_f32_e32 v4, v2
	v_mul_f32_e32 v0, v107, v0
	v_add_f32_e32 v6, v6, v110
	v_add_f32_e32 v2, 1.0, v3
	v_mul_f32_e32 v65, v0, v4
	v_add_f32_e32 v4, v5, v81
	v_rcp_f32_e32 v2, v2
	v_mul_f32_e32 v4, 0xbfb8aa3b, v4
	v_exp_f32_e32 v4, v4
	v_add_f32_e32 v3, v20, v116
	v_mul_f32_e32 v3, 0xbfb8aa3b, v3
	v_mul_f32_e32 v2, v120, v2
	v_exp_f32_e32 v3, v3
	v_exp_f32_e32 v2, v2
	v_add_f32_e32 v4, 1.0, v4
	v_rcp_f32_e32 v4, v4
	v_mul_f32_e32 v6, 0xbfb8aa3b, v6
	v_exp_f32_e32 v6, v6
	v_add_f32_e32 v0, 1.0, v3
	v_fma_f32 v3, -v2, v2, 1.0
	v_add_f32_e32 v5, v21, v117
	ds_read_b128 v[122:125], v89 offset:13984
	ds_read_b128 v[126:129], v89 offset:14240
	v_rcp_f32_e32 v0, v0
	v_max_f32_e32 v3, 0, v3
	v_mul_f32_e32 v5, 0xbfb8aa3b, v5
	v_mul_f32_e32 v4, v121, v4
	v_sqrt_f32_e32 v3, v3
	v_exp_f32_e32 v5, v5
	v_exp_f32_e32 v4, v4
	v_add_f32_e32 v6, 1.0, v6
	v_add_f32_e32 v7, v7, v111
	v_rcp_f32_e32 v6, v6
	v_mul_f32_e32 v7, 0xbfb8aa3b, v7
	v_exp_f32_e32 v7, v7
	v_mul_f32_e32 v0, v108, v0
	v_mul_f32_e32 v3, v0, v3
	v_add_f32_e32 v0, 1.0, v5
	v_fma_f32 v5, -v4, v4, 1.0
	s_waitcnt lgkmcnt(1)
	v_add_f32_e32 v18, v22, v122
	v_rcp_f32_e32 v0, v0
	v_max_f32_e32 v5, 0, v5
	v_mul_f32_e32 v18, 0xbfb8aa3b, v18
	s_waitcnt lgkmcnt(0)
	v_mul_f32_e32 v6, v126, v6
	v_sqrt_f32_e32 v5, v5
	v_exp_f32_e32 v19, v18
	v_exp_f32_e32 v18, v6
	v_add_f32_e32 v7, 1.0, v7
	v_rcp_f32_e32 v7, v7
	v_mul_f32_e32 v0, v105, v0
	v_mul_f32_e32 v5, v0, v5
	v_add_f32_e32 v0, 1.0, v19
	v_fma_f32 v6, -v18, v18, 1.0
	v_rcp_f32_e32 v0, v0
	v_max_f32_e32 v6, 0, v6
	v_add_f32_e32 v19, v23, v123
	v_mul_f32_e32 v7, v127, v7
	v_sqrt_f32_e32 v6, v6
	v_mul_f32_e32 v19, 0xbfb8aa3b, v19
	v_exp_f32_e32 v20, v7
	v_add_f32_e32 v7, v8, v112
	v_exp_f32_e32 v21, v19
	v_mul_f32_e32 v7, 0xbfb8aa3b, v7
	v_exp_f32_e32 v7, v7
	v_mul_f32_e32 v0, v104, v0
	v_mul_f32_e32 v19, v0, v6
	v_fma_f32 v6, -v20, v20, 1.0
	v_add_f32_e32 v0, 1.0, v21
	v_max_f32_e32 v6, 0, v6
	v_rcp_f32_e32 v0, v0
	v_sqrt_f32_e32 v8, v6
	v_add_f32_e32 v6, 1.0, v7
	v_add_f32_e32 v7, v24, v124
	v_rcp_f32_e32 v6, v6
	v_mul_f32_e32 v7, 0xbfb8aa3b, v7
	v_exp_f32_e32 v7, v7
	v_mul_f32_e32 v0, v101, v0
	v_mul_f32_e32 v6, v128, v6
	v_mul_f32_e32 v21, v0, v8
	v_add_f32_e32 v8, v9, v113
	v_exp_f32_e32 v6, v6
	v_add_f32_e32 v0, 1.0, v7
	v_mul_f32_e32 v8, 0xbfb8aa3b, v8
	ds_read_b128 v[78:81], v89 offset:13760
	v_rcp_f32_e32 v0, v0
	v_exp_f32_e32 v8, v8
	v_fma_f32 v7, -v6, v6, 1.0
	v_max_f32_e32 v7, 0, v7
	v_mul_f32_e32 v0, v98, v0
	v_add_f32_e32 v8, 1.0, v8
	ds_read_b128 v[96:99], v89 offset:13792
	s_waitcnt lgkmcnt(1)
	v_add_f32_e32 v10, v10, v78
	v_sqrt_f32_e32 v7, v7
	v_rcp_f32_e32 v8, v8
	v_mul_f32_e32 v10, 0xbfb8aa3b, v10
	v_exp_f32_e32 v10, v10
	v_add_f32_e32 v9, v25, v125
	v_mul_f32_e32 v9, 0xbfb8aa3b, v9
	v_mul_f32_e32 v7, v0, v7
	v_mul_f32_e32 v0, v129, v8
	v_exp_f32_e32 v9, v9
	v_exp_f32_e32 v8, v0
	ds_read_b128 v[100:103], v89 offset:14016
	ds_read_b128 v[104:107], v89 offset:14272
	v_add_f32_e32 v10, 1.0, v10
	v_add_f32_e32 v11, v11, v79
	v_rcp_f32_e32 v10, v10
	v_mul_f32_e32 v11, 0xbfb8aa3b, v11
	v_exp_f32_e32 v11, v11
	v_add_f32_e32 v0, 1.0, v9
	v_fma_f32 v9, -v8, v8, 1.0
	s_waitcnt lgkmcnt(1)
	v_add_f32_e32 v22, v26, v100
	v_rcp_f32_e32 v0, v0
	v_max_f32_e32 v9, 0, v9
	v_mul_f32_e32 v22, 0xbfb8aa3b, v22
	s_waitcnt lgkmcnt(0)
	v_mul_f32_e32 v10, v104, v10
	v_sqrt_f32_e32 v9, v9
	v_exp_f32_e32 v23, v22
	v_exp_f32_e32 v22, v10
	v_add_f32_e32 v11, 1.0, v11
	v_rcp_f32_e32 v11, v11
	v_mul_f32_e32 v0, v92, v0
	v_mul_f32_e32 v9, v0, v9
	v_add_f32_e32 v0, 1.0, v23
	v_fma_f32 v10, -v22, v22, 1.0
	v_add_f32_e32 v23, v27, v101
	v_rcp_f32_e32 v0, v0
	v_max_f32_e32 v10, 0, v10
	v_mul_f32_e32 v23, 0xbfb8aa3b, v23
	v_mul_f32_e32 v11, v105, v11
	v_sqrt_f32_e32 v10, v10
	v_exp_f32_e32 v25, v23
	v_exp_f32_e32 v24, v11
	v_mul_f32_e32 v0, v94, v0
	v_mul_f32_e32 v23, v0, v10
	v_add_f32_e32 v0, 1.0, v25
	v_fma_f32 v10, -v24, v24, 1.0
	v_add_f32_e32 v11, v12, v80
	v_rcp_f32_e32 v0, v0
	v_mul_f32_e32 v11, 0xbfb8aa3b, v11
	v_max_f32_e32 v10, 0, v10
	v_exp_f32_e32 v11, v11
	v_sqrt_f32_e32 v12, v10
	v_mul_f32_e32 v0, v93, v0
	v_add_f32_e32 v14, v14, v96
	v_add_f32_e32 v10, 1.0, v11
	v_mul_f32_e32 v25, v0, v12
	v_add_f32_e32 v12, v13, v81
	v_rcp_f32_e32 v10, v10
	v_mul_f32_e32 v12, 0xbfb8aa3b, v12
	v_exp_f32_e32 v12, v12
	v_add_f32_e32 v11, v28, v102
	v_mul_f32_e32 v11, 0xbfb8aa3b, v11
	v_mul_f32_e32 v10, v106, v10
	v_exp_f32_e32 v11, v11
	v_exp_f32_e32 v10, v10
	v_add_f32_e32 v12, 1.0, v12
	v_rcp_f32_e32 v12, v12
	v_mul_f32_e32 v14, 0xbfb8aa3b, v14
	v_exp_f32_e32 v14, v14
	v_add_f32_e32 v0, 1.0, v11
	v_fma_f32 v11, -v10, v10, 1.0
	v_add_f32_e32 v13, v29, v103
	ds_read_b128 v[108:111], v89 offset:14048
	ds_read_b128 v[112:115], v89 offset:14304
	v_rcp_f32_e32 v0, v0
	v_max_f32_e32 v11, 0, v11
	v_mul_f32_e32 v13, 0xbfb8aa3b, v13
	v_mul_f32_e32 v12, v107, v12
	v_sqrt_f32_e32 v11, v11
	v_exp_f32_e32 v13, v13
	v_exp_f32_e32 v12, v12
	v_add_f32_e32 v14, 1.0, v14
	v_rcp_f32_e32 v14, v14
	v_mul_f32_e32 v0, v83, v0
	v_mul_f32_e32 v11, v0, v11
	v_add_f32_e32 v0, 1.0, v13
	v_fma_f32 v13, -v12, v12, 1.0
	s_waitcnt lgkmcnt(1)
; #define GAS __attribute__((address_space(1)))
; template <int PASS>
; __device__ __forceinline__ void lru_unit(const LruPtrs& args, LAS unsigned char* lds, int chunk, int bl, int g, int ck) {
;     ...
; #pragma unroll
;         for (int q = 0; q < 8; ++q) {
;             const f32x4 br = *(const LAS f32x4*)(PRM + 5 * 64 + 8 * q + 4 * hi), bi = *(const LAS f32x4*)(PRM + 6 * 64 + 8 * q + 4 * hi), cf = *(const LAS f32x4*)(PRM + 7 * 64 + 8 * q + 4 * hi);
; #pragma unroll
;             for (int p = 0; p < 4; ++p) { const int rb = q >> 2, r = (q & 3) * 4 + p;
;                 const float rr = pg8::sigm(ar[rb][r] + br[p]), ii = pg8::sigm(ai_[rb][r] + bi[p]);
;                 const float a0 = __builtin_amdgcn_exp2f(cf[p] * rr);
;                 av[q][p] = a0; uv[q][p] = __builtin_amdgcn_sqrtf(fmaxf(1.f - a0 * a0, 0.f)) * (ii * xc[q][p]); }
;         }
;     } else {
; #pragma unroll
;         for (int i = 0; i < 4; ++i) { const int idx = lane + 64 * i, r = idx >> 3, ch = idx & 7;
;             gtile[i] = *(const GAS v4u*)(Z + ((size_t)bl * T + ck * 256 + w * 32 + r) * LDZ + ZC_GA + g * 64 + ch * 8); }
; #pragma unroll
;         for (int q = 0; q < 8; ++q) { const v4u st = stash[q * 64];
; #pragma unroll
;             for (int p = 0; p < 4; ++p) { av[q][p] = pg8::bf_lo(st[p]); uv[q][p] = pg8::bf_hi(st[p]); } }
;         if (w == 0) { const GAS unsigned* gs = (const GAS unsigned*)((GAS v4u*)(ws + WS_STASH) + ((size_t)((bl * 16 + g) * 32 + ck) * NWAVES) * 8 * 64);
; #pragma unroll
;             for (int ww = 0; ww < 8; ++ww) gagg[ww] = gs[(size_t)((ww * 8 + (lane >> 3)) * 64 + 31 + 32 * ((lane >> 2) & 1)) * 4 + (lane & 3)]; }
;     }
;     float pA = 1.f, pH = 0.f;
;     if (PASS == 3) { typedef float f32x2v __attribute__((ext_vector_type(2))); f32x2v ag[4];
; #pragma unroll
;         for (int j = 0; j < 4; ++j) { const int cc = 4 * w + j; ag[j] = (f32x2v){1.f, 0.f}; if (cc < ck) ag[j] = *(const GAS f32x2v*)(AGG + ((size_t)(bl * 32 + cc) * D + g * 64 + lane) * 2); }
; #pragma unroll
;         for (int j = 0; j < 4; ++j) { pH = ag[j].x * pH + ag[j].y; pA = pA * ag[j].x; } }
;     ...
;     if (PASS == 1) {
; #pragma unroll
;     for (int q = 0; q < 8; ++q)
;         asm volatile("s_nop 1\n\t"
;             LRU_STEP("row_shr:1 row_mask:0xf bank_mask:0xf") LRU_STEP("row_shr:2 row_mask:0xf bank_mask:0xf") LRU_STEP("row_shr:4 row_mask:0xf bank_mask:0xf")
	v_add_f32_e32 v26, v30, v108
	v_rcp_f32_e32 v0, v0
	v_max_f32_e32 v13, 0, v13
	v_mul_f32_e32 v26, 0xbfb8aa3b, v26
	s_waitcnt lgkmcnt(0)
	v_mul_f32_e32 v14, v112, v14
	v_add_f32_e32 v15, v15, v97
	v_sqrt_f32_e32 v13, v13
	v_exp_f32_e32 v27, v26
	v_exp_f32_e32 v26, v14
	v_mul_f32_e32 v15, 0xbfb8aa3b, v15
	v_exp_f32_e32 v15, v15
	v_mul_f32_e32 v0, v82, v0
	v_mul_f32_e32 v13, v0, v13
	v_add_f32_e32 v0, 1.0, v27
	v_fma_f32 v14, -v26, v26, 1.0
	v_rcp_f32_e32 v0, v0
	v_max_f32_e32 v14, 0, v14
	v_add_f32_e32 v27, v31, v109
	v_add_f32_e32 v15, 1.0, v15
	v_sqrt_f32_e32 v14, v14
	v_mul_f32_e32 v27, 0xbfb8aa3b, v27
	v_rcp_f32_e32 v15, v15
	v_exp_f32_e32 v28, v27
	v_mul_f32_e32 v0, v77, v0
	v_mul_f32_e32 v27, v0, v14
	v_mul_f32_e32 v14, v113, v15
	v_add_f32_e32 v0, 1.0, v28
	v_exp_f32_e32 v28, v14
	v_add_f32_e32 v14, v16, v98
	v_mul_f32_e32 v14, 0xbfb8aa3b, v14
	v_rcp_f32_e32 v0, v0
	v_fma_f32 v15, -v28, v28, 1.0
	v_exp_f32_e32 v14, v14
	v_max_f32_e32 v15, 0, v15
	v_sqrt_f32_e32 v15, v15
	v_mul_f32_e32 v0, v76, v0
	v_add_f32_e32 v14, 1.0, v14
	v_rcp_f32_e32 v14, v14
	v_mul_f32_e32 v29, v0, v15
	v_add_f32_e32 v15, v17, v99
	v_mul_f32_e32 v15, 0xbfb8aa3b, v15
	v_exp_f32_e32 v15, v15
	v_add_f32_e32 v16, v32, v110
	v_mul_f32_e32 v16, 0xbfb8aa3b, v16
	v_mul_f32_e32 v14, v114, v14
	v_exp_f32_e32 v16, v16
	v_exp_f32_e32 v14, v14
	v_add_f32_e32 v15, 1.0, v15
	v_rcp_f32_e32 v15, v15
	v_add_f32_e32 v0, 1.0, v16
	v_fma_f32 v16, -v14, v14, 1.0
	v_max_f32_e32 v17, 0, v16
	v_add_f32_e32 v16, v33, v111
	v_mul_f32_e32 v16, 0xbfb8aa3b, v16
	v_mul_f32_e32 v15, v115, v15
	v_exp_f32_e32 v30, v16
	v_exp_f32_e32 v16, v15
	v_rcp_f32_e32 v0, v0
	v_sqrt_f32_e32 v15, v17
	v_add_f32_e32 v17, 1.0, v30
	v_fma_f32 v30, -v16, v16, 1.0
	v_rcp_f32_e32 v17, v17
	v_max_f32_e32 v30, 0, v30
	v_sqrt_f32_e32 v30, v30
	v_mul_f32_e32 v0, v74, v0
	s_mov_b64 s[4:5], 0x29c00000
	v_mul_f32_e32 v15, v0, v15
	v_mul_f32_e32 v0, v75, v17
	v_lshl_add_u64 v[70:71], v[72:73], 0, s[4:5]
	v_mul_f32_e32 v17, v0, v30
	v_add_co_u32_e32 v72, vcc, s2, v72
	s_nop 1
	v_fmac_f32_dpp v67, v67, v66 row_shr:1 row_mask:0xf bank_mask:0xf
	v_fmac_f32_dpp v69, v69, v68 row_shr:1 row_mask:0xf bank_mask:0xf
	v_fmac_f32_dpp v35, v35, v34 row_shr:1 row_mask:0xf bank_mask:0xf
	v_fmac_f32_dpp v37, v37, v36 row_shr:1 row_mask:0xf bank_mask:0xf
	v_mul_f32_dpp v66, v66, v66 row_shr:1 row_mask:0xf bank_mask:0xf
	v_mul_f32_dpp v68, v68, v68 row_shr:1 row_mask:0xf bank_mask:0xf
	v_mul_f32_dpp v34, v34, v34 row_shr:1 row_mask:0xf bank_mask:0xf
	v_mul_f32_dpp v36, v36, v36 row_shr:1 row_mask:0xf bank_mask:0xf
	v_fmac_f32_dpp v67, v67, v66 row_shr:2 row_mask:0xf bank_mask:0xf
	v_fmac_f32_dpp v69, v69, v68 row_shr:2 row_mask:0xf bank_mask:0xf
	v_fmac_f32_dpp v35, v35, v34 row_shr:2 row_mask:0xf bank_mask:0xf
	v_fmac_f32_dpp v37, v37, v36 row_shr:2 row_mask:0xf bank_mask:0xf
	v_mul_f32_dpp v66, v66, v66 row_shr:2 row_mask:0xf bank_mask:0xf
	v_mul_f32_dpp v68, v68, v68 row_shr:2 row_mask:0xf bank_mask:0xf
	v_mul_f32_dpp v34, v34, v34 row_shr:2 row_mask:0xf bank_mask:0xf
	v_mul_f32_dpp v36, v36, v36 row_shr:2 row_mask:0xf bank_mask:0xf
	v_fmac_f32_dpp v67, v67, v66 row_shr:4 row_mask:0xf bank_mask:0xf
	v_fmac_f32_dpp v69, v69, v68 row_shr:4 row_mask:0xf bank_mask:0xf
	v_fmac_f32_dpp v35, v35, v34 row_shr:4 row_mask:0xf bank_mask:0xf
	v_fmac_f32_dpp v37, v37, v36 row_shr:4 row_mask:0xf bank_mask:0xf
	v_mul_f32_dpp v66, v66, v66 row_shr:4 row_mask:0xf bank_mask:0xf
	v_mul_f32_dpp v68, v68, v68 row_shr:4 row_mask:0xf bank_mask:0xf
	v_mul_f32_dpp v34, v34, v34 row_shr:4 row_mask:0xf bank_mask:0xf
	v_mul_f32_dpp v36, v36, v36 row_shr:4 row_mask:0xf bank_mask:0xf
	v_fmac_f32_dpp v67, v67, v66 row_shr:8 row_mask:0xf bank_mask:0xf
	v_fmac_f32_dpp v69, v69, v68 row_shr:8 row_mask:0xf bank_mask:0xf
	v_fmac_f32_dpp v35, v35, v34 row_shr:8 row_mask:0xf bank_mask:0xf
	v_fmac_f32_dpp v37, v37, v36 row_shr:8 row_mask:0xf bank_mask:0xf
	v_mul_f32_dpp v66, v66, v66 row_shr:8 row_mask:0xf bank_mask:0xf
	v_mul_f32_dpp v68, v68, v68 row_shr:8 row_mask:0xf bank_mask:0xf
	v_mul_f32_dpp v34, v34, v34 row_shr:8 row_mask:0xf bank_mask:0xf
	v_mul_f32_dpp v36, v36, v36 row_shr:8 row_mask:0xf bank_mask:0xf
	v_fmac_f32_dpp v67, v67, v66 row_bcast:15 row_mask:0xa bank_mask:0xf
	v_fmac_f32_dpp v69, v69, v68 row_bcast:15 row_mask:0xa bank_mask:0xf
	v_fmac_f32_dpp v35, v35, v34 row_bcast:15 row_mask:0xa bank_mask:0xf
	v_fmac_f32_dpp v37, v37, v36 row_bcast:15 row_mask:0xa bank_mask:0xf
	v_mul_f32_dpp v66, v66, v66 row_bcast:15 row_mask:0xa bank_mask:0xf
	v_mul_f32_dpp v68, v68, v68 row_bcast:15 row_mask:0xa bank_mask:0xf
	v_mul_f32_dpp v34, v34, v34 row_bcast:15 row_mask:0xa bank_mask:0xf
	v_mul_f32_dpp v36, v36, v36 row_bcast:15 row_mask:0xa bank_mask:0xf

; template <int PASS>
; __device__ __forceinline__ void lru_unit(const LruPtrs& args, LAS unsigned char* lds, int chunk, int bl, int g, int ck) {
;     ...
; #pragma unroll
;     for (int q = 0; q < 8; ++q)
;         asm volatile("s_nop 1\n\t"
;             LRU_STEP("row_shr:1 row_mask:0xf bank_mask:0xf") LRU_STEP("row_shr:2 row_mask:0xf bank_mask:0xf") LRU_STEP("row_shr:4 row_mask:0xf bank_mask:0xf")
;             LRU_STEP("row_shr:8 row_mask:0xf bank_mask:0xf") LRU_STEP("row_bcast:15 row_mask:0xa bank_mask:0xf")
;             : "+v"(uv[q][0]), "+v"(av[q][0]), "+v"(uv[q][1]), "+v"(av[q][1]), "+v"(uv[q][2]), "+v"(av[q][2]), "+v"(uv[q][3]), "+v"(av[q][3]));
	s_nop 1
	v_fmac_f32_dpp v51, v51, v50 row_shr:1 row_mask:0xf bank_mask:0xf
	v_fmac_f32_dpp v53, v53, v52 row_shr:1 row_mask:0xf bank_mask:0xf
	v_fmac_f32_dpp v39, v39, v38 row_shr:1 row_mask:0xf bank_mask:0xf
	v_fmac_f32_dpp v41, v41, v40 row_shr:1 row_mask:0xf bank_mask:0xf
	v_mul_f32_dpp v50, v50, v50 row_shr:1 row_mask:0xf bank_mask:0xf
	v_mul_f32_dpp v52, v52, v52 row_shr:1 row_mask:0xf bank_mask:0xf
	v_mul_f32_dpp v38, v38, v38 row_shr:1 row_mask:0xf bank_mask:0xf
	v_mul_f32_dpp v40, v40, v40 row_shr:1 row_mask:0xf bank_mask:0xf
	v_fmac_f32_dpp v51, v51, v50 row_shr:2 row_mask:0xf bank_mask:0xf
	v_fmac_f32_dpp v53, v53, v52 row_shr:2 row_mask:0xf bank_mask:0xf
	v_fmac_f32_dpp v39, v39, v38 row_shr:2 row_mask:0xf bank_mask:0xf
	v_fmac_f32_dpp v41, v41, v40 row_shr:2 row_mask:0xf bank_mask:0xf
	v_mul_f32_dpp v50, v50, v50 row_shr:2 row_mask:0xf bank_mask:0xf
	v_mul_f32_dpp v52, v52, v52 row_shr:2 row_mask:0xf bank_mask:0xf
	v_mul_f32_dpp v38, v38, v38 row_shr:2 row_mask:0xf bank_mask:0xf
	v_mul_f32_dpp v40, v40, v40 row_shr:2 row_mask:0xf bank_mask:0xf
	v_fmac_f32_dpp v51, v51, v50 row_shr:4 row_mask:0xf bank_mask:0xf
	v_fmac_f32_dpp v53, v53, v52 row_shr:4 row_mask:0xf bank_mask:0xf
	v_fmac_f32_dpp v39, v39, v38 row_shr:4 row_mask:0xf bank_mask:0xf
	v_fmac_f32_dpp v41, v41, v40 row_shr:4 row_mask:0xf bank_mask:0xf
	v_mul_f32_dpp v50, v50, v50 row_shr:4 row_mask:0xf bank_mask:0xf
	v_mul_f32_dpp v52, v52, v52 row_shr:4 row_mask:0xf bank_mask:0xf
	v_mul_f32_dpp v38, v38, v38 row_shr:4 row_mask:0xf bank_mask:0xf
	v_mul_f32_dpp v40, v40, v40 row_shr:4 row_mask:0xf bank_mask:0xf
	v_fmac_f32_dpp v51, v51, v50 row_shr:8 row_mask:0xf bank_mask:0xf
	v_fmac_f32_dpp v53, v53, v52 row_shr:8 row_mask:0xf bank_mask:0xf
	v_fmac_f32_dpp v39, v39, v38 row_shr:8 row_mask:0xf bank_mask:0xf
	v_fmac_f32_dpp v41, v41, v40 row_shr:8 row_mask:0xf bank_mask:0xf
	v_mul_f32_dpp v50, v50, v50 row_shr:8 row_mask:0xf bank_mask:0xf
	v_mul_f32_dpp v52, v52, v52 row_shr:8 row_mask:0xf bank_mask:0xf
	v_mul_f32_dpp v38, v38, v38 row_shr:8 row_mask:0xf bank_mask:0xf
	v_mul_f32_dpp v40, v40, v40 row_shr:8 row_mask:0xf bank_mask:0xf
	v_fmac_f32_dpp v51, v51, v50 row_bcast:15 row_mask:0xa bank_mask:0xf
	v_fmac_f32_dpp v53, v53, v52 row_bcast:15 row_mask:0xa bank_mask:0xf
	v_fmac_f32_dpp v39, v39, v38 row_bcast:15 row_mask:0xa bank_mask:0xf
	v_fmac_f32_dpp v41, v41, v40 row_bcast:15 row_mask:0xa bank_mask:0xf
	v_mul_f32_dpp v50, v50, v50 row_bcast:15 row_mask:0xa bank_mask:0xf
	v_mul_f32_dpp v52, v52, v52 row_bcast:15 row_mask:0xa bank_mask:0xf
	v_mul_f32_dpp v38, v38, v38 row_bcast:15 row_mask:0xa bank_mask:0xf
	v_mul_f32_dpp v40, v40, v40 row_bcast:15 row_mask:0xa bank_mask:0xf

; template <int PASS>
; __device__ __forceinline__ void lru_unit(const LruPtrs& args, LAS unsigned char* lds, int chunk, int bl, int g, int ck) {
;     ...
; #pragma unroll
;     for (int q = 0; q < 8; ++q)
;         asm volatile("s_nop 1\n\t"
;             LRU_STEP("row_shr:1 row_mask:0xf bank_mask:0xf") LRU_STEP("row_shr:2 row_mask:0xf bank_mask:0xf") LRU_STEP("row_shr:4 row_mask:0xf bank_mask:0xf")
;             LRU_STEP("row_shr:8 row_mask:0xf bank_mask:0xf") LRU_STEP("row_bcast:15 row_mask:0xa bank_mask:0xf")
;             : "+v"(uv[q][0]), "+v"(av[q][0]), "+v"(uv[q][1]), "+v"(av[q][1]), "+v"(uv[q][2]), "+v"(av[q][2]), "+v"(uv[q][3]), "+v"(av[q][3]));
	s_nop 1
	v_fmac_f32_dpp v55, v55, v54 row_shr:1 row_mask:0xf bank_mask:0xf
	v_fmac_f32_dpp v57, v57, v56 row_shr:1 row_mask:0xf bank_mask:0xf
	v_fmac_f32_dpp v43, v43, v42 row_shr:1 row_mask:0xf bank_mask:0xf
	v_fmac_f32_dpp v45, v45, v44 row_shr:1 row_mask:0xf bank_mask:0xf
	v_mul_f32_dpp v54, v54, v54 row_shr:1 row_mask:0xf bank_mask:0xf
	v_mul_f32_dpp v56, v56, v56 row_shr:1 row_mask:0xf bank_mask:0xf
	v_mul_f32_dpp v42, v42, v42 row_shr:1 row_mask:0xf bank_mask:0xf
	v_mul_f32_dpp v44, v44, v44 row_shr:1 row_mask:0xf bank_mask:0xf
	v_fmac_f32_dpp v55, v55, v54 row_shr:2 row_mask:0xf bank_mask:0xf
	v_fmac_f32_dpp v57, v57, v56 row_shr:2 row_mask:0xf bank_mask:0xf
	v_fmac_f32_dpp v43, v43, v42 row_shr:2 row_mask:0xf bank_mask:0xf
	v_fmac_f32_dpp v45, v45, v44 row_shr:2 row_mask:0xf bank_mask:0xf
	v_mul_f32_dpp v54, v54, v54 row_shr:2 row_mask:0xf bank_mask:0xf
	v_mul_f32_dpp v56, v56, v56 row_shr:2 row_mask:0xf bank_mask:0xf
	v_mul_f32_dpp v42, v42, v42 row_shr:2 row_mask:0xf bank_mask:0xf
	v_mul_f32_dpp v44, v44, v44 row_shr:2 row_mask:0xf bank_mask:0xf
	v_fmac_f32_dpp v55, v55, v54 row_shr:4 row_mask:0xf bank_mask:0xf
	v_fmac_f32_dpp v57, v57, v56 row_shr:4 row_mask:0xf bank_mask:0xf
	v_fmac_f32_dpp v43, v43, v42 row_shr:4 row_mask:0xf bank_mask:0xf
	v_fmac_f32_dpp v45, v45, v44 row_shr:4 row_mask:0xf bank_mask:0xf
	v_mul_f32_dpp v54, v54, v54 row_shr:4 row_mask:0xf bank_mask:0xf
	v_mul_f32_dpp v56, v56, v56 row_shr:4 row_mask:0xf bank_mask:0xf
	v_mul_f32_dpp v42, v42, v42 row_shr:4 row_mask:0xf bank_mask:0xf
	v_mul_f32_dpp v44, v44, v44 row_shr:4 row_mask:0xf bank_mask:0xf
	v_fmac_f32_dpp v55, v55, v54 row_shr:8 row_mask:0xf bank_mask:0xf
	v_fmac_f32_dpp v57, v57, v56 row_shr:8 row_mask:0xf bank_mask:0xf
	v_fmac_f32_dpp v43, v43, v42 row_shr:8 row_mask:0xf bank_mask:0xf
	v_fmac_f32_dpp v45, v45, v44 row_shr:8 row_mask:0xf bank_mask:0xf
	v_mul_f32_dpp v54, v54, v54 row_shr:8 row_mask:0xf bank_mask:0xf
	v_mul_f32_dpp v56, v56, v56 row_shr:8 row_mask:0xf bank_mask:0xf
	v_mul_f32_dpp v42, v42, v42 row_shr:8 row_mask:0xf bank_mask:0xf
	v_mul_f32_dpp v44, v44, v44 row_shr:8 row_mask:0xf bank_mask:0xf
	v_fmac_f32_dpp v55, v55, v54 row_bcast:15 row_mask:0xa bank_mask:0xf
	v_fmac_f32_dpp v57, v57, v56 row_bcast:15 row_mask:0xa bank_mask:0xf
	v_fmac_f32_dpp v43, v43, v42 row_bcast:15 row_mask:0xa bank_mask:0xf
	v_fmac_f32_dpp v45, v45, v44 row_bcast:15 row_mask:0xa bank_mask:0xf
	v_mul_f32_dpp v54, v54, v54 row_bcast:15 row_mask:0xa bank_mask:0xf
	v_mul_f32_dpp v56, v56, v56 row_bcast:15 row_mask:0xa bank_mask:0xf
	v_mul_f32_dpp v42, v42, v42 row_bcast:15 row_mask:0xa bank_mask:0xf
	v_mul_f32_dpp v44, v44, v44 row_bcast:15 row_mask:0xa bank_mask:0xf

; template <int PASS>
; __device__ __forceinline__ void lru_unit(const LruPtrs& args, LAS unsigned char* lds, int chunk, int bl, int g, int ck) {
;     ...
; #pragma unroll
;     for (int q = 0; q < 8; ++q)
;         asm volatile("s_nop 1\n\t"
;             LRU_STEP("row_shr:1 row_mask:0xf bank_mask:0xf") LRU_STEP("row_shr:2 row_mask:0xf bank_mask:0xf") LRU_STEP("row_shr:4 row_mask:0xf bank_mask:0xf")
;             LRU_STEP("row_shr:8 row_mask:0xf bank_mask:0xf") LRU_STEP("row_bcast:15 row_mask:0xa bank_mask:0xf")
;             : "+v"(uv[q][0]), "+v"(av[q][0]), "+v"(uv[q][1]), "+v"(av[q][1]), "+v"(uv[q][2]), "+v"(av[q][2]), "+v"(uv[q][3]), "+v"(av[q][3]));
	s_nop 1
	v_fmac_f32_dpp v59, v59, v58 row_shr:1 row_mask:0xf bank_mask:0xf
	v_fmac_f32_dpp v61, v61, v60 row_shr:1 row_mask:0xf bank_mask:0xf
	v_fmac_f32_dpp v47, v47, v46 row_shr:1 row_mask:0xf bank_mask:0xf
	v_fmac_f32_dpp v49, v49, v48 row_shr:1 row_mask:0xf bank_mask:0xf
	v_mul_f32_dpp v58, v58, v58 row_shr:1 row_mask:0xf bank_mask:0xf
	v_mul_f32_dpp v60, v60, v60 row_shr:1 row_mask:0xf bank_mask:0xf
	v_mul_f32_dpp v46, v46, v46 row_shr:1 row_mask:0xf bank_mask:0xf
	v_mul_f32_dpp v48, v48, v48 row_shr:1 row_mask:0xf bank_mask:0xf
	v_fmac_f32_dpp v59, v59, v58 row_shr:2 row_mask:0xf bank_mask:0xf
	v_fmac_f32_dpp v61, v61, v60 row_shr:2 row_mask:0xf bank_mask:0xf
	v_fmac_f32_dpp v47, v47, v46 row_shr:2 row_mask:0xf bank_mask:0xf
	v_fmac_f32_dpp v49, v49, v48 row_shr:2 row_mask:0xf bank_mask:0xf
	v_mul_f32_dpp v58, v58, v58 row_shr:2 row_mask:0xf bank_mask:0xf
	v_mul_f32_dpp v60, v60, v60 row_shr:2 row_mask:0xf bank_mask:0xf
	v_mul_f32_dpp v46, v46, v46 row_shr:2 row_mask:0xf bank_mask:0xf
	v_mul_f32_dpp v48, v48, v48 row_shr:2 row_mask:0xf bank_mask:0xf
	v_fmac_f32_dpp v59, v59, v58 row_shr:4 row_mask:0xf bank_mask:0xf
	v_fmac_f32_dpp v61, v61, v60 row_shr:4 row_mask:0xf bank_mask:0xf
	v_fmac_f32_dpp v47, v47, v46 row_shr:4 row_mask:0xf bank_mask:0xf
	v_fmac_f32_dpp v49, v49, v48 row_shr:4 row_mask:0xf bank_mask:0xf
	v_mul_f32_dpp v58, v58, v58 row_shr:4 row_mask:0xf bank_mask:0xf
	v_mul_f32_dpp v60, v60, v60 row_shr:4 row_mask:0xf bank_mask:0xf
	v_mul_f32_dpp v46, v46, v46 row_shr:4 row_mask:0xf bank_mask:0xf
	v_mul_f32_dpp v48, v48, v48 row_shr:4 row_mask:0xf bank_mask:0xf
	v_fmac_f32_dpp v59, v59, v58 row_shr:8 row_mask:0xf bank_mask:0xf
	v_fmac_f32_dpp v61, v61, v60 row_shr:8 row_mask:0xf bank_mask:0xf
	v_fmac_f32_dpp v47, v47, v46 row_shr:8 row_mask:0xf bank_mask:0xf
	v_fmac_f32_dpp v49, v49, v48 row_shr:8 row_mask:0xf bank_mask:0xf
	v_mul_f32_dpp v58, v58, v58 row_shr:8 row_mask:0xf bank_mask:0xf
	v_mul_f32_dpp v60, v60, v60 row_shr:8 row_mask:0xf bank_mask:0xf
	v_mul_f32_dpp v46, v46, v46 row_shr:8 row_mask:0xf bank_mask:0xf
	v_mul_f32_dpp v48, v48, v48 row_shr:8 row_mask:0xf bank_mask:0xf
	v_fmac_f32_dpp v59, v59, v58 row_bcast:15 row_mask:0xa bank_mask:0xf
	v_fmac_f32_dpp v61, v61, v60 row_bcast:15 row_mask:0xa bank_mask:0xf
	v_fmac_f32_dpp v47, v47, v46 row_bcast:15 row_mask:0xa bank_mask:0xf
	v_fmac_f32_dpp v49, v49, v48 row_bcast:15 row_mask:0xa bank_mask:0xf
	v_mul_f32_dpp v58, v58, v58 row_bcast:15 row_mask:0xa bank_mask:0xf
	v_mul_f32_dpp v60, v60, v60 row_bcast:15 row_mask:0xa bank_mask:0xf
	v_mul_f32_dpp v46, v46, v46 row_bcast:15 row_mask:0xa bank_mask:0xf
	v_mul_f32_dpp v48, v48, v48 row_bcast:15 row_mask:0xa bank_mask:0xf

; template <int PASS>
; __device__ __forceinline__ void lru_unit(const LruPtrs& args, LAS unsigned char* lds, int chunk, int bl, int g, int ck) {
;     ...
;     if (PASS == 1) {
; #pragma unroll
;     for (int q = 0; q < 8; ++q)
;         asm volatile("s_nop 1\n\t"
;             LRU_STEP("row_shr:1 row_mask:0xf bank_mask:0xf") LRU_STEP("row_shr:2 row_mask:0xf bank_mask:0xf") LRU_STEP("row_shr:4 row_mask:0xf bank_mask:0xf")
;             LRU_STEP("row_shr:8 row_mask:0xf bank_mask:0xf") LRU_STEP("row_bcast:15 row_mask:0xa bank_mask:0xf")
;             : "+v"(uv[q][0]), "+v"(av[q][0]), "+v"(uv[q][1]), "+v"(av[q][1]), "+v"(uv[q][2]), "+v"(av[q][2]), "+v"(uv[q][3]), "+v"(av[q][3]));
	s_nop 1
	v_fmac_f32_dpp v63, v63, v62 row_shr:1 row_mask:0xf bank_mask:0xf
	v_fmac_f32_dpp v65, v65, v64 row_shr:1 row_mask:0xf bank_mask:0xf
	v_fmac_f32_dpp v3, v3, v2 row_shr:1 row_mask:0xf bank_mask:0xf
	v_fmac_f32_dpp v5, v5, v4 row_shr:1 row_mask:0xf bank_mask:0xf
	v_mul_f32_dpp v62, v62, v62 row_shr:1 row_mask:0xf bank_mask:0xf
	v_mul_f32_dpp v64, v64, v64 row_shr:1 row_mask:0xf bank_mask:0xf
	v_mul_f32_dpp v2, v2, v2 row_shr:1 row_mask:0xf bank_mask:0xf
	v_mul_f32_dpp v4, v4, v4 row_shr:1 row_mask:0xf bank_mask:0xf
	v_fmac_f32_dpp v63, v63, v62 row_shr:2 row_mask:0xf bank_mask:0xf
	v_fmac_f32_dpp v65, v65, v64 row_shr:2 row_mask:0xf bank_mask:0xf
	v_fmac_f32_dpp v3, v3, v2 row_shr:2 row_mask:0xf bank_mask:0xf
	v_fmac_f32_dpp v5, v5, v4 row_shr:2 row_mask:0xf bank_mask:0xf
	v_mul_f32_dpp v62, v62, v62 row_shr:2 row_mask:0xf bank_mask:0xf
	v_mul_f32_dpp v64, v64, v64 row_shr:2 row_mask:0xf bank_mask:0xf
	v_mul_f32_dpp v2, v2, v2 row_shr:2 row_mask:0xf bank_mask:0xf
	v_mul_f32_dpp v4, v4, v4 row_shr:2 row_mask:0xf bank_mask:0xf
	v_fmac_f32_dpp v63, v63, v62 row_shr:4 row_mask:0xf bank_mask:0xf
	v_fmac_f32_dpp v65, v65, v64 row_shr:4 row_mask:0xf bank_mask:0xf
	v_fmac_f32_dpp v3, v3, v2 row_shr:4 row_mask:0xf bank_mask:0xf
	v_fmac_f32_dpp v5, v5, v4 row_shr:4 row_mask:0xf bank_mask:0xf
	v_mul_f32_dpp v62, v62, v62 row_shr:4 row_mask:0xf bank_mask:0xf
	v_mul_f32_dpp v64, v64, v64 row_shr:4 row_mask:0xf bank_mask:0xf
	v_mul_f32_dpp v2, v2, v2 row_shr:4 row_mask:0xf bank_mask:0xf
	v_mul_f32_dpp v4, v4, v4 row_shr:4 row_mask:0xf bank_mask:0xf
	v_fmac_f32_dpp v63, v63, v62 row_shr:8 row_mask:0xf bank_mask:0xf
	v_fmac_f32_dpp v65, v65, v64 row_shr:8 row_mask:0xf bank_mask:0xf
	v_fmac_f32_dpp v3, v3, v2 row_shr:8 row_mask:0xf bank_mask:0xf
	v_fmac_f32_dpp v5, v5, v4 row_shr:8 row_mask:0xf bank_mask:0xf
	v_mul_f32_dpp v62, v62, v62 row_shr:8 row_mask:0xf bank_mask:0xf
	v_mul_f32_dpp v64, v64, v64 row_shr:8 row_mask:0xf bank_mask:0xf
	v_mul_f32_dpp v2, v2, v2 row_shr:8 row_mask:0xf bank_mask:0xf
	v_mul_f32_dpp v4, v4, v4 row_shr:8 row_mask:0xf bank_mask:0xf
	v_fmac_f32_dpp v63, v63, v62 row_bcast:15 row_mask:0xa bank_mask:0xf
	v_fmac_f32_dpp v65, v65, v64 row_bcast:15 row_mask:0xa bank_mask:0xf
	v_fmac_f32_dpp v3, v3, v2 row_bcast:15 row_mask:0xa bank_mask:0xf
	v_fmac_f32_dpp v5, v5, v4 row_bcast:15 row_mask:0xa bank_mask:0xf
	v_mul_f32_dpp v62, v62, v62 row_bcast:15 row_mask:0xa bank_mask:0xf
	v_mul_f32_dpp v64, v64, v64 row_bcast:15 row_mask:0xa bank_mask:0xf
	v_mul_f32_dpp v2, v2, v2 row_bcast:15 row_mask:0xa bank_mask:0xf
	v_mul_f32_dpp v4, v4, v4 row_bcast:15 row_mask:0xa bank_mask:0xf

; template <int PASS>
; __device__ __forceinline__ void lru_unit(const LruPtrs& args, LAS unsigned char* lds, int chunk, int bl, int g, int ck) {
;     ...
;     if (PASS == 1) {
; #pragma unroll
;     for (int q = 0; q < 8; ++q)
;         asm volatile("s_nop 1\n\t"
;             LRU_STEP("row_shr:1 row_mask:0xf bank_mask:0xf") LRU_STEP("row_shr:2 row_mask:0xf bank_mask:0xf") LRU_STEP("row_shr:4 row_mask:0xf bank_mask:0xf")
;             LRU_STEP("row_shr:8 row_mask:0xf bank_mask:0xf") LRU_STEP("row_bcast:15 row_mask:0xa bank_mask:0xf")
;             : "+v"(uv[q][0]), "+v"(av[q][0]), "+v"(uv[q][1]), "+v"(av[q][1]), "+v"(uv[q][2]), "+v"(av[q][2]), "+v"(uv[q][3]), "+v"(av[q][3]));
	s_nop 1
	v_fmac_f32_dpp v19, v19, v18 row_shr:1 row_mask:0xf bank_mask:0xf
	v_fmac_f32_dpp v21, v21, v20 row_shr:1 row_mask:0xf bank_mask:0xf
	v_fmac_f32_dpp v7, v7, v6 row_shr:1 row_mask:0xf bank_mask:0xf
	v_fmac_f32_dpp v9, v9, v8 row_shr:1 row_mask:0xf bank_mask:0xf
	v_mul_f32_dpp v18, v18, v18 row_shr:1 row_mask:0xf bank_mask:0xf
	v_mul_f32_dpp v20, v20, v20 row_shr:1 row_mask:0xf bank_mask:0xf
	v_mul_f32_dpp v6, v6, v6 row_shr:1 row_mask:0xf bank_mask:0xf
	v_mul_f32_dpp v8, v8, v8 row_shr:1 row_mask:0xf bank_mask:0xf
	v_fmac_f32_dpp v19, v19, v18 row_shr:2 row_mask:0xf bank_mask:0xf
	v_fmac_f32_dpp v21, v21, v20 row_shr:2 row_mask:0xf bank_mask:0xf
	v_fmac_f32_dpp v7, v7, v6 row_shr:2 row_mask:0xf bank_mask:0xf
	v_fmac_f32_dpp v9, v9, v8 row_shr:2 row_mask:0xf bank_mask:0xf
	v_mul_f32_dpp v18, v18, v18 row_shr:2 row_mask:0xf bank_mask:0xf
	v_mul_f32_dpp v20, v20, v20 row_shr:2 row_mask:0xf bank_mask:0xf
	v_mul_f32_dpp v6, v6, v6 row_shr:2 row_mask:0xf bank_mask:0xf
	v_mul_f32_dpp v8, v8, v8 row_shr:2 row_mask:0xf bank_mask:0xf
	v_fmac_f32_dpp v19, v19, v18 row_shr:4 row_mask:0xf bank_mask:0xf
	v_fmac_f32_dpp v21, v21, v20 row_shr:4 row_mask:0xf bank_mask:0xf
	v_fmac_f32_dpp v7, v7, v6 row_shr:4 row_mask:0xf bank_mask:0xf
	v_fmac_f32_dpp v9, v9, v8 row_shr:4 row_mask:0xf bank_mask:0xf
	v_mul_f32_dpp v18, v18, v18 row_shr:4 row_mask:0xf bank_mask:0xf
	v_mul_f32_dpp v20, v20, v20 row_shr:4 row_mask:0xf bank_mask:0xf
	v_mul_f32_dpp v6, v6, v6 row_shr:4 row_mask:0xf bank_mask:0xf
	v_mul_f32_dpp v8, v8, v8 row_shr:4 row_mask:0xf bank_mask:0xf
	v_fmac_f32_dpp v19, v19, v18 row_shr:8 row_mask:0xf bank_mask:0xf
	v_fmac_f32_dpp v21, v21, v20 row_shr:8 row_mask:0xf bank_mask:0xf
	v_fmac_f32_dpp v7, v7, v6 row_shr:8 row_mask:0xf bank_mask:0xf
	v_fmac_f32_dpp v9, v9, v8 row_shr:8 row_mask:0xf bank_mask:0xf
	v_mul_f32_dpp v18, v18, v18 row_shr:8 row_mask:0xf bank_mask:0xf
	v_mul_f32_dpp v20, v20, v20 row_shr:8 row_mask:0xf bank_mask:0xf
	v_mul_f32_dpp v6, v6, v6 row_shr:8 row_mask:0xf bank_mask:0xf
	v_mul_f32_dpp v8, v8, v8 row_shr:8 row_mask:0xf bank_mask:0xf
	v_fmac_f32_dpp v19, v19, v18 row_bcast:15 row_mask:0xa bank_mask:0xf
	v_fmac_f32_dpp v21, v21, v20 row_bcast:15 row_mask:0xa bank_mask:0xf
	v_fmac_f32_dpp v7, v7, v6 row_bcast:15 row_mask:0xa bank_mask:0xf
	v_fmac_f32_dpp v9, v9, v8 row_bcast:15 row_mask:0xa bank_mask:0xf
	v_mul_f32_dpp v18, v18, v18 row_bcast:15 row_mask:0xa bank_mask:0xf
	v_mul_f32_dpp v20, v20, v20 row_bcast:15 row_mask:0xa bank_mask:0xf
	v_mul_f32_dpp v6, v6, v6 row_bcast:15 row_mask:0xa bank_mask:0xf
	v_mul_f32_dpp v8, v8, v8 row_bcast:15 row_mask:0xa bank_mask:0xf

; template <int PASS>
; __device__ __forceinline__ void lru_unit(const LruPtrs& args, LAS unsigned char* lds, int chunk, int bl, int g, int ck) {
;     ...
;     if (PASS == 1) {
; #pragma unroll
;     for (int q = 0; q < 8; ++q)
;         asm volatile("s_nop 1\n\t"
;             LRU_STEP("row_shr:1 row_mask:0xf bank_mask:0xf") LRU_STEP("row_shr:2 row_mask:0xf bank_mask:0xf") LRU_STEP("row_shr:4 row_mask:0xf bank_mask:0xf")
;             LRU_STEP("row_shr:8 row_mask:0xf bank_mask:0xf") LRU_STEP("row_bcast:15 row_mask:0xa bank_mask:0xf")
;             : "+v"(uv[q][0]), "+v"(av[q][0]), "+v"(uv[q][1]), "+v"(av[q][1]), "+v"(uv[q][2]), "+v"(av[q][2]), "+v"(uv[q][3]), "+v"(av[q][3]));
	s_nop 1
	v_fmac_f32_dpp v23, v23, v22 row_shr:1 row_mask:0xf bank_mask:0xf
	v_fmac_f32_dpp v25, v25, v24 row_shr:1 row_mask:0xf bank_mask:0xf
	v_fmac_f32_dpp v11, v11, v10 row_shr:1 row_mask:0xf bank_mask:0xf
	v_fmac_f32_dpp v13, v13, v12 row_shr:1 row_mask:0xf bank_mask:0xf
	v_mul_f32_dpp v22, v22, v22 row_shr:1 row_mask:0xf bank_mask:0xf
	v_mul_f32_dpp v24, v24, v24 row_shr:1 row_mask:0xf bank_mask:0xf
	v_mul_f32_dpp v10, v10, v10 row_shr:1 row_mask:0xf bank_mask:0xf
	v_mul_f32_dpp v12, v12, v12 row_shr:1 row_mask:0xf bank_mask:0xf
	v_fmac_f32_dpp v23, v23, v22 row_shr:2 row_mask:0xf bank_mask:0xf
	v_fmac_f32_dpp v25, v25, v24 row_shr:2 row_mask:0xf bank_mask:0xf
	v_fmac_f32_dpp v11, v11, v10 row_shr:2 row_mask:0xf bank_mask:0xf
	v_fmac_f32_dpp v13, v13, v12 row_shr:2 row_mask:0xf bank_mask:0xf
	v_mul_f32_dpp v22, v22, v22 row_shr:2 row_mask:0xf bank_mask:0xf
	v_mul_f32_dpp v24, v24, v24 row_shr:2 row_mask:0xf bank_mask:0xf
	v_mul_f32_dpp v10, v10, v10 row_shr:2 row_mask:0xf bank_mask:0xf
	v_mul_f32_dpp v12, v12, v12 row_shr:2 row_mask:0xf bank_mask:0xf
	v_fmac_f32_dpp v23, v23, v22 row_shr:4 row_mask:0xf bank_mask:0xf
	v_fmac_f32_dpp v25, v25, v24 row_shr:4 row_mask:0xf bank_mask:0xf
	v_fmac_f32_dpp v11, v11, v10 row_shr:4 row_mask:0xf bank_mask:0xf
	v_fmac_f32_dpp v13, v13, v12 row_shr:4 row_mask:0xf bank_mask:0xf
	v_mul_f32_dpp v22, v22, v22 row_shr:4 row_mask:0xf bank_mask:0xf
	v_mul_f32_dpp v24, v24, v24 row_shr:4 row_mask:0xf bank_mask:0xf
	v_mul_f32_dpp v10, v10, v10 row_shr:4 row_mask:0xf bank_mask:0xf
	v_mul_f32_dpp v12, v12, v12 row_shr:4 row_mask:0xf bank_mask:0xf
	v_fmac_f32_dpp v23, v23, v22 row_shr:8 row_mask:0xf bank_mask:0xf
	v_fmac_f32_dpp v25, v25, v24 row_shr:8 row_mask:0xf bank_mask:0xf
	v_fmac_f32_dpp v11, v11, v10 row_shr:8 row_mask:0xf bank_mask:0xf
	v_fmac_f32_dpp v13, v13, v12 row_shr:8 row_mask:0xf bank_mask:0xf
	v_mul_f32_dpp v22, v22, v22 row_shr:8 row_mask:0xf bank_mask:0xf
	v_mul_f32_dpp v24, v24, v24 row_shr:8 row_mask:0xf bank_mask:0xf
	v_mul_f32_dpp v10, v10, v10 row_shr:8 row_mask:0xf bank_mask:0xf
	v_mul_f32_dpp v12, v12, v12 row_shr:8 row_mask:0xf bank_mask:0xf
	v_fmac_f32_dpp v23, v23, v22 row_bcast:15 row_mask:0xa bank_mask:0xf
	v_fmac_f32_dpp v25, v25, v24 row_bcast:15 row_mask:0xa bank_mask:0xf
	v_fmac_f32_dpp v11, v11, v10 row_bcast:15 row_mask:0xa bank_mask:0xf
	v_fmac_f32_dpp v13, v13, v12 row_bcast:15 row_mask:0xa bank_mask:0xf
	v_mul_f32_dpp v22, v22, v22 row_bcast:15 row_mask:0xa bank_mask:0xf
	v_mul_f32_dpp v24, v24, v24 row_bcast:15 row_mask:0xa bank_mask:0xf
	v_mul_f32_dpp v10, v10, v10 row_bcast:15 row_mask:0xa bank_mask:0xf
	v_mul_f32_dpp v12, v12, v12 row_bcast:15 row_mask:0xa bank_mask:0xf

; template <int PASS>
; __device__ __forceinline__ void lru_unit(const LruPtrs& args, LAS unsigned char* lds, int chunk, int bl, int g, int ck) {
;     ...
;     if (PASS == 1) {
; #pragma unroll
;     for (int q = 0; q < 8; ++q)
;         asm volatile("s_nop 1\n\t"
;             LRU_STEP("row_shr:1 row_mask:0xf bank_mask:0xf") LRU_STEP("row_shr:2 row_mask:0xf bank_mask:0xf") LRU_STEP("row_shr:4 row_mask:0xf bank_mask:0xf")
;             LRU_STEP("row_shr:8 row_mask:0xf bank_mask:0xf") LRU_STEP("row_bcast:15 row_mask:0xa bank_mask:0xf")
;             : "+v"(uv[q][0]), "+v"(av[q][0]), "+v"(uv[q][1]), "+v"(av[q][1]), "+v"(uv[q][2]), "+v"(av[q][2]), "+v"(uv[q][3]), "+v"(av[q][3]));
	s_nop 1
	v_fmac_f32_dpp v27, v27, v26 row_shr:1 row_mask:0xf bank_mask:0xf
	v_fmac_f32_dpp v29, v29, v28 row_shr:1 row_mask:0xf bank_mask:0xf
	v_fmac_f32_dpp v15, v15, v14 row_shr:1 row_mask:0xf bank_mask:0xf
	v_fmac_f32_dpp v17, v17, v16 row_shr:1 row_mask:0xf bank_mask:0xf
	v_mul_f32_dpp v26, v26, v26 row_shr:1 row_mask:0xf bank_mask:0xf
	v_mul_f32_dpp v28, v28, v28 row_shr:1 row_mask:0xf bank_mask:0xf
	v_mul_f32_dpp v14, v14, v14 row_shr:1 row_mask:0xf bank_mask:0xf
	v_mul_f32_dpp v16, v16, v16 row_shr:1 row_mask:0xf bank_mask:0xf
	v_fmac_f32_dpp v27, v27, v26 row_shr:2 row_mask:0xf bank_mask:0xf
	v_fmac_f32_dpp v29, v29, v28 row_shr:2 row_mask:0xf bank_mask:0xf
	v_fmac_f32_dpp v15, v15, v14 row_shr:2 row_mask:0xf bank_mask:0xf
	v_fmac_f32_dpp v17, v17, v16 row_shr:2 row_mask:0xf bank_mask:0xf
	v_mul_f32_dpp v26, v26, v26 row_shr:2 row_mask:0xf bank_mask:0xf
	v_mul_f32_dpp v28, v28, v28 row_shr:2 row_mask:0xf bank_mask:0xf
	v_mul_f32_dpp v14, v14, v14 row_shr:2 row_mask:0xf bank_mask:0xf
	v_mul_f32_dpp v16, v16, v16 row_shr:2 row_mask:0xf bank_mask:0xf
	v_fmac_f32_dpp v27, v27, v26 row_shr:4 row_mask:0xf bank_mask:0xf
	v_fmac_f32_dpp v29, v29, v28 row_shr:4 row_mask:0xf bank_mask:0xf
	v_fmac_f32_dpp v15, v15, v14 row_shr:4 row_mask:0xf bank_mask:0xf
	v_fmac_f32_dpp v17, v17, v16 row_shr:4 row_mask:0xf bank_mask:0xf
	v_mul_f32_dpp v26, v26, v26 row_shr:4 row_mask:0xf bank_mask:0xf
	v_mul_f32_dpp v28, v28, v28 row_shr:4 row_mask:0xf bank_mask:0xf
	v_mul_f32_dpp v14, v14, v14 row_shr:4 row_mask:0xf bank_mask:0xf
	v_mul_f32_dpp v16, v16, v16 row_shr:4 row_mask:0xf bank_mask:0xf
	v_fmac_f32_dpp v27, v27, v26 row_shr:8 row_mask:0xf bank_mask:0xf
	v_fmac_f32_dpp v29, v29, v28 row_shr:8 row_mask:0xf bank_mask:0xf
	v_fmac_f32_dpp v15, v15, v14 row_shr:8 row_mask:0xf bank_mask:0xf
	v_fmac_f32_dpp v17, v17, v16 row_shr:8 row_mask:0xf bank_mask:0xf
	v_mul_f32_dpp v26, v26, v26 row_shr:8 row_mask:0xf bank_mask:0xf
	v_mul_f32_dpp v28, v28, v28 row_shr:8 row_mask:0xf bank_mask:0xf
	v_mul_f32_dpp v14, v14, v14 row_shr:8 row_mask:0xf bank_mask:0xf
	v_mul_f32_dpp v16, v16, v16 row_shr:8 row_mask:0xf bank_mask:0xf
	v_fmac_f32_dpp v27, v27, v26 row_bcast:15 row_mask:0xa bank_mask:0xf
	v_fmac_f32_dpp v29, v29, v28 row_bcast:15 row_mask:0xa bank_mask:0xf
	v_fmac_f32_dpp v15, v15, v14 row_bcast:15 row_mask:0xa bank_mask:0xf
	v_fmac_f32_dpp v17, v17, v16 row_bcast:15 row_mask:0xa bank_mask:0xf
	v_mul_f32_dpp v26, v26, v26 row_bcast:15 row_mask:0xa bank_mask:0xf
	v_mul_f32_dpp v28, v28, v28 row_bcast:15 row_mask:0xa bank_mask:0xf
	v_mul_f32_dpp v14, v14, v14 row_bcast:15 row_mask:0xa bank_mask:0xf
	v_mul_f32_dpp v16, v16, v16 row_bcast:15 row_mask:0xa bank_mask:0xf

; __device__ __forceinline__ unsigned cvt_pk_bf16(float lo, float hi) { unsigned r; asm volatile("v_cvt_pk_bf16_f32 %0, %1, %2" : "=v"(r) : "v"(lo), "v"(hi)); return r; }
; #define GAS __attribute__((address_space(1)))
; template <int PASS>
; __device__ __forceinline__ void lru_unit(const LruPtrs& args, LAS unsigned char* lds, int chunk, int bl, int g, int ck) {
;     ...
; #pragma unroll
;     for (int q = 0; q < 8; ++q) { v4u st;
; #pragma unroll
;         for (int p = 0; p < 4; ++p) st[p] = pg8::cvt_pk_bf16(av[q][p], uv[q][p]);
;         stash[q * 64] = st; }
;     }
;     ...
;     if (PASS == 1 && n == 31) {
; #pragma unroll
;         for (int q = 0; q < 8; ++q)
; #pragma unroll
;             for (int p = 0; p < 4; ++p) { const int ci = 8 * q + 4 * hi + p; WAG[(w * 64 + ci) * 2] = av[q][p]; WAG[(w * 64 + ci) * 2 + 1] = uv[q][p]; }
;     }
;     if (PASS == 3) { PART[(w * 64 + lane) * 2] = pA; PART[(w * 64 + lane) * 2 + 1] = pH; }
;     __syncthreads();
;     if (PASS == 1) {
;         if (w == 0) { float A = 1.f, H = 0.f;
; #pragma unroll
;             for (int ww = 0; ww < 8; ++ww) { const float a = WAG[(ww * 64 + lane) * 2], h = WAG[(ww * 64 + lane) * 2 + 1]; H = a * H + h; A = A * a; }
;             GAS float* dst = AGG + ((size_t)(bl * 32 + ck) * D + g * 64 + lane) * 2; dst[0] = A; dst[1] = H; }
	s_nop 0
	v_cvt_pk_bf16_f32 v30, v66, v67
	v_cvt_pk_bf16_f32 v31, v68, v69
	v_cvt_pk_bf16_f32 v32, v34, v35
	v_cvt_pk_bf16_f32 v33, v36, v37
	s_nop 0
	v_addc_co_u32_e32 v73, vcc, 0, v73, vcc
	global_store_dwordx4 v[72:73], v[30:33], off offset:-4096 sc1
	v_cmp_eq_u32_e32 vcc, 31, v87
	s_nop 0
	v_cvt_pk_bf16_f32 v30, v50, v51
	v_cvt_pk_bf16_f32 v31, v52, v53
	v_cvt_pk_bf16_f32 v32, v38, v39
	v_cvt_pk_bf16_f32 v33, v40, v41
	global_store_dwordx4 v[70:71], v[30:33], off offset:1024 sc1
	s_nop 1
	v_cvt_pk_bf16_f32 v30, v54, v55
	v_cvt_pk_bf16_f32 v31, v56, v57
	v_cvt_pk_bf16_f32 v32, v42, v43
	v_cvt_pk_bf16_f32 v33, v44, v45
	global_store_dwordx4 v[70:71], v[30:33], off offset:2048 sc1
	s_nop 1
	v_cvt_pk_bf16_f32 v30, v58, v59
	v_cvt_pk_bf16_f32 v31, v60, v61
	v_cvt_pk_bf16_f32 v32, v46, v47
	v_cvt_pk_bf16_f32 v33, v48, v49
	global_store_dwordx4 v[70:71], v[30:33], off offset:3072 sc1
	s_nop 1
	v_cvt_pk_bf16_f32 v30, v62, v63
	v_cvt_pk_bf16_f32 v31, v64, v65
	v_cvt_pk_bf16_f32 v32, v2, v3
	v_cvt_pk_bf16_f32 v33, v4, v5
	global_store_dwordx4 v[72:73], v[30:33], off sc1
	s_nop 1
	v_cvt_pk_bf16_f32 v30, v18, v19
	v_cvt_pk_bf16_f32 v31, v20, v21
	v_cvt_pk_bf16_f32 v32, v6, v7
	v_cvt_pk_bf16_f32 v33, v8, v9
	global_store_dwordx4 v[72:73], v[30:33], off offset:1024 sc1
	s_nop 1
	v_cvt_pk_bf16_f32 v30, v22, v23
	v_cvt_pk_bf16_f32 v31, v24, v25
	v_cvt_pk_bf16_f32 v32, v10, v11
	v_cvt_pk_bf16_f32 v33, v12, v13
	global_store_dwordx4 v[72:73], v[30:33], off offset:2048 sc1
	s_nop 1
	v_cvt_pk_bf16_f32 v30, v26, v27
	v_cvt_pk_bf16_f32 v31, v28, v29
	v_cvt_pk_bf16_f32 v32, v14, v15
	v_cvt_pk_bf16_f32 v33, v16, v17
	global_store_dwordx4 v[72:73], v[30:33], off offset:3072 sc1
	s_and_saveexec_b64 s[4:5], vcc
	s_cbranch_execz .LBB0_447
	v_or_b32_e32 v0, s47, v88
	v_lshl_add_u32 v0, v0, 3, 0
	ds_write_b128 v0, v[66:69]
	ds_write_b128 v0, v[34:37] offset:16
	ds_write_b128 v0, v[50:53] offset:64
	ds_write_b128 v0, v[38:41] offset:80
	ds_write_b128 v0, v[54:57] offset:128
	ds_write_b128 v0, v[42:45] offset:144
	ds_write_b128 v0, v[58:61] offset:192
	ds_write_b128 v0, v[46:49] offset:208
	ds_write_b128 v0, v[62:65] offset:256
	ds_write_b128 v0, v[2:5] offset:272
	ds_write_b128 v0, v[18:21] offset:320
	ds_write_b128 v0, v[6:9] offset:336
	ds_write_b128 v0, v[22:25] offset:384
	ds_write_b128 v0, v[10:13] offset:400
	ds_write_b128 v0, v[26:29] offset:448
	ds_write_b128 v0, v[14:17] offset:464
.LBB0_447:
	s_or_b64 exec, exec, s[4:5]
	s_cmp_gt_u32 s18, 63
	s_waitcnt lgkmcnt(0)
	s_barrier
	s_cbranch_scc1 .LBB0_403
	v_lshlrev_b32_e32 v0, 3, v86
	v_add_u32_e32 v0, 0, v0
	ds_read2st64_b64 v[2:5], v0 offset1:1
	ds_read2st64_b64 v[6:9], v0 offset0:2 offset1:3
	ds_read2st64_b64 v[10:13], v0 offset0:4 offset1:5
	ds_read2st64_b64 v[14:17], v0 offset0:6 offset1:7
	s_lshl_b32 s2, s46, 15
	s_waitcnt lgkmcnt(3)
	v_fma_f32 v0, 0, v2, v3
	v_fmac_f32_e32 v5, v0, v4
	s_waitcnt lgkmcnt(2)
	v_fma_f32 v0, v5, v6, v7
	v_fma_f32 v0, v0, v8, v9
	v_mul_f32_e32 v2, v2, v4
	s_waitcnt lgkmcnt(1)
	v_fma_f32 v3, v0, v10, v11
	v_mov_b32_e32 v7, v12
	v_pk_mul_f32 v[18:19], v[2:3], v[6:7]
	v_mov_b32_e32 v9, v13
	s_lshl_b32 s4, s45, 10
	v_pk_mul_f32 v[8:9], v[18:19], v[8:9]
	v_pk_fma_f32 v[2:3], v[2:3], v[6:7], v[12:13]
	s_or_b32 s2, s2, s4
	v_mov_b32_e32 v9, v3
	s_waitcnt lgkmcnt(0)
	v_mov_b32_e32 v11, v14
	s_or_b32 s2, s2, s44
	v_pk_mul_f32 v[6:7], v[8:9], v[10:11]
	v_or_b32_e32 v0, s2, v86
	v_mov_b32_e32 v3, v14
	v_pk_mul_f32 v[6:7], v[6:7], v[12:13]
	v_pk_fma_f32 v[8:9], v[8:9], v[10:11], v[14:15]
	v_lshlrev_b32_e32 v0, 1, v0
	v_mov_b32_e32 v8, v6
	v_pk_mov_b32 v[2:3], v[2:3], v[16:17] op_sel:[1,0]
	v_lshl_add_u64 v[4:5], v[0:1], 2, s[42:43]
	v_pk_mul_f32 v[6:7], v[6:7], v[2:3]
	v_pk_fma_f32 v[2:3], v[8:9], v[2:3], v[16:17]
	v_pk_mul_f32 v[6:7], v[6:7], v[16:17]
	v_add_co_u32_e32 v2, vcc, 0x3600000, v4
	v_mov_b32_e32 v7, v3
	s_nop 0
	v_addc_co_u32_e32 v3, vcc, 0, v5, vcc
	global_store_dwordx2 v[2:3], v[6:7], off sc1
	s_branch .LBB0_403

; #define PG8_LAS __attribute__((address_space(3)))
; __device__ __forceinline__ u32x4 pack8(const f32x4 v0, const f32x4 v1) { u32x4 w; w.x = cvt_pk_bf16(v0[0], v0[1]); w.y = cvt_pk_bf16(v0[2], v0[3]); w.z = cvt_pk_bf16(v1[0], v1[1]); w.w = cvt_pk_bf16(v1[2], v1[3]); return w; }
;     __device__ __forceinline__ void operator()(f32x4 (&acc)[2][2][4][2], const Unit& u, int wr, int wc, int fr, int fq) const {
;     ...
;         for (int ai = 0; ai < 2; ++ai)
; #pragma unroll
;             for (int m = 0; m < 4; ++m) { const int row = ai * HALF + wr * 64 + m * 16 + fr;
;                 const f32x4 a = *(const PG8_LAS f32x4*)(xs + row * 8), b = *(const PG8_LAS f32x4*)(xs + row * 8 + 4);
;                 const float M = fmaxf(fmaxf(a[0], a[2]), fmaxf(b[0], b[2]));
;                 const float tot = a[1] * __builtin_amdgcn_exp2f(a[0] - M) + a[3] * __builtin_amdgcn_exp2f(a[2] - M) + b[1] * __builtin_amdgcn_exp2f(b[0] - M) + b[3] * __builtin_amdgcn_exp2f(b[2] - M);
;                 const float f = __builtin_amdgcn_exp2f(lm[ai][m] - M) * __builtin_amdgcn_rcpf(tot);
;                 bf16_t* rowp = base + (size_t)(ai * HALF + m * 16) * u.ldo;
; #pragma unroll
;                 for (int bj = 0; bj < 2; ++bj) *(u32x4*)(rowp + bj * HALF) = pack8(acc[ai][bj][m][0] * f, acc[ai][bj][m][1] * f); }
.LBB0_477:
	s_or_b64 exec, exec, s[44:45]
	v_add_u32_e32 v12, s53, v161
	v_ashrrev_i32_e32 v13, 31, v12
	s_waitcnt lgkmcnt(0)
	v_lshlrev_b64 v[10:11], 11, v[12:13]
	v_lshl_add_u64 v[10:11], s[42:43], 0, v[10:11]
	v_lshlrev_b32_e32 v160, 3, v160
	v_lshl_add_u32 v12, v12, 5, 0
	s_waitcnt lgkmcnt(0)
	s_barrier
	v_lshl_add_u64 v[10:11], v[10:11], 0, s[18:19]
	v_ashrrev_i32_e32 v161, 31, v160
	v_add_u32_e32 v12, 0x20400, v12
	v_lshl_add_u64 v[10:11], v[160:161], 1, v[10:11]
	ds_read_b128 v[160:163], v12
	ds_read_b128 v[164:167], v12 offset:16
	s_mov_b64 s[42:43], -1
	s_waitcnt lgkmcnt(0)
	v_max_f32_e32 v13, v166, v166
	v_max_f32_e32 v18, v164, v164
	v_max_f32_e32 v13, v18, v13
	v_max3_f32 v13, v160, v162, v13
	v_sub_f32_e32 v18, v160, v13
	v_exp_f32_e32 v168, v18
	v_sub_f32_e32 v18, v162, v13
	v_exp_f32_e32 v169, v18
	v_mov_b32_e32 v162, v161
	v_sub_f32_e32 v18, v164, v13
	v_mov_b32_e32 v164, v167
	v_pk_mul_f32 v[160:161], v[162:163], v[168:169]
	v_exp_f32_e32 v163, v18
	v_sub_f32_e32 v18, v166, v13
	v_exp_f32_e32 v162, v18
	v_add_f32_e32 v18, v160, v161
	v_sub_f32_e32 v13, v153, v13
	v_exp_f32_e32 v13, v13
	v_pk_mul_f32 v[162:163], v[164:165], v[162:163]
	s_nop 0
	v_add_f32_e32 v18, v163, v18
	v_add_f32_e32 v18, v162, v18
	v_rcp_f32_e32 v18, v18
	s_nop 0
	v_mul_f32_e32 v18, v13, v18
	v_pk_mul_f32 v[144:145], v[144:145], v[18:19] op_sel_hi:[1,0]
	v_pk_mul_f32 v[138:139], v[138:139], v[18:19] op_sel_hi:[1,0]
	v_pk_mul_f32 v[150:151], v[150:151], v[18:19] op_sel_hi:[1,0]
	v_pk_mul_f32 v[152:153], v[142:143], v[18:19] op_sel_hi:[1,0]
	v_cvt_pk_bf16_f32 v142, v138, v139
	v_cvt_pk_bf16_f32 v143, v144, v145
	v_pk_mul_f32 v[138:139], v[140:141], v[18:19] op_sel_hi:[1,0]
	v_cvt_pk_bf16_f32 v144, v152, v153
	v_cvt_pk_bf16_f32 v145, v150, v151
	v_pk_mul_f32 v[140:141], v[146:147], v[18:19] op_sel_hi:[1,0]
	global_store_dwordx4 v[10:11], v[142:145], off sc1
	v_cvt_pk_bf16_f32 v138, v138, v139
	s_nop 1
	v_pk_mul_f32 v[142:143], v[148:149], v[18:19] op_sel_hi:[1,0]
	v_pk_mul_f32 v[144:145], v[154:155], v[18:19] op_sel_hi:[1,0]
	v_cvt_pk_bf16_f32 v139, v142, v143
	v_cvt_pk_bf16_f32 v140, v140, v141
	s_nop 0
	v_cvt_pk_bf16_f32 v141, v144, v145
	global_store_dwordx4 v[10:11], v[138:141], off offset:256 sc1
	ds_read_b128 v[138:141], v12 offset:512
	ds_read_b128 v[142:145], v12 offset:528
	s_waitcnt lgkmcnt(0)
	v_max_f32_e32 v13, v144, v144
	v_max_f32_e32 v18, v142, v142
	v_max_f32_e32 v13, v18, v13
	v_max3_f32 v13, v138, v140, v13
	v_sub_f32_e32 v18, v138, v13
	v_exp_f32_e32 v146, v18
	v_sub_f32_e32 v18, v140, v13
	v_exp_f32_e32 v147, v18
	v_mov_b32_e32 v140, v139
	v_sub_f32_e32 v18, v142, v13
	v_mov_b32_e32 v142, v145
	v_pk_mul_f32 v[138:139], v[140:141], v[146:147]
	v_exp_f32_e32 v141, v18
	v_sub_f32_e32 v18, v144, v13
	v_exp_f32_e32 v140, v18
	v_add_f32_e32 v18, v138, v139
	v_sub_f32_e32 v13, v117, v13
	v_exp_f32_e32 v13, v13
	v_pk_mul_f32 v[140:141], v[142:143], v[140:141]
	s_nop 0
	v_add_f32_e32 v18, v141, v18
	v_add_f32_e32 v18, v140, v18
	v_rcp_f32_e32 v18, v18
	s_nop 0
	v_mul_f32_e32 v18, v13, v18
	v_pk_mul_f32 v[116:117], v[126:127], v[18:19] op_sel_hi:[1,0]
	v_pk_mul_f32 v[124:125], v[124:125], v[18:19] op_sel_hi:[1,0]
	v_pk_mul_f32 v[126:127], v[136:137], v[18:19] op_sel_hi:[1,0]
	v_pk_mul_f32 v[136:137], v[122:123], v[18:19] op_sel_hi:[1,0]
	v_cvt_pk_bf16_f32 v122, v124, v125
	v_cvt_pk_bf16_f32 v123, v116, v117
	v_pk_mul_f32 v[116:117], v[120:121], v[18:19] op_sel_hi:[1,0]
	v_cvt_pk_bf16_f32 v124, v136, v137
	v_cvt_pk_bf16_f32 v125, v126, v127
	v_add_co_u32_e32 v126, vcc, s79, v10
	v_pk_mul_f32 v[114:115], v[114:115], v[18:19] op_sel_hi:[1,0]
	s_nop 0
	v_addc_co_u32_e32 v127, vcc, 0, v11, vcc
	global_store_dwordx4 v[126:127], v[122:125], off sc1
	v_pk_mul_f32 v[120:121], v[128:129], v[18:19] op_sel_hi:[1,0]
	v_pk_mul_f32 v[118:119], v[118:119], v[18:19] op_sel_hi:[1,0]
	v_cvt_pk_bf16_f32 v114, v114, v115
	v_cvt_pk_bf16_f32 v115, v116, v117
	s_nop 0
	v_cvt_pk_bf16_f32 v116, v118, v119
	v_cvt_pk_bf16_f32 v117, v120, v121
	global_store_dwordx4 v[126:127], v[114:117], off offset:256 sc1
	ds_read_b128 v[114:117], v12 offset:1024
	ds_read_b128 v[118:121], v12 offset:1040
	s_waitcnt lgkmcnt(0)
	v_max_f32_e32 v13, v120, v120
	v_max_f32_e32 v18, v118, v118
	v_max_f32_e32 v13, v18, v13
	v_max3_f32 v13, v114, v116, v13
	v_sub_f32_e32 v18, v114, v13
	v_exp_f32_e32 v122, v18
	v_sub_f32_e32 v18, v116, v13
	v_exp_f32_e32 v123, v18
	v_mov_b32_e32 v116, v115
	v_sub_f32_e32 v18, v118, v13
	v_mov_b32_e32 v118, v121
	v_pk_mul_f32 v[114:115], v[116:117], v[122:123]
	v_exp_f32_e32 v117, v18
	v_sub_f32_e32 v18, v120, v13
	v_exp_f32_e32 v116, v18
	v_add_f32_e32 v18, v114, v115
	v_sub_f32_e32 v13, v99, v13
	v_exp_f32_e32 v13, v13
	v_pk_mul_f32 v[116:117], v[118:119], v[116:117]
	s_nop 0
	v_add_f32_e32 v18, v117, v18
	v_add_f32_e32 v18, v116, v18
	v_rcp_f32_e32 v18, v18
	s_nop 0
	v_mul_f32_e32 v18, v13, v18
	v_pk_mul_f32 v[98:99], v[108:109], v[18:19] op_sel_hi:[1,0]
	v_pk_mul_f32 v[106:107], v[106:107], v[18:19] op_sel_hi:[1,0]
	v_pk_mul_f32 v[108:109], v[112:113], v[18:19] op_sel_hi:[1,0]
	v_pk_mul_f32 v[112:113], v[104:105], v[18:19] op_sel_hi:[1,0]
	v_cvt_pk_bf16_f32 v104, v106, v107
	v_cvt_pk_bf16_f32 v105, v98, v99
	v_pk_mul_f32 v[98:99], v[102:103], v[18:19] op_sel_hi:[1,0]
	v_cvt_pk_bf16_f32 v106, v112, v113
	v_cvt_pk_bf16_f32 v107, v108, v109
	v_add_co_u32_e32 v108, vcc, s27, v10
	v_pk_mul_f32 v[96:97], v[96:97], v[18:19] op_sel_hi:[1,0]
	s_nop 0
	v_addc_co_u32_e32 v109, vcc, 0, v11, vcc
	global_store_dwordx4 v[108:109], v[104:107], off sc1
	v_pk_mul_f32 v[102:103], v[110:111], v[18:19] op_sel_hi:[1,0]
	v_pk_mul_f32 v[100:101], v[100:101], v[18:19] op_sel_hi:[1,0]
	v_cvt_pk_bf16_f32 v96, v96, v97
	v_cvt_pk_bf16_f32 v97, v98, v99
	s_nop 0
	v_cvt_pk_bf16_f32 v98, v100, v101
	v_cvt_pk_bf16_f32 v99, v102, v103
	global_store_dwordx4 v[108:109], v[96:99], off offset:256 sc1
	ds_read_b128 v[96:99], v12 offset:1536
	ds_read_b128 v[100:103], v12 offset:1552
	s_waitcnt lgkmcnt(0)
; #define PG8_LAS __attribute__((address_space(3)))
; __device__ __forceinline__ u32x4 pack8(const f32x4 v0, const f32x4 v1) { u32x4 w; w.x = cvt_pk_bf16(v0[0], v0[1]); w.y = cvt_pk_bf16(v0[2], v0[3]); w.z = cvt_pk_bf16(v1[0], v1[1]); w.w = cvt_pk_bf16(v1[2], v1[3]); return w; }
;     __device__ __forceinline__ void operator()(f32x4 (&acc)[2][2][4][2], const Unit& u, int wr, int wc, int fr, int fq) const {
;     ...
;         for (int ai = 0; ai < 2; ++ai)
; #pragma unroll
;             for (int m = 0; m < 4; ++m) { const int row = ai * HALF + wr * 64 + m * 16 + fr;
;                 const f32x4 a = *(const PG8_LAS f32x4*)(xs + row * 8), b = *(const PG8_LAS f32x4*)(xs + row * 8 + 4);
;                 const float M = fmaxf(fmaxf(a[0], a[2]), fmaxf(b[0], b[2]));
;                 const float tot = a[1] * __builtin_amdgcn_exp2f(a[0] - M) + a[3] * __builtin_amdgcn_exp2f(a[2] - M) + b[1] * __builtin_amdgcn_exp2f(b[0] - M) + b[3] * __builtin_amdgcn_exp2f(b[2] - M);
;                 const float f = __builtin_amdgcn_exp2f(lm[ai][m] - M) * __builtin_amdgcn_rcpf(tot);
;                 bf16_t* rowp = base + (size_t)(ai * HALF + m * 16) * u.ldo;
; #pragma unroll
;                 for (int bj = 0; bj < 2; ++bj) *(u32x4*)(rowp + bj * HALF) = pack8(acc[ai][bj][m][0] * f, acc[ai][bj][m][1] * f); }
	v_max_f32_e32 v13, v102, v102
	v_max_f32_e32 v18, v100, v100
	v_max_f32_e32 v13, v18, v13
	v_max3_f32 v13, v96, v98, v13
	v_sub_f32_e32 v18, v96, v13
	v_exp_f32_e32 v104, v18
	v_sub_f32_e32 v18, v98, v13
	v_exp_f32_e32 v105, v18
	v_mov_b32_e32 v98, v97
	v_sub_f32_e32 v18, v100, v13
	v_mov_b32_e32 v100, v103
	v_pk_mul_f32 v[96:97], v[98:99], v[104:105]
	v_exp_f32_e32 v99, v18
	v_sub_f32_e32 v18, v102, v13
	v_exp_f32_e32 v98, v18
	v_add_f32_e32 v18, v96, v97
	v_sub_f32_e32 v13, v83, v13
	v_exp_f32_e32 v13, v13
	v_pk_mul_f32 v[98:99], v[100:101], v[98:99]
	s_nop 0
	v_add_f32_e32 v18, v99, v18
	v_add_f32_e32 v18, v98, v18
	v_rcp_f32_e32 v18, v18
	s_nop 0
	v_mul_f32_e32 v18, v13, v18
	v_pk_mul_f32 v[82:83], v[90:91], v[18:19] op_sel_hi:[1,0]
	v_pk_mul_f32 v[88:89], v[88:89], v[18:19] op_sel_hi:[1,0]
	v_pk_mul_f32 v[90:91], v[94:95], v[18:19] op_sel_hi:[1,0]
	v_pk_mul_f32 v[94:95], v[86:87], v[18:19] op_sel_hi:[1,0]
	v_cvt_pk_bf16_f32 v86, v88, v89
	v_cvt_pk_bf16_f32 v87, v82, v83
	v_add_co_u32_e32 v82, vcc, s78, v10
	v_pk_mul_f32 v[78:79], v[78:79], v[18:19] op_sel_hi:[1,0]
	s_nop 0
	v_addc_co_u32_e32 v83, vcc, 0, v11, vcc
	v_pk_mul_f32 v[80:81], v[80:81], v[18:19] op_sel_hi:[1,0]
	v_cvt_pk_bf16_f32 v88, v94, v95
	v_cvt_pk_bf16_f32 v89, v90, v91
	global_store_dwordx4 v[82:83], v[86:89], off sc1
	v_pk_mul_f32 v[84:85], v[84:85], v[18:19] op_sel_hi:[1,0]
	v_cvt_pk_bf16_f32 v78, v78, v79
	s_nop 0
	v_pk_mul_f32 v[86:87], v[92:93], v[18:19] op_sel_hi:[1,0]
	v_cvt_pk_bf16_f32 v79, v84, v85
	v_cvt_pk_bf16_f32 v80, v80, v81
	s_nop 0
	v_cvt_pk_bf16_f32 v81, v86, v87
	global_store_dwordx4 v[82:83], v[78:81], off offset:256 sc1
	ds_read_b128 v[78:81], v12 offset:4096
	ds_read_b128 v[82:85], v12 offset:4112
	s_waitcnt lgkmcnt(0)
	v_max_f32_e32 v13, v84, v84
	v_max_f32_e32 v18, v82, v82
	v_max_f32_e32 v13, v18, v13
	v_max3_f32 v13, v78, v80, v13
	v_sub_f32_e32 v18, v78, v13
	v_exp_f32_e32 v86, v18
	v_sub_f32_e32 v18, v80, v13
	v_exp_f32_e32 v87, v18
	v_mov_b32_e32 v80, v79
	v_sub_f32_e32 v18, v82, v13
	v_mov_b32_e32 v82, v85
	v_pk_mul_f32 v[78:79], v[80:81], v[86:87]
	v_exp_f32_e32 v81, v18
	v_sub_f32_e32 v18, v84, v13
	v_exp_f32_e32 v80, v18
	v_add_f32_e32 v18, v78, v79
	v_sub_f32_e32 v13, v67, v13
	v_exp_f32_e32 v13, v13
	v_pk_mul_f32 v[80:81], v[82:83], v[80:81]
	s_nop 0
	v_add_f32_e32 v18, v81, v18
	v_add_f32_e32 v18, v80, v18
	v_rcp_f32_e32 v18, v18
	s_nop 0
	v_mul_f32_e32 v18, v13, v18
	v_pk_mul_f32 v[66:67], v[70:71], v[18:19] op_sel_hi:[1,0]
	v_pk_mul_f32 v[70:71], v[76:77], v[18:19] op_sel_hi:[1,0]
	v_pk_mul_f32 v[68:69], v[68:69], v[18:19] op_sel_hi:[1,0]
	v_pk_mul_f32 v[72:73], v[72:73], v[18:19] op_sel_hi:[1,0]
	v_cvt_pk_bf16_f32 v66, v66, v67
	v_pk_mul_f32 v[62:63], v[62:63], v[18:19] op_sel_hi:[1,0]
	v_cvt_pk_bf16_f32 v67, v72, v73
	v_cvt_pk_bf16_f32 v68, v68, v69
	v_cvt_pk_bf16_f32 v69, v70, v71
	v_add_co_u32_e32 v70, vcc, s80, v10
	v_pk_mul_f32 v[64:65], v[64:65], v[18:19] op_sel_hi:[1,0]
	s_nop 0
	v_addc_co_u32_e32 v71, vcc, 0, v11, vcc
	global_store_dwordx4 v[70:71], v[66:69], off sc1
	s_nop 1
	v_pk_mul_f32 v[66:67], v[74:75], v[18:19] op_sel_hi:[1,0]
	v_pk_mul_f32 v[68:69], v[60:61], v[18:19] op_sel_hi:[1,0]
	v_cvt_pk_bf16_f32 v60, v62, v63
	v_cvt_pk_bf16_f32 v61, v64, v65
	s_nop 0
	v_cvt_pk_bf16_f32 v62, v68, v69
	v_cvt_pk_bf16_f32 v63, v66, v67
	global_store_dwordx4 v[70:71], v[60:63], off offset:256 sc1
	ds_read_b128 v[60:63], v12 offset:4608
	ds_read_b128 v[64:67], v12 offset:4624
	s_waitcnt lgkmcnt(0)
; #define PG8_LAS __attribute__((address_space(3)))
; __device__ __forceinline__ u32x4 pack8(const f32x4 v0, const f32x4 v1) { u32x4 w; w.x = cvt_pk_bf16(v0[0], v0[1]); w.y = cvt_pk_bf16(v0[2], v0[3]); w.z = cvt_pk_bf16(v1[0], v1[1]); w.w = cvt_pk_bf16(v1[2], v1[3]); return w; }
;     __device__ __forceinline__ void operator()(f32x4 (&acc)[2][2][4][2], const Unit& u, int wr, int wc, int fr, int fq) const {
;     ...
;         for (int ai = 0; ai < 2; ++ai)
; #pragma unroll
;             for (int m = 0; m < 4; ++m) { const int row = ai * HALF + wr * 64 + m * 16 + fr;
;                 const f32x4 a = *(const PG8_LAS f32x4*)(xs + row * 8), b = *(const PG8_LAS f32x4*)(xs + row * 8 + 4);
;                 const float M = fmaxf(fmaxf(a[0], a[2]), fmaxf(b[0], b[2]));
;                 const float tot = a[1] * __builtin_amdgcn_exp2f(a[0] - M) + a[3] * __builtin_amdgcn_exp2f(a[2] - M) + b[1] * __builtin_amdgcn_exp2f(b[0] - M) + b[3] * __builtin_amdgcn_exp2f(b[2] - M);
;                 const float f = __builtin_amdgcn_exp2f(lm[ai][m] - M) * __builtin_amdgcn_rcpf(tot);
;                 bf16_t* rowp = base + (size_t)(ai * HALF + m * 16) * u.ldo;
; #pragma unroll
;                 for (int bj = 0; bj < 2; ++bj) *(u32x4*)(rowp + bj * HALF) = pack8(acc[ai][bj][m][0] * f, acc[ai][bj][m][1] * f); }
	v_max_f32_e32 v13, v66, v66
	v_max_f32_e32 v18, v64, v64
	v_max_f32_e32 v13, v18, v13
	v_max3_f32 v13, v60, v62, v13
	v_sub_f32_e32 v18, v60, v13
	v_exp_f32_e32 v68, v18
	v_sub_f32_e32 v18, v62, v13
	v_exp_f32_e32 v69, v18
	v_mov_b32_e32 v62, v61
	v_sub_f32_e32 v18, v64, v13
	v_mov_b32_e32 v64, v67
	v_pk_mul_f32 v[60:61], v[62:63], v[68:69]
	v_exp_f32_e32 v63, v18
	v_sub_f32_e32 v18, v66, v13
	v_exp_f32_e32 v62, v18
	v_add_f32_e32 v18, v60, v61
	v_sub_f32_e32 v13, v51, v13
	v_exp_f32_e32 v13, v13
	v_pk_mul_f32 v[62:63], v[64:65], v[62:63]
	s_nop 0
	v_add_f32_e32 v18, v63, v18
	v_add_f32_e32 v18, v62, v18
	v_rcp_f32_e32 v18, v18
	s_nop 0
	v_mul_f32_e32 v18, v13, v18
	v_pk_mul_f32 v[52:53], v[52:53], v[18:19] op_sel_hi:[1,0]
	v_pk_mul_f32 v[50:51], v[54:55], v[18:19] op_sel_hi:[1,0]
	v_pk_mul_f32 v[54:55], v[58:59], v[18:19] op_sel_hi:[1,0]
	v_pk_mul_f32 v[58:59], v[48:49], v[18:19] op_sel_hi:[1,0]
	v_cvt_pk_bf16_f32 v48, v52, v53
	v_add_co_u32_e32 v52, vcc, s81, v10
	v_cvt_pk_bf16_f32 v49, v50, v51
	v_pk_mul_f32 v[42:43], v[42:43], v[18:19] op_sel_hi:[1,0]
	s_nop 0
	v_addc_co_u32_e32 v53, vcc, 0, v11, vcc
	v_pk_mul_f32 v[44:45], v[44:45], v[18:19] op_sel_hi:[1,0]
	v_cvt_pk_bf16_f32 v50, v58, v59
	v_cvt_pk_bf16_f32 v51, v54, v55
	global_store_dwordx4 v[52:53], v[48:51], off sc1
	v_pk_mul_f32 v[46:47], v[46:47], v[18:19] op_sel_hi:[1,0]
	v_cvt_pk_bf16_f32 v42, v42, v43
	s_nop 0
	v_pk_mul_f32 v[48:49], v[56:57], v[18:19] op_sel_hi:[1,0]
	v_cvt_pk_bf16_f32 v43, v46, v47
	v_cvt_pk_bf16_f32 v44, v44, v45
	s_nop 0
	v_cvt_pk_bf16_f32 v45, v48, v49
	global_store_dwordx4 v[52:53], v[42:45], off offset:256 sc1
	ds_read_b128 v[42:45], v12 offset:5120
	ds_read_b128 v[46:49], v12 offset:5136
	s_waitcnt lgkmcnt(0)
	v_max_f32_e32 v13, v48, v48
	v_max_f32_e32 v18, v46, v46
	v_max_f32_e32 v13, v18, v13
	v_max3_f32 v13, v42, v44, v13
	v_sub_f32_e32 v18, v42, v13
	v_exp_f32_e32 v50, v18
	v_sub_f32_e32 v18, v44, v13
	v_exp_f32_e32 v51, v18
	v_mov_b32_e32 v44, v43
	v_sub_f32_e32 v18, v46, v13
	v_mov_b32_e32 v46, v49
	v_pk_mul_f32 v[42:43], v[44:45], v[50:51]
	v_exp_f32_e32 v45, v18
	v_sub_f32_e32 v18, v48, v13
	v_exp_f32_e32 v44, v18
	v_add_f32_e32 v18, v42, v43
	v_sub_f32_e32 v13, v35, v13
	v_exp_f32_e32 v13, v13
	v_pk_mul_f32 v[44:45], v[46:47], v[44:45]
	s_nop 0
	v_add_f32_e32 v18, v45, v18
	v_add_f32_e32 v18, v44, v18
	v_rcp_f32_e32 v18, v18
	s_nop 0
	v_mul_f32_e32 v18, v13, v18
	v_pk_mul_f32 v[34:35], v[36:37], v[18:19] op_sel_hi:[1,0]
	v_pk_mul_f32 v[32:33], v[32:33], v[18:19] op_sel_hi:[1,0]
	v_pk_mul_f32 v[36:37], v[40:41], v[18:19] op_sel_hi:[1,0]
	v_pk_mul_f32 v[40:41], v[30:31], v[18:19] op_sel_hi:[1,0]
	v_cvt_pk_bf16_f32 v30, v32, v33
	v_cvt_pk_bf16_f32 v31, v34, v35
	v_add_co_u32_e32 v34, vcc, s82, v10
	v_pk_mul_f32 v[24:25], v[24:25], v[18:19] op_sel_hi:[1,0]
	s_nop 0
	v_addc_co_u32_e32 v35, vcc, 0, v11, vcc
	v_pk_mul_f32 v[26:27], v[26:27], v[18:19] op_sel_hi:[1,0]
	v_cvt_pk_bf16_f32 v32, v40, v41
	v_cvt_pk_bf16_f32 v33, v36, v37
	global_store_dwordx4 v[34:35], v[30:33], off sc1
	v_pk_mul_f32 v[28:29], v[28:29], v[18:19] op_sel_hi:[1,0]
	v_cvt_pk_bf16_f32 v24, v24, v25
	v_add_co_u32_e32 v10, vcc, s83, v10
	v_pk_mul_f32 v[30:31], v[38:39], v[18:19] op_sel_hi:[1,0]
	v_cvt_pk_bf16_f32 v25, v28, v29
	v_cvt_pk_bf16_f32 v26, v26, v27
	s_nop 0
	v_addc_co_u32_e32 v11, vcc, 0, v11, vcc
	v_cvt_pk_bf16_f32 v27, v30, v31
	global_store_dwordx4 v[34:35], v[24:27], off offset:256 sc1
	ds_read_b128 v[24:27], v12 offset:5632
	ds_read_b128 v[28:31], v12 offset:5648
	s_andn2_b64 vcc, exec, s[40:41]
	s_waitcnt lgkmcnt(0)
	v_max_f32_e32 v12, v30, v30
	v_max_f32_e32 v13, v28, v28
	v_max_f32_e32 v12, v13, v12
	v_max3_f32 v18, v24, v26, v12
	v_sub_f32_e32 v12, v24, v18
	v_sub_f32_e32 v13, v26, v18
	v_sub_f32_e32 v24, v28, v18
	v_exp_f32_e32 v12, v12
	v_exp_f32_e32 v13, v13
	v_mov_b32_e32 v26, v25
	v_exp_f32_e32 v25, v24
	v_sub_f32_e32 v24, v30, v18
	v_exp_f32_e32 v24, v24
	v_pk_mul_f32 v[12:13], v[26:27], v[12:13]
	v_mov_b32_e32 v28, v31
	v_add_f32_e32 v12, v12, v13
	v_pk_mul_f32 v[24:25], v[28:29], v[24:25]
	v_sub_f32_e32 v13, v19, v18
	v_add_f32_e32 v12, v25, v12
	v_add_f32_e32 v12, v24, v12
	v_exp_f32_e32 v13, v13
	v_rcp_f32_e32 v12, v12
	s_nop 0
	v_mul_f32_e32 v18, v13, v12
	v_pk_mul_f32 v[12:13], v[16:17], v[18:19] op_sel_hi:[1,0]
	v_pk_mul_f32 v[20:21], v[20:21], v[18:19] op_sel_hi:[1,0]
	v_pk_mul_f32 v[14:15], v[14:15], v[18:19] op_sel_hi:[1,0]
	v_cvt_pk_bf16_f32 v12, v12, v13
	v_cvt_pk_bf16_f32 v13, v20, v21
	v_pk_mul_f32 v[16:17], v[22:23], v[18:19] op_sel_hi:[1,0]
	v_cvt_pk_bf16_f32 v14, v14, v15
	v_pk_mul_f32 v[8:9], v[8:9], v[18:19] op_sel_hi:[1,0]
	v_cvt_pk_bf16_f32 v15, v16, v17
	global_store_dwordx4 v[10:11], v[12:15], off sc1
	v_pk_mul_f32 v[6:7], v[6:7], v[18:19] op_sel_hi:[1,0]
	s_nop 0
	v_pk_mul_f32 v[12:13], v[4:5], v[18:19] op_sel_hi:[1,0]
	v_pk_mul_f32 v[4:5], v[2:3], v[18:19] op_sel_hi:[1,0]
	v_cvt_pk_bf16_f32 v2, v6, v7
	v_cvt_pk_bf16_f32 v3, v8, v9
	s_nop 0
	v_cvt_pk_bf16_f32 v4, v4, v5
	v_cvt_pk_bf16_f32 v5, v12, v13
	global_store_dwordx4 v[10:11], v[2:5], off offset:256 sc1
	s_cbranch_vccnz .LBB0_456
	s_andn2_b64 vcc, exec, s[6:7]
	s_cbranch_vccnz .LBB0_455
	s_barrier
	s_branch .LBB0_455

; __device__ __forceinline__ unsigned xb_add(unsigned* p, unsigned v) { return __hip_atomic_fetch_add(p, v, __ATOMIC_RELAXED, __HIP_MEMORY_SCOPE_AGENT); }
; __device__ __forceinline__ void xcd_barrier(const XcdBarrier& b) {
;     ...
;         const unsigned old = xb_add(&bar[XB_XSUB(b.x)], 1u);
;         const unsigned gen = old / nloc;
;         if (old + 1u == (gen + 1u) * nloc) {
;             __builtin_amdgcn_fence(__ATOMIC_RELEASE, "agent");
;             asm volatile("s_waitcnt vmcnt(0)" ::: "memory");
;             const unsigned og = xb_add(&bar[XB_TOP], 1u);
.LBB0_513:
	s_andn2_saveexec_b64 s[14:15], s[14:15]
	s_cbranch_execz .LBB0_533
	s_mov_b64 s[14:15], exec
	s_waitcnt lgkmcnt(0)
	s_waitcnt vmcnt(0)
	buffer_inv sc1
	v_mbcnt_lo_u32_b32 v2, s14, 0
	v_mbcnt_hi_u32_b32 v2, s15, v2
	v_cmp_eq_u32_e32 vcc, 0, v2
	s_and_saveexec_b64 s[40:41], vcc
	s_cbranch_execz .LBB0_516
	s_bcnt1_i32_b64 s2, s[14:15]
	v_mov_b32_e32 v3, s2
	v_mov_b32_e32 v4, 0x7000
	global_atomic_add v3, v4, v3, s[8:9] offset:1024 sc0

; __device__ __forceinline__ int crow(int r,int hi){return (r&3)+8*(r>>2)+4*hi;}
; template<int THRL> __device__ __forceinline__ void attn_unit(int b,int h,int qb,const bf16*Q,const bf16*__restrict__ K,const bf16*__restrict__ V,bf16*O,const bf16*GF,const float*CBh,const unsigned*KN,const unsigned*QN,char*shm){
;     ...
;   {auto rr=__builtin_amdgcn_permlane32_swap(__float_as_uint(l_reg),__float_as_uint(l_reg),false,false);l_reg=__uint_as_float(rr[0])+__uint_as_float(rr[1]);}
;   if(hi==0)wsf[32+r32]=l_reg;asm volatile("s_waitcnt lgkmcnt(0)":::"memory");
;   float rli[16];
;   #pragma unroll
;   for(int r=0;r<16;++r)rli[r]=__builtin_amdgcn_rcpf(wsf[32+crow(r,hi)]);
;   bf16*Ow=O+(rowbase+q0+wid*QBLK)*DM+h*D;
;   const bf16*Gw=GF+(rowbase+q0+wid*QBLK)*DM+h*D;
;   { bf16*stg=(bf16*)(shm+LDS_OST)+wid*2048;
;     #pragma unroll
;     for(int r=0;r<16;++r){const int orow=crow(r,hi);
;       #pragma unroll
;       for(int d0=0;d0<2;++d0)stg[orow*64+d0*32+r32]=__float2bfloat16(o[d0][r]*rli[r]);}
;     asm volatile("s_waitcnt lgkmcnt(0)":::"memory");
.LBB0_534:
	s_or_b64 exec, exec, s[6:7]
	s_waitcnt lgkmcnt(0)
	ds_read_b128 v[34:37], v216 offset:49280
	ds_read_b128 v[38:41], v216 offset:49312
	s_lshl_b64 s[6:7], s[42:43], 1
	s_add_u32 s2, s62, s6
	s_addc_u32 s7, s63, s7
	s_waitcnt lgkmcnt(1)
	v_rcp_f32_e32 v0, v34
	v_rcp_f32_e32 v42, v35
	s_lshl_b32 s6, s67, 12
	s_add_i32 s8, s6, 0
	v_lshl_add_u32 v49, v190, 1, s8
	v_mul_f32_e32 v18, v18, v0
	v_mul_f32_e32 v0, v2, v0
	v_rcp_f32_e32 v43, v36
	v_lshl_add_u32 v50, v191, 9, v49
	v_cvt_pk_bf16_f32 v0, v0, s0
	v_rcp_f32_e32 v44, v37
	s_waitcnt lgkmcnt(0)
	v_rcp_f32_e32 v45, v38
	ds_read_b128 v[34:37], v216 offset:49344
	v_rcp_f32_e32 v46, v39
	v_rcp_f32_e32 v47, v40
	v_rcp_f32_e32 v48, v41
	ds_read_b128 v[38:41], v216 offset:49376
	ds_write_b16 v50, v0 offset:51264
	v_mul_f32_e32 v0, v19, v42
	v_cvt_pk_bf16_f32 v0, v0, s0
	ds_write_b16 v50, v0 offset:51328
	v_mul_f32_e32 v0, v3, v42
	v_cvt_pk_bf16_f32 v0, v0, s0
	v_mul_f32_e32 v2, v20, v43
	ds_write_b16 v50, v0 offset:51392
	v_lshl_add_u32 v0, v213, 7, v49
	v_cvt_pk_bf16_f32 v2, v2, s0
	ds_write_b16 v0, v2 offset:51200
	v_mul_f32_e32 v2, v4, v43
	v_cvt_pk_bf16_f32 v2, v2, s0
	ds_write_b16 v0, v2 offset:51264
	v_mul_f32_e32 v2, v21, v44
	v_lshl_add_u32 v0, v212, 7, v49
	v_cvt_pk_bf16_f32 v2, v2, s0
	ds_write_b16 v0, v2 offset:51200
	v_mul_f32_e32 v2, v5, v44
	v_cvt_pk_bf16_f32 v2, v2, s0
	ds_write_b16 v0, v2 offset:51264
	v_mul_f32_e32 v2, v22, v45
	v_lshl_add_u32 v0, v211, 7, v49
	v_cvt_pk_bf16_f32 v2, v2, s0
	ds_write_b16 v0, v2 offset:51200
	v_mul_f32_e32 v2, v6, v45
	v_cvt_pk_bf16_f32 v2, v2, s0
	ds_write_b16 v0, v2 offset:51264
	v_mul_f32_e32 v2, v23, v46
	v_lshl_add_u32 v0, v210, 7, v49
	v_cvt_pk_bf16_f32 v2, v2, s0
	ds_write_b16 v0, v2 offset:51200
	v_mul_f32_e32 v2, v7, v46
	v_cvt_pk_bf16_f32 v2, v2, s0
	ds_write_b16 v0, v2 offset:51264
	v_mul_f32_e32 v2, v24, v47
	v_lshl_add_u32 v0, v209, 7, v49
	v_cvt_pk_bf16_f32 v2, v2, s0
	ds_write_b16 v0, v2 offset:51200
	v_mul_f32_e32 v2, v8, v47
	v_cvt_pk_bf16_f32 v2, v2, s0
	s_waitcnt lgkmcnt(13)
	v_rcp_f32_e32 v34, v34
	ds_write_b16 v0, v2 offset:51264
	v_mul_f32_e32 v2, v25, v48
	v_lshl_add_u32 v0, v208, 7, v49
	v_cvt_pk_bf16_f32 v2, v2, s0
	ds_write_b16 v0, v2 offset:51200
	v_mul_f32_e32 v2, v9, v48
	v_cvt_pk_bf16_f32 v2, v2, s0
	v_rcp_f32_e32 v35, v35
	ds_write_b16 v0, v2 offset:51264
	v_mul_f32_e32 v2, v26, v34
	v_lshl_add_u32 v0, v207, 7, v49
	v_cvt_pk_bf16_f32 v2, v2, s0
	ds_write_b16 v0, v2 offset:51200
	v_mul_f32_e32 v2, v10, v34
	v_cvt_pk_bf16_f32 v2, v2, s0
	v_rcp_f32_e32 v36, v36
	ds_write_b16 v0, v2 offset:51264
	v_mul_f32_e32 v2, v27, v35
	v_lshl_add_u32 v0, v206, 7, v49
	v_cvt_pk_bf16_f32 v2, v2, s0
	ds_write_b16 v0, v2 offset:51200
	v_mul_f32_e32 v2, v11, v35
	v_cvt_pk_bf16_f32 v2, v2, s0
	v_rcp_f32_e32 v37, v37
	ds_write_b16 v0, v2 offset:51264
	v_mul_f32_e32 v2, v28, v36
	v_lshl_add_u32 v0, v205, 7, v49
	v_cvt_pk_bf16_f32 v2, v2, s0
	ds_write_b16 v0, v2 offset:51200
	v_mul_f32_e32 v2, v12, v36
	v_cvt_pk_bf16_f32 v2, v2, s0
	s_waitcnt lgkmcnt(14)
	v_rcp_f32_e32 v38, v38
	ds_write_b16 v0, v2 offset:51264
	v_mul_f32_e32 v2, v29, v37
	v_lshl_add_u32 v0, v204, 7, v49
	v_cvt_pk_bf16_f32 v2, v2, s0
	ds_write_b16 v0, v2 offset:51200
	v_mul_f32_e32 v2, v13, v37
	v_cvt_pk_bf16_f32 v2, v2, s0
	v_rcp_f32_e32 v39, v39
	ds_write_b16 v0, v2 offset:51264
	v_mul_f32_e32 v2, v30, v38
	v_lshl_add_u32 v0, v203, 7, v49
	v_cvt_pk_bf16_f32 v2, v2, s0
	ds_write_b16 v0, v2 offset:51200
	v_mul_f32_e32 v2, v14, v38
	v_cvt_pk_bf16_f32 v2, v2, s0
	v_rcp_f32_e32 v40, v40
	ds_write_b16 v0, v2 offset:51264
	v_mul_f32_e32 v2, v31, v39
	v_lshl_add_u32 v0, v202, 7, v49
	v_cvt_pk_bf16_f32 v2, v2, s0
	ds_write_b16 v0, v2 offset:51200
	v_mul_f32_e32 v2, v15, v39
	v_cvt_pk_bf16_f32 v2, v2, s0
	v_rcp_f32_e32 v41, v41
	ds_write_b16 v0, v2 offset:51264
	v_mul_f32_e32 v2, v32, v40
	v_lshl_add_u32 v0, v193, 7, v49
	v_cvt_pk_bf16_f32 v2, v2, s0
	ds_write_b16 v0, v2 offset:51200
	v_mul_f32_e32 v2, v16, v40
	v_cvt_pk_bf16_f32 v2, v2, s0
	ds_write_b16 v0, v2 offset:51264
	v_mul_f32_e32 v2, v33, v41
	v_lshl_add_u32 v0, v187, 7, v49
	v_cvt_pk_bf16_f32 v2, v2, s0
	ds_write_b16 v0, v2 offset:51200
	v_mul_f32_e32 v2, v17, v41
	v_cvt_pk_bf16_f32 v2, v2, s0
	ds_write_b16 v0, v2 offset:51264
	s_add_u32 s6, s2, s66
	v_lshlrev_b32_e32 v0, 1, v189
	v_cvt_pk_bf16_f32 v18, v18, s0
	s_addc_u32 s7, s7, 0
	v_and_b32_e32 v0, 0x70, v0
	ds_write_b16 v50, v18 offset:51200
	v_lshl_add_u64 v[2:3], s[6:7], 0, v[0:1]
	v_and_b32_e32 v4, 0x3800, v186
	v_mov_b32_e32 v5, v1
	s_waitcnt lgkmcnt(0)
; template<int THRL> __device__ __forceinline__ void attn_unit(int b,int h,int qb,const bf16*Q,const bf16*__restrict__ K,const bf16*__restrict__ V,bf16*O,const bf16*GF,const float*CBh,const unsigned*KN,const unsigned*QN,char*shm){
;     ...
;     u32x4 gg[4];
;     #pragma unroll
;     for(int i=0;i<4;++i){const int row=i*8+(lane>>3),ch=lane&7; gg[i]=*(const u32x4*)(Gw+(long)row*DM+ch*8);}
;     #pragma unroll
;     for(int i=0;i<4;++i){const int row=i*8+(lane>>3),ch=lane&7; const u32x4 v=*(const u32x4*)(stg+row*64+ch*8);
;       *(u32x4*)(Ow+(long)row*DM+ch*8)=mul_bf16x8(v,gg[i]);} }
;   asm volatile("s_waitcnt vmcnt(0) lgkmcnt(0)\n\ts_barrier":::"memory");
	v_lshl_add_u64 v[2:3], v[2:3], 0, v[4:5]
	global_load_dwordx4 v[8:11], v[2:3], off
	v_add_co_u32_e32 v4, vcc, s31, v2
	s_mov_b32 s2, 0xc000
	s_nop 0
	v_addc_co_u32_e32 v5, vcc, 0, v3, vcc
	global_load_dwordx4 v[12:15], v[4:5], off
	v_add_co_u32_e32 v4, vcc, s79, v2
	v_lshrrev_b32_e32 v32, 3, v188
	s_nop 0
	v_addc_co_u32_e32 v5, vcc, 0, v3, vcc
	global_load_dwordx4 v[16:19], v[4:5], off
	v_add_co_u32_e32 v2, vcc, s2, v2
	v_add_u32_e32 v33, s8, v0
	s_nop 0
	v_addc_co_u32_e32 v3, vcc, 0, v3, vcc
	global_load_dwordx4 v[2:5], v[2:3], off
	v_lshl_add_u32 v6, v32, 7, v33
	ds_read_b128 v[20:23], v6 offset:51200
	v_or_b32_e32 v34, 8, v32
	v_lshl_add_u64 v[6:7], s[14:15], 0, v[0:1]
	v_lshl_add_u32 v0, v34, 7, v33
	ds_read_b128 v[24:27], v0 offset:51200
	s_waitcnt lgkmcnt(1)
	v_lshlrev_b32_e32 v28, 16, v20
	v_and_b32_e32 v29, 0xffff0000, v20
	v_lshlrev_b32_e32 v20, 16, v21
	v_and_b32_e32 v21, 0xffff0000, v21
	v_lshlrev_b32_e32 v0, 11, v32
	s_waitcnt vmcnt(3)
	v_lshlrev_b32_e32 v30, 16, v8
	v_and_b32_e32 v31, 0xffff0000, v8
	v_pk_mul_f32 v[28:29], v[30:31], v[28:29]
	s_nop 0
	v_cvt_pk_bf16_f32 v8, v28, v29
	v_lshlrev_b32_e32 v28, 16, v9
	v_and_b32_e32 v29, 0xffff0000, v9
	v_pk_mul_f32 v[20:21], v[28:29], v[20:21]
	v_lshlrev_b32_e32 v28, 16, v10
	v_cvt_pk_bf16_f32 v9, v20, v21
	v_lshlrev_b32_e32 v20, 16, v22
	v_and_b32_e32 v21, 0xffff0000, v22
	v_and_b32_e32 v29, 0xffff0000, v10
	v_pk_mul_f32 v[20:21], v[28:29], v[20:21]
	v_lshlrev_b32_e32 v22, 16, v11
	v_cvt_pk_bf16_f32 v10, v20, v21
	v_lshlrev_b32_e32 v20, 16, v23
	v_and_b32_e32 v21, 0xffff0000, v23
	v_and_b32_e32 v23, 0xffff0000, v11
	v_pk_mul_f32 v[20:21], v[22:23], v[20:21]
	s_waitcnt vmcnt(1)
	v_lshlrev_b32_e32 v22, 16, v16
	v_cvt_pk_bf16_f32 v11, v20, v21
	v_lshl_add_u64 v[20:21], v[6:7], 0, v[0:1]
	global_store_dwordx4 v[20:21], v[8:11], off sc1
	v_lshlrev_b32_e32 v0, 11, v34
	v_lshl_add_u64 v[20:21], v[6:7], 0, v[0:1]
	s_waitcnt lgkmcnt(0)
	v_lshlrev_b32_e32 v8, 16, v24
	v_and_b32_e32 v9, 0xffff0000, v24
	v_lshlrev_b32_e32 v10, 16, v12
	v_and_b32_e32 v11, 0xffff0000, v12
	v_pk_mul_f32 v[8:9], v[10:11], v[8:9]
	v_lshlrev_b32_e32 v10, 16, v25
	v_and_b32_e32 v11, 0xffff0000, v25
	v_lshlrev_b32_e32 v12, 16, v13
	v_and_b32_e32 v13, 0xffff0000, v13
	v_pk_mul_f32 v[10:11], v[12:13], v[10:11]
	v_cvt_pk_bf16_f32 v8, v8, v9
	v_cvt_pk_bf16_f32 v9, v10, v11
	v_lshlrev_b32_e32 v10, 16, v26
	v_and_b32_e32 v11, 0xffff0000, v26
	v_lshlrev_b32_e32 v12, 16, v14
	v_and_b32_e32 v13, 0xffff0000, v14
	v_pk_mul_f32 v[10:11], v[12:13], v[10:11]
	v_lshlrev_b32_e32 v12, 16, v27
	v_and_b32_e32 v13, 0xffff0000, v27
	v_lshlrev_b32_e32 v14, 16, v15
	v_and_b32_e32 v15, 0xffff0000, v15
	v_pk_mul_f32 v[12:13], v[14:15], v[12:13]
	v_or_b32_e32 v0, 16, v32
	v_cvt_pk_bf16_f32 v10, v10, v11
	v_cvt_pk_bf16_f32 v11, v12, v13
	v_lshl_add_u32 v12, v0, 7, v33
	ds_read_b128 v[12:15], v12 offset:51200
	v_or_b32_e32 v24, 24, v32
	global_store_dwordx4 v[20:21], v[8:11], off sc1
	v_and_b32_e32 v23, 0xffff0000, v16
	v_lshlrev_b32_e32 v16, 16, v17
	v_lshl_add_u32 v8, v24, 7, v33
	ds_read_b128 v[8:11], v8 offset:51200
	s_waitcnt lgkmcnt(1)
	v_lshlrev_b32_e32 v20, 16, v12
	v_and_b32_e32 v21, 0xffff0000, v12
	v_pk_mul_f32 v[20:21], v[22:23], v[20:21]
	v_and_b32_e32 v17, 0xffff0000, v17
	v_cvt_pk_bf16_f32 v12, v20, v21
	v_lshlrev_b32_e32 v20, 16, v13
	v_and_b32_e32 v21, 0xffff0000, v13
	v_pk_mul_f32 v[16:17], v[16:17], v[20:21]
	v_lshlrev_b32_e32 v20, 16, v18
	v_cvt_pk_bf16_f32 v13, v16, v17
	v_lshlrev_b32_e32 v16, 16, v14
	v_and_b32_e32 v17, 0xffff0000, v14
	v_and_b32_e32 v21, 0xffff0000, v18
	v_pk_mul_f32 v[16:17], v[20:21], v[16:17]
	v_lshlrev_b32_e32 v18, 16, v19
	v_cvt_pk_bf16_f32 v14, v16, v17
	v_lshlrev_b32_e32 v16, 16, v15
	v_and_b32_e32 v17, 0xffff0000, v15
	v_and_b32_e32 v19, 0xffff0000, v19
	v_pk_mul_f32 v[16:17], v[18:19], v[16:17]
	v_lshlrev_b32_e32 v0, 11, v0
	v_cvt_pk_bf16_f32 v15, v16, v17
	v_lshl_add_u64 v[16:17], v[6:7], 0, v[0:1]
	global_store_dwordx4 v[16:17], v[12:15], off sc1
	v_lshlrev_b32_e32 v0, 11, v24
	v_lshl_add_u64 v[6:7], v[6:7], 0, v[0:1]
	s_waitcnt lgkmcnt(0)
	v_lshlrev_b32_e32 v12, 16, v8
	v_and_b32_e32 v13, 0xffff0000, v8
	s_waitcnt vmcnt(3)
	v_lshlrev_b32_e32 v14, 16, v2
	v_and_b32_e32 v15, 0xffff0000, v2
	v_pk_mul_f32 v[12:13], v[14:15], v[12:13]
	v_lshlrev_b32_e32 v8, 16, v9
	v_cvt_pk_bf16_f32 v2, v12, v13
	v_and_b32_e32 v9, 0xffff0000, v9
	v_lshlrev_b32_e32 v12, 16, v3
	v_and_b32_e32 v13, 0xffff0000, v3
	v_pk_mul_f32 v[8:9], v[12:13], v[8:9]
	v_lshlrev_b32_e32 v12, 16, v4
	v_cvt_pk_bf16_f32 v3, v8, v9
	v_lshlrev_b32_e32 v8, 16, v10
	v_and_b32_e32 v9, 0xffff0000, v10
	v_and_b32_e32 v13, 0xffff0000, v4
	v_pk_mul_f32 v[8:9], v[12:13], v[8:9]
	v_lshlrev_b32_e32 v10, 16, v5
	v_cvt_pk_bf16_f32 v4, v8, v9
	v_lshlrev_b32_e32 v8, 16, v11
	v_and_b32_e32 v9, 0xffff0000, v11
	v_and_b32_e32 v11, 0xffff0000, v5
	v_pk_mul_f32 v[8:9], v[10:11], v[8:9]
	s_nop 0
	v_cvt_pk_bf16_f32 v5, v8, v9
	global_store_dwordx4 v[6:7], v[2:5], off sc1
	s_waitcnt vmcnt(0) lgkmcnt(0)
	s_barrier

; __device__ __forceinline__ unsigned cvt_pk_bf16(float lo, float hi) { unsigned r; asm volatile("v_cvt_pk_bf16_f32 %0, %1, %2" : "=v"(r) : "v"(lo), "v"(hi)); return r; }
; #define LAS __attribute__((address_space(3)))
; template <int PASS>
; __device__ __forceinline__ void lru_unit(const LruPtrs& args, LAS unsigned char* lds, int chunk, int bl, int g, int ck) {
;     ...
;         LAS bf16* GT = (LAS bf16*)(lds + RING_OFF + 32768 + w * 4864);
; #pragma unroll
;         for (int i = 0; i < 4; ++i) { const int idx = lane + 64 * i, r = idx >> 3, ch = idx & 7;
;             *(LAS v2u*)(GT + r * 68 + ch * 8) = (v2u){gtile[i].x, gtile[i].y}; *(LAS v2u*)(GT + r * 68 + ch * 8 + 4) = (v2u){gtile[i].z, gtile[i].w}; }
;         asm volatile("s_waitcnt lgkmcnt(0)" ::: "memory");
; #pragma unroll
;         for (int q = 0; q < 8; ++q) { const f32x4 cr = *(const LAS f32x4*)(CARW + w * 64 + 8 * q + 4 * hi);
;             LAS v2u* gl = (LAS v2u*)(GT + n * 68 + 8 * q + 4 * hi);
;             const v2u gw = *gl;
;             const float h0 = (uv[q][0] + av[q][0] * cr[0]) * pg8::bf_lo(gw.x), h1 = (uv[q][1] + av[q][1] * cr[1]) * pg8::bf_hi(gw.x);
;             const float h2 = (uv[q][2] + av[q][2] * cr[2]) * pg8::bf_lo(gw.y), h3 = (uv[q][3] + av[q][3] * cr[3]) * pg8::bf_hi(gw.y);
;             v2u o; o.x = pg8::cvt_pk_bf16(h0, h1); o.y = pg8::cvt_pk_bf16(h2, h3); *gl = o; }
.LBB0_556:
	s_mulk_i32 s14, 0x1300
	v_and_b32_e32 v59, 0xffff0000, v5
	v_lshlrev_b32_e32 v60, 16, v5
	s_add_i32 s6, s14, 0
	v_mul_u32_u24_e32 v5, 0x88, v69
	v_add3_u32 v0, s6, v0, v5
	v_lshrrev_b32_e32 v58, 3, v68
	v_and_b32_e32 v61, 0xffff0000, v4
	v_lshlrev_b32_e32 v62, 16, v4
	v_and_b32_e32 v4, 31, v68
	v_add_u32_e32 v68, 0x8000, v0
	s_waitcnt lgkmcnt(0)
	s_barrier
	ds_write2_b64 v68, v[30:31], v[32:33] offset1:1
	v_add_u32_e32 v32, 0x8440, v0
	v_add_u32_e32 v33, 0x8880, v0
	v_add_u32_e32 v0, 0x8cc0, v0
	s_lshl_b32 s7, s15, 2
	v_and_b32_e32 v58, 4, v58
	ds_write2_b64 v32, v[34:35], v[36:37] offset1:1
	ds_write2_b64 v33, v[42:43], v[44:45] offset1:1
	ds_write2_b64 v0, v[46:47], v[48:49] offset1:1
	s_add_i32 s7, s7, 0
	s_waitcnt lgkmcnt(0)
	v_lshl_add_u32 v34, v58, 2, s7
	v_mul_u32_u24_e32 v4, 0x88, v4
	v_lshlrev_b32_e32 v5, 1, v58
	v_and_b32_e32 v64, 0xffff0000, v9
	v_lshlrev_b32_e32 v65, 16, v9
	v_and_b32_e32 v66, 0xffff0000, v8
	v_lshlrev_b32_e32 v67, 16, v8
	v_and_b32_e32 v8, 0xffff0000, v13
	v_lshlrev_b32_e32 v9, 16, v13
	v_and_b32_e32 v71, 0xffff0000, v12
	v_lshlrev_b32_e32 v72, 16, v12
	v_and_b32_e32 v12, 0xffff0000, v17
	v_lshlrev_b32_e32 v13, 16, v17
	v_and_b32_e32 v74, 0xffff0000, v16
	v_lshlrev_b32_e32 v75, 16, v16
	v_and_b32_e32 v16, 0xffff0000, v21
	v_lshlrev_b32_e32 v17, 16, v21
	v_and_b32_e32 v77, 0xffff0000, v20
	v_lshlrev_b32_e32 v78, 16, v20
	v_and_b32_e32 v20, 0xffff0000, v25
	v_lshlrev_b32_e32 v21, 16, v25
	v_and_b32_e32 v80, 0xffff0000, v24
	v_lshlrev_b32_e32 v81, 16, v24
	v_and_b32_e32 v24, 0xffff0000, v29
	v_lshlrev_b32_e32 v25, 16, v29
	v_and_b32_e32 v83, 0xffff0000, v28
	v_lshlrev_b32_e32 v84, 16, v28
	v_add3_u32 v35, s6, v4, v5
	ds_read_b128 v[28:31], v34 offset:8192
	ds_read_b64 v[4:5], v35 offset:32768
	v_and_b32_e32 v86, 0xffff0000, v41
	v_lshlrev_b32_e32 v41, 16, v41
	v_and_b32_e32 v88, 0xffff0000, v39
	v_lshlrev_b32_e32 v36, 16, v39
	v_and_b32_e32 v37, 0xffff0000, v38
	v_lshlrev_b32_e32 v38, 16, v38
	v_and_b32_e32 v87, 0xffff0000, v40
	v_lshlrev_b32_e32 v40, 16, v40
	s_waitcnt lgkmcnt(1)
	v_fmac_f32_e32 v37, v28, v38
	s_waitcnt lgkmcnt(0)
	v_lshlrev_b32_e32 v28, 16, v4
	v_fmac_f32_e32 v88, v29, v36
	v_and_b32_e32 v4, 0xffff0000, v4
	v_lshlrev_b32_e32 v29, 16, v5
	v_fmac_f32_e32 v86, v31, v41
	v_and_b32_e32 v5, 0xffff0000, v5
	v_mul_f32_e32 v4, v88, v4
	v_fmac_f32_e32 v87, v30, v40
	v_mul_f32_e32 v5, v86, v5
	v_mul_f32_e32 v28, v37, v28
	v_mul_f32_e32 v29, v87, v29
	v_cvt_pk_bf16_f32 v4, v28, v4
	v_cvt_pk_bf16_f32 v5, v29, v5
	ds_write_b64 v35, v[4:5] offset:32768
	ds_read_b128 v[28:31], v34 offset:8224
	ds_read_b64 v[4:5], v35 offset:32784
	v_and_b32_e32 v85, 0xffff0000, v27
	v_lshlrev_b32_e32 v27, 16, v27
	v_and_b32_e32 v36, 0xffff0000, v26
	v_lshlrev_b32_e32 v26, 16, v26
	s_waitcnt lgkmcnt(1)
	v_fmac_f32_e32 v36, v28, v26
	s_waitcnt lgkmcnt(0)
	v_lshlrev_b32_e32 v26, 16, v4
	v_fmac_f32_e32 v85, v29, v27
	v_and_b32_e32 v4, 0xffff0000, v4
	v_lshlrev_b32_e32 v27, 16, v5
	v_fmac_f32_e32 v24, v31, v25
	v_and_b32_e32 v5, 0xffff0000, v5
	v_mul_f32_e32 v4, v85, v4
	v_fmac_f32_e32 v83, v30, v84
	v_mul_f32_e32 v5, v24, v5
	v_mul_f32_e32 v26, v36, v26
	v_mul_f32_e32 v27, v83, v27
	v_cvt_pk_bf16_f32 v4, v26, v4
	v_cvt_pk_bf16_f32 v5, v27, v5
	ds_write_b64 v35, v[4:5] offset:32784
	ds_read_b128 v[24:27], v34 offset:8256
	ds_read_b64 v[4:5], v35 offset:32800
	v_and_b32_e32 v82, 0xffff0000, v23
	v_lshlrev_b32_e32 v23, 16, v23
	v_and_b32_e32 v28, 0xffff0000, v22
	v_lshlrev_b32_e32 v22, 16, v22
	s_waitcnt lgkmcnt(1)
	v_fmac_f32_e32 v28, v24, v22
	s_waitcnt lgkmcnt(0)
	v_lshlrev_b32_e32 v22, 16, v4
	v_fmac_f32_e32 v82, v25, v23
	v_and_b32_e32 v4, 0xffff0000, v4
	v_lshlrev_b32_e32 v23, 16, v5
	v_fmac_f32_e32 v20, v27, v21
	v_and_b32_e32 v5, 0xffff0000, v5
	v_mul_f32_e32 v4, v82, v4
	v_fmac_f32_e32 v80, v26, v81
	v_mul_f32_e32 v5, v20, v5
	v_mul_f32_e32 v22, v28, v22
	v_mul_f32_e32 v23, v80, v23
	v_cvt_pk_bf16_f32 v4, v22, v4
	v_cvt_pk_bf16_f32 v5, v23, v5
	ds_write_b64 v35, v[4:5] offset:32800
	ds_read_b128 v[20:23], v34 offset:8288
	ds_read_b64 v[4:5], v35 offset:32816
	v_and_b32_e32 v79, 0xffff0000, v19
	v_lshlrev_b32_e32 v19, 16, v19
	v_and_b32_e32 v24, 0xffff0000, v18
	v_lshlrev_b32_e32 v18, 16, v18
	s_waitcnt lgkmcnt(1)
; __device__ __forceinline__ unsigned cvt_pk_bf16(float lo, float hi) { unsigned r; asm volatile("v_cvt_pk_bf16_f32 %0, %1, %2" : "=v"(r) : "v"(lo), "v"(hi)); return r; }
; #define GAS __attribute__((address_space(1)))
; #define LAS __attribute__((address_space(3)))
; template <int PASS>
; __device__ __forceinline__ void lru_unit(const LruPtrs& args, LAS unsigned char* lds, int chunk, int bl, int g, int ck) {
;     ...
;         for (int q = 0; q < 8; ++q) { const f32x4 cr = *(const LAS f32x4*)(CARW + w * 64 + 8 * q + 4 * hi);
;             LAS v2u* gl = (LAS v2u*)(GT + n * 68 + 8 * q + 4 * hi);
;             const v2u gw = *gl;
;             const float h0 = (uv[q][0] + av[q][0] * cr[0]) * pg8::bf_lo(gw.x), h1 = (uv[q][1] + av[q][1] * cr[1]) * pg8::bf_hi(gw.x);
;             const float h2 = (uv[q][2] + av[q][2] * cr[2]) * pg8::bf_lo(gw.y), h3 = (uv[q][3] + av[q][3] * cr[3]) * pg8::bf_hi(gw.y);
;             v2u o; o.x = pg8::cvt_pk_bf16(h0, h1); o.y = pg8::cvt_pk_bf16(h2, h3); *gl = o; }
;         asm volatile("s_waitcnt lgkmcnt(0)" ::: "memory");
; #pragma unroll
;         for (int i = 0; i < 4; ++i) { const int idx = lane + 64 * i, r = idx >> 3, ch = idx & 7;
;             const v2u a = *(const LAS v2u*)(GT + r * 68 + ch * 8), b = *(const LAS v2u*)(GT + r * 68 + ch * 8 + 4);
;             *(GAS v4u*)(Z + ((size_t)bl * T + ck * 256 + w * 32 + r) * LDZ + ZC_GA + g * 64 + ch * 8) = (v4u){a.x, a.y, b.x, b.y}; }
;         __syncthreads();
	v_fmac_f32_e32 v24, v20, v18
	s_waitcnt lgkmcnt(0)
	v_lshlrev_b32_e32 v18, 16, v4
	v_fmac_f32_e32 v79, v21, v19
	v_and_b32_e32 v4, 0xffff0000, v4
	v_lshlrev_b32_e32 v19, 16, v5
	v_fmac_f32_e32 v16, v23, v17
	v_and_b32_e32 v5, 0xffff0000, v5
	v_mul_f32_e32 v4, v79, v4
	v_fmac_f32_e32 v77, v22, v78
	v_mul_f32_e32 v5, v16, v5
	v_mul_f32_e32 v18, v24, v18
	v_mul_f32_e32 v19, v77, v19
	v_cvt_pk_bf16_f32 v4, v18, v4
	v_cvt_pk_bf16_f32 v5, v19, v5
	ds_write_b64 v35, v[4:5] offset:32816
	ds_read_b128 v[16:19], v34 offset:8320
	ds_read_b64 v[4:5], v35 offset:32832
	v_and_b32_e32 v76, 0xffff0000, v15
	v_lshlrev_b32_e32 v15, 16, v15
	v_and_b32_e32 v20, 0xffff0000, v14
	v_lshlrev_b32_e32 v14, 16, v14
	s_waitcnt lgkmcnt(1)
	v_fmac_f32_e32 v20, v16, v14
	s_waitcnt lgkmcnt(0)
	v_lshlrev_b32_e32 v14, 16, v4
	v_fmac_f32_e32 v76, v17, v15
	v_and_b32_e32 v4, 0xffff0000, v4
	v_lshlrev_b32_e32 v15, 16, v5
	v_fmac_f32_e32 v12, v19, v13
	v_and_b32_e32 v5, 0xffff0000, v5
	v_mul_f32_e32 v4, v76, v4
	v_fmac_f32_e32 v74, v18, v75
	v_mul_f32_e32 v5, v12, v5
	v_mul_f32_e32 v14, v20, v14
	v_mul_f32_e32 v15, v74, v15
	v_cvt_pk_bf16_f32 v4, v14, v4
	v_cvt_pk_bf16_f32 v5, v15, v5
	ds_write_b64 v35, v[4:5] offset:32832
	ds_read_b128 v[12:15], v34 offset:8352
	ds_read_b64 v[4:5], v35 offset:32848
	v_and_b32_e32 v73, 0xffff0000, v11
	v_lshlrev_b32_e32 v11, 16, v11
	v_and_b32_e32 v16, 0xffff0000, v10
	v_lshlrev_b32_e32 v10, 16, v10
	s_waitcnt lgkmcnt(1)
	v_fmac_f32_e32 v16, v12, v10
	s_waitcnt lgkmcnt(0)
	v_lshlrev_b32_e32 v10, 16, v4
	v_fmac_f32_e32 v73, v13, v11
	v_and_b32_e32 v4, 0xffff0000, v4
	v_lshlrev_b32_e32 v11, 16, v5
	v_fmac_f32_e32 v8, v15, v9
	v_and_b32_e32 v5, 0xffff0000, v5
	v_mul_f32_e32 v4, v73, v4
	v_fmac_f32_e32 v71, v14, v72
	v_mul_f32_e32 v5, v8, v5
	v_mul_f32_e32 v10, v16, v10
	v_mul_f32_e32 v11, v71, v11
	v_cvt_pk_bf16_f32 v4, v10, v4
	v_cvt_pk_bf16_f32 v5, v11, v5
	ds_write_b64 v35, v[4:5] offset:32848
	ds_read_b128 v[8:11], v34 offset:8384
	ds_read_b64 v[4:5], v35 offset:32864
	v_and_b32_e32 v70, 0xffff0000, v7
	v_lshlrev_b32_e32 v7, 16, v7
	v_and_b32_e32 v12, 0xffff0000, v6
	v_lshlrev_b32_e32 v6, 16, v6
	s_waitcnt lgkmcnt(1)
	v_fmac_f32_e32 v12, v8, v6
	s_waitcnt lgkmcnt(0)
	v_lshlrev_b32_e32 v6, 16, v4
	v_fmac_f32_e32 v70, v9, v7
	v_and_b32_e32 v4, 0xffff0000, v4
	v_lshlrev_b32_e32 v7, 16, v5
	v_fmac_f32_e32 v64, v11, v65
	v_and_b32_e32 v5, 0xffff0000, v5
	v_mul_f32_e32 v4, v70, v4
	v_fmac_f32_e32 v66, v10, v67
	v_mul_f32_e32 v5, v64, v5
	v_mul_f32_e32 v6, v12, v6
	v_mul_f32_e32 v7, v66, v7
	v_cvt_pk_bf16_f32 v4, v6, v4
	v_cvt_pk_bf16_f32 v5, v7, v5
	ds_write_b64 v35, v[4:5] offset:32864
	ds_read_b128 v[4:7], v34 offset:8416
	ds_read_b64 v[8:9], v35 offset:32880
	v_and_b32_e32 v63, 0xffff0000, v3
	v_lshlrev_b32_e32 v3, 16, v3
	v_and_b32_e32 v10, 0xffff0000, v2
	v_lshlrev_b32_e32 v2, 16, v2
	s_waitcnt lgkmcnt(1)
	v_fmac_f32_e32 v10, v4, v2
	s_waitcnt lgkmcnt(0)
	v_lshlrev_b32_e32 v2, 16, v8
	v_fmac_f32_e32 v63, v5, v3
	v_and_b32_e32 v3, 0xffff0000, v8
	v_mul_f32_e32 v2, v10, v2
	v_mul_f32_e32 v3, v63, v3
	v_fmac_f32_e32 v61, v6, v62
	v_lshlrev_b32_e32 v4, 16, v9
	v_fmac_f32_e32 v59, v7, v60
	v_and_b32_e32 v5, 0xffff0000, v9
	v_mul_f32_e32 v4, v61, v4
	v_mul_f32_e32 v5, v59, v5
	v_cvt_pk_bf16_f32 v2, v2, v3
	v_cvt_pk_bf16_f32 v3, v4, v5
	ds_write_b64 v35, v[2:3] offset:32880
	s_waitcnt lgkmcnt(0)
	ds_read2_b64 v[2:5], v68 offset1:1
	ds_read2_b64 v[6:9], v32 offset1:1
	ds_read2_b64 v[10:13], v33 offset1:1
	ds_read2_b64 v[14:17], v0 offset1:1
	v_lshl_add_u64 v[52:53], v[52:53], 0, s[34:35]
	v_lshl_add_u64 v[54:55], v[54:55], 0, s[34:35]
	v_lshl_add_u64 v[56:57], v[56:57], 0, s[34:35]
	v_lshl_add_u64 v[18:19], v[50:51], 0, s[34:35]
	s_waitcnt lgkmcnt(3)
	global_store_dwordx4 v[52:53], v[2:5], off sc1
	s_waitcnt lgkmcnt(2)
	global_store_dwordx4 v[54:55], v[6:9], off sc1
	s_waitcnt lgkmcnt(1)
	global_store_dwordx4 v[56:57], v[10:13], off sc1
	s_waitcnt lgkmcnt(0)
	global_store_dwordx4 v[18:19], v[14:17], off sc1
	s_barrier
	s_mov_b64 s[6:7], 0

; __device__ __forceinline__ u32x4 pack8(const f32x4 v0, const f32x4 v1) { u32x4 w; w.x = cvt_pk_bf16(v0[0], v0[1]); w.y = cvt_pk_bf16(v0[2], v0[3]); w.z = cvt_pk_bf16(v1[0], v1[1]); w.w = cvt_pk_bf16(v1[2], v1[3]); return w; }
; __device__ __forceinline__ void unpack8(const u32x4 w, f32x4& v0, f32x4& v1) { v0[0] = bf_lo(w.x); v0[1] = bf_hi(w.x); v0[2] = bf_lo(w.y); v0[3] = bf_hi(w.y); v1[0] = bf_lo(w.z); v1[1] = bf_hi(w.z); v1[2] = bf_lo(w.w); v1[3] = bf_hi(w.w); }
;     __device__ __forceinline__ void operator()(f32x4 (&acc)[2][2][4][2], const Unit& u, int wr, int wc, int fr, int fq) const {
;     ...
;         const size_t lo = (size_t)(wr * 64 + fr) * LDZ + wc * 32 + 8 * fq;
; #pragma unroll
;         for (int ai = 0; ai < 2; ++ai) {
;             u32x4 gw[4][2];
; #pragma unroll
;             for (int m = 0; m < 4; ++m)
; #pragma unroll
;                 for (int bj = 0; bj < 2; ++bj) gw[m][bj] = *(const u32x4*)(u.G + lo + (size_t)(ai * HALF + m * 16) * LDZ + bj * HALF);
; #pragma unroll
;             for (int m = 0; m < 4; ++m)
; #pragma unroll
;                 for (int bj = 0; bj < 2; ++bj) { f32x4 g0, g1; unpack8(gw[m][bj], g0, g1);
;                     *(u32x4*)(u.O + lo + (size_t)(ai * HALF + m * 16) * LDZ + bj * HALF) = pack8(acc[ai][bj][m][0] * g0, acc[ai][bj][m][1] * g1); }
.LBB0_701:
	v_mov_b32_e32 v116, v175
	v_mov_b32_e32 v114, v174
	v_mov_b64_e32 v[234:235], v[200:201]
	v_add_u32_e32 v114, s54, v114
	v_lshlrev_b32_e32 v116, 3, v116
	v_ashrrev_i32_e32 v115, 31, v114
	v_ashrrev_i32_e32 v117, 31, v116
	v_lshlrev_b64 v[114:115], 10, v[114:115]
	v_lshl_add_u64 v[116:117], v[116:117], 0, s[18:19]
	v_lshl_add_u64 v[114:115], v[116:117], 0, v[114:115]
	v_lshlrev_b64 v[114:115], 1, v[114:115]
	v_lshl_add_u64 v[170:171], s[44:45], 0, v[114:115]
	global_load_dwordx4 v[154:157], v[170:171], off
	global_load_dwordx4 v[150:153], v[170:171], off offset:256
	v_add_co_u32_e32 v116, vcc, s79, v170
	v_lshl_add_u64 v[168:169], s[42:43], 0, v[114:115]
	s_nop 0
	v_addc_co_u32_e32 v117, vcc, 0, v171, vcc
	global_load_dwordx4 v[146:149], v[116:117], off
	global_load_dwordx4 v[118:121], v[116:117], off offset:256
	v_add_co_u32_e32 v138, vcc, s27, v170
	v_mov_b64_e32 v[200:201], v[230:231]
	s_nop 0
	v_addc_co_u32_e32 v139, vcc, 0, v171, vcc
	global_load_dwordx4 v[114:117], v[138:139], off
	v_add_co_u32_e32 v140, vcc, s78, v170
	s_waitcnt vmcnt(0)
	v_lshlrev_b32_e32 v178, 16, v154
	v_addc_co_u32_e32 v141, vcc, 0, v171, vcc
	global_load_dwordx4 v[158:161], v[138:139], off offset:256
	global_load_dwordx4 v[142:145], v[140:141], off
	s_nop 0
	global_load_dwordx4 v[138:141], v[140:141], off offset:256
	v_and_b32_e32 v179, 0xffff0000, v154
	v_lshlrev_b32_e32 v154, 16, v155
	v_and_b32_e32 v155, 0xffff0000, v155
	v_lshlrev_b32_e32 v180, 16, v156
	v_and_b32_e32 v181, 0xffff0000, v156
	v_lshlrev_b32_e32 v156, 16, v157
	v_and_b32_e32 v157, 0xffff0000, v157
	v_lshlrev_b32_e32 v182, 16, v150
	v_and_b32_e32 v183, 0xffff0000, v150
	v_lshlrev_b32_e32 v150, 16, v151
	v_and_b32_e32 v151, 0xffff0000, v151
	v_pk_mul_f32 v[124:125], v[124:125], v[154:155]
	v_pk_mul_f32 v[122:123], v[122:123], v[178:179]
	v_pk_mul_f32 v[128:129], v[128:129], v[156:157]
	v_pk_mul_f32 v[132:133], v[132:133], v[150:151]
	v_lshlrev_b32_e32 v150, 16, v146
	v_and_b32_e32 v151, 0xffff0000, v146
	v_add_co_u32_e32 v172, vcc, s79, v168
	v_lshlrev_b32_e32 v184, 16, v152
	v_and_b32_e32 v185, 0xffff0000, v152
	v_lshlrev_b32_e32 v152, 16, v153
	v_and_b32_e32 v153, 0xffff0000, v153
	v_pk_mul_f32 v[126:127], v[126:127], v[180:181]
	v_pk_mul_f32 v[130:131], v[130:131], v[182:183]
	v_lshlrev_b32_e32 v146, 16, v147
	v_and_b32_e32 v147, 0xffff0000, v147
	v_cvt_pk_bf16_f32 v122, v122, v123
	v_cvt_pk_bf16_f32 v123, v124, v125
	v_cvt_pk_bf16_f32 v124, v126, v127
	v_cvt_pk_bf16_f32 v125, v128, v129
	v_pk_mul_f32 v[128:129], v[106:107], v[150:151]
	global_store_dwordx4 v[168:169], v[122:125], off sc1
	v_cvt_pk_bf16_f32 v106, v130, v131
	v_cvt_pk_bf16_f32 v107, v132, v133
	v_addc_co_u32_e32 v173, vcc, 0, v169, vcc
	v_pk_mul_f32 v[136:137], v[136:137], v[152:153]
	v_pk_mul_f32 v[134:135], v[134:135], v[184:185]
	v_lshlrev_b32_e32 v152, 16, v148
	v_and_b32_e32 v153, 0xffff0000, v148
	v_lshlrev_b32_e32 v148, 16, v149
	v_and_b32_e32 v149, 0xffff0000, v149
	v_pk_mul_f32 v[126:127], v[108:109], v[146:147]
	v_cvt_pk_bf16_f32 v108, v134, v135
	v_cvt_pk_bf16_f32 v109, v136, v137
	global_store_dwordx4 v[168:169], v[106:109], off offset:256 sc1
	v_lshlrev_b32_e32 v154, 16, v118
	v_and_b32_e32 v155, 0xffff0000, v118
	v_cvt_pk_bf16_f32 v106, v128, v129
	v_cvt_pk_bf16_f32 v107, v126, v127
	v_lshlrev_b32_e32 v118, 16, v119
	v_and_b32_e32 v119, 0xffff0000, v119
	v_lshlrev_b32_e32 v156, 16, v120
	v_and_b32_e32 v157, 0xffff0000, v120
	v_pk_mul_f32 v[112:113], v[112:113], v[148:149]
	v_pk_mul_f32 v[110:111], v[110:111], v[152:153]
	v_pk_mul_f32 v[104:105], v[104:105], v[118:119]
	v_cvt_pk_bf16_f32 v108, v110, v111
	v_cvt_pk_bf16_f32 v109, v112, v113
	global_store_dwordx4 v[172:173], v[106:109], off sc1
	v_pk_mul_f32 v[102:103], v[102:103], v[154:155]
	s_nop 0
	v_lshlrev_b32_e32 v106, 16, v121
	v_and_b32_e32 v107, 0xffff0000, v121
	v_pk_mul_f32 v[106:107], v[100:101], v[106:107]
	v_pk_mul_f32 v[100:101], v[98:99], v[156:157]
	v_cvt_pk_bf16_f32 v98, v102, v103
	v_cvt_pk_bf16_f32 v99, v104, v105
	v_lshlrev_b32_e32 v102, 16, v116
	v_cvt_pk_bf16_f32 v100, v100, v101
	v_cvt_pk_bf16_f32 v101, v106, v107
	global_store_dwordx4 v[172:173], v[98:101], off offset:256 sc1
	v_and_b32_e32 v103, 0xffff0000, v116
	v_lshlrev_b32_e32 v104, 16, v117
	v_lshlrev_b32_e32 v98, 16, v114
	v_and_b32_e32 v99, 0xffff0000, v114
	v_and_b32_e32 v105, 0xffff0000, v117
	v_pk_mul_f32 v[94:95], v[94:95], v[98:99]
	v_lshlrev_b32_e32 v100, 16, v115
	v_and_b32_e32 v101, 0xffff0000, v115
	v_pk_mul_f32 v[98:99], v[92:93], v[104:105]
	v_pk_mul_f32 v[92:93], v[90:91], v[102:103]
	v_cvt_pk_bf16_f32 v90, v94, v95
	v_add_co_u32_e32 v94, vcc, s27, v168
	v_pk_mul_f32 v[96:97], v[96:97], v[100:101]
	s_nop 0
	v_addc_co_u32_e32 v95, vcc, 0, v169, vcc
	v_cvt_pk_bf16_f32 v91, v96, v97
	v_cvt_pk_bf16_f32 v92, v92, v93
	v_cvt_pk_bf16_f32 v93, v98, v99
	global_store_dwordx4 v[94:95], v[90:93], off sc1
	s_waitcnt vmcnt(7)
	v_lshlrev_b32_e32 v96, 16, v160
	v_and_b32_e32 v97, 0xffff0000, v160
	v_lshlrev_b32_e32 v90, 16, v158
	v_and_b32_e32 v91, 0xffff0000, v158
	v_lshlrev_b32_e32 v92, 16, v159
	v_and_b32_e32 v93, 0xffff0000, v159
	v_lshlrev_b32_e32 v98, 16, v161
	v_and_b32_e32 v99, 0xffff0000, v161
	v_pk_mul_f32 v[88:89], v[88:89], v[92:93]
	v_pk_mul_f32 v[86:87], v[86:87], v[90:91]
	v_pk_mul_f32 v[90:91], v[84:85], v[98:99]
	v_pk_mul_f32 v[84:85], v[82:83], v[96:97]
	v_cvt_pk_bf16_f32 v82, v86, v87
	v_cvt_pk_bf16_f32 v83, v88, v89
	s_waitcnt vmcnt(6)
; __device__ __forceinline__ u32x4 pack8(const f32x4 v0, const f32x4 v1) { u32x4 w; w.x = cvt_pk_bf16(v0[0], v0[1]); w.y = cvt_pk_bf16(v0[2], v0[3]); w.z = cvt_pk_bf16(v1[0], v1[1]); w.w = cvt_pk_bf16(v1[2], v1[3]); return w; }
; __device__ __forceinline__ void unpack8(const u32x4 w, f32x4& v0, f32x4& v1) { v0[0] = bf_lo(w.x); v0[1] = bf_hi(w.x); v0[2] = bf_lo(w.y); v0[3] = bf_hi(w.y); v1[0] = bf_lo(w.z); v1[1] = bf_hi(w.z); v1[2] = bf_lo(w.w); v1[3] = bf_hi(w.w); }
;     __device__ __forceinline__ void operator()(f32x4 (&acc)[2][2][4][2], const Unit& u, int wr, int wc, int fr, int fq) const {
;     ...
;         const size_t lo = (size_t)(wr * 64 + fr) * LDZ + wc * 32 + 8 * fq;
; #pragma unroll
;         for (int ai = 0; ai < 2; ++ai) {
;             u32x4 gw[4][2];
; #pragma unroll
;             for (int m = 0; m < 4; ++m)
; #pragma unroll
;                 for (int bj = 0; bj < 2; ++bj) gw[m][bj] = *(const u32x4*)(u.G + lo + (size_t)(ai * HALF + m * 16) * LDZ + bj * HALF);
; #pragma unroll
;             for (int m = 0; m < 4; ++m)
; #pragma unroll
;                 for (int bj = 0; bj < 2; ++bj) { f32x4 g0, g1; unpack8(gw[m][bj], g0, g1);
;                     *(u32x4*)(u.O + lo + (size_t)(ai * HALF + m * 16) * LDZ + bj * HALF) = pack8(acc[ai][bj][m][0] * g0, acc[ai][bj][m][1] * g1); }
	v_lshlrev_b32_e32 v86, 16, v144
	v_cvt_pk_bf16_f32 v84, v84, v85
	v_cvt_pk_bf16_f32 v85, v90, v91
	global_store_dwordx4 v[94:95], v[82:85], off offset:256 sc1
	v_and_b32_e32 v87, 0xffff0000, v144
	v_lshlrev_b32_e32 v88, 16, v145
	v_lshlrev_b32_e32 v82, 16, v142
	v_and_b32_e32 v83, 0xffff0000, v142
	v_and_b32_e32 v89, 0xffff0000, v145
	v_pk_mul_f32 v[78:79], v[78:79], v[82:83]
	v_lshlrev_b32_e32 v84, 16, v143
	v_and_b32_e32 v85, 0xffff0000, v143
	v_pk_mul_f32 v[82:83], v[76:77], v[88:89]
	v_pk_mul_f32 v[76:77], v[74:75], v[86:87]
	v_cvt_pk_bf16_f32 v74, v78, v79
	v_add_co_u32_e32 v78, vcc, s78, v168
	v_pk_mul_f32 v[80:81], v[80:81], v[84:85]
	s_nop 0
	v_addc_co_u32_e32 v79, vcc, 0, v169, vcc
	v_cvt_pk_bf16_f32 v75, v80, v81
	v_cvt_pk_bf16_f32 v76, v76, v77
	v_cvt_pk_bf16_f32 v77, v82, v83
	global_store_dwordx4 v[78:79], v[74:77], off sc1
	s_waitcnt vmcnt(7)
	v_lshlrev_b32_e32 v80, 16, v140
	v_and_b32_e32 v81, 0xffff0000, v140
	v_lshlrev_b32_e32 v74, 16, v138
	v_and_b32_e32 v75, 0xffff0000, v138
	v_lshlrev_b32_e32 v82, 16, v141
	v_and_b32_e32 v83, 0xffff0000, v141
	v_lshlrev_b32_e32 v76, 16, v139
	v_and_b32_e32 v77, 0xffff0000, v139
	v_pk_mul_f32 v[70:71], v[70:71], v[74:75]
	v_pk_mul_f32 v[74:75], v[68:69], v[82:83]
	v_pk_mul_f32 v[68:69], v[66:67], v[80:81]
	v_cvt_pk_bf16_f32 v66, v70, v71
	v_pk_mul_f32 v[72:73], v[72:73], v[76:77]
	s_nop 0
	v_cvt_pk_bf16_f32 v67, v72, v73
	v_cvt_pk_bf16_f32 v68, v68, v69
	v_cvt_pk_bf16_f32 v69, v74, v75
	global_store_dwordx4 v[78:79], v[66:69], off offset:256 sc1
	s_nop 1
	v_add_co_u32_e32 v66, vcc, s80, v170
	s_nop 1
	v_addc_co_u32_e32 v67, vcc, 0, v171, vcc
	global_load_dwordx4 v[74:77], v[66:67], off
	global_load_dwordx4 v[78:81], v[66:67], off offset:256
	v_add_co_u32_e32 v66, vcc, s81, v170
	s_waitcnt vmcnt(1)
	v_lshlrev_b32_e32 v98, 16, v74
	v_addc_co_u32_e32 v67, vcc, 0, v171, vcc
	global_load_dwordx4 v[82:85], v[66:67], off
	global_load_dwordx4 v[86:89], v[66:67], off offset:256
	v_add_co_u32_e32 v66, vcc, s82, v170
	v_and_b32_e32 v99, 0xffff0000, v74
	s_nop 0
	v_addc_co_u32_e32 v67, vcc, 0, v171, vcc
	global_load_dwordx4 v[90:93], v[66:67], off
	global_load_dwordx4 v[94:97], v[66:67], off offset:256
	v_add_co_u32_e32 v66, vcc, s83, v170
	v_lshlrev_b32_e32 v74, 16, v75
	s_nop 0
	v_addc_co_u32_e32 v67, vcc, 0, v171, vcc
	global_load_dwordx4 v[70:73], v[66:67], off
	s_nop 0
	global_load_dwordx4 v[66:69], v[66:67], off offset:256
	v_and_b32_e32 v75, 0xffff0000, v75
	v_lshlrev_b32_e32 v100, 16, v76
	v_and_b32_e32 v101, 0xffff0000, v76
	v_lshlrev_b32_e32 v76, 16, v77
	v_and_b32_e32 v77, 0xffff0000, v77
	v_pk_mul_f32 v[62:63], v[62:63], v[98:99]
	v_pk_mul_f32 v[64:65], v[64:65], v[74:75]
	v_pk_mul_f32 v[74:75], v[60:61], v[76:77]
	v_pk_mul_f32 v[60:61], v[58:59], v[100:101]
	v_cvt_pk_bf16_f32 v58, v62, v63
	v_add_co_u32_e32 v62, vcc, s80, v168
	v_cvt_pk_bf16_f32 v59, v64, v65
	v_cvt_pk_bf16_f32 v60, v60, v61
	v_cvt_pk_bf16_f32 v61, v74, v75
	s_waitcnt vmcnt(6)
	v_lshlrev_b32_e32 v64, 16, v80
	v_addc_co_u32_e32 v63, vcc, 0, v169, vcc
	global_store_dwordx4 v[62:63], v[58:61], off sc1
	v_and_b32_e32 v65, 0xffff0000, v80
	v_lshlrev_b32_e32 v74, 16, v81
	v_lshlrev_b32_e32 v58, 16, v78
	v_and_b32_e32 v59, 0xffff0000, v78
	v_lshlrev_b32_e32 v60, 16, v79
	v_and_b32_e32 v61, 0xffff0000, v79
	v_and_b32_e32 v75, 0xffff0000, v81
	v_pk_mul_f32 v[56:57], v[56:57], v[60:61]
	v_pk_mul_f32 v[54:55], v[54:55], v[58:59]
	v_pk_mul_f32 v[58:59], v[52:53], v[74:75]
	v_pk_mul_f32 v[52:53], v[50:51], v[64:65]
	v_cvt_pk_bf16_f32 v50, v54, v55
	v_cvt_pk_bf16_f32 v51, v56, v57
	s_waitcnt vmcnt(6)
	v_lshlrev_b32_e32 v54, 16, v84
	v_cvt_pk_bf16_f32 v52, v52, v53
	v_cvt_pk_bf16_f32 v53, v58, v59
	global_store_dwordx4 v[62:63], v[50:53], off offset:256 sc1
	v_and_b32_e32 v55, 0xffff0000, v84
	v_lshlrev_b32_e32 v56, 16, v85
	v_lshlrev_b32_e32 v50, 16, v82
	v_and_b32_e32 v51, 0xffff0000, v82
	v_and_b32_e32 v57, 0xffff0000, v85
	v_pk_mul_f32 v[46:47], v[46:47], v[50:51]
	v_lshlrev_b32_e32 v52, 16, v83
	v_and_b32_e32 v53, 0xffff0000, v83
	v_pk_mul_f32 v[50:51], v[44:45], v[56:57]
	v_pk_mul_f32 v[44:45], v[42:43], v[54:55]
	v_cvt_pk_bf16_f32 v42, v46, v47
	v_add_co_u32_e32 v46, vcc, s81, v168
	v_pk_mul_f32 v[48:49], v[48:49], v[52:53]
	s_nop 0
	v_addc_co_u32_e32 v47, vcc, 0, v169, vcc
	v_cvt_pk_bf16_f32 v43, v48, v49
	v_cvt_pk_bf16_f32 v44, v44, v45
	v_cvt_pk_bf16_f32 v45, v50, v51
	global_store_dwordx4 v[46:47], v[42:45], off sc1
	s_waitcnt vmcnt(7)
; __device__ __forceinline__ u32x4 pack8(const f32x4 v0, const f32x4 v1) { u32x4 w; w.x = cvt_pk_bf16(v0[0], v0[1]); w.y = cvt_pk_bf16(v0[2], v0[3]); w.z = cvt_pk_bf16(v1[0], v1[1]); w.w = cvt_pk_bf16(v1[2], v1[3]); return w; }
; __device__ __forceinline__ void unpack8(const u32x4 w, f32x4& v0, f32x4& v1) { v0[0] = bf_lo(w.x); v0[1] = bf_hi(w.x); v0[2] = bf_lo(w.y); v0[3] = bf_hi(w.y); v1[0] = bf_lo(w.z); v1[1] = bf_hi(w.z); v1[2] = bf_lo(w.w); v1[3] = bf_hi(w.w); }
;     __device__ __forceinline__ void operator()(f32x4 (&acc)[2][2][4][2], const Unit& u, int wr, int wc, int fr, int fq) const {
;     ...
;         const size_t lo = (size_t)(wr * 64 + fr) * LDZ + wc * 32 + 8 * fq;
; #pragma unroll
;         for (int ai = 0; ai < 2; ++ai) {
;             u32x4 gw[4][2];
; #pragma unroll
;             for (int m = 0; m < 4; ++m)
; #pragma unroll
;                 for (int bj = 0; bj < 2; ++bj) gw[m][bj] = *(const u32x4*)(u.G + lo + (size_t)(ai * HALF + m * 16) * LDZ + bj * HALF);
; #pragma unroll
;             for (int m = 0; m < 4; ++m)
; #pragma unroll
;                 for (int bj = 0; bj < 2; ++bj) { f32x4 g0, g1; unpack8(gw[m][bj], g0, g1);
;                     *(u32x4*)(u.O + lo + (size_t)(ai * HALF + m * 16) * LDZ + bj * HALF) = pack8(acc[ai][bj][m][0] * g0, acc[ai][bj][m][1] * g1); }
	v_lshlrev_b32_e32 v48, 16, v88
	v_and_b32_e32 v49, 0xffff0000, v88
	v_lshlrev_b32_e32 v42, 16, v86
	v_and_b32_e32 v43, 0xffff0000, v86
	v_lshlrev_b32_e32 v44, 16, v87
	v_and_b32_e32 v45, 0xffff0000, v87
	v_lshlrev_b32_e32 v50, 16, v89
	v_and_b32_e32 v51, 0xffff0000, v89
	v_pk_mul_f32 v[40:41], v[40:41], v[44:45]
	v_pk_mul_f32 v[38:39], v[38:39], v[42:43]
	v_pk_mul_f32 v[42:43], v[36:37], v[50:51]
	v_pk_mul_f32 v[36:37], v[34:35], v[48:49]
	v_cvt_pk_bf16_f32 v34, v38, v39
	v_cvt_pk_bf16_f32 v35, v40, v41
	s_waitcnt vmcnt(6)
	v_lshlrev_b32_e32 v38, 16, v92
	v_cvt_pk_bf16_f32 v36, v36, v37
	v_cvt_pk_bf16_f32 v37, v42, v43
	global_store_dwordx4 v[46:47], v[34:37], off offset:256 sc1
	v_and_b32_e32 v39, 0xffff0000, v92
	v_lshlrev_b32_e32 v40, 16, v93
	v_lshlrev_b32_e32 v34, 16, v90
	v_and_b32_e32 v35, 0xffff0000, v90
	v_and_b32_e32 v41, 0xffff0000, v93
	v_pk_mul_f32 v[30:31], v[30:31], v[34:35]
	v_lshlrev_b32_e32 v36, 16, v91
	v_and_b32_e32 v37, 0xffff0000, v91
	v_pk_mul_f32 v[34:35], v[28:29], v[40:41]
	v_pk_mul_f32 v[28:29], v[26:27], v[38:39]
	v_cvt_pk_bf16_f32 v26, v30, v31
	v_add_co_u32_e32 v30, vcc, s82, v168
	v_pk_mul_f32 v[32:33], v[32:33], v[36:37]
	s_nop 0
	v_addc_co_u32_e32 v31, vcc, 0, v169, vcc
	v_cvt_pk_bf16_f32 v27, v32, v33
	v_cvt_pk_bf16_f32 v28, v28, v29
	v_cvt_pk_bf16_f32 v29, v34, v35
	global_store_dwordx4 v[30:31], v[26:29], off sc1
	s_waitcnt vmcnt(7)
	v_lshlrev_b32_e32 v32, 16, v96
	v_and_b32_e32 v33, 0xffff0000, v96
	v_lshlrev_b32_e32 v26, 16, v94
	v_and_b32_e32 v27, 0xffff0000, v94
	v_lshlrev_b32_e32 v28, 16, v95
	v_and_b32_e32 v29, 0xffff0000, v95
	v_lshlrev_b32_e32 v34, 16, v97
	v_and_b32_e32 v35, 0xffff0000, v97
	v_pk_mul_f32 v[24:25], v[24:25], v[28:29]
	v_pk_mul_f32 v[22:23], v[22:23], v[26:27]
	v_pk_mul_f32 v[26:27], v[20:21], v[34:35]
	v_pk_mul_f32 v[20:21], v[18:19], v[32:33]
	v_cvt_pk_bf16_f32 v18, v22, v23
	v_cvt_pk_bf16_f32 v19, v24, v25
	s_waitcnt vmcnt(6)
	v_lshlrev_b32_e32 v22, 16, v72
	v_cvt_pk_bf16_f32 v20, v20, v21
	v_cvt_pk_bf16_f32 v21, v26, v27
	global_store_dwordx4 v[30:31], v[18:21], off offset:256 sc1
	v_and_b32_e32 v23, 0xffff0000, v72
	v_lshlrev_b32_e32 v24, 16, v73
	v_lshlrev_b32_e32 v18, 16, v70
	v_and_b32_e32 v19, 0xffff0000, v70
	v_and_b32_e32 v25, 0xffff0000, v73
	v_pk_mul_f32 v[14:15], v[14:15], v[18:19]
	v_lshlrev_b32_e32 v20, 16, v71
	v_and_b32_e32 v21, 0xffff0000, v71
	v_pk_mul_f32 v[18:19], v[12:13], v[24:25]
	v_pk_mul_f32 v[12:13], v[10:11], v[22:23]
	v_cvt_pk_bf16_f32 v10, v14, v15
	v_add_co_u32_e32 v14, vcc, s83, v168
	v_pk_mul_f32 v[16:17], v[16:17], v[20:21]
	s_nop 0
	v_addc_co_u32_e32 v15, vcc, 0, v169, vcc
	v_cvt_pk_bf16_f32 v11, v16, v17
	v_cvt_pk_bf16_f32 v12, v12, v13
	v_cvt_pk_bf16_f32 v13, v18, v19
	global_store_dwordx4 v[14:15], v[10:13], off sc1
	s_waitcnt vmcnt(7)
	v_lshlrev_b32_e32 v16, 16, v68
	v_and_b32_e32 v17, 0xffff0000, v68
	v_lshlrev_b32_e32 v10, 16, v66
	v_and_b32_e32 v11, 0xffff0000, v66
	v_lshlrev_b32_e32 v18, 16, v69
	v_and_b32_e32 v19, 0xffff0000, v69
	v_lshlrev_b32_e32 v12, 16, v67
	v_and_b32_e32 v13, 0xffff0000, v67
	v_pk_mul_f32 v[6:7], v[6:7], v[10:11]
	v_pk_mul_f32 v[10:11], v[4:5], v[18:19]
	v_pk_mul_f32 v[4:5], v[2:3], v[16:17]
	s_andn2_b64 vcc, exec, s[40:41]
	s_mov_b64 s[40:41], -1
	v_pk_mul_f32 v[8:9], v[8:9], v[12:13]
	v_cvt_pk_bf16_f32 v2, v6, v7
	s_nop 0
	v_cvt_pk_bf16_f32 v3, v8, v9
	v_cvt_pk_bf16_f32 v4, v4, v5
	v_cvt_pk_bf16_f32 v5, v10, v11
	global_store_dwordx4 v[14:15], v[2:5], off offset:256 sc1
	s_cbranch_vccnz .LBB0_696
	s_andn2_b64 vcc, exec, s[6:7]
	s_cbranch_vccnz .LBB0_695
	s_barrier
	s_branch .LBB0_695

; __device__ __forceinline__ unsigned xb_add(unsigned* p, unsigned v) { return __hip_atomic_fetch_add(p, v, __ATOMIC_RELAXED, __HIP_MEMORY_SCOPE_AGENT); }
; __device__ __forceinline__ void xcd_barrier(const XcdBarrier& b) {
;     ...
;         const unsigned old = xb_add(&bar[XB_XSUB(b.x)], 1u);
;         const unsigned gen = old / nloc;
;         if (old + 1u == (gen + 1u) * nloc) {
;             __builtin_amdgcn_fence(__ATOMIC_RELEASE, "agent");
;             asm volatile("s_waitcnt vmcnt(0)" ::: "memory");
;             const unsigned og = xb_add(&bar[XB_TOP], 1u);
.LBB0_737:
	s_andn2_saveexec_b64 s[14:15], s[14:15]
	s_cbranch_execz .LBB0_757
	s_mov_b64 s[14:15], exec
	s_waitcnt lgkmcnt(0)
	s_waitcnt vmcnt(0)
	buffer_inv sc1
	v_mbcnt_lo_u32_b32 v2, s14, 0
	v_mbcnt_hi_u32_b32 v2, s15, v2
	v_cmp_eq_u32_e32 vcc, 0, v2
	s_and_saveexec_b64 s[38:39], vcc
	s_cbranch_execz .LBB0_740
	s_bcnt1_i32_b64 s2, s[14:15]
	v_mov_b32_e32 v3, s2
	v_mov_b32_e32 v4, 0x7000
	global_atomic_add v3, v4, v3, s[8:9] offset:1024 sc0

; __device__ __forceinline__ u32x4 pack8(const f32x4 v0, const f32x4 v1) { u32x4 w; w.x = cvt_pk_bf16(v0[0], v0[1]); w.y = cvt_pk_bf16(v0[2], v0[3]); w.z = cvt_pk_bf16(v1[0], v1[1]); w.w = cvt_pk_bf16(v1[2], v1[3]); return w; }
; __device__ __forceinline__ void unpack8(const u32x4 w, f32x4& v0, f32x4& v1) { v0[0] = bf_lo(w.x); v0[1] = bf_hi(w.x); v0[2] = bf_lo(w.y); v0[3] = bf_hi(w.y); v1[0] = bf_lo(w.z); v1[1] = bf_hi(w.z); v1[2] = bf_lo(w.w); v1[3] = bf_hi(w.w); }
;     __device__ __forceinline__ void operator()(f32x4 (&acc)[2][2][4][2], const Unit& u, int wr, int wc, int fr, int fq) const {
;     ...
;             for (int m = 0; m < 4; ++m)
; #pragma unroll
;                 for (int bj = 0; bj < 2; ++bj) { f32x4 g0, g1; unpack8(gw[m][bj], g0, g1);
;                     if (last) { *(u32x4*)(u.O + lo + (size_t)(ai * HALF + m * 16) * u.ldo + bj * HALF) = pack8(acc[ai][bj][m][0] * g0, acc[ai][bj][m][1] * g1); }
;                     else { f32x4 h0, h1; unpack8(hw[m][bj], h0, h1);
; #pragma unroll
;                         for (int e = 0; e < 4; ++e) { acc[ai][bj][m][0][e] *= g0[e] * __builtin_amdgcn_rcpf(fmaxf(h0[e], 1e-20f)); acc[ai][bj][m][1][e] *= g1[e] * __builtin_amdgcn_rcpf(fmaxf(h1[e], 1e-20f)); } } }
.LBB0_797:
	v_lshlrev_b64 v[186:187], 10, v[218:219]
	s_andn2_b64 vcc, exec, s[50:51]
	v_lshl_add_u64 v[218:219], v[186:187], 1, s[46:47]
	s_cbranch_vccnz .LBB0_799
	v_pk_mul_f32 v[188:189], v[128:129], v[226:227]
	v_pk_mul_f32 v[186:187], v[126:127], v[222:223]
	v_pk_mul_f32 v[190:191], v[124:125], v[228:229]
	v_pk_mul_f32 v[192:193], v[122:123], v[224:225]
	v_cvt_pk_bf16_f32 v186, v186, v187
	v_cvt_pk_bf16_f32 v187, v188, v189
	v_mov_b32_e32 v214, v124
	v_cvt_pk_bf16_f32 v188, v192, v193
	v_cvt_pk_bf16_f32 v189, v190, v191
	v_lshl_add_u64 v[190:191], v[218:219], 0, s[18:19]
	v_lshl_add_u64 v[190:191], v[216:217], 1, v[190:191]
	global_store_dwordx4 v[190:191], v[186:189], off sc1
	v_mov_b32_e32 v192, v122
	v_mov_b32_e32 v193, v123
	v_mov_b32_e32 v215, v125
	v_mov_b32_e32 v190, v126
	v_mov_b32_e32 v191, v127
	v_mov_b32_e32 v212, v128
	v_mov_b32_e32 v213, v129

; __device__ __forceinline__ u32x4 pack8(const f32x4 v0, const f32x4 v1) { u32x4 w; w.x = cvt_pk_bf16(v0[0], v0[1]); w.y = cvt_pk_bf16(v0[2], v0[3]); w.z = cvt_pk_bf16(v1[0], v1[1]); w.w = cvt_pk_bf16(v1[2], v1[3]); return w; }
; __device__ __forceinline__ void unpack8(const u32x4 w, f32x4& v0, f32x4& v1) { v0[0] = bf_lo(w.x); v0[1] = bf_hi(w.x); v0[2] = bf_lo(w.y); v0[3] = bf_hi(w.y); v1[0] = bf_lo(w.z); v1[1] = bf_hi(w.z); v1[2] = bf_lo(w.w); v1[3] = bf_hi(w.w); }
;     __device__ __forceinline__ void operator()(f32x4 (&acc)[2][2][4][2], const Unit& u, int wr, int wc, int fr, int fq) const {
;     ...
;             for (int m = 0; m < 4; ++m)
; #pragma unroll
;                 for (int bj = 0; bj < 2; ++bj) { f32x4 g0, g1; unpack8(gw[m][bj], g0, g1);
;                     if (last) { *(u32x4*)(u.O + lo + (size_t)(ai * HALF + m * 16) * u.ldo + bj * HALF) = pack8(acc[ai][bj][m][0] * g0, acc[ai][bj][m][1] * g1); }
;                     else { f32x4 h0, h1; unpack8(hw[m][bj], h0, h1);
; #pragma unroll
;                         for (int e = 0; e < 4; ++e) { acc[ai][bj][m][0][e] *= g0[e] * __builtin_amdgcn_rcpf(fmaxf(h0[e], 1e-20f)); acc[ai][bj][m][1][e] *= g1[e] * __builtin_amdgcn_rcpf(fmaxf(h1[e], 1e-20f)); } } }
.LBB0_801:
	s_andn2_b64 vcc, exec, s[46:47]
	s_cbranch_vccnz .LBB0_803
	v_pk_mul_f32 v[126:127], v[120:121], v[126:127]
	v_pk_mul_f32 v[122:123], v[118:119], v[122:123]
	v_pk_mul_f32 v[124:125], v[114:115], v[124:125]
	v_cvt_pk_bf16_f32 v122, v122, v123
	v_cvt_pk_bf16_f32 v123, v126, v127
	v_lshl_add_u64 v[126:127], v[218:219], 0, s[18:19]
	v_lshl_add_u64 v[126:127], v[216:217], 1, v[126:127]
	v_mov_b32_e32 v184, v114
	v_mov_b32_e32 v185, v115
	v_mov_b32_e32 v188, v116
	v_mov_b32_e32 v189, v117
	v_mov_b32_e32 v182, v118
	v_mov_b32_e32 v183, v119
	v_mov_b32_e32 v186, v120
	v_mov_b32_e32 v187, v121
	v_pk_mul_f32 v[128:129], v[116:117], v[128:129]
	v_cvt_pk_bf16_f32 v124, v124, v125
	s_nop 0
	v_cvt_pk_bf16_f32 v125, v128, v129
	global_store_dwordx4 v[126:127], v[122:125], off offset:256 sc1

; __device__ __forceinline__ u32x4 pack8(const f32x4 v0, const f32x4 v1) { u32x4 w; w.x = cvt_pk_bf16(v0[0], v0[1]); w.y = cvt_pk_bf16(v0[2], v0[3]); w.z = cvt_pk_bf16(v1[0], v1[1]); w.w = cvt_pk_bf16(v1[2], v1[3]); return w; }
; __device__ __forceinline__ void unpack8(const u32x4 w, f32x4& v0, f32x4& v1) { v0[0] = bf_lo(w.x); v0[1] = bf_hi(w.x); v0[2] = bf_lo(w.y); v0[3] = bf_hi(w.y); v1[0] = bf_lo(w.z); v1[1] = bf_hi(w.z); v1[2] = bf_lo(w.w); v1[3] = bf_hi(w.w); }
;     __device__ __forceinline__ void operator()(f32x4 (&acc)[2][2][4][2], const Unit& u, int wr, int wc, int fr, int fq) const {
;     ...
;             for (int m = 0; m < 4; ++m)
; #pragma unroll
;                 for (int bj = 0; bj < 2; ++bj) { f32x4 g0, g1; unpack8(gw[m][bj], g0, g1);
;                     if (last) { *(u32x4*)(u.O + lo + (size_t)(ai * HALF + m * 16) * u.ldo + bj * HALF) = pack8(acc[ai][bj][m][0] * g0, acc[ai][bj][m][1] * g1); }
;                     else { f32x4 h0, h1; unpack8(hw[m][bj], h0, h1);
; #pragma unroll
;                         for (int e = 0; e < 4; ++e) { acc[ai][bj][m][0][e] *= g0[e] * __builtin_amdgcn_rcpf(fmaxf(h0[e], 1e-20f)); acc[ai][bj][m][1][e] *= g1[e] * __builtin_amdgcn_rcpf(fmaxf(h1[e], 1e-20f)); } } }
.LBB0_805:
	s_andn2_b64 vcc, exec, s[46:47]
	s_cbranch_vccnz .LBB0_807
	v_pk_mul_f32 v[118:119], v[112:113], v[118:119]
	v_pk_mul_f32 v[114:115], v[110:111], v[114:115]
	v_pk_mul_f32 v[116:117], v[106:107], v[116:117]
	v_cvt_pk_bf16_f32 v114, v114, v115
	v_cvt_pk_bf16_f32 v115, v118, v119
	v_lshl_add_u64 v[118:119], v[218:219], 0, s[18:19]
	v_lshl_add_u64 v[118:119], v[216:217], 1, v[118:119]
	v_add_co_u32_e32 v118, vcc, 0x8000, v118
	v_mov_b32_e32 v176, v106
	s_nop 0
	v_addc_co_u32_e32 v119, vcc, 0, v119, vcc
	v_mov_b32_e32 v177, v107
	v_mov_b32_e32 v180, v108
	v_mov_b32_e32 v181, v109
	v_mov_b32_e32 v174, v110
	v_mov_b32_e32 v175, v111
	v_mov_b32_e32 v178, v112
	v_mov_b32_e32 v179, v113
	v_pk_mul_f32 v[120:121], v[108:109], v[120:121]
	v_cvt_pk_bf16_f32 v116, v116, v117
	s_nop 0
	v_cvt_pk_bf16_f32 v117, v120, v121
	global_store_dwordx4 v[118:119], v[114:117], off sc1

; __device__ __forceinline__ u32x4 pack8(const f32x4 v0, const f32x4 v1) { u32x4 w; w.x = cvt_pk_bf16(v0[0], v0[1]); w.y = cvt_pk_bf16(v0[2], v0[3]); w.z = cvt_pk_bf16(v1[0], v1[1]); w.w = cvt_pk_bf16(v1[2], v1[3]); return w; }
; __device__ __forceinline__ void unpack8(const u32x4 w, f32x4& v0, f32x4& v1) { v0[0] = bf_lo(w.x); v0[1] = bf_hi(w.x); v0[2] = bf_lo(w.y); v0[3] = bf_hi(w.y); v1[0] = bf_lo(w.z); v1[1] = bf_hi(w.z); v1[2] = bf_lo(w.w); v1[3] = bf_hi(w.w); }
;     __device__ __forceinline__ void operator()(f32x4 (&acc)[2][2][4][2], const Unit& u, int wr, int wc, int fr, int fq) const {
;     ...
;             for (int m = 0; m < 4; ++m)
; #pragma unroll
;                 for (int bj = 0; bj < 2; ++bj) { f32x4 g0, g1; unpack8(gw[m][bj], g0, g1);
;                     if (last) { *(u32x4*)(u.O + lo + (size_t)(ai * HALF + m * 16) * u.ldo + bj * HALF) = pack8(acc[ai][bj][m][0] * g0, acc[ai][bj][m][1] * g1); }
;                     else { f32x4 h0, h1; unpack8(hw[m][bj], h0, h1);
; #pragma unroll
;                         for (int e = 0; e < 4; ++e) { acc[ai][bj][m][0][e] *= g0[e] * __builtin_amdgcn_rcpf(fmaxf(h0[e], 1e-20f)); acc[ai][bj][m][1][e] *= g1[e] * __builtin_amdgcn_rcpf(fmaxf(h1[e], 1e-20f)); } } }
.LBB0_809:
	s_andn2_b64 vcc, exec, s[46:47]
	s_cbranch_vccnz .LBB0_811
	v_pk_mul_f32 v[110:111], v[104:105], v[110:111]
	v_pk_mul_f32 v[106:107], v[102:103], v[106:107]
	v_pk_mul_f32 v[108:109], v[98:99], v[108:109]
	v_cvt_pk_bf16_f32 v106, v106, v107
	v_cvt_pk_bf16_f32 v107, v110, v111
	v_lshl_add_u64 v[110:111], v[218:219], 0, s[18:19]
	v_lshl_add_u64 v[110:111], v[216:217], 1, v[110:111]
	v_add_co_u32_e32 v110, vcc, 0x8000, v110
	v_mov_b32_e32 v168, v98
	s_nop 0
	v_addc_co_u32_e32 v111, vcc, 0, v111, vcc
	v_mov_b32_e32 v169, v99
	v_mov_b32_e32 v172, v100
	v_mov_b32_e32 v173, v101
	v_mov_b32_e32 v166, v102
	v_mov_b32_e32 v167, v103
	v_mov_b32_e32 v170, v104
	v_mov_b32_e32 v171, v105
	v_pk_mul_f32 v[112:113], v[100:101], v[112:113]
	v_cvt_pk_bf16_f32 v108, v108, v109
	s_nop 0
	v_cvt_pk_bf16_f32 v109, v112, v113
	global_store_dwordx4 v[110:111], v[106:109], off offset:256 sc1

; __device__ __forceinline__ u32x4 pack8(const f32x4 v0, const f32x4 v1) { u32x4 w; w.x = cvt_pk_bf16(v0[0], v0[1]); w.y = cvt_pk_bf16(v0[2], v0[3]); w.z = cvt_pk_bf16(v1[0], v1[1]); w.w = cvt_pk_bf16(v1[2], v1[3]); return w; }
; __device__ __forceinline__ void unpack8(const u32x4 w, f32x4& v0, f32x4& v1) { v0[0] = bf_lo(w.x); v0[1] = bf_hi(w.x); v0[2] = bf_lo(w.y); v0[3] = bf_hi(w.y); v1[0] = bf_lo(w.z); v1[1] = bf_hi(w.z); v1[2] = bf_lo(w.w); v1[3] = bf_hi(w.w); }
;     __device__ __forceinline__ void operator()(f32x4 (&acc)[2][2][4][2], const Unit& u, int wr, int wc, int fr, int fq) const {
;     ...
;             for (int m = 0; m < 4; ++m)
; #pragma unroll
;                 for (int bj = 0; bj < 2; ++bj) { f32x4 g0, g1; unpack8(gw[m][bj], g0, g1);
;                     if (last) { *(u32x4*)(u.O + lo + (size_t)(ai * HALF + m * 16) * u.ldo + bj * HALF) = pack8(acc[ai][bj][m][0] * g0, acc[ai][bj][m][1] * g1); }
;                     else { f32x4 h0, h1; unpack8(hw[m][bj], h0, h1);
; #pragma unroll
;                         for (int e = 0; e < 4; ++e) { acc[ai][bj][m][0][e] *= g0[e] * __builtin_amdgcn_rcpf(fmaxf(h0[e], 1e-20f)); acc[ai][bj][m][1][e] *= g1[e] * __builtin_amdgcn_rcpf(fmaxf(h1[e], 1e-20f)); } } }
.LBB0_813:
	s_andn2_b64 vcc, exec, s[46:47]
	s_cbranch_vccnz .LBB0_815
	v_pk_mul_f32 v[102:103], v[96:97], v[102:103]
	v_pk_mul_f32 v[98:99], v[94:95], v[98:99]
	v_pk_mul_f32 v[100:101], v[90:91], v[100:101]
	v_cvt_pk_bf16_f32 v98, v98, v99
	v_cvt_pk_bf16_f32 v99, v102, v103
	v_lshl_add_u64 v[102:103], v[218:219], 0, s[18:19]
	v_lshl_add_u64 v[102:103], v[216:217], 1, v[102:103]
	v_add_co_u32_e32 v102, vcc, 0x10000, v102
	v_mov_b32_e32 v160, v90
	s_nop 0
	v_addc_co_u32_e32 v103, vcc, 0, v103, vcc
	v_mov_b32_e32 v161, v91
	v_mov_b32_e32 v164, v92
	v_mov_b32_e32 v165, v93
	v_mov_b32_e32 v158, v94
	v_mov_b32_e32 v159, v95
	v_mov_b32_e32 v162, v96
	v_mov_b32_e32 v163, v97
	v_pk_mul_f32 v[104:105], v[92:93], v[104:105]
	v_cvt_pk_bf16_f32 v100, v100, v101
	s_nop 0
	v_cvt_pk_bf16_f32 v101, v104, v105
	global_store_dwordx4 v[102:103], v[98:101], off sc1

; __device__ __forceinline__ u32x4 pack8(const f32x4 v0, const f32x4 v1) { u32x4 w; w.x = cvt_pk_bf16(v0[0], v0[1]); w.y = cvt_pk_bf16(v0[2], v0[3]); w.z = cvt_pk_bf16(v1[0], v1[1]); w.w = cvt_pk_bf16(v1[2], v1[3]); return w; }
; __device__ __forceinline__ void unpack8(const u32x4 w, f32x4& v0, f32x4& v1) { v0[0] = bf_lo(w.x); v0[1] = bf_hi(w.x); v0[2] = bf_lo(w.y); v0[3] = bf_hi(w.y); v1[0] = bf_lo(w.z); v1[1] = bf_hi(w.z); v1[2] = bf_lo(w.w); v1[3] = bf_hi(w.w); }
;     __device__ __forceinline__ void operator()(f32x4 (&acc)[2][2][4][2], const Unit& u, int wr, int wc, int fr, int fq) const {
;     ...
;             for (int m = 0; m < 4; ++m)
; #pragma unroll
;                 for (int bj = 0; bj < 2; ++bj) { f32x4 g0, g1; unpack8(gw[m][bj], g0, g1);
;                     if (last) { *(u32x4*)(u.O + lo + (size_t)(ai * HALF + m * 16) * u.ldo + bj * HALF) = pack8(acc[ai][bj][m][0] * g0, acc[ai][bj][m][1] * g1); }
;                     else { f32x4 h0, h1; unpack8(hw[m][bj], h0, h1);
; #pragma unroll
;                         for (int e = 0; e < 4; ++e) { acc[ai][bj][m][0][e] *= g0[e] * __builtin_amdgcn_rcpf(fmaxf(h0[e], 1e-20f)); acc[ai][bj][m][1][e] *= g1[e] * __builtin_amdgcn_rcpf(fmaxf(h1[e], 1e-20f)); } } }
.LBB0_817:
	s_andn2_b64 vcc, exec, s[46:47]
	s_cbranch_vccnz .LBB0_819
	v_pk_mul_f32 v[94:95], v[88:89], v[94:95]
	v_pk_mul_f32 v[90:91], v[86:87], v[90:91]
	v_pk_mul_f32 v[92:93], v[82:83], v[92:93]
	v_cvt_pk_bf16_f32 v90, v90, v91
	v_cvt_pk_bf16_f32 v91, v94, v95
	v_lshl_add_u64 v[94:95], v[218:219], 0, s[18:19]
	v_lshl_add_u64 v[94:95], v[216:217], 1, v[94:95]
	v_add_co_u32_e32 v94, vcc, 0x10000, v94
	v_mov_b32_e32 v152, v82
	s_nop 0
	v_addc_co_u32_e32 v95, vcc, 0, v95, vcc
	v_mov_b32_e32 v153, v83
	v_mov_b32_e32 v156, v84
	v_mov_b32_e32 v157, v85
	v_mov_b32_e32 v150, v86
	v_mov_b32_e32 v151, v87
	v_mov_b32_e32 v154, v88
	v_mov_b32_e32 v155, v89
	v_pk_mul_f32 v[96:97], v[84:85], v[96:97]
	v_cvt_pk_bf16_f32 v92, v92, v93
	s_nop 0
	v_cvt_pk_bf16_f32 v93, v96, v97
	global_store_dwordx4 v[94:95], v[90:93], off offset:256 sc1

; __device__ __forceinline__ u32x4 pack8(const f32x4 v0, const f32x4 v1) { u32x4 w; w.x = cvt_pk_bf16(v0[0], v0[1]); w.y = cvt_pk_bf16(v0[2], v0[3]); w.z = cvt_pk_bf16(v1[0], v1[1]); w.w = cvt_pk_bf16(v1[2], v1[3]); return w; }
; __device__ __forceinline__ void unpack8(const u32x4 w, f32x4& v0, f32x4& v1) { v0[0] = bf_lo(w.x); v0[1] = bf_hi(w.x); v0[2] = bf_lo(w.y); v0[3] = bf_hi(w.y); v1[0] = bf_lo(w.z); v1[1] = bf_hi(w.z); v1[2] = bf_lo(w.w); v1[3] = bf_hi(w.w); }
;     __device__ __forceinline__ void operator()(f32x4 (&acc)[2][2][4][2], const Unit& u, int wr, int wc, int fr, int fq) const {
;     ...
;             for (int m = 0; m < 4; ++m)
; #pragma unroll
;                 for (int bj = 0; bj < 2; ++bj) { f32x4 g0, g1; unpack8(gw[m][bj], g0, g1);
;                     if (last) { *(u32x4*)(u.O + lo + (size_t)(ai * HALF + m * 16) * u.ldo + bj * HALF) = pack8(acc[ai][bj][m][0] * g0, acc[ai][bj][m][1] * g1); }
;                     else { f32x4 h0, h1; unpack8(hw[m][bj], h0, h1);
; #pragma unroll
;                         for (int e = 0; e < 4; ++e) { acc[ai][bj][m][0][e] *= g0[e] * __builtin_amdgcn_rcpf(fmaxf(h0[e], 1e-20f)); acc[ai][bj][m][1][e] *= g1[e] * __builtin_amdgcn_rcpf(fmaxf(h1[e], 1e-20f)); } } }
.LBB0_821:
	s_andn2_b64 vcc, exec, s[46:47]
	s_cbranch_vccnz .LBB0_823
	v_pk_mul_f32 v[86:87], v[80:81], v[86:87]
	v_pk_mul_f32 v[82:83], v[78:79], v[82:83]
	v_pk_mul_f32 v[84:85], v[74:75], v[84:85]
	v_cvt_pk_bf16_f32 v82, v82, v83
	v_cvt_pk_bf16_f32 v83, v86, v87
	v_lshl_add_u64 v[86:87], v[218:219], 0, s[18:19]
	v_lshl_add_u64 v[86:87], v[216:217], 1, v[86:87]
	v_add_co_u32_e32 v86, vcc, 0x18000, v86
	v_mov_b32_e32 v144, v74
	s_nop 0
	v_addc_co_u32_e32 v87, vcc, 0, v87, vcc
	v_mov_b32_e32 v145, v75
	v_mov_b32_e32 v148, v76
	v_mov_b32_e32 v149, v77
	v_mov_b32_e32 v142, v78
	v_mov_b32_e32 v143, v79
	v_mov_b32_e32 v146, v80
	v_mov_b32_e32 v147, v81
	v_pk_mul_f32 v[88:89], v[76:77], v[88:89]
	v_cvt_pk_bf16_f32 v84, v84, v85
	s_nop 0
	v_cvt_pk_bf16_f32 v85, v88, v89
	global_store_dwordx4 v[86:87], v[82:85], off sc1

; __device__ __forceinline__ u32x4 pack8(const f32x4 v0, const f32x4 v1) { u32x4 w; w.x = cvt_pk_bf16(v0[0], v0[1]); w.y = cvt_pk_bf16(v0[2], v0[3]); w.z = cvt_pk_bf16(v1[0], v1[1]); w.w = cvt_pk_bf16(v1[2], v1[3]); return w; }
; __device__ __forceinline__ void unpack8(const u32x4 w, f32x4& v0, f32x4& v1) { v0[0] = bf_lo(w.x); v0[1] = bf_hi(w.x); v0[2] = bf_lo(w.y); v0[3] = bf_hi(w.y); v1[0] = bf_lo(w.z); v1[1] = bf_hi(w.z); v1[2] = bf_lo(w.w); v1[3] = bf_hi(w.w); }
;     __device__ __forceinline__ void operator()(f32x4 (&acc)[2][2][4][2], const Unit& u, int wr, int wc, int fr, int fq) const {
;     ...
;             for (int m = 0; m < 4; ++m)
; #pragma unroll
;                 for (int bj = 0; bj < 2; ++bj) { f32x4 g0, g1; unpack8(gw[m][bj], g0, g1);
;                     if (last) { *(u32x4*)(u.O + lo + (size_t)(ai * HALF + m * 16) * u.ldo + bj * HALF) = pack8(acc[ai][bj][m][0] * g0, acc[ai][bj][m][1] * g1); }
;                     else { f32x4 h0, h1; unpack8(hw[m][bj], h0, h1);
; #pragma unroll
;                         for (int e = 0; e < 4; ++e) { acc[ai][bj][m][0][e] *= g0[e] * __builtin_amdgcn_rcpf(fmaxf(h0[e], 1e-20f)); acc[ai][bj][m][1][e] *= g1[e] * __builtin_amdgcn_rcpf(fmaxf(h1[e], 1e-20f)); } } }
.LBB0_825:
	s_andn2_b64 vcc, exec, s[46:47]
	s_cbranch_vccnz .LBB0_827
	v_pk_mul_f32 v[78:79], v[72:73], v[78:79]
	v_pk_mul_f32 v[74:75], v[70:71], v[74:75]
	v_pk_mul_f32 v[76:77], v[66:67], v[76:77]
	v_cvt_pk_bf16_f32 v74, v74, v75
	v_cvt_pk_bf16_f32 v75, v78, v79
	v_lshl_add_u64 v[78:79], v[218:219], 0, s[18:19]
	v_lshl_add_u64 v[78:79], v[216:217], 1, v[78:79]
	v_add_co_u32_e32 v78, vcc, 0x18000, v78
	v_mov_b32_e32 v136, v66
	s_nop 0
	v_addc_co_u32_e32 v79, vcc, 0, v79, vcc
	v_mov_b32_e32 v137, v67
	v_mov_b32_e32 v140, v68
	v_mov_b32_e32 v141, v69
	v_mov_b32_e32 v134, v70
	v_mov_b32_e32 v135, v71
	v_mov_b32_e32 v138, v72
	v_mov_b32_e32 v139, v73
	v_pk_mul_f32 v[80:81], v[68:69], v[80:81]
	v_cvt_pk_bf16_f32 v76, v76, v77
	s_nop 0
	v_cvt_pk_bf16_f32 v77, v80, v81
	global_store_dwordx4 v[78:79], v[74:77], off offset:256 sc1

; __device__ __forceinline__ u32x4 pack8(const f32x4 v0, const f32x4 v1) { u32x4 w; w.x = cvt_pk_bf16(v0[0], v0[1]); w.y = cvt_pk_bf16(v0[2], v0[3]); w.z = cvt_pk_bf16(v1[0], v1[1]); w.w = cvt_pk_bf16(v1[2], v1[3]); return w; }
; __device__ __forceinline__ void unpack8(const u32x4 w, f32x4& v0, f32x4& v1) { v0[0] = bf_lo(w.x); v0[1] = bf_hi(w.x); v0[2] = bf_lo(w.y); v0[3] = bf_hi(w.y); v1[0] = bf_lo(w.z); v1[1] = bf_hi(w.z); v1[2] = bf_lo(w.w); v1[3] = bf_hi(w.w); }
;     __device__ __forceinline__ void operator()(f32x4 (&acc)[2][2][4][2], const Unit& u, int wr, int wc, int fr, int fq) const {
;     ...
;             for (int m = 0; m < 4; ++m)
; #pragma unroll
;                 for (int bj = 0; bj < 2; ++bj) { f32x4 g0, g1; unpack8(gw[m][bj], g0, g1);
;                     if (last) { *(u32x4*)(u.O + lo + (size_t)(ai * HALF + m * 16) * u.ldo + bj * HALF) = pack8(acc[ai][bj][m][0] * g0, acc[ai][bj][m][1] * g1); }
;                     else { f32x4 h0, h1; unpack8(hw[m][bj], h0, h1);
; #pragma unroll
;                         for (int e = 0; e < 4; ++e) { acc[ai][bj][m][0][e] *= g0[e] * __builtin_amdgcn_rcpf(fmaxf(h0[e], 1e-20f)); acc[ai][bj][m][1][e] *= g1[e] * __builtin_amdgcn_rcpf(fmaxf(h1[e], 1e-20f)); } } }
.LBB0_845:
	s_andn2_b64 vcc, exec, s[46:47]
	s_cbranch_vccnz .LBB0_847
	v_pk_mul_f32 v[124:125], v[64:65], v[224:225]
	v_pk_mul_f32 v[122:123], v[62:63], v[220:221]
	v_pk_mul_f32 v[126:127], v[60:61], v[226:227]
	v_pk_mul_f32 v[128:129], v[58:59], v[222:223]
	v_cvt_pk_bf16_f32 v122, v122, v123
	v_cvt_pk_bf16_f32 v123, v124, v125
	v_mov_b32_e32 v132, v60
	v_cvt_pk_bf16_f32 v124, v128, v129
	v_cvt_pk_bf16_f32 v125, v126, v127
	v_lshl_add_u64 v[126:127], v[218:219], 0, s[18:19]
	v_lshl_add_u64 v[126:127], v[216:217], 1, v[126:127]
	v_add_co_u32_e32 v126, vcc, 0x40000, v126
	v_mov_b32_e32 v128, v58
	s_nop 0
	v_addc_co_u32_e32 v127, vcc, 0, v127, vcc
	global_store_dwordx4 v[126:127], v[122:125], off sc1
	v_mov_b32_e32 v129, v59
	v_mov_b32_e32 v133, v61
	v_mov_b32_e32 v126, v62
	v_mov_b32_e32 v127, v63
	v_mov_b32_e32 v130, v64
	v_mov_b32_e32 v131, v65

; __device__ __forceinline__ u32x4 pack8(const f32x4 v0, const f32x4 v1) { u32x4 w; w.x = cvt_pk_bf16(v0[0], v0[1]); w.y = cvt_pk_bf16(v0[2], v0[3]); w.z = cvt_pk_bf16(v1[0], v1[1]); w.w = cvt_pk_bf16(v1[2], v1[3]); return w; }
; __device__ __forceinline__ void unpack8(const u32x4 w, f32x4& v0, f32x4& v1) { v0[0] = bf_lo(w.x); v0[1] = bf_hi(w.x); v0[2] = bf_lo(w.y); v0[3] = bf_hi(w.y); v1[0] = bf_lo(w.z); v1[1] = bf_hi(w.z); v1[2] = bf_lo(w.w); v1[3] = bf_hi(w.w); }
;     __device__ __forceinline__ void operator()(f32x4 (&acc)[2][2][4][2], const Unit& u, int wr, int wc, int fr, int fq) const {
;     ...
;             for (int m = 0; m < 4; ++m)
; #pragma unroll
;                 for (int bj = 0; bj < 2; ++bj) { f32x4 g0, g1; unpack8(gw[m][bj], g0, g1);
;                     if (last) { *(u32x4*)(u.O + lo + (size_t)(ai * HALF + m * 16) * u.ldo + bj * HALF) = pack8(acc[ai][bj][m][0] * g0, acc[ai][bj][m][1] * g1); }
;                     else { f32x4 h0, h1; unpack8(hw[m][bj], h0, h1);
; #pragma unroll
;                         for (int e = 0; e < 4; ++e) { acc[ai][bj][m][0][e] *= g0[e] * __builtin_amdgcn_rcpf(fmaxf(h0[e], 1e-20f)); acc[ai][bj][m][1][e] *= g1[e] * __builtin_amdgcn_rcpf(fmaxf(h1[e], 1e-20f)); } } }
.LBB0_849:
	s_andn2_b64 vcc, exec, s[46:47]
	s_cbranch_vccnz .LBB0_851
	v_pk_mul_f32 v[60:61], v[56:57], v[124:125]
	v_pk_mul_f32 v[58:59], v[54:55], v[122:123]
	v_pk_mul_f32 v[62:63], v[52:53], v[120:121]
	v_pk_mul_f32 v[64:65], v[50:51], v[118:119]
	v_cvt_pk_bf16_f32 v58, v58, v59
	v_cvt_pk_bf16_f32 v59, v60, v61
	s_nop 0
	v_cvt_pk_bf16_f32 v60, v64, v65
	v_cvt_pk_bf16_f32 v61, v62, v63
	v_lshl_add_u64 v[62:63], v[218:219], 0, s[18:19]
	v_lshl_add_u64 v[62:63], v[216:217], 1, v[62:63]
	v_add_co_u32_e32 v62, vcc, 0x40000, v62
	v_mov_b32_e32 v64, v52
	s_nop 0
	v_addc_co_u32_e32 v63, vcc, 0, v63, vcc
	global_store_dwordx4 v[62:63], v[58:61], off offset:256 sc1
	v_mov_b32_e32 v65, v53
	v_mov_b32_e32 v62, v56
	v_mov_b32_e32 v60, v50
	v_mov_b32_e32 v61, v51
	v_mov_b32_e32 v58, v54
	v_mov_b32_e32 v59, v55
	v_mov_b32_e32 v63, v57

; __device__ __forceinline__ u32x4 pack8(const f32x4 v0, const f32x4 v1) { u32x4 w; w.x = cvt_pk_bf16(v0[0], v0[1]); w.y = cvt_pk_bf16(v0[2], v0[3]); w.z = cvt_pk_bf16(v1[0], v1[1]); w.w = cvt_pk_bf16(v1[2], v1[3]); return w; }
; __device__ __forceinline__ void unpack8(const u32x4 w, f32x4& v0, f32x4& v1) { v0[0] = bf_lo(w.x); v0[1] = bf_hi(w.x); v0[2] = bf_lo(w.y); v0[3] = bf_hi(w.y); v1[0] = bf_lo(w.z); v1[1] = bf_hi(w.z); v1[2] = bf_lo(w.w); v1[3] = bf_hi(w.w); }
;     __device__ __forceinline__ void operator()(f32x4 (&acc)[2][2][4][2], const Unit& u, int wr, int wc, int fr, int fq) const {
;     ...
;             for (int m = 0; m < 4; ++m)
; #pragma unroll
;                 for (int bj = 0; bj < 2; ++bj) { f32x4 g0, g1; unpack8(gw[m][bj], g0, g1);
;                     if (last) { *(u32x4*)(u.O + lo + (size_t)(ai * HALF + m * 16) * u.ldo + bj * HALF) = pack8(acc[ai][bj][m][0] * g0, acc[ai][bj][m][1] * g1); }
;                     else { f32x4 h0, h1; unpack8(hw[m][bj], h0, h1);
; #pragma unroll
;                         for (int e = 0; e < 4; ++e) { acc[ai][bj][m][0][e] *= g0[e] * __builtin_amdgcn_rcpf(fmaxf(h0[e], 1e-20f)); acc[ai][bj][m][1][e] *= g1[e] * __builtin_amdgcn_rcpf(fmaxf(h1[e], 1e-20f)); } } }
.LBB0_853:
	s_andn2_b64 vcc, exec, s[46:47]
	s_cbranch_vccnz .LBB0_855
	v_pk_mul_f32 v[54:55], v[48:49], v[54:55]
	v_pk_mul_f32 v[50:51], v[46:47], v[50:51]
	v_pk_mul_f32 v[52:53], v[42:43], v[52:53]
	v_cvt_pk_bf16_f32 v50, v50, v51
	v_cvt_pk_bf16_f32 v51, v54, v55
	v_lshl_add_u64 v[54:55], v[218:219], 0, s[18:19]
	v_lshl_add_u64 v[54:55], v[216:217], 1, v[54:55]
	v_add_co_u32_e32 v54, vcc, 0x48000, v54
	v_mov_b32_e32 v112, v42
	s_nop 0
	v_addc_co_u32_e32 v55, vcc, 0, v55, vcc
	v_mov_b32_e32 v113, v43
	v_mov_b32_e32 v116, v44
	v_mov_b32_e32 v117, v45
	v_mov_b32_e32 v110, v46
	v_mov_b32_e32 v111, v47
	v_mov_b32_e32 v114, v48
	v_mov_b32_e32 v115, v49
	v_pk_mul_f32 v[56:57], v[44:45], v[56:57]
	v_cvt_pk_bf16_f32 v52, v52, v53
	s_nop 0
	v_cvt_pk_bf16_f32 v53, v56, v57
	global_store_dwordx4 v[54:55], v[50:53], off sc1

; __device__ __forceinline__ u32x4 pack8(const f32x4 v0, const f32x4 v1) { u32x4 w; w.x = cvt_pk_bf16(v0[0], v0[1]); w.y = cvt_pk_bf16(v0[2], v0[3]); w.z = cvt_pk_bf16(v1[0], v1[1]); w.w = cvt_pk_bf16(v1[2], v1[3]); return w; }
; __device__ __forceinline__ void unpack8(const u32x4 w, f32x4& v0, f32x4& v1) { v0[0] = bf_lo(w.x); v0[1] = bf_hi(w.x); v0[2] = bf_lo(w.y); v0[3] = bf_hi(w.y); v1[0] = bf_lo(w.z); v1[1] = bf_hi(w.z); v1[2] = bf_lo(w.w); v1[3] = bf_hi(w.w); }
;     __device__ __forceinline__ void operator()(f32x4 (&acc)[2][2][4][2], const Unit& u, int wr, int wc, int fr, int fq) const {
;     ...
;             for (int m = 0; m < 4; ++m)
; #pragma unroll
;                 for (int bj = 0; bj < 2; ++bj) { f32x4 g0, g1; unpack8(gw[m][bj], g0, g1);
;                     if (last) { *(u32x4*)(u.O + lo + (size_t)(ai * HALF + m * 16) * u.ldo + bj * HALF) = pack8(acc[ai][bj][m][0] * g0, acc[ai][bj][m][1] * g1); }
;                     else { f32x4 h0, h1; unpack8(hw[m][bj], h0, h1);
; #pragma unroll
;                         for (int e = 0; e < 4; ++e) { acc[ai][bj][m][0][e] *= g0[e] * __builtin_amdgcn_rcpf(fmaxf(h0[e], 1e-20f)); acc[ai][bj][m][1][e] *= g1[e] * __builtin_amdgcn_rcpf(fmaxf(h1[e], 1e-20f)); } } }
.LBB0_857:
	s_andn2_b64 vcc, exec, s[46:47]
	s_cbranch_vccnz .LBB0_859
	v_pk_mul_f32 v[44:45], v[40:41], v[54:55]
	v_pk_mul_f32 v[42:43], v[38:39], v[50:51]
	v_pk_mul_f32 v[46:47], v[36:37], v[56:57]
	v_pk_mul_f32 v[48:49], v[34:35], v[52:53]
	v_cvt_pk_bf16_f32 v42, v42, v43
	v_cvt_pk_bf16_f32 v43, v44, v45
	s_nop 0
	v_cvt_pk_bf16_f32 v44, v48, v49
	v_cvt_pk_bf16_f32 v45, v46, v47
	v_lshl_add_u64 v[46:47], v[218:219], 0, s[18:19]
	v_lshl_add_u64 v[46:47], v[216:217], 1, v[46:47]
	v_add_co_u32_e32 v46, vcc, 0x48000, v46
	v_mov_b32_e32 v48, v36
	s_nop 0
	v_addc_co_u32_e32 v47, vcc, 0, v47, vcc
	global_store_dwordx4 v[46:47], v[42:45], off offset:256 sc1
	v_mov_b32_e32 v49, v37
	v_mov_b32_e32 v46, v40
	v_mov_b32_e32 v44, v34
	v_mov_b32_e32 v45, v35
	v_mov_b32_e32 v42, v38
	v_mov_b32_e32 v43, v39
	v_mov_b32_e32 v47, v41

; __device__ __forceinline__ u32x4 pack8(const f32x4 v0, const f32x4 v1) { u32x4 w; w.x = cvt_pk_bf16(v0[0], v0[1]); w.y = cvt_pk_bf16(v0[2], v0[3]); w.z = cvt_pk_bf16(v1[0], v1[1]); w.w = cvt_pk_bf16(v1[2], v1[3]); return w; }
; __device__ __forceinline__ void unpack8(const u32x4 w, f32x4& v0, f32x4& v1) { v0[0] = bf_lo(w.x); v0[1] = bf_hi(w.x); v0[2] = bf_lo(w.y); v0[3] = bf_hi(w.y); v1[0] = bf_lo(w.z); v1[1] = bf_hi(w.z); v1[2] = bf_lo(w.w); v1[3] = bf_hi(w.w); }
;     __device__ __forceinline__ void operator()(f32x4 (&acc)[2][2][4][2], const Unit& u, int wr, int wc, int fr, int fq) const {
;     ...
;             for (int m = 0; m < 4; ++m)
; #pragma unroll
;                 for (int bj = 0; bj < 2; ++bj) { f32x4 g0, g1; unpack8(gw[m][bj], g0, g1);
;                     if (last) { *(u32x4*)(u.O + lo + (size_t)(ai * HALF + m * 16) * u.ldo + bj * HALF) = pack8(acc[ai][bj][m][0] * g0, acc[ai][bj][m][1] * g1); }
;                     else { f32x4 h0, h1; unpack8(hw[m][bj], h0, h1);
; #pragma unroll
;                         for (int e = 0; e < 4; ++e) { acc[ai][bj][m][0][e] *= g0[e] * __builtin_amdgcn_rcpf(fmaxf(h0[e], 1e-20f)); acc[ai][bj][m][1][e] *= g1[e] * __builtin_amdgcn_rcpf(fmaxf(h1[e], 1e-20f)); } } }
.LBB0_861:
	s_andn2_b64 vcc, exec, s[46:47]
	s_cbranch_vccnz .LBB0_863
	v_pk_mul_f32 v[38:39], v[32:33], v[38:39]
	v_pk_mul_f32 v[34:35], v[30:31], v[34:35]
	v_pk_mul_f32 v[36:37], v[26:27], v[36:37]
	v_cvt_pk_bf16_f32 v34, v34, v35
	v_cvt_pk_bf16_f32 v35, v38, v39
	v_lshl_add_u64 v[38:39], v[218:219], 0, s[18:19]
	v_lshl_add_u64 v[38:39], v[216:217], 1, v[38:39]
	v_add_co_u32_e32 v38, vcc, 0x50000, v38
	v_mov_b32_e32 v96, v26
	s_nop 0
	v_addc_co_u32_e32 v39, vcc, 0, v39, vcc
	v_mov_b32_e32 v97, v27
	v_mov_b32_e32 v100, v28
	v_mov_b32_e32 v101, v29
	v_mov_b32_e32 v94, v30
	v_mov_b32_e32 v95, v31
	v_mov_b32_e32 v98, v32
	v_mov_b32_e32 v99, v33
	v_pk_mul_f32 v[40:41], v[28:29], v[40:41]
	v_cvt_pk_bf16_f32 v36, v36, v37
	s_nop 0
	v_cvt_pk_bf16_f32 v37, v40, v41
	global_store_dwordx4 v[38:39], v[34:37], off sc1

; __device__ __forceinline__ u32x4 pack8(const f32x4 v0, const f32x4 v1) { u32x4 w; w.x = cvt_pk_bf16(v0[0], v0[1]); w.y = cvt_pk_bf16(v0[2], v0[3]); w.z = cvt_pk_bf16(v1[0], v1[1]); w.w = cvt_pk_bf16(v1[2], v1[3]); return w; }
; __device__ __forceinline__ void unpack8(const u32x4 w, f32x4& v0, f32x4& v1) { v0[0] = bf_lo(w.x); v0[1] = bf_hi(w.x); v0[2] = bf_lo(w.y); v0[3] = bf_hi(w.y); v1[0] = bf_lo(w.z); v1[1] = bf_hi(w.z); v1[2] = bf_lo(w.w); v1[3] = bf_hi(w.w); }
;     __device__ __forceinline__ void operator()(f32x4 (&acc)[2][2][4][2], const Unit& u, int wr, int wc, int fr, int fq) const {
;     ...
;             for (int m = 0; m < 4; ++m)
; #pragma unroll
;                 for (int bj = 0; bj < 2; ++bj) { f32x4 g0, g1; unpack8(gw[m][bj], g0, g1);
;                     if (last) { *(u32x4*)(u.O + lo + (size_t)(ai * HALF + m * 16) * u.ldo + bj * HALF) = pack8(acc[ai][bj][m][0] * g0, acc[ai][bj][m][1] * g1); }
;                     else { f32x4 h0, h1; unpack8(hw[m][bj], h0, h1);
; #pragma unroll
;                         for (int e = 0; e < 4; ++e) { acc[ai][bj][m][0][e] *= g0[e] * __builtin_amdgcn_rcpf(fmaxf(h0[e], 1e-20f)); acc[ai][bj][m][1][e] *= g1[e] * __builtin_amdgcn_rcpf(fmaxf(h1[e], 1e-20f)); } } }
.LBB0_865:
	s_andn2_b64 vcc, exec, s[46:47]
	s_cbranch_vccnz .LBB0_867
	v_pk_mul_f32 v[28:29], v[24:25], v[38:39]
	v_pk_mul_f32 v[26:27], v[22:23], v[34:35]
	v_pk_mul_f32 v[30:31], v[20:21], v[40:41]
	v_pk_mul_f32 v[32:33], v[18:19], v[36:37]
	v_cvt_pk_bf16_f32 v26, v26, v27
	v_cvt_pk_bf16_f32 v27, v28, v29
	s_nop 0
	v_cvt_pk_bf16_f32 v28, v32, v33
	v_cvt_pk_bf16_f32 v29, v30, v31
	v_lshl_add_u64 v[30:31], v[218:219], 0, s[18:19]
	v_lshl_add_u64 v[30:31], v[216:217], 1, v[30:31]
	v_add_co_u32_e32 v30, vcc, 0x50000, v30
	v_mov_b32_e32 v32, v20
	s_nop 0
	v_addc_co_u32_e32 v31, vcc, 0, v31, vcc
	global_store_dwordx4 v[30:31], v[26:29], off offset:256 sc1
	v_mov_b32_e32 v33, v21
	v_mov_b32_e32 v30, v24
	v_mov_b32_e32 v28, v18
	v_mov_b32_e32 v29, v19
	v_mov_b32_e32 v26, v22
	v_mov_b32_e32 v27, v23
	v_mov_b32_e32 v31, v25

; __device__ __forceinline__ u32x4 pack8(const f32x4 v0, const f32x4 v1) { u32x4 w; w.x = cvt_pk_bf16(v0[0], v0[1]); w.y = cvt_pk_bf16(v0[2], v0[3]); w.z = cvt_pk_bf16(v1[0], v1[1]); w.w = cvt_pk_bf16(v1[2], v1[3]); return w; }
; __device__ __forceinline__ void unpack8(const u32x4 w, f32x4& v0, f32x4& v1) { v0[0] = bf_lo(w.x); v0[1] = bf_hi(w.x); v0[2] = bf_lo(w.y); v0[3] = bf_hi(w.y); v1[0] = bf_lo(w.z); v1[1] = bf_hi(w.z); v1[2] = bf_lo(w.w); v1[3] = bf_hi(w.w); }
;     __device__ __forceinline__ void operator()(f32x4 (&acc)[2][2][4][2], const Unit& u, int wr, int wc, int fr, int fq) const {
;     ...
;             for (int m = 0; m < 4; ++m)
; #pragma unroll
;                 for (int bj = 0; bj < 2; ++bj) { f32x4 g0, g1; unpack8(gw[m][bj], g0, g1);
;                     if (last) { *(u32x4*)(u.O + lo + (size_t)(ai * HALF + m * 16) * u.ldo + bj * HALF) = pack8(acc[ai][bj][m][0] * g0, acc[ai][bj][m][1] * g1); }
;                     else { f32x4 h0, h1; unpack8(hw[m][bj], h0, h1);
; #pragma unroll
;                         for (int e = 0; e < 4; ++e) { acc[ai][bj][m][0][e] *= g0[e] * __builtin_amdgcn_rcpf(fmaxf(h0[e], 1e-20f)); acc[ai][bj][m][1][e] *= g1[e] * __builtin_amdgcn_rcpf(fmaxf(h1[e], 1e-20f)); } } }
.LBB0_869:
	s_andn2_b64 vcc, exec, s[46:47]
	s_cbranch_vccnz .LBB0_871
	v_pk_mul_f32 v[22:23], v[16:17], v[22:23]
	v_pk_mul_f32 v[18:19], v[14:15], v[18:19]
	v_pk_mul_f32 v[20:21], v[10:11], v[20:21]
	v_cvt_pk_bf16_f32 v18, v18, v19
	v_cvt_pk_bf16_f32 v19, v22, v23
	v_lshl_add_u64 v[22:23], v[218:219], 0, s[18:19]
	v_lshl_add_u64 v[22:23], v[216:217], 1, v[22:23]
	v_add_co_u32_e32 v22, vcc, 0x58000, v22
	v_mov_b32_e32 v80, v10
	s_nop 0
	v_addc_co_u32_e32 v23, vcc, 0, v23, vcc
	v_mov_b32_e32 v81, v11
	v_mov_b32_e32 v84, v12
	v_mov_b32_e32 v85, v13
	v_mov_b32_e32 v78, v14
	v_mov_b32_e32 v79, v15
	v_mov_b32_e32 v82, v16
	v_mov_b32_e32 v83, v17
	v_pk_mul_f32 v[24:25], v[12:13], v[24:25]
	v_cvt_pk_bf16_f32 v20, v20, v21
	s_nop 0
	v_cvt_pk_bf16_f32 v21, v24, v25
	global_store_dwordx4 v[22:23], v[18:21], off sc1

; __device__ __forceinline__ u32x4 pack8(const f32x4 v0, const f32x4 v1) { u32x4 w; w.x = cvt_pk_bf16(v0[0], v0[1]); w.y = cvt_pk_bf16(v0[2], v0[3]); w.z = cvt_pk_bf16(v1[0], v1[1]); w.w = cvt_pk_bf16(v1[2], v1[3]); return w; }
; __device__ __forceinline__ void unpack8(const u32x4 w, f32x4& v0, f32x4& v1) { v0[0] = bf_lo(w.x); v0[1] = bf_hi(w.x); v0[2] = bf_lo(w.y); v0[3] = bf_hi(w.y); v1[0] = bf_lo(w.z); v1[1] = bf_hi(w.z); v1[2] = bf_lo(w.w); v1[3] = bf_hi(w.w); }
;     __device__ __forceinline__ void operator()(f32x4 (&acc)[2][2][4][2], const Unit& u, int wr, int wc, int fr, int fq) const {
;     ...
;             for (int m = 0; m < 4; ++m)
; #pragma unroll
;                 for (int bj = 0; bj < 2; ++bj) { f32x4 g0, g1; unpack8(gw[m][bj], g0, g1);
;                     if (last) { *(u32x4*)(u.O + lo + (size_t)(ai * HALF + m * 16) * u.ldo + bj * HALF) = pack8(acc[ai][bj][m][0] * g0, acc[ai][bj][m][1] * g1); }
;                     else { f32x4 h0, h1; unpack8(hw[m][bj], h0, h1);
; #pragma unroll
;                         for (int e = 0; e < 4; ++e) { acc[ai][bj][m][0][e] *= g0[e] * __builtin_amdgcn_rcpf(fmaxf(h0[e], 1e-20f)); acc[ai][bj][m][1][e] *= g1[e] * __builtin_amdgcn_rcpf(fmaxf(h1[e], 1e-20f)); } } }
.LBB0_875:
	v_pk_mul_f32 v[12:13], v[8:9], v[22:23]
	v_pk_mul_f32 v[10:11], v[6:7], v[18:19]
	v_pk_mul_f32 v[14:15], v[4:5], v[24:25]
	v_pk_mul_f32 v[16:17], v[2:3], v[20:21]
	v_cvt_pk_bf16_f32 v10, v10, v11
	v_cvt_pk_bf16_f32 v11, v12, v13
	s_nop 0
	v_cvt_pk_bf16_f32 v12, v16, v17
	v_cvt_pk_bf16_f32 v13, v14, v15
	v_lshl_add_u64 v[14:15], v[218:219], 0, s[18:19]
	v_lshl_add_u64 v[14:15], v[216:217], 1, v[14:15]
	v_add_co_u32_e32 v14, vcc, 0x58000, v14
	v_mov_b32_e32 v16, v4
	s_nop 0
	v_addc_co_u32_e32 v15, vcc, 0, v15, vcc
	global_store_dwordx4 v[14:15], v[10:13], off offset:256 sc1
	v_mov_b32_e32 v17, v5
	v_mov_b32_e32 v14, v8
	v_mov_b32_e32 v12, v2
	v_mov_b32_e32 v13, v3
	v_mov_b32_e32 v10, v6
	v_mov_b32_e32 v11, v7
	v_mov_b32_e32 v15, v9
	s_andn2_b64 vcc, exec, s[6:7]
	s_mov_b64 s[6:7], -1
	s_cbranch_vccnz .LBB0_768

; __device__ __forceinline__ float shx(float v, int lane, int m) { return __builtin_bit_cast(float, __builtin_amdgcn_ds_bpermute((lane ^ m) << 2, __builtin_bit_cast(int, v))); }
; __device__ __forceinline__ u32x4 pack8(const f32x4 v0, const f32x4 v1) { u32x4 w; w.x = cvt_pk_bf16(v0[0], v0[1]); w.y = cvt_pk_bf16(v0[2], v0[3]); w.z = cvt_pk_bf16(v1[0], v1[1]); w.w = cvt_pk_bf16(v1[2], v1[3]); return w; }
;     __device__ __forceinline__ void operator()(f32x4 (&acc)[2][2][4][2], const Unit& u, int wr, int wc, int fr, int fq) const {
;     ...
;             for (int m = 0; m < 4; ++m) { bf16_t* rowp = base + (size_t)(ai * HALF + m * 16) * u.ldo; float s = 0.f;
; #pragma unroll
;                 for (int bj = 0; bj < 2; ++bj) { const f32x4 v0 = acc[ai][bj][m][0], v1 = acc[ai][bj][m][1];
;                     s += (v0[0] * v0[0] + v0[1] * v0[1]) + (v0[2] * v0[2] + v0[3] * v0[3]) + (v1[0] * v1[0] + v1[1] * v1[1]) + (v1[2] * v1[2] + v1[3] * v1[3]);
;                     __builtin_nontemporal_store(pack8(v0, v1), (u32x4*)(rowp + bj * HALF)); }
;                 s += shx(s, lane_, 16); s += shx(s, lane_, 32);
;                 if (fq == 0) SSP[(size_t)(u.z + ai * HALF + wr * 64 + m * 16 + fr) * 16 + u.pn * 4 + wc] = s; }
.LBB0_955:
	v_mov_b32_e32 v150, v145
	v_mov_b32_e32 v151, v144
	v_lshrrev_b32_e32 v242, 3, v144
	v_mul_i32_i24_e32 v242, 0xffffc040, v242
	s_lshl_b32 s48, s61, 6
	v_add_u32_e32 v242, s48, v242
	v_ashrrev_i32_e32 v243, 31, v242
	v_add_u32_e32 v244, 0x4000, v242
	v_mov_b32_e32 v245, 0
	s_nop 0
	v_add_u32_e32 v140, s62, v151
	v_ashrrev_i32_e32 v141, 31, v140
	v_lshlrev_b64 v[142:143], 11, v[140:141]
	v_lshl_add_u64 v[142:143], s[6:7], 0, v[142:143]
	v_lshlrev_b32_e32 v148, 3, v150
	v_lshl_add_u64 v[142:143], v[142:143], 0, s[18:19]
	v_ashrrev_i32_e32 v149, 31, v148
	v_lshlrev_b32_e32 v141, 2, v151
	v_lshl_add_u64 v[142:143], v[148:149], 1, v[142:143]
	v_lshl_add_u32 v141, v150, 6, v141
	v_cmp_eq_u32_e32 vcc, 0, v150
	v_mul_f32_e32 v149, v127, v127
	v_mul_f32_e32 v150, v129, v129
	v_fmac_f32_e32 v149, v126, v126
	v_fmac_f32_e32 v150, v128, v128
	v_cvt_pk_bf16_f32 v126, v126, v127
	v_cvt_pk_bf16_f32 v127, v128, v129
	v_mul_f32_e32 v128, v119, v119
	v_mul_f32_e32 v129, v121, v121
	v_fmac_f32_e32 v128, v118, v118
	v_fmac_f32_e32 v129, v120, v120
	v_add_f32_e32 v149, v149, v150
	v_mul_f32_e32 v150, v123, v123
	v_add_f32_e32 v128, v128, v129
	v_mul_f32_e32 v129, v115, v115
	v_fmac_f32_e32 v150, v122, v122
	v_fmac_f32_e32 v129, v114, v114
	v_add_f32_e32 v149, v149, v150
	v_mul_f32_e32 v150, v125, v125
	v_add_f32_e32 v128, v128, v129
	v_mul_f32_e32 v129, v117, v117
	v_fmac_f32_e32 v150, v124, v124
	v_fmac_f32_e32 v129, v116, v116
	v_add_f32_e32 v149, v150, v149
	v_add_f32_e32 v128, v129, v128
	v_xor_b32_e32 v148, 64, v141
	v_add_f32_e32 v149, v149, v128
	ds_bpermute_b32 v150, v148, v149
	v_xor_b32_e32 v141, 0x80, v141
	v_cvt_pk_bf16_f32 v128, v122, v123
	v_cvt_pk_bf16_f32 v129, v124, v125
	v_cvt_pk_bf16_f32 v122, v118, v119
	s_waitcnt lgkmcnt(0)
	v_add_f32_e32 v118, v149, v150
	ds_bpermute_b32 v119, v141, v118
	v_cvt_pk_bf16_f32 v123, v120, v121
	v_cvt_pk_bf16_f32 v124, v114, v115
	v_cvt_pk_bf16_f32 v125, v116, v117
	v_mov_b32_e32 v238, v122
	v_mov_b32_e32 v239, v123
	v_mov_b32_e32 v240, v124
	v_mov_b32_e32 v241, v125
	v_mov_b32_dpp v122, v126 row_ror:8 row_mask:0xf bank_mask:0x3
	v_mov_b32_dpp v123, v127 row_ror:8 row_mask:0xf bank_mask:0x3
	v_mov_b32_dpp v124, v128 row_ror:8 row_mask:0xf bank_mask:0x3
	v_mov_b32_dpp v125, v129 row_ror:8 row_mask:0xf bank_mask:0x3
	v_mov_b32_dpp v126, v238 row_ror:8 row_mask:0xf bank_mask:0xc
	v_mov_b32_dpp v127, v239 row_ror:8 row_mask:0xf bank_mask:0xc
	v_mov_b32_dpp v128, v240 row_ror:8 row_mask:0xf bank_mask:0xc
	v_mov_b32_dpp v129, v241 row_ror:8 row_mask:0xf bank_mask:0xc
	v_lshl_add_u64 v[246:247], v[142:143], 0, v[242:243]
	v_lshl_add_u64 v[248:249], v[142:143], 0, v[244:245]
	global_store_dwordx4 v[246:247], v[126:129], off sc1 nt
	global_store_dwordx4 v[248:249], v[122:125], off sc1 nt
	s_nop 1
	s_and_saveexec_b64 s[6:7], vcc
	s_cbranch_execz .LBB0_957
	v_add_u32_e32 v114, s8, v140
	v_ashrrev_i32_e32 v115, 31, v114
	s_lshl_b32 s48, s56, 2
	v_lshlrev_b64 v[114:115], 6, v[114:115]
	s_ashr_i32 s49, s48, 31
	v_lshl_add_u64 v[114:115], s[14:15], 0, v[114:115]
	v_lshl_add_u64 v[114:115], s[48:49], 2, v[114:115]
	s_lshl_b32 s48, s61, 2
	s_mov_b32 s49, s19
	s_waitcnt lgkmcnt(0)
	v_add_f32_e32 v116, v118, v119
	v_lshl_add_u64 v[114:115], v[114:115], 0, s[48:49]
	global_store_dword v[114:115], v116, off sc1
.LBB0_957:
	s_or_b64 exec, exec, s[6:7]
	v_mul_f32_e32 v114, v111, v111
	v_mul_f32_e32 v115, v113, v113
	v_fmac_f32_e32 v114, v110, v110
	v_fmac_f32_e32 v115, v112, v112
	v_add_f32_e32 v114, v114, v115
	v_mul_f32_e32 v115, v107, v107
	v_fmac_f32_e32 v115, v106, v106
	v_cvt_pk_bf16_f32 v110, v110, v111
	v_cvt_pk_bf16_f32 v111, v112, v113
	v_cvt_pk_bf16_f32 v112, v106, v107
	v_mul_f32_e32 v106, v103, v103
	v_mul_f32_e32 v107, v105, v105
	v_fmac_f32_e32 v106, v102, v102
	v_fmac_f32_e32 v107, v104, v104
	v_add_f32_e32 v106, v106, v107
	v_mul_f32_e32 v107, v99, v99
	v_fmac_f32_e32 v107, v98, v98
	v_add_f32_e32 v114, v114, v115
	v_mul_f32_e32 v115, v109, v109
	v_add_f32_e32 v106, v106, v107
	v_mul_f32_e32 v107, v101, v101
	v_fmac_f32_e32 v115, v108, v108
	v_fmac_f32_e32 v107, v100, v100
	v_add_f32_e32 v114, v115, v114
	v_add_f32_e32 v106, v107, v106
	v_add_f32_e32 v107, v114, v106
	v_cvt_pk_bf16_f32 v113, v108, v109
	ds_bpermute_b32 v108, v148, v107
	v_add_co_u32_e64 v114, s[6:7], s79, v142
	s_nop 1
	v_addc_co_u32_e64 v115, s[6:7], 0, v143, s[6:7]
	v_cvt_pk_bf16_f32 v106, v102, v103
	s_waitcnt lgkmcnt(0)
	v_add_f32_e32 v102, v107, v108
	ds_bpermute_b32 v103, v141, v102
	v_cvt_pk_bf16_f32 v107, v104, v105
	v_cvt_pk_bf16_f32 v108, v98, v99
	v_cvt_pk_bf16_f32 v109, v100, v101
	v_mov_b32_e32 v238, v106
	v_mov_b32_e32 v239, v107
	v_mov_b32_e32 v240, v108
	v_mov_b32_e32 v241, v109
	v_mov_b32_dpp v106, v110 row_ror:8 row_mask:0xf bank_mask:0x3
	v_mov_b32_dpp v107, v111 row_ror:8 row_mask:0xf bank_mask:0x3
	v_mov_b32_dpp v108, v112 row_ror:8 row_mask:0xf bank_mask:0x3
	v_mov_b32_dpp v109, v113 row_ror:8 row_mask:0xf bank_mask:0x3
	v_mov_b32_dpp v110, v238 row_ror:8 row_mask:0xf bank_mask:0xc
	v_mov_b32_dpp v111, v239 row_ror:8 row_mask:0xf bank_mask:0xc
	v_mov_b32_dpp v112, v240 row_ror:8 row_mask:0xf bank_mask:0xc
	v_mov_b32_dpp v113, v241 row_ror:8 row_mask:0xf bank_mask:0xc
	v_lshl_add_u64 v[246:247], v[114:115], 0, v[242:243]
	v_lshl_add_u64 v[248:249], v[114:115], 0, v[244:245]
	global_store_dwordx4 v[246:247], v[110:113], off sc1 nt
	global_store_dwordx4 v[248:249], v[106:109], off sc1 nt
	s_nop 1
	s_and_saveexec_b64 s[6:7], vcc
	s_cbranch_execz .LBB0_959
	v_add3_u32 v98, s8, 16, v140
	v_ashrrev_i32_e32 v99, 31, v98
	s_lshl_b32 s48, s56, 2
	v_lshlrev_b64 v[98:99], 6, v[98:99]
	s_ashr_i32 s49, s48, 31
	v_lshl_add_u64 v[98:99], s[14:15], 0, v[98:99]
	v_lshl_add_u64 v[98:99], s[48:49], 2, v[98:99]
	s_lshl_b32 s48, s61, 2
	s_mov_b32 s49, s19
	s_waitcnt lgkmcnt(0)
	v_add_f32_e32 v100, v102, v103
	v_lshl_add_u64 v[98:99], v[98:99], 0, s[48:49]
	global_store_dword v[98:99], v100, off sc1
; __device__ __forceinline__ float shx(float v, int lane, int m) { return __builtin_bit_cast(float, __builtin_amdgcn_ds_bpermute((lane ^ m) << 2, __builtin_bit_cast(int, v))); }
; __device__ __forceinline__ u32x4 pack8(const f32x4 v0, const f32x4 v1) { u32x4 w; w.x = cvt_pk_bf16(v0[0], v0[1]); w.y = cvt_pk_bf16(v0[2], v0[3]); w.z = cvt_pk_bf16(v1[0], v1[1]); w.w = cvt_pk_bf16(v1[2], v1[3]); return w; }
;     __device__ __forceinline__ void operator()(f32x4 (&acc)[2][2][4][2], const Unit& u, int wr, int wc, int fr, int fq) const {
;     ...
;             for (int m = 0; m < 4; ++m) { bf16_t* rowp = base + (size_t)(ai * HALF + m * 16) * u.ldo; float s = 0.f;
; #pragma unroll
;                 for (int bj = 0; bj < 2; ++bj) { const f32x4 v0 = acc[ai][bj][m][0], v1 = acc[ai][bj][m][1];
;                     s += (v0[0] * v0[0] + v0[1] * v0[1]) + (v0[2] * v0[2] + v0[3] * v0[3]) + (v1[0] * v1[0] + v1[1] * v1[1]) + (v1[2] * v1[2] + v1[3] * v1[3]);
;                     __builtin_nontemporal_store(pack8(v0, v1), (u32x4*)(rowp + bj * HALF)); }
;                 s += shx(s, lane_, 16); s += shx(s, lane_, 32);
;                 if (fq == 0) SSP[(size_t)(u.z + ai * HALF + wr * 64 + m * 16 + fr) * 16 + u.pn * 4 + wc] = s; }
.LBB0_959:
	s_or_b64 exec, exec, s[6:7]
	v_mul_f32_e32 v98, v95, v95
	v_mul_f32_e32 v99, v97, v97
	v_fmac_f32_e32 v98, v94, v94
	v_fmac_f32_e32 v99, v96, v96
	v_add_f32_e32 v98, v98, v99
	v_mul_f32_e32 v99, v91, v91
	v_fmac_f32_e32 v99, v90, v90
	v_cvt_pk_bf16_f32 v94, v94, v95
	v_cvt_pk_bf16_f32 v95, v96, v97
	v_cvt_pk_bf16_f32 v96, v90, v91
	v_mul_f32_e32 v90, v87, v87
	v_mul_f32_e32 v91, v89, v89
	v_fmac_f32_e32 v90, v86, v86
	v_fmac_f32_e32 v91, v88, v88
	v_add_f32_e32 v90, v90, v91
	v_mul_f32_e32 v91, v83, v83
	v_fmac_f32_e32 v91, v82, v82
	v_add_f32_e32 v98, v98, v99
	v_mul_f32_e32 v99, v93, v93
	v_add_f32_e32 v90, v90, v91
	v_mul_f32_e32 v91, v85, v85
	v_fmac_f32_e32 v99, v92, v92
	v_fmac_f32_e32 v91, v84, v84
	v_add_f32_e32 v98, v99, v98
	v_add_f32_e32 v90, v91, v90
	v_add_f32_e32 v91, v98, v90
	v_cvt_pk_bf16_f32 v97, v92, v93
	ds_bpermute_b32 v92, v148, v91
	v_add_co_u32_e64 v98, s[6:7], s27, v142
	s_nop 1
	v_addc_co_u32_e64 v99, s[6:7], 0, v143, s[6:7]
	v_cvt_pk_bf16_f32 v90, v86, v87
	s_waitcnt lgkmcnt(0)
	v_add_f32_e32 v86, v91, v92
	ds_bpermute_b32 v87, v141, v86
	v_cvt_pk_bf16_f32 v91, v88, v89
	v_cvt_pk_bf16_f32 v92, v82, v83
	v_cvt_pk_bf16_f32 v93, v84, v85
	v_mov_b32_e32 v238, v90
	v_mov_b32_e32 v239, v91
	v_mov_b32_e32 v240, v92
	v_mov_b32_e32 v241, v93
	v_mov_b32_dpp v90, v94 row_ror:8 row_mask:0xf bank_mask:0x3
	v_mov_b32_dpp v91, v95 row_ror:8 row_mask:0xf bank_mask:0x3
	v_mov_b32_dpp v92, v96 row_ror:8 row_mask:0xf bank_mask:0x3
	v_mov_b32_dpp v93, v97 row_ror:8 row_mask:0xf bank_mask:0x3
	v_mov_b32_dpp v94, v238 row_ror:8 row_mask:0xf bank_mask:0xc
	v_mov_b32_dpp v95, v239 row_ror:8 row_mask:0xf bank_mask:0xc
	v_mov_b32_dpp v96, v240 row_ror:8 row_mask:0xf bank_mask:0xc
	v_mov_b32_dpp v97, v241 row_ror:8 row_mask:0xf bank_mask:0xc
	v_lshl_add_u64 v[246:247], v[98:99], 0, v[242:243]
	v_lshl_add_u64 v[248:249], v[98:99], 0, v[244:245]
	global_store_dwordx4 v[246:247], v[94:97], off sc1 nt
	global_store_dwordx4 v[248:249], v[90:93], off sc1 nt
	s_nop 1
	s_and_saveexec_b64 s[6:7], vcc
	s_cbranch_execz .LBB0_961
	v_add3_u32 v82, s8, 32, v140
	v_ashrrev_i32_e32 v83, 31, v82
	s_lshl_b32 s48, s56, 2
	v_lshlrev_b64 v[82:83], 6, v[82:83]
	s_ashr_i32 s49, s48, 31
	v_lshl_add_u64 v[82:83], s[14:15], 0, v[82:83]
	v_lshl_add_u64 v[82:83], s[48:49], 2, v[82:83]
	s_lshl_b32 s48, s61, 2
	s_mov_b32 s49, s19
	s_waitcnt lgkmcnt(0)
	v_add_f32_e32 v84, v86, v87
	v_lshl_add_u64 v[82:83], v[82:83], 0, s[48:49]
	global_store_dword v[82:83], v84, off sc1
.LBB0_961:
	s_or_b64 exec, exec, s[6:7]
	v_mul_f32_e32 v82, v79, v79
	v_mul_f32_e32 v83, v81, v81
	v_fmac_f32_e32 v82, v78, v78
	v_fmac_f32_e32 v83, v80, v80
	v_add_f32_e32 v82, v82, v83
	v_mul_f32_e32 v83, v75, v75
	v_fmac_f32_e32 v83, v74, v74
	v_cvt_pk_bf16_f32 v78, v78, v79
	v_cvt_pk_bf16_f32 v79, v80, v81
	v_cvt_pk_bf16_f32 v80, v74, v75
	v_mul_f32_e32 v74, v71, v71
	v_mul_f32_e32 v75, v73, v73
	v_fmac_f32_e32 v74, v70, v70
	v_fmac_f32_e32 v75, v72, v72
	v_add_f32_e32 v74, v74, v75
	v_mul_f32_e32 v75, v67, v67
	v_fmac_f32_e32 v75, v66, v66
	v_add_f32_e32 v82, v82, v83
	v_mul_f32_e32 v83, v77, v77
	v_add_f32_e32 v74, v74, v75
	v_mul_f32_e32 v75, v69, v69
	v_fmac_f32_e32 v83, v76, v76
	v_fmac_f32_e32 v75, v68, v68
	v_add_f32_e32 v82, v83, v82
	v_add_f32_e32 v74, v75, v74
	v_add_f32_e32 v75, v82, v74
	v_cvt_pk_bf16_f32 v81, v76, v77
	ds_bpermute_b32 v76, v148, v75
	v_add_co_u32_e64 v82, s[6:7], s78, v142
	s_nop 1
	v_addc_co_u32_e64 v83, s[6:7], 0, v143, s[6:7]
	v_cvt_pk_bf16_f32 v74, v70, v71
	s_waitcnt lgkmcnt(0)
	v_add_f32_e32 v70, v75, v76
	ds_bpermute_b32 v71, v141, v70
	v_cvt_pk_bf16_f32 v75, v72, v73
	v_cvt_pk_bf16_f32 v76, v66, v67
	v_cvt_pk_bf16_f32 v77, v68, v69
	v_mov_b32_e32 v238, v74
	v_mov_b32_e32 v239, v75
	v_mov_b32_e32 v240, v76
	v_mov_b32_e32 v241, v77
	v_mov_b32_dpp v74, v78 row_ror:8 row_mask:0xf bank_mask:0x3
	v_mov_b32_dpp v75, v79 row_ror:8 row_mask:0xf bank_mask:0x3
	v_mov_b32_dpp v76, v80 row_ror:8 row_mask:0xf bank_mask:0x3
	v_mov_b32_dpp v77, v81 row_ror:8 row_mask:0xf bank_mask:0x3
	v_mov_b32_dpp v78, v238 row_ror:8 row_mask:0xf bank_mask:0xc
	v_mov_b32_dpp v79, v239 row_ror:8 row_mask:0xf bank_mask:0xc
	v_mov_b32_dpp v80, v240 row_ror:8 row_mask:0xf bank_mask:0xc
	v_mov_b32_dpp v81, v241 row_ror:8 row_mask:0xf bank_mask:0xc
	v_lshl_add_u64 v[246:247], v[82:83], 0, v[242:243]
	v_lshl_add_u64 v[248:249], v[82:83], 0, v[244:245]
	global_store_dwordx4 v[246:247], v[78:81], off sc1 nt
	global_store_dwordx4 v[248:249], v[74:77], off sc1 nt
	s_nop 1
	s_and_saveexec_b64 s[6:7], vcc
	s_cbranch_execz .LBB0_963
	v_add3_u32 v66, s8, 48, v140
	v_ashrrev_i32_e32 v67, 31, v66
	s_lshl_b32 s48, s56, 2
	v_lshlrev_b64 v[66:67], 6, v[66:67]
	s_ashr_i32 s49, s48, 31
	v_lshl_add_u64 v[66:67], s[14:15], 0, v[66:67]
	v_lshl_add_u64 v[66:67], s[48:49], 2, v[66:67]
	s_lshl_b32 s48, s61, 2
	s_mov_b32 s49, s19
	s_waitcnt lgkmcnt(0)
	v_add_f32_e32 v68, v70, v71
	v_lshl_add_u64 v[66:67], v[66:67], 0, s[48:49]
	global_store_dword v[66:67], v68, off sc1
; __device__ __forceinline__ float shx(float v, int lane, int m) { return __builtin_bit_cast(float, __builtin_amdgcn_ds_bpermute((lane ^ m) << 2, __builtin_bit_cast(int, v))); }
; __device__ __forceinline__ u32x4 pack8(const f32x4 v0, const f32x4 v1) { u32x4 w; w.x = cvt_pk_bf16(v0[0], v0[1]); w.y = cvt_pk_bf16(v0[2], v0[3]); w.z = cvt_pk_bf16(v1[0], v1[1]); w.w = cvt_pk_bf16(v1[2], v1[3]); return w; }
;     __device__ __forceinline__ void operator()(f32x4 (&acc)[2][2][4][2], const Unit& u, int wr, int wc, int fr, int fq) const {
;     ...
;             for (int m = 0; m < 4; ++m) { bf16_t* rowp = base + (size_t)(ai * HALF + m * 16) * u.ldo; float s = 0.f;
; #pragma unroll
;                 for (int bj = 0; bj < 2; ++bj) { const f32x4 v0 = acc[ai][bj][m][0], v1 = acc[ai][bj][m][1];
;                     s += (v0[0] * v0[0] + v0[1] * v0[1]) + (v0[2] * v0[2] + v0[3] * v0[3]) + (v1[0] * v1[0] + v1[1] * v1[1]) + (v1[2] * v1[2] + v1[3] * v1[3]);
;                     __builtin_nontemporal_store(pack8(v0, v1), (u32x4*)(rowp + bj * HALF)); }
;                 s += shx(s, lane_, 16); s += shx(s, lane_, 32);
;                 if (fq == 0) SSP[(size_t)(u.z + ai * HALF + wr * 64 + m * 16 + fr) * 16 + u.pn * 4 + wc] = s; }
.LBB0_963:
	s_or_b64 exec, exec, s[6:7]
	v_mul_f32_e32 v66, v63, v63
	v_mul_f32_e32 v67, v65, v65
	v_fmac_f32_e32 v66, v62, v62
	v_fmac_f32_e32 v67, v64, v64
	v_add_f32_e32 v66, v66, v67
	v_mul_f32_e32 v67, v59, v59
	v_fmac_f32_e32 v67, v58, v58
	v_cvt_pk_bf16_f32 v62, v62, v63
	v_cvt_pk_bf16_f32 v63, v64, v65
	v_cvt_pk_bf16_f32 v64, v58, v59
	v_mul_f32_e32 v58, v55, v55
	v_mul_f32_e32 v59, v57, v57
	v_fmac_f32_e32 v58, v54, v54
	v_fmac_f32_e32 v59, v56, v56
	v_add_f32_e32 v58, v58, v59
	v_mul_f32_e32 v59, v51, v51
	v_fmac_f32_e32 v59, v50, v50
	v_add_f32_e32 v66, v66, v67
	v_mul_f32_e32 v67, v61, v61
	v_add_f32_e32 v58, v58, v59
	v_mul_f32_e32 v59, v53, v53
	v_fmac_f32_e32 v67, v60, v60
	v_fmac_f32_e32 v59, v52, v52
	v_add_f32_e32 v66, v67, v66
	v_add_f32_e32 v58, v59, v58
	v_add_f32_e32 v59, v66, v58
	v_cvt_pk_bf16_f32 v65, v60, v61
	ds_bpermute_b32 v60, v148, v59
	v_add_co_u32_e64 v66, s[6:7], s80, v142
	s_nop 1
	v_addc_co_u32_e64 v67, s[6:7], 0, v143, s[6:7]
	v_cvt_pk_bf16_f32 v58, v54, v55
	s_waitcnt lgkmcnt(0)
	v_add_f32_e32 v54, v59, v60
	ds_bpermute_b32 v55, v141, v54
	v_cvt_pk_bf16_f32 v59, v56, v57
	v_cvt_pk_bf16_f32 v60, v50, v51
	v_cvt_pk_bf16_f32 v61, v52, v53
	v_mov_b32_e32 v238, v58
	v_mov_b32_e32 v239, v59
	v_mov_b32_e32 v240, v60
	v_mov_b32_e32 v241, v61
	v_mov_b32_dpp v58, v62 row_ror:8 row_mask:0xf bank_mask:0x3
	v_mov_b32_dpp v59, v63 row_ror:8 row_mask:0xf bank_mask:0x3
	v_mov_b32_dpp v60, v64 row_ror:8 row_mask:0xf bank_mask:0x3
	v_mov_b32_dpp v61, v65 row_ror:8 row_mask:0xf bank_mask:0x3
	v_mov_b32_dpp v62, v238 row_ror:8 row_mask:0xf bank_mask:0xc
	v_mov_b32_dpp v63, v239 row_ror:8 row_mask:0xf bank_mask:0xc
	v_mov_b32_dpp v64, v240 row_ror:8 row_mask:0xf bank_mask:0xc
	v_mov_b32_dpp v65, v241 row_ror:8 row_mask:0xf bank_mask:0xc
	v_lshl_add_u64 v[246:247], v[66:67], 0, v[242:243]
	v_lshl_add_u64 v[248:249], v[66:67], 0, v[244:245]
	global_store_dwordx4 v[246:247], v[62:65], off sc1 nt
	global_store_dwordx4 v[248:249], v[58:61], off sc1 nt
	s_nop 1
	s_and_saveexec_b64 s[6:7], vcc
	s_cbranch_execz .LBB0_965
	s_add_i32 s2, s8, 0x80
	v_add_u32_e32 v50, s2, v140
	v_ashrrev_i32_e32 v51, 31, v50
	s_lshl_b32 s48, s56, 2
	v_lshlrev_b64 v[50:51], 6, v[50:51]
	s_ashr_i32 s49, s48, 31
	v_lshl_add_u64 v[50:51], s[14:15], 0, v[50:51]
	v_lshl_add_u64 v[50:51], s[48:49], 2, v[50:51]
	s_lshl_b32 s48, s61, 2
	s_mov_b32 s49, s19
	s_waitcnt lgkmcnt(0)
	v_add_f32_e32 v52, v54, v55
	v_lshl_add_u64 v[50:51], v[50:51], 0, s[48:49]
	global_store_dword v[50:51], v52, off sc1
.LBB0_965:
	s_or_b64 exec, exec, s[6:7]
	v_mul_f32_e32 v50, v47, v47
	v_mul_f32_e32 v51, v49, v49
	v_fmac_f32_e32 v50, v46, v46
	v_fmac_f32_e32 v51, v48, v48
	v_add_f32_e32 v50, v50, v51
	v_mul_f32_e32 v51, v43, v43
	v_fmac_f32_e32 v51, v42, v42
	v_cvt_pk_bf16_f32 v46, v46, v47
	v_cvt_pk_bf16_f32 v47, v48, v49
	v_cvt_pk_bf16_f32 v48, v42, v43
	v_mul_f32_e32 v42, v39, v39
	v_mul_f32_e32 v43, v41, v41
	v_fmac_f32_e32 v42, v38, v38
	v_fmac_f32_e32 v43, v40, v40
	v_add_f32_e32 v42, v42, v43
	v_mul_f32_e32 v43, v35, v35
	v_fmac_f32_e32 v43, v34, v34
	v_add_f32_e32 v50, v50, v51
	v_mul_f32_e32 v51, v45, v45
	v_add_f32_e32 v42, v42, v43
	v_mul_f32_e32 v43, v37, v37
	v_fmac_f32_e32 v51, v44, v44
	v_fmac_f32_e32 v43, v36, v36
	v_add_f32_e32 v50, v51, v50
	v_add_f32_e32 v42, v43, v42
	v_add_f32_e32 v43, v50, v42
	v_cvt_pk_bf16_f32 v49, v44, v45
	ds_bpermute_b32 v44, v148, v43
	v_add_co_u32_e64 v50, s[6:7], s81, v142
	s_nop 1
	v_addc_co_u32_e64 v51, s[6:7], 0, v143, s[6:7]
	v_cvt_pk_bf16_f32 v42, v38, v39
	s_waitcnt lgkmcnt(0)
	v_add_f32_e32 v38, v43, v44
	ds_bpermute_b32 v39, v141, v38
	v_cvt_pk_bf16_f32 v43, v40, v41
	v_cvt_pk_bf16_f32 v44, v34, v35
	v_cvt_pk_bf16_f32 v45, v36, v37
	v_mov_b32_e32 v238, v42
	v_mov_b32_e32 v239, v43
	v_mov_b32_e32 v240, v44
	v_mov_b32_e32 v241, v45
	v_mov_b32_dpp v42, v46 row_ror:8 row_mask:0xf bank_mask:0x3
	v_mov_b32_dpp v43, v47 row_ror:8 row_mask:0xf bank_mask:0x3
	v_mov_b32_dpp v44, v48 row_ror:8 row_mask:0xf bank_mask:0x3
	v_mov_b32_dpp v45, v49 row_ror:8 row_mask:0xf bank_mask:0x3
	v_mov_b32_dpp v46, v238 row_ror:8 row_mask:0xf bank_mask:0xc
	v_mov_b32_dpp v47, v239 row_ror:8 row_mask:0xf bank_mask:0xc
	v_mov_b32_dpp v48, v240 row_ror:8 row_mask:0xf bank_mask:0xc
	v_mov_b32_dpp v49, v241 row_ror:8 row_mask:0xf bank_mask:0xc
	v_lshl_add_u64 v[246:247], v[50:51], 0, v[242:243]
	v_lshl_add_u64 v[248:249], v[50:51], 0, v[244:245]
	global_store_dwordx4 v[246:247], v[46:49], off sc1 nt
	global_store_dwordx4 v[248:249], v[42:45], off sc1 nt
	s_nop 1
	s_and_saveexec_b64 s[6:7], vcc
	s_cbranch_execz .LBB0_967
	s_add_i32 s2, s8, 0x90
	v_add_u32_e32 v34, s2, v140
	v_ashrrev_i32_e32 v35, 31, v34
	s_lshl_b32 s48, s56, 2
	v_lshlrev_b64 v[34:35], 6, v[34:35]
	s_ashr_i32 s49, s48, 31
	v_lshl_add_u64 v[34:35], s[14:15], 0, v[34:35]
	v_lshl_add_u64 v[34:35], s[48:49], 2, v[34:35]
	s_lshl_b32 s48, s61, 2
	s_mov_b32 s49, s19
	s_waitcnt lgkmcnt(0)
	v_add_f32_e32 v36, v38, v39
	v_lshl_add_u64 v[34:35], v[34:35], 0, s[48:49]
	global_store_dword v[34:35], v36, off sc1
; __device__ __forceinline__ float shx(float v, int lane, int m) { return __builtin_bit_cast(float, __builtin_amdgcn_ds_bpermute((lane ^ m) << 2, __builtin_bit_cast(int, v))); }
; __device__ __forceinline__ u32x4 pack8(const f32x4 v0, const f32x4 v1) { u32x4 w; w.x = cvt_pk_bf16(v0[0], v0[1]); w.y = cvt_pk_bf16(v0[2], v0[3]); w.z = cvt_pk_bf16(v1[0], v1[1]); w.w = cvt_pk_bf16(v1[2], v1[3]); return w; }
;     __device__ __forceinline__ void operator()(f32x4 (&acc)[2][2][4][2], const Unit& u, int wr, int wc, int fr, int fq) const {
;     ...
;             for (int m = 0; m < 4; ++m) { bf16_t* rowp = base + (size_t)(ai * HALF + m * 16) * u.ldo; float s = 0.f;
; #pragma unroll
;                 for (int bj = 0; bj < 2; ++bj) { const f32x4 v0 = acc[ai][bj][m][0], v1 = acc[ai][bj][m][1];
;                     s += (v0[0] * v0[0] + v0[1] * v0[1]) + (v0[2] * v0[2] + v0[3] * v0[3]) + (v1[0] * v1[0] + v1[1] * v1[1]) + (v1[2] * v1[2] + v1[3] * v1[3]);
;                     __builtin_nontemporal_store(pack8(v0, v1), (u32x4*)(rowp + bj * HALF)); }
;                 s += shx(s, lane_, 16); s += shx(s, lane_, 32);
;                 if (fq == 0) SSP[(size_t)(u.z + ai * HALF + wr * 64 + m * 16 + fr) * 16 + u.pn * 4 + wc] = s; }
.LBB0_967:
	s_or_b64 exec, exec, s[6:7]
	v_mul_f32_e32 v34, v31, v31
	v_mul_f32_e32 v35, v33, v33
	v_fmac_f32_e32 v34, v30, v30
	v_fmac_f32_e32 v35, v32, v32
	v_add_f32_e32 v34, v34, v35
	v_mul_f32_e32 v35, v27, v27
	v_fmac_f32_e32 v35, v26, v26
	v_cvt_pk_bf16_f32 v30, v30, v31
	v_cvt_pk_bf16_f32 v31, v32, v33
	v_cvt_pk_bf16_f32 v32, v26, v27
	v_mul_f32_e32 v26, v23, v23
	v_mul_f32_e32 v27, v25, v25
	v_fmac_f32_e32 v26, v22, v22
	v_fmac_f32_e32 v27, v24, v24
	v_add_f32_e32 v26, v26, v27
	v_mul_f32_e32 v27, v19, v19
	v_fmac_f32_e32 v27, v18, v18
	v_add_f32_e32 v34, v34, v35
	v_mul_f32_e32 v35, v29, v29
	v_add_f32_e32 v26, v26, v27
	v_mul_f32_e32 v27, v21, v21
	v_fmac_f32_e32 v35, v28, v28
	v_fmac_f32_e32 v27, v20, v20
	v_add_f32_e32 v34, v35, v34
	v_add_f32_e32 v26, v27, v26
	v_add_f32_e32 v27, v34, v26
	v_cvt_pk_bf16_f32 v33, v28, v29
	ds_bpermute_b32 v28, v148, v27
	v_add_co_u32_e64 v34, s[6:7], s82, v142
	s_nop 1
	v_addc_co_u32_e64 v35, s[6:7], 0, v143, s[6:7]
	v_cvt_pk_bf16_f32 v26, v22, v23
	s_waitcnt lgkmcnt(0)
	v_add_f32_e32 v22, v27, v28
	ds_bpermute_b32 v23, v141, v22
	v_cvt_pk_bf16_f32 v27, v24, v25
	v_cvt_pk_bf16_f32 v28, v18, v19
	v_cvt_pk_bf16_f32 v29, v20, v21
	v_mov_b32_e32 v238, v26
	v_mov_b32_e32 v239, v27
	v_mov_b32_e32 v240, v28
	v_mov_b32_e32 v241, v29
	v_mov_b32_dpp v26, v30 row_ror:8 row_mask:0xf bank_mask:0x3
	v_mov_b32_dpp v27, v31 row_ror:8 row_mask:0xf bank_mask:0x3
	v_mov_b32_dpp v28, v32 row_ror:8 row_mask:0xf bank_mask:0x3
	v_mov_b32_dpp v29, v33 row_ror:8 row_mask:0xf bank_mask:0x3
	v_mov_b32_dpp v30, v238 row_ror:8 row_mask:0xf bank_mask:0xc
	v_mov_b32_dpp v31, v239 row_ror:8 row_mask:0xf bank_mask:0xc
	v_mov_b32_dpp v32, v240 row_ror:8 row_mask:0xf bank_mask:0xc
	v_mov_b32_dpp v33, v241 row_ror:8 row_mask:0xf bank_mask:0xc
	v_lshl_add_u64 v[246:247], v[34:35], 0, v[242:243]
	v_lshl_add_u64 v[248:249], v[34:35], 0, v[244:245]
	global_store_dwordx4 v[246:247], v[30:33], off sc1 nt
	global_store_dwordx4 v[248:249], v[26:29], off sc1 nt
	s_nop 1
	s_and_saveexec_b64 s[6:7], vcc
	s_cbranch_execz .LBB0_969
	s_add_i32 s2, s8, 0xa0
	v_add_u32_e32 v18, s2, v140
	v_ashrrev_i32_e32 v19, 31, v18
	s_lshl_b32 s48, s56, 2
	v_lshlrev_b64 v[18:19], 6, v[18:19]
	s_ashr_i32 s49, s48, 31
	v_lshl_add_u64 v[18:19], s[14:15], 0, v[18:19]
	v_lshl_add_u64 v[18:19], s[48:49], 2, v[18:19]
	s_lshl_b32 s48, s61, 2
	s_mov_b32 s49, s19
	s_waitcnt lgkmcnt(0)
	v_add_f32_e32 v20, v22, v23
	v_lshl_add_u64 v[18:19], v[18:19], 0, s[48:49]
	global_store_dword v[18:19], v20, off sc1
.LBB0_969:
	s_or_b64 exec, exec, s[6:7]
	v_mul_f32_e32 v18, v15, v15
	v_mul_f32_e32 v19, v17, v17
	v_fmac_f32_e32 v18, v14, v14
	v_fmac_f32_e32 v19, v16, v16
	v_add_f32_e32 v18, v18, v19
	v_mul_f32_e32 v19, v11, v11
	v_fmac_f32_e32 v19, v10, v10
	v_cvt_pk_bf16_f32 v14, v14, v15
	v_cvt_pk_bf16_f32 v15, v16, v17
	v_cvt_pk_bf16_f32 v16, v10, v11
	v_mul_f32_e32 v10, v7, v7
	v_mul_f32_e32 v11, v9, v9
	v_fmac_f32_e32 v10, v6, v6
	v_fmac_f32_e32 v11, v8, v8
	v_add_f32_e32 v10, v10, v11
	v_mul_f32_e32 v11, v3, v3
	v_fmac_f32_e32 v11, v2, v2
	v_add_f32_e32 v18, v18, v19
	v_mul_f32_e32 v19, v13, v13
	v_add_f32_e32 v10, v10, v11
	v_mul_f32_e32 v11, v5, v5
	v_fmac_f32_e32 v19, v12, v12
	v_fmac_f32_e32 v11, v4, v4
	v_add_f32_e32 v18, v19, v18
	v_add_f32_e32 v10, v11, v10
	v_add_f32_e32 v11, v18, v10
	v_cvt_pk_bf16_f32 v17, v12, v13
	ds_bpermute_b32 v12, v148, v11
	v_add_co_u32_e64 v18, s[6:7], s83, v142
	s_nop 1
	v_addc_co_u32_e64 v19, s[6:7], 0, v143, s[6:7]
	v_cvt_pk_bf16_f32 v10, v6, v7
	s_waitcnt lgkmcnt(0)
	v_add_f32_e32 v6, v11, v12
	ds_bpermute_b32 v7, v141, v6
	v_cvt_pk_bf16_f32 v11, v8, v9
	v_cvt_pk_bf16_f32 v12, v2, v3
	v_cvt_pk_bf16_f32 v13, v4, v5
	v_mov_b32_e32 v238, v10
	v_mov_b32_e32 v239, v11
	v_mov_b32_e32 v240, v12
	v_mov_b32_e32 v241, v13
	v_mov_b32_dpp v10, v14 row_ror:8 row_mask:0xf bank_mask:0x3
	v_mov_b32_dpp v11, v15 row_ror:8 row_mask:0xf bank_mask:0x3
	v_mov_b32_dpp v12, v16 row_ror:8 row_mask:0xf bank_mask:0x3
	v_mov_b32_dpp v13, v17 row_ror:8 row_mask:0xf bank_mask:0x3
	v_mov_b32_dpp v14, v238 row_ror:8 row_mask:0xf bank_mask:0xc
	v_mov_b32_dpp v15, v239 row_ror:8 row_mask:0xf bank_mask:0xc
	v_mov_b32_dpp v16, v240 row_ror:8 row_mask:0xf bank_mask:0xc
	v_mov_b32_dpp v17, v241 row_ror:8 row_mask:0xf bank_mask:0xc
	v_lshl_add_u64 v[246:247], v[18:19], 0, v[242:243]
	v_lshl_add_u64 v[248:249], v[18:19], 0, v[244:245]
	global_store_dwordx4 v[246:247], v[14:17], off sc1 nt
	global_store_dwordx4 v[248:249], v[10:13], off sc1 nt
	s_nop 1
	s_and_saveexec_b64 s[6:7], vcc
	s_cbranch_execz .LBB0_971
	s_add_i32 s2, s8, 0xb0
	v_add_u32_e32 v2, s2, v140
	v_ashrrev_i32_e32 v3, 31, v2
	s_lshl_b32 s48, s56, 2
	v_lshlrev_b64 v[2:3], 6, v[2:3]
	s_ashr_i32 s49, s48, 31
	v_lshl_add_u64 v[2:3], s[14:15], 0, v[2:3]
	v_lshl_add_u64 v[2:3], s[48:49], 2, v[2:3]
	s_lshl_b32 s48, s61, 2
	s_mov_b32 s49, s19
	s_waitcnt lgkmcnt(0)
	v_add_f32_e32 v4, v6, v7
	v_lshl_add_u64 v[2:3], v[2:3], 0, s[48:49]
	global_store_dword v[2:3], v4, off sc1

; __device__ __forceinline__ unsigned xb_add(unsigned* p, unsigned v) { return __hip_atomic_fetch_add(p, v, __ATOMIC_RELAXED, __HIP_MEMORY_SCOPE_AGENT); }
; __device__ __forceinline__ void xcd_barrier(const XcdBarrier& b) {
;     ...
;         const unsigned old = xb_add(&bar[XB_XSUB(b.x)], 1u);
;         const unsigned gen = old / nloc;
;         if (old + 1u == (gen + 1u) * nloc) {
;             __builtin_amdgcn_fence(__ATOMIC_RELEASE, "agent");
;             asm volatile("s_waitcnt vmcnt(0)" ::: "memory");
;             const unsigned og = xb_add(&bar[XB_TOP], 1u);
.LBB0_1006:
	s_andn2_saveexec_b64 s[8:9], s[8:9]
	s_cbranch_execz .LBB0_1026
	s_mov_b64 s[8:9], exec
	s_waitcnt lgkmcnt(0)
	s_waitcnt vmcnt(0)
	buffer_inv sc1
	v_mbcnt_lo_u32_b32 v1, s8, 0
	v_mbcnt_hi_u32_b32 v1, s9, v1
	v_cmp_eq_u32_e32 vcc, 0, v1
	s_and_saveexec_b64 s[10:11], vcc
	s_cbranch_execz .LBB0_1009
	s_bcnt1_i32_b64 s8, s[8:9]
	v_mov_b32_e32 v2, 0x7000
	v_mov_b32_e32 v3, s8
	global_atomic_add v2, v2, v3, s[4:5] offset:1024 sc0
